# GEMM units (out-proj, F2, mix, up, down): first-phase ds_read_b128 fragment loads issued at the K-loop exit, overlapping the epilogue
# baseline (speedup 1.0000x reference)
; __device__ __forceinline__ unsigned cvt_pk_bf16(float lo, float hi) { const f32x2 v = {lo, hi}; return __builtin_bit_cast(unsigned, __builtin_convertvector(v, bf16x2_t)); }
; #define WS_SHR(c) v += __builtin_bit_cast(float, __builtin_amdgcn_update_dpp(0, __builtin_bit_cast(int, v), c, 0xf, 0xf, true))
; __device__ __forceinline__ float wave_sum(float v, int lane) {
;     (void)lane;
;     ...
;     WS_SHR(0x111); WS_SHR(0x112); WS_SHR(0x114); WS_SHR(0x118);
;     ...
;     v += __builtin_bit_cast(float, __builtin_amdgcn_update_dpp(0, __builtin_bit_cast(int, v), 0x142, 0xa, 0xf, false));
;     v += __builtin_bit_cast(float, __builtin_amdgcn_update_dpp(0, __builtin_bit_cast(int, v), 0x143, 0xc, 0xf, false));
;     return __builtin_bit_cast(float, __builtin_amdgcn_readlane(__builtin_bit_cast(int, v), 63));
; __device__ __forceinline__ void norm_mod_phase(Frame& F, int L, const float* gvec, int sh_chunk, int nrows, const float* pg, const float* pg2, const float* xlat, const float* xctx) {
;     ...
;         for (int j = 0; j < 8; ++j) ss += (v[j].x * v[j].x + v[j].y * v[j].y) + (v[j].z * v[j].z + v[j].w * v[j].w);
;         const float rstd = rsqrtf(wave_sum(ss, lane) * (1.0f / D) + EPS);
;         u32x2* o = (u32x2*)(A + (size_t)r * D) + lane;
; #pragma unroll
;         for (int j = 0; j < 8; ++j) { const f32x4 y = v[j] * rstd * vq[64 * j] + vq[64 * j + D / 4];
;             u32x2 w; w.x = cvt_pk_bf16(y.x, y.y); w.y = cvt_pk_bf16(y.z, y.w); o[64 * j] = w; }
.LBB0_211:
	v_pk_mul_f32 v[16:17], v[34:35], v[34:35]
	v_pk_mul_f32 v[20:21], v[38:39], v[38:39]
	v_pk_mul_f32 v[24:25], v[36:37], v[36:37]
	v_pk_mul_f32 v[28:29], v[32:33], v[32:33]
	v_pk_mul_f32 v[8:9], v[42:43], v[42:43]
	v_pk_mul_f32 v[12:13], v[40:41], v[40:41]
	v_mov_b32_e32 v142, v28
	v_mov_b32_e32 v143, v24
	v_mov_b32_e32 v24, v29
	v_mov_b32_e32 v28, v16
	v_mov_b32_e32 v29, v20
	v_mov_b32_e32 v20, v17
	v_pk_add_f32 v[16:17], v[28:29], v[20:21]
	v_pk_mov_b32 v[20:21], v[12:13], v[8:9] op_sel:[1,0]
	v_mov_b32_e32 v13, v9
	v_pk_add_f32 v[8:9], v[20:21], v[12:13]
	v_pk_add_f32 v[24:25], v[142:143], v[24:25]
	v_pk_add_f32 v[8:9], v[8:9], v[8:9] op_sel_hi:[0,1]
	v_mul_f32_e32 v8, v44, v44
	v_pk_add_f32 v[16:17], v[24:25], v[16:17]
	v_pk_fma_f32 v[12:13], v[44:45], v[44:45], v[8:9] op_sel_hi:[1,1,0]
	v_mul_f32_e32 v8, v46, v46
	v_pk_add_f32 v[16:17], v[16:17], v[16:17] op_sel_hi:[0,1]
	v_pk_fma_f32 v[20:21], v[46:47], v[46:47], v[8:9] op_sel_hi:[1,1,0]
	v_mul_f32_e32 v12, v48, v48
	v_mul_f32_e32 v20, v49, v49
	v_mul_f32_e32 v8, v50, v50
	v_mul_f32_e32 v16, v51, v51
	v_pk_mul_f32 v[0:1], v[54:55], v[54:55]
	v_pk_mul_f32 v[4:5], v[52:53], v[52:53]
	v_pk_add_f32 v[12:13], v[12:13], v[20:21]
	v_pk_add_f32 v[8:9], v[8:9], v[16:17]
	s_ashr_i32 s11, s10, 31
	v_pk_add_f32 v[8:9], v[12:13], v[8:9]
	v_pk_mov_b32 v[12:13], v[4:5], v[0:1] op_sel:[1,0]
	v_mov_b32_e32 v5, v1
	v_pk_add_f32 v[0:1], v[12:13], v[4:5]
	v_pk_add_f32 v[8:9], v[8:9], v[8:9] op_sel_hi:[0,1]
	v_pk_add_f32 v[0:1], v[0:1], v[0:1] op_sel_hi:[0,1]
	v_mul_f32_e32 v0, v56, v56
	v_pk_fma_f32 v[4:5], v[56:57], v[56:57], v[0:1] op_sel_hi:[1,1,0]
	v_mul_f32_e32 v0, v58, v58
	v_pk_fma_f32 v[12:13], v[58:59], v[58:59], v[0:1] op_sel_hi:[1,1,0]
	v_mul_f32_e32 v4, v60, v60
	v_mul_f32_e32 v12, v61, v61
	v_mul_f32_e32 v0, v62, v62
	v_mul_f32_e32 v8, v63, v63
	v_pk_add_f32 v[4:5], v[4:5], v[12:13]
	v_pk_add_f32 v[0:1], v[0:1], v[8:9]
	s_add_i32 s26, s26, 8
	v_pk_add_f32 v[0:1], v[4:5], v[0:1]
	s_nop 0
	v_add_f32_e32 v0, v0, v1
	v_mov_b32_e32 v1, v177
	s_nop 0
	v_add_f32_dpp v0, v0, v0 row_shr:1 row_mask:0xf bank_mask:0xf bound_ctrl:1
	s_nop 1
	v_add_f32_dpp v0, v0, v0 row_shr:2 row_mask:0xf bank_mask:0xf bound_ctrl:1
	s_nop 1
	v_add_f32_dpp v0, v0, v0 row_shr:4 row_mask:0xf bank_mask:0xf bound_ctrl:1
	s_nop 1
	v_add_f32_dpp v0, v0, v0 row_shr:8 row_mask:0xf bank_mask:0xf bound_ctrl:1
	s_nop 1
	v_mov_b32_dpp v1, v0 row_bcast:15 row_mask:0xa bank_mask:0xf
	v_add_f32_e32 v0, v0, v1
	v_mov_b32_e32 v1, v177
	s_nop 1
	v_mov_b32_dpp v1, v0 row_bcast:31 row_mask:0xc bank_mask:0xf
	v_add_f32_e32 v0, v0, v1
	s_nop 0
	v_readlane_b32 s4, v0, 63
	s_nop 1
	v_fma_f32 v0, s4, v241, v238
	v_cmp_gt_f32_e32 vcc, s85, v0
	v_mul_f32_e32 v1, 0x4b800000, v0
	s_lshl_b64 s[4:5], s[10:11], 12
	v_cndmask_b32_e32 v0, v0, v1, vcc
	v_rsq_f32_e32 v0, v0
	s_nop 0
	v_mul_f32_e32 v1, 0x45800000, v0
	v_cndmask_b32_e32 v4, v0, v1, vcc
	v_pk_mul_f32 v[8:9], v[32:33], v[4:5] op_sel_hi:[1,0]
	v_pk_mul_f32 v[12:13], v[34:35], v[4:5] op_sel_hi:[1,0]
	ds_read_b128 v[32:35], v196
	ds_read_b128 v[142:145], v196 offset:8192
	v_lshl_add_u64 v[0:1], v[66:67], 0, s[4:5]
	v_readlane_b32 s4, v254, 42
	s_cmp_lt_i32 s26, s4
	s_waitcnt lgkmcnt(0)
	v_pk_fma_f32 v[12:13], v[34:35], v[12:13], v[144:145]
	v_pk_fma_f32 v[8:9], v[32:33], v[8:9], v[142:143]
	s_nop 0
	v_cvt_pk_bf16_f32 v8, v8, v9
	v_cvt_pk_bf16_f32 v9, v12, v13
	global_store_dwordx2 v[0:1], v[8:9], off sc1
	v_pk_mul_f32 v[8:9], v[36:37], v[4:5] op_sel_hi:[1,0]
	v_pk_mul_f32 v[12:13], v[38:39], v[4:5] op_sel_hi:[1,0]
	ds_read_b128 v[32:35], v196 offset:1024
	ds_read_b128 v[36:39], v196 offset:9216
	s_waitcnt lgkmcnt(0)
	v_pk_fma_f32 v[12:13], v[34:35], v[12:13], v[38:39]
	v_pk_fma_f32 v[8:9], v[32:33], v[8:9], v[36:37]
	s_nop 0
	v_cvt_pk_bf16_f32 v8, v8, v9
	v_cvt_pk_bf16_f32 v9, v12, v13
	global_store_dwordx2 v[0:1], v[8:9], off offset:512 sc1
	ds_read_b128 v[32:35], v196 offset:2048
	ds_read_b128 v[36:39], v196 offset:10240
	v_pk_mul_f32 v[8:9], v[40:41], v[4:5] op_sel_hi:[1,0]
	v_pk_mul_f32 v[12:13], v[42:43], v[4:5] op_sel_hi:[1,0]
	v_mov_b32_e32 v40, v31
	v_mov_b32_e32 v41, v27
	s_waitcnt lgkmcnt(0)
	v_pk_fma_f32 v[12:13], v[34:35], v[12:13], v[38:39]
	v_pk_fma_f32 v[8:9], v[32:33], v[8:9], v[36:37]
	v_mov_b32_e32 v42, v23
	v_cvt_pk_bf16_f32 v8, v8, v9
	v_cvt_pk_bf16_f32 v9, v12, v13
	global_store_dwordx2 v[0:1], v[8:9], off offset:1024 sc1
	ds_read_b128 v[32:35], v196 offset:3072
	ds_read_b128 v[36:39], v196 offset:11264
	v_pk_mul_f32 v[8:9], v[44:45], v[4:5] op_sel_hi:[1,0]
	v_pk_mul_f32 v[12:13], v[46:47], v[4:5] op_sel_hi:[1,0]
	v_mov_b32_e32 v43, v19
	v_mov_b32_e32 v44, v15
	s_waitcnt lgkmcnt(0)
	v_pk_fma_f32 v[12:13], v[12:13], v[34:35], v[38:39]
	v_pk_fma_f32 v[8:9], v[8:9], v[32:33], v[36:37]
	v_mov_b32_e32 v45, v11
	v_cvt_pk_bf16_f32 v8, v8, v9
	v_cvt_pk_bf16_f32 v9, v12, v13
	global_store_dwordx2 v[0:1], v[8:9], off offset:1536 sc1
	ds_read_b128 v[32:35], v196 offset:4096
	ds_read_b128 v[36:39], v196 offset:12288
	v_pk_mul_f32 v[8:9], v[48:49], v[4:5] op_sel_hi:[1,0]
	v_pk_mul_f32 v[12:13], v[50:51], v[4:5] op_sel_hi:[1,0]
	v_mov_b32_e32 v46, v7
	v_mov_b32_e32 v47, v3
	s_waitcnt lgkmcnt(0)
	v_pk_fma_f32 v[12:13], v[12:13], v[34:35], v[38:39]
	v_pk_fma_f32 v[8:9], v[8:9], v[32:33], v[36:37]
	s_nop 0
	v_cvt_pk_bf16_f32 v8, v8, v9
	v_cvt_pk_bf16_f32 v9, v12, v13
	global_store_dwordx2 v[0:1], v[8:9], off offset:2048 sc1
	ds_read_b128 v[32:35], v196 offset:5120
	ds_read_b128 v[36:39], v196 offset:13312
	v_pk_mul_f32 v[8:9], v[52:53], v[4:5] op_sel_hi:[1,0]
	v_pk_mul_f32 v[12:13], v[54:55], v[4:5] op_sel_hi:[1,0]
	s_waitcnt lgkmcnt(0)
	v_pk_fma_f32 v[8:9], v[8:9], v[32:33], v[36:37]
	v_pk_fma_f32 v[12:13], v[12:13], v[34:35], v[38:39]
	v_cvt_pk_bf16_f32 v8, v8, v9
	v_cvt_pk_bf16_f32 v9, v12, v13
	global_store_dwordx2 v[0:1], v[8:9], off offset:2560 sc1
	ds_read_b128 v[32:35], v196 offset:6144
	ds_read_b128 v[36:39], v196 offset:14336
	v_pk_mul_f32 v[8:9], v[56:57], v[4:5] op_sel_hi:[1,0]
	v_pk_mul_f32 v[12:13], v[58:59], v[4:5] op_sel_hi:[1,0]
	s_waitcnt lgkmcnt(0)
	v_pk_fma_f32 v[8:9], v[8:9], v[32:33], v[36:37]
	v_pk_fma_f32 v[12:13], v[12:13], v[34:35], v[38:39]
	v_cvt_pk_bf16_f32 v8, v8, v9
	v_cvt_pk_bf16_f32 v9, v12, v13
	global_store_dwordx2 v[0:1], v[8:9], off offset:3072 sc1
	ds_read_b128 v[32:35], v196 offset:7168
	ds_read_b128 v[36:39], v196 offset:15360
	v_pk_mul_f32 v[8:9], v[60:61], v[4:5] op_sel_hi:[1,0]
	v_pk_mul_f32 v[4:5], v[62:63], v[4:5] op_sel_hi:[1,0]
	s_waitcnt lgkmcnt(0)
	v_pk_fma_f32 v[8:9], v[8:9], v[32:33], v[36:37]
	v_pk_fma_f32 v[4:5], v[4:5], v[34:35], v[38:39]
	v_cvt_pk_bf16_f32 v8, v8, v9
	v_cvt_pk_bf16_f32 v9, v4, v5
	v_mov_b32_e32 v32, v30
	v_mov_b32_e32 v33, v26
	v_mov_b32_e32 v34, v22
	v_mov_b32_e32 v35, v18
	v_mov_b32_e32 v36, v14
	v_mov_b32_e32 v37, v10
	v_mov_b32_e32 v38, v6
	v_mov_b32_e32 v39, v2
	global_store_dwordx2 v[0:1], v[8:9], off offset:3584 sc1
	s_cbranch_scc0 .LBB0_232

; #define LAS __attribute__((address_space(3)))
; __device__ __forceinline__ unsigned cvt_pk_bf16(float lo, float hi) { const f32x2 v = {lo, hi}; return __builtin_bit_cast(unsigned, __builtin_convertvector(v, bf16x2_t)); }
; __device__ __forceinline__ float bf_lo(unsigned u) { return __uint_as_float(u << 16); }
; __device__ __forceinline__ float bf_hi(unsigned u) { return __uint_as_float(u & 0xffff0000u); }
; __device__ __forceinline__ void norm_mod_phase(Frame& F, int L, const float* gvec, int sh_chunk, int nrows, const float* pg, const float* pg2, const float* xlat, const float* xctx) {
;     ...
;         if (h2) {
;             const LAS f32x4* gq = vq + 3 * (D / 4); u32x2* xw_ = (u32x2*)((bf16_t*)(F.ws + WS_XB) + (size_t)r * D) + lane;
; #pragma unroll
;             for (int j = 0; j < 8; ++j) { const u32x2 yy = aux[1][j]; const f32x4 y4 = {bf_lo(yy.x), bf_hi(yy.x), bf_lo(yy.y), bf_hi(yy.y)}; v[j] += gq[64 * j] * y4; u32x2 w; w.x = cvt_pk_bf16(v[j].x, v[j].y); w.y = cvt_pk_bf16(v[j].z, v[j].w); xw_[64 * j] = w; }
;         }
;         if (hc) {
;             const LAS f32x4* gq = vq + 2 * (D / 4); u32x2* xw_ = (u32x2*)((bf16_t*)(F.ws + WS_XC) + (size_t)(r - MLAT) * D) + lane;
; #pragma unroll
;             for (int j = 0; j < 8; ++j) { f32x4 p = {0.f, 0.f, 0.f, 0.f};
; #pragma unroll
;                 for (int q = 0; q < 4; ++q) { const u32x2 w = aux[q][j]; p += (f32x4){bf_lo(w.x), bf_hi(w.x), bf_lo(w.y), bf_hi(w.y)}; }
;                 v[j] += gq[64 * j] * p; u32x2 w; w.x = cvt_pk_bf16(v[j].x, v[j].y); w.y = cvt_pk_bf16(v[j].z, v[j].w); xw_[64 * j] = w; }
.LBB0_226:
	s_and_b64 vcc, exec, s[40:41]
	v_lshlrev_b32_e32 v194, 16, v130
	v_and_b32_e32 v195, 0xffff0000, v130
	v_lshlrev_b32_e32 v192, 16, v131
	v_and_b32_e32 v193, 0xffff0000, v131
	v_lshlrev_b32_e32 v188, 16, v134
	v_and_b32_e32 v189, 0xffff0000, v134
	v_lshlrev_b32_e32 v190, 16, v135
	v_and_b32_e32 v191, 0xffff0000, v135
	v_lshlrev_b32_e32 v174, 16, v136
	v_and_b32_e32 v175, 0xffff0000, v136
	v_lshlrev_b32_e32 v172, 16, v137
	v_and_b32_e32 v173, 0xffff0000, v137
	v_lshlrev_b32_e32 v168, 16, v138
	v_and_b32_e32 v169, 0xffff0000, v138
	v_lshlrev_b32_e32 v170, 16, v139
	v_and_b32_e32 v171, 0xffff0000, v139
	v_lshlrev_b32_e32 v158, 16, v140
	v_and_b32_e32 v159, 0xffff0000, v140
	v_lshlrev_b32_e32 v156, 16, v141
	v_and_b32_e32 v157, 0xffff0000, v141
	v_lshlrev_b32_e32 v152, 16, v94
	v_and_b32_e32 v153, 0xffff0000, v94
	v_lshlrev_b32_e32 v154, 16, v95
	v_and_b32_e32 v155, 0xffff0000, v95
	v_lshlrev_b32_e32 v28, 16, v112
	v_and_b32_e32 v29, 0xffff0000, v112
	v_lshlrev_b32_e32 v24, 16, v113
	v_and_b32_e32 v25, 0xffff0000, v113
	v_lshlrev_b32_e32 v16, 16, v114
	v_and_b32_e32 v17, 0xffff0000, v114
	v_lshlrev_b32_e32 v20, 16, v115
	v_and_b32_e32 v21, 0xffff0000, v115
	s_cbranch_vccnz .LBB0_228
	ds_read_b128 v[198:201], v196 offset:24576
	s_ashr_i32 s11, s10, 31
	s_lshl_b64 s[4:5], s[10:11], 12
	v_lshl_add_u64 v[150:151], v[74:75], 0, s[4:5]
	s_waitcnt lgkmcnt(0)
	v_pk_fma_f32 v[34:35], v[200:201], v[192:193], v[34:35]
	v_pk_fma_f32 v[32:33], v[198:199], v[194:195], v[32:33]
	v_cvt_pk_bf16_f32 v199, v34, v35
	v_cvt_pk_bf16_f32 v198, v32, v33
	global_store_dwordx2 v[150:151], v[198:199], off sc1
	ds_read_b128 v[198:201], v196 offset:25600
	s_waitcnt lgkmcnt(0)
	v_pk_fma_f32 v[38:39], v[200:201], v[190:191], v[38:39]
	v_pk_fma_f32 v[36:37], v[198:199], v[188:189], v[36:37]
	v_cvt_pk_bf16_f32 v199, v38, v39
	v_cvt_pk_bf16_f32 v198, v36, v37
	global_store_dwordx2 v[150:151], v[198:199], off offset:512 sc1
	ds_read_b128 v[198:201], v196 offset:26624
	s_waitcnt lgkmcnt(0)
	v_pk_fma_f32 v[42:43], v[200:201], v[172:173], v[42:43]
	v_pk_fma_f32 v[40:41], v[198:199], v[174:175], v[40:41]
	v_cvt_pk_bf16_f32 v199, v42, v43
	v_cvt_pk_bf16_f32 v198, v40, v41
	global_store_dwordx2 v[150:151], v[198:199], off offset:1024 sc1
	ds_read_b128 v[198:201], v196 offset:27648
	s_waitcnt lgkmcnt(0)
	v_pk_fma_f32 v[46:47], v[200:201], v[170:171], v[46:47]
	v_pk_fma_f32 v[44:45], v[198:199], v[168:169], v[44:45]
	v_cvt_pk_bf16_f32 v199, v46, v47
	v_cvt_pk_bf16_f32 v198, v44, v45
	global_store_dwordx2 v[150:151], v[198:199], off offset:1536 sc1
	ds_read_b128 v[198:201], v196 offset:28672
	s_waitcnt lgkmcnt(0)
	v_pk_fma_f32 v[50:51], v[200:201], v[156:157], v[50:51]
	v_pk_fma_f32 v[48:49], v[198:199], v[158:159], v[48:49]
	v_cvt_pk_bf16_f32 v199, v50, v51
	v_cvt_pk_bf16_f32 v198, v48, v49
	global_store_dwordx2 v[150:151], v[198:199], off offset:2048 sc1
	ds_read_b128 v[198:201], v196 offset:29696
	s_waitcnt lgkmcnt(0)
	v_pk_fma_f32 v[54:55], v[200:201], v[154:155], v[54:55]
	v_pk_fma_f32 v[52:53], v[198:199], v[152:153], v[52:53]
	v_cvt_pk_bf16_f32 v199, v54, v55
	v_cvt_pk_bf16_f32 v198, v52, v53
	global_store_dwordx2 v[150:151], v[198:199], off offset:2560 sc1
	ds_read_b128 v[198:201], v196 offset:30720
	s_waitcnt lgkmcnt(0)
	v_pk_fma_f32 v[58:59], v[200:201], v[24:25], v[58:59]
	v_pk_fma_f32 v[56:57], v[198:199], v[28:29], v[56:57]
	v_cvt_pk_bf16_f32 v199, v58, v59
	v_cvt_pk_bf16_f32 v198, v56, v57
	global_store_dwordx2 v[150:151], v[198:199], off offset:3072 sc1
	ds_read_b128 v[198:201], v196 offset:31744
	s_waitcnt lgkmcnt(0)
	v_pk_fma_f32 v[62:63], v[200:201], v[20:21], v[62:63]
	v_pk_fma_f32 v[60:61], v[198:199], v[16:17], v[60:61]
	v_cvt_pk_bf16_f32 v199, v62, v63
	v_cvt_pk_bf16_f32 v198, v60, v61
	global_store_dwordx2 v[150:151], v[198:199], off offset:3584 sc1
.LBB0_228:
	s_and_b64 vcc, exec, s[38:39]
	s_cbranch_vccnz .LBB0_211
	v_pk_add_f32 v[148:149], v[148:149], 0 op_sel_hi:[1,0]
	v_pk_add_f32 v[146:147], v[146:147], 0 op_sel_hi:[1,0]
	v_pk_add_f32 v[148:149], v[148:149], v[156:157]
	v_pk_add_f32 v[146:147], v[146:147], v[158:159]
	v_lshlrev_b32_e32 v156, 16, v84
	v_and_b32_e32 v157, 0xffff0000, v84
	v_lshlrev_b32_e32 v158, 16, v85
	v_and_b32_e32 v159, 0xffff0000, v85
	v_pk_add_f32 v[148:149], v[148:149], v[158:159]
	v_pk_add_f32 v[146:147], v[146:147], v[156:157]
	v_lshlrev_b32_e32 v156, 16, v102
	v_and_b32_e32 v157, 0xffff0000, v102
	v_lshlrev_b32_e32 v158, 16, v103
	v_and_b32_e32 v159, 0xffff0000, v103
	v_pk_add_f32 v[156:157], v[146:147], v[156:157]
	v_pk_add_f32 v[158:159], v[148:149], v[158:159]
	ds_read_b128 v[146:149], v196 offset:20480
	s_add_i32 s4, s10, 0xffffc000
	s_mov_b32 s5, s92
	s_lshl_b64 s[4:5], s[4:5], 12
	v_lshl_add_u64 v[150:151], v[76:77], 0, s[4:5]
	s_waitcnt lgkmcnt(0)
; #define LAS __attribute__((address_space(3)))
; __device__ __forceinline__ unsigned cvt_pk_bf16(float lo, float hi) { const f32x2 v = {lo, hi}; return __builtin_bit_cast(unsigned, __builtin_convertvector(v, bf16x2_t)); }
; __device__ __forceinline__ float bf_lo(unsigned u) { return __uint_as_float(u << 16); }
; __device__ __forceinline__ float bf_hi(unsigned u) { return __uint_as_float(u & 0xffff0000u); }
; __device__ __forceinline__ void norm_mod_phase(Frame& F, int L, const float* gvec, int sh_chunk, int nrows, const float* pg, const float* pg2, const float* xlat, const float* xctx) {
;     ...
;         if (hc) {
;             const LAS f32x4* gq = vq + 2 * (D / 4); u32x2* xw_ = (u32x2*)((bf16_t*)(F.ws + WS_XC) + (size_t)(r - MLAT) * D) + lane;
; #pragma unroll
;             for (int j = 0; j < 8; ++j) { f32x4 p = {0.f, 0.f, 0.f, 0.f};
; #pragma unroll
;                 for (int q = 0; q < 4; ++q) { const u32x2 w = aux[q][j]; p += (f32x4){bf_lo(w.x), bf_hi(w.x), bf_lo(w.y), bf_hi(w.y)}; }
;                 v[j] += gq[64 * j] * p; u32x2 w; w.x = cvt_pk_bf16(v[j].x, v[j].y); w.y = cvt_pk_bf16(v[j].z, v[j].w); xw_[64 * j] = w; }
	v_pk_fma_f32 v[50:51], v[158:159], v[148:149], v[50:51]
	v_pk_fma_f32 v[48:49], v[156:157], v[146:147], v[48:49]
	v_cvt_pk_bf16_f32 v147, v50, v51
	v_cvt_pk_bf16_f32 v146, v48, v49
	v_pk_add_f32 v[144:145], v[144:145], 0 op_sel_hi:[1,0]
	v_pk_add_f32 v[142:143], v[142:143], 0 op_sel_hi:[1,0]
	global_store_dwordx2 v[150:151], v[146:147], off offset:2048 sc1
	v_pk_add_f32 v[142:143], v[142:143], v[152:153]
	v_pk_add_f32 v[144:145], v[144:145], v[154:155]
	v_lshlrev_b32_e32 v146, 16, v82
	v_and_b32_e32 v147, 0xffff0000, v82
	v_lshlrev_b32_e32 v148, 16, v83
	v_and_b32_e32 v149, 0xffff0000, v83
	v_pk_add_f32 v[144:145], v[144:145], v[148:149]
	v_pk_add_f32 v[142:143], v[142:143], v[146:147]
	v_lshlrev_b32_e32 v146, 16, v100
	v_and_b32_e32 v147, 0xffff0000, v100
	v_lshlrev_b32_e32 v148, 16, v101
	v_and_b32_e32 v149, 0xffff0000, v101
	v_pk_add_f32 v[186:187], v[186:187], 0 op_sel_hi:[1,0]
	v_pk_add_f32 v[184:185], v[184:185], 0 op_sel_hi:[1,0]
	v_pk_add_f32 v[166:167], v[166:167], 0 op_sel_hi:[1,0]
	v_pk_add_f32 v[164:165], v[164:165], 0 op_sel_hi:[1,0]
	v_pk_add_f32 v[146:147], v[142:143], v[146:147]
	v_pk_add_f32 v[148:149], v[144:145], v[148:149]
	ds_read_b128 v[142:145], v196 offset:21504
	v_pk_add_f32 v[184:185], v[184:185], v[194:195]
	v_pk_add_f32 v[186:187], v[186:187], v[192:193]
	v_lshlrev_b32_e32 v192, 16, v92
	v_and_b32_e32 v193, 0xffff0000, v92
	v_lshlrev_b32_e32 v194, 16, v93
	v_and_b32_e32 v195, 0xffff0000, v93
	v_pk_add_f32 v[164:165], v[164:165], v[174:175]
	v_pk_add_f32 v[166:167], v[166:167], v[172:173]
	v_lshlrev_b32_e32 v172, 16, v88
	v_and_b32_e32 v173, 0xffff0000, v88
	v_lshlrev_b32_e32 v174, 16, v89
	v_and_b32_e32 v175, 0xffff0000, v89
	v_pk_add_f32 v[186:187], v[186:187], v[194:195]
	v_pk_add_f32 v[184:185], v[184:185], v[192:193]
	v_lshlrev_b32_e32 v192, 16, v110
	v_and_b32_e32 v193, 0xffff0000, v110
	v_lshlrev_b32_e32 v194, 16, v111
	v_and_b32_e32 v195, 0xffff0000, v111
	v_pk_add_f32 v[166:167], v[166:167], v[174:175]
	v_pk_add_f32 v[164:165], v[164:165], v[172:173]
	v_lshlrev_b32_e32 v172, 16, v106
	v_and_b32_e32 v173, 0xffff0000, v106
	v_lshlrev_b32_e32 v174, 16, v107
	v_and_b32_e32 v175, 0xffff0000, v107
	v_pk_add_f32 v[192:193], v[184:185], v[192:193]
	v_pk_add_f32 v[194:195], v[186:187], v[194:195]
	ds_read_b128 v[184:187], v196 offset:16384
	v_pk_add_f32 v[172:173], v[164:165], v[172:173]
	v_pk_add_f32 v[174:175], v[166:167], v[174:175]
	ds_read_b128 v[164:167], v196 offset:18432
	s_waitcnt lgkmcnt(2)
	v_pk_fma_f32 v[54:55], v[148:149], v[144:145], v[54:55]
	v_pk_fma_f32 v[52:53], v[146:147], v[142:143], v[52:53]
	v_cvt_pk_bf16_f32 v143, v54, v55
	v_cvt_pk_bf16_f32 v142, v52, v53
	global_store_dwordx2 v[150:151], v[142:143], off offset:2560 sc1
	ds_read_b128 v[142:145], v196 offset:22528
	s_waitcnt lgkmcnt(2)
	v_pk_fma_f32 v[34:35], v[194:195], v[186:187], v[34:35]
	v_pk_fma_f32 v[32:33], v[192:193], v[184:185], v[32:33]
	s_waitcnt lgkmcnt(1)
; #define LAS __attribute__((address_space(3)))
; __device__ __forceinline__ unsigned cvt_pk_bf16(float lo, float hi) { const f32x2 v = {lo, hi}; return __builtin_bit_cast(unsigned, __builtin_convertvector(v, bf16x2_t)); }
; __device__ __forceinline__ float bf_lo(unsigned u) { return __uint_as_float(u << 16); }
; __device__ __forceinline__ float bf_hi(unsigned u) { return __uint_as_float(u & 0xffff0000u); }
; __device__ __forceinline__ void norm_mod_phase(Frame& F, int L, const float* gvec, int sh_chunk, int nrows, const float* pg, const float* pg2, const float* xlat, const float* xctx) {
;     ...
;         if (hc) {
;             const LAS f32x4* gq = vq + 2 * (D / 4); u32x2* xw_ = (u32x2*)((bf16_t*)(F.ws + WS_XC) + (size_t)(r - MLAT) * D) + lane;
; #pragma unroll
;             for (int j = 0; j < 8; ++j) { f32x4 p = {0.f, 0.f, 0.f, 0.f};
; #pragma unroll
;                 for (int q = 0; q < 4; ++q) { const u32x2 w = aux[q][j]; p += (f32x4){bf_lo(w.x), bf_hi(w.x), bf_lo(w.y), bf_hi(w.y)}; }
;                 v[j] += gq[64 * j] * p; u32x2 w; w.x = cvt_pk_bf16(v[j].x, v[j].y); w.y = cvt_pk_bf16(v[j].z, v[j].w); xw_[64 * j] = w; }
	v_pk_fma_f32 v[42:43], v[174:175], v[166:167], v[42:43]
	v_pk_fma_f32 v[40:41], v[172:173], v[164:165], v[40:41]
	v_pk_add_f32 v[12:13], v[12:13], 0 op_sel_hi:[1,0]
	v_pk_add_f32 v[8:9], v[8:9], 0 op_sel_hi:[1,0]
	v_cvt_pk_bf16_f32 v184, v32, v33
	v_cvt_pk_bf16_f32 v185, v34, v35
	v_pk_add_f32 v[182:183], v[182:183], 0 op_sel_hi:[1,0]
	v_pk_add_f32 v[180:181], v[180:181], 0 op_sel_hi:[1,0]
	v_cvt_pk_bf16_f32 v164, v40, v41
	v_cvt_pk_bf16_f32 v165, v42, v43
	v_pk_add_f32 v[162:163], v[162:163], 0 op_sel_hi:[1,0]
	v_pk_add_f32 v[160:161], v[160:161], 0 op_sel_hi:[1,0]
	v_pk_add_f32 v[8:9], v[8:9], v[28:29]
	v_pk_add_f32 v[12:13], v[12:13], v[24:25]
	v_lshlrev_b32_e32 v24, 16, v80
	v_and_b32_e32 v25, 0xffff0000, v80
	v_lshlrev_b32_e32 v28, 16, v81
	v_and_b32_e32 v29, 0xffff0000, v81
	global_store_dwordx2 v[150:151], v[184:185], off sc1
	v_pk_add_f32 v[180:181], v[180:181], v[188:189]
	v_pk_add_f32 v[182:183], v[182:183], v[190:191]
	v_lshlrev_b32_e32 v184, 16, v90
	v_and_b32_e32 v185, 0xffff0000, v90
	v_lshlrev_b32_e32 v186, 16, v91
	v_and_b32_e32 v187, 0xffff0000, v91
	global_store_dwordx2 v[150:151], v[164:165], off offset:1024 sc1
	v_pk_add_f32 v[160:161], v[160:161], v[168:169]
	v_pk_add_f32 v[162:163], v[162:163], v[170:171]
	v_lshlrev_b32_e32 v164, 16, v86
	v_and_b32_e32 v165, 0xffff0000, v86
	v_lshlrev_b32_e32 v166, 16, v87
	v_and_b32_e32 v167, 0xffff0000, v87
	v_pk_add_f32 v[12:13], v[12:13], v[28:29]
	v_pk_add_f32 v[8:9], v[8:9], v[24:25]
	v_lshlrev_b32_e32 v24, 16, v98
	v_and_b32_e32 v25, 0xffff0000, v98
	v_lshlrev_b32_e32 v28, 16, v99
	v_and_b32_e32 v29, 0xffff0000, v99
	v_pk_add_f32 v[182:183], v[182:183], v[186:187]
	v_pk_add_f32 v[180:181], v[180:181], v[184:185]
	v_lshlrev_b32_e32 v184, 16, v108
	v_and_b32_e32 v185, 0xffff0000, v108
	v_lshlrev_b32_e32 v186, 16, v109
	v_and_b32_e32 v187, 0xffff0000, v109
	v_pk_add_f32 v[162:163], v[162:163], v[166:167]
	v_pk_add_f32 v[160:161], v[160:161], v[164:165]
	v_lshlrev_b32_e32 v164, 16, v104
	v_and_b32_e32 v165, 0xffff0000, v104
	v_lshlrev_b32_e32 v166, 16, v105
	v_and_b32_e32 v167, 0xffff0000, v105
	v_pk_add_f32 v[8:9], v[8:9], v[24:25]
	v_pk_add_f32 v[12:13], v[12:13], v[28:29]
	v_pk_add_f32 v[184:185], v[180:181], v[184:185]
	v_pk_add_f32 v[186:187], v[182:183], v[186:187]
	ds_read_b128 v[180:183], v196 offset:17408
	v_pk_add_f32 v[164:165], v[160:161], v[164:165]
	v_pk_add_f32 v[166:167], v[162:163], v[166:167]
	ds_read_b128 v[160:163], v196 offset:19456
	s_waitcnt lgkmcnt(2)
	v_pk_fma_f32 v[58:59], v[12:13], v[144:145], v[58:59]
	v_pk_fma_f32 v[56:57], v[8:9], v[142:143], v[56:57]
	ds_read_b128 v[142:145], v196 offset:23552
	v_cvt_pk_bf16_f32 v8, v56, v57
	v_cvt_pk_bf16_f32 v9, v58, v59
	v_pk_add_f32 v[4:5], v[4:5], 0 op_sel_hi:[1,0]
	v_pk_add_f32 v[0:1], v[0:1], 0 op_sel_hi:[1,0]
	global_store_dwordx2 v[150:151], v[8:9], off offset:3072 sc1
	v_pk_add_f32 v[0:1], v[0:1], v[16:17]
	v_pk_add_f32 v[4:5], v[4:5], v[20:21]
	v_lshlrev_b32_e32 v8, 16, v78
	v_and_b32_e32 v9, 0xffff0000, v78
	v_lshlrev_b32_e32 v12, 16, v79
	v_and_b32_e32 v13, 0xffff0000, v79
	v_pk_add_f32 v[4:5], v[4:5], v[12:13]
	v_pk_add_f32 v[0:1], v[0:1], v[8:9]
	v_lshlrev_b32_e32 v8, 16, v96
	v_and_b32_e32 v9, 0xffff0000, v96
	v_lshlrev_b32_e32 v12, 16, v97
	v_and_b32_e32 v13, 0xffff0000, v97
	v_pk_add_f32 v[0:1], v[0:1], v[8:9]
	v_pk_add_f32 v[4:5], v[4:5], v[12:13]
	s_waitcnt lgkmcnt(2)
	v_pk_fma_f32 v[38:39], v[186:187], v[182:183], v[38:39]
	v_pk_fma_f32 v[36:37], v[184:185], v[180:181], v[36:37]
	s_waitcnt lgkmcnt(1)
	v_pk_fma_f32 v[46:47], v[166:167], v[162:163], v[46:47]
	v_pk_fma_f32 v[44:45], v[164:165], v[160:161], v[44:45]
	s_waitcnt lgkmcnt(0)
	v_pk_fma_f32 v[62:63], v[4:5], v[144:145], v[62:63]
	v_pk_fma_f32 v[60:61], v[0:1], v[142:143], v[60:61]
	v_cvt_pk_bf16_f32 v180, v36, v37
	v_cvt_pk_bf16_f32 v181, v38, v39
	v_cvt_pk_bf16_f32 v160, v44, v45
	v_cvt_pk_bf16_f32 v161, v46, v47
	v_cvt_pk_bf16_f32 v0, v60, v61
	v_cvt_pk_bf16_f32 v1, v62, v63
	global_store_dwordx2 v[150:151], v[180:181], off offset:512 sc1
	global_store_dwordx2 v[150:151], v[160:161], off offset:1536 sc1
	global_store_dwordx2 v[150:151], v[0:1], off offset:3584 sc1
	s_branch .LBB0_211

; __device__ __forceinline__ float silu_f(float v) { return v * __builtin_amdgcn_rcpf(1.0f + __expf(-v)); }
; __device__ __forceinline__ void ssd_conv_phase(Frame& F, int j, bool skip_ctx_c) {
;     ...
;         for (int i = 0; i < 10; ++i) { const int tt = tl - 1 + i; raw[i] = (tt >= 0 && tt < T) ? *(const u32x4*)(pre + (size_t)(seq0 + tt) * XBC + c0) : (u32x4){0u, 0u, 0u, 0u}; }
;         float o[8][8];
;         { float pa[8], pb[8], pc[8]; unpack8(raw[0], pa); unpack8(raw[1], pb);
; #pragma unroll
;           for (int i = 0; i < 8; ++i) { unpack8(raw[i + 2], pc);
; #pragma unroll
;               for (int c = 0; c < 8; ++c) o[i][c] = silu_f(bi[c] + w0[c] * pa[c] + w1[c] * pb[c] + w2[c] * pc[c]);
; #pragma unroll
;               for (int c = 0; c < 8; ++c) { pa[c] = pb[c]; pb[c] = pc[c]; } } }
.LBB0_406:
	s_or_b64 exec, exec, s[4:5]
	s_waitcnt vmcnt(0)
	v_lshlrev_b32_e32 v75, 16, v20
	v_lshlrev_b32_e32 v81, 16, v24
	v_lshlrev_b32_e32 v80, 16, v16
	v_mov_b32_e32 v78, v52
	v_mov_b32_e32 v79, v48
	v_fma_f32 v75, v56, v75, v60
	v_pk_mul_f32 v[82:83], v[78:79], v[80:81]
	v_lshlrev_b32_e32 v77, 16, v21
	v_add_f32_e32 v75, v75, v82
	v_add_f32_e32 v75, v75, v83
	v_mul_f32_e32 v82, 0xbfb8aa3b, v75
	v_lshlrev_b32_e32 v89, 16, v25
	v_lshlrev_b32_e32 v88, 16, v17
	v_mov_b32_e32 v86, v54
	v_mov_b32_e32 v87, v50
	v_exp_f32_e32 v85, v82
	v_fma_f32 v77, v58, v77, v62
	v_pk_mul_f32 v[82:83], v[86:87], v[88:89]
	v_lshlrev_b32_e32 v84, 16, v22
	v_add_f32_e32 v77, v77, v82
	v_add_f32_e32 v77, v77, v83
	v_mul_f32_e32 v82, 0xbfb8aa3b, v77
	v_exp_f32_e32 v82, v82
	v_add_f32_e32 v83, 1.0, v85
	v_fma_f32 v95, v0, v84, v12
	v_lshlrev_b32_e32 v91, 16, v26
	v_lshlrev_b32_e32 v90, 16, v18
	v_mov_b32_e32 v84, v4
	v_mov_b32_e32 v85, v8
	v_rcp_f32_e32 v96, v83
	v_add_f32_e32 v97, 1.0, v82
	v_pk_mul_f32 v[82:83], v[84:85], v[90:91]
	v_lshlrev_b32_e32 v94, 16, v23
	v_add_f32_e32 v82, v95, v82
	v_add_f32_e32 v99, v82, v83
	v_mul_f32_e32 v82, 0xbfb8aa3b, v99
	v_exp_f32_e32 v98, v82
	v_lshlrev_b32_e32 v103, 16, v27
	v_lshlrev_b32_e32 v102, 16, v19
	v_mov_b32_e32 v82, v6
	v_mov_b32_e32 v83, v10
	v_fma_f32 v100, v2, v94, v14
	v_pk_mul_f32 v[94:95], v[82:83], v[102:103]
	v_rcp_f32_e32 v97, v97
	v_add_f32_e32 v98, 1.0, v98
	v_add_f32_e32 v94, v100, v94
	v_rcp_f32_e32 v100, v98
	v_mul_f32_e32 v98, v75, v96
	v_fma_f32 v75, v56, v80, v60
	v_lshlrev_b32_e32 v104, 16, v28
	v_fmac_f32_e32 v75, v52, v81
	v_fmac_f32_e32 v75, v48, v104
	v_mul_f32_e32 v96, v77, v97
	v_mul_f32_e32 v77, 0xbfb8aa3b, v75
	v_exp_f32_e32 v77, v77
	v_fma_f32 v88, v58, v88, v62
	v_fmac_f32_e32 v88, v54, v89
	v_lshlrev_b32_e32 v106, 16, v29
	v_add_f32_e32 v54, 1.0, v77
	v_fma_f32 v77, v0, v90, v12
	v_lshlrev_b32_e32 v108, 16, v30
	v_fmac_f32_e32 v77, v4, v91
	v_fmac_f32_e32 v88, v50, v106
	v_fmac_f32_e32 v77, v8, v108
	v_fma_f32 v8, v2, v102, v14
	v_mul_f32_e32 v50, 0xbfb8aa3b, v88
	v_lshlrev_b32_e32 v80, 16, v31
	v_fmac_f32_e32 v8, v6, v103
	v_exp_f32_e32 v50, v50
	v_fmac_f32_e32 v8, v10, v80
	v_mul_f32_e32 v4, 0xbfb8aa3b, v77
	v_mul_f32_e32 v6, 0xbfb8aa3b, v8
	v_add_f32_e32 v94, v94, v95
	v_exp_f32_e32 v4, v4
	v_exp_f32_e32 v6, v6
	v_mul_f32_e32 v95, 0xbfb8aa3b, v94
	v_exp_f32_e32 v95, v95
	v_add_f32_e32 v50, 1.0, v50
	v_rcp_f32_e32 v10, v50
	v_add_f32_e32 v4, 1.0, v4
	v_add_f32_e32 v6, 1.0, v6
	v_rcp_f32_e32 v4, v4
	v_rcp_f32_e32 v6, v6
	v_add_f32_e32 v95, 1.0, v95
	v_rcp_f32_e32 v101, v95
	v_mul_f32_e32 v95, v99, v100
	v_mul_f32_e32 v100, v88, v10
	v_lshlrev_b32_e32 v88, 16, v32
	v_mov_b32_e32 v105, v88
	v_mul_f32_e32 v99, v77, v4
	v_mul_f32_e32 v97, v8, v6
	v_fma_f32 v4, v56, v81, v60
	v_fma_f32 v8, v0, v91, v12
	v_pk_mul_f32 v[90:91], v[78:79], v[104:105]
	v_rcp_f32_e32 v54, v54
	v_fma_f32 v6, v58, v89, v62
	v_lshlrev_b32_e32 v89, 16, v36
	v_add_f32_e32 v4, v4, v90
	v_fma_f32 v10, v56, v104, v60
	v_add_f32_e32 v4, v4, v91
	v_pk_mul_f32 v[90:91], v[78:79], v[88:89]
	v_mul_f32_e32 v94, v94, v101
	v_add_f32_e32 v10, v10, v90
	v_lshlrev_b32_e32 v90, 16, v33
	v_mov_b32_e32 v107, v90
	v_mul_f32_e32 v101, v75, v54
	v_fma_f32 v75, v2, v103, v14
	v_pk_mul_f32 v[102:103], v[86:87], v[106:107]
	v_mul_f32_e32 v50, 0xbfb8aa3b, v4
	v_add_f32_e32 v6, v6, v102
	v_add_f32_e32 v6, v6, v103
	v_mul_f32_e32 v77, 0xbfb8aa3b, v6
	v_exp_f32_e32 v77, v77
	v_add_f32_e32 v10, v10, v91
	v_exp_f32_e32 v50, v50
	v_mul_f32_e32 v54, 0xbfb8aa3b, v10
	v_lshlrev_b32_e32 v91, 16, v37
	v_add_f32_e32 v77, 1.0, v77
	v_exp_f32_e32 v54, v54
	v_fma_f32 v81, v58, v106, v62
	v_rcp_f32_e32 v77, v77
	v_pk_mul_f32 v[102:103], v[86:87], v[90:91]
	v_lshlrev_b32_e32 v110, 16, v34
	v_add_f32_e32 v81, v81, v102
	v_add_f32_e32 v81, v81, v103
	v_add_f32_e32 v50, 1.0, v50
	v_mul_f32_e32 v102, 0xbfb8aa3b, v81
	v_mov_b32_e32 v109, v110
	v_rcp_f32_e32 v50, v50
	v_add_f32_e32 v54, 1.0, v54
	v_exp_f32_e32 v103, v102
	v_mul_f32_e32 v102, v6, v77
	v_fma_f32 v6, v0, v108, v12
	v_pk_mul_f32 v[108:109], v[84:85], v[108:109]
	v_rcp_f32_e32 v54, v54
	v_lshlrev_b32_e32 v111, 16, v38
	v_add_f32_e32 v8, v8, v108
	v_add_f32_e32 v8, v8, v109
	v_pk_mul_f32 v[108:109], v[84:85], v[110:111]
	v_mul_f32_e32 v105, v4, v50
	v_add_f32_e32 v6, v6, v108
	v_add_f32_e32 v4, 1.0, v103
	v_add_f32_e32 v6, v6, v109
	v_mul_f32_e32 v106, v10, v54
	v_rcp_f32_e32 v4, v4
	v_mul_f32_e32 v10, 0xbfb8aa3b, v8
	v_mul_f32_e32 v50, 0xbfb8aa3b, v6
	v_exp_f32_e32 v10, v10
	v_exp_f32_e32 v50, v50
	v_lshlrev_b32_e32 v116, 16, v35
	v_mul_f32_e32 v107, v81, v4
	v_mov_b32_e32 v81, v116
	v_add_f32_e32 v4, 1.0, v10
	v_add_f32_e32 v10, 1.0, v50
	v_fma_f32 v50, v2, v80, v14
	v_pk_mul_f32 v[80:81], v[82:83], v[80:81]
	v_lshlrev_b32_e32 v117, 16, v39
	v_add_f32_e32 v54, v75, v80
	v_add_f32_e32 v54, v54, v81
	v_mul_f32_e32 v75, 0xbfb8aa3b, v54
	v_exp_f32_e32 v75, v75
	v_pk_mul_f32 v[80:81], v[82:83], v[116:117]
	v_rcp_f32_e32 v4, v4
	v_add_f32_e32 v50, v50, v80
	v_add_f32_e32 v50, v50, v81
	v_add_f32_e32 v75, 1.0, v75
	v_mul_f32_e32 v77, 0xbfb8aa3b, v50
	v_rcp_f32_e32 v75, v75
	v_exp_f32_e32 v77, v77
	v_rcp_f32_e32 v10, v10
	v_lshlrev_b32_e32 v81, 16, v44
	v_lshlrev_b32_e32 v80, 16, v40
	v_mul_f32_e32 v108, v8, v4
	v_mul_f32_e32 v103, v54, v75
	v_fma_f32 v4, v56, v88, v60
	v_pk_mov_b32 v[112:113], v[88:89], v[80:81] op_sel:[1,0]
	v_fma_f32 v54, v56, v89, v60
	v_pk_mul_f32 v[88:89], v[78:79], v[80:81]
	v_add_f32_e32 v77, 1.0, v77
	v_add_f32_e32 v54, v54, v88
	v_lshlrev_b32_e32 v120, 16, v41
	v_lshlrev_b32_e32 v121, 16, v45
	v_rcp_f32_e32 v77, v77
	v_add_f32_e32 v54, v54, v89
	v_pk_mov_b32 v[88:89], v[90:91], v[120:121] op_sel:[1,0]
; __device__ __forceinline__ float silu_f(float v) { return v * __builtin_amdgcn_rcpf(1.0f + __expf(-v)); }
; __device__ __forceinline__ void ssd_conv_phase(Frame& F, int j, bool skip_ctx_c) {
;     ...
;         for (int i = 0; i < 10; ++i) { const int tt = tl - 1 + i; raw[i] = (tt >= 0 && tt < T) ? *(const u32x4*)(pre + (size_t)(seq0 + tt) * XBC + c0) : (u32x4){0u, 0u, 0u, 0u}; }
;         float o[8][8];
;         { float pa[8], pb[8], pc[8]; unpack8(raw[0], pa); unpack8(raw[1], pb);
; #pragma unroll
;           for (int i = 0; i < 8; ++i) { unpack8(raw[i + 2], pc);
; #pragma unroll
;               for (int c = 0; c < 8; ++c) o[i][c] = silu_f(bi[c] + w0[c] * pa[c] + w1[c] * pb[c] + w2[c] * pc[c]);
; #pragma unroll
;               for (int c = 0; c < 8; ++c) { pa[c] = pb[c]; pb[c] = pc[c]; } } }
	v_mul_f32_e32 v109, v6, v10
	v_fma_f32 v6, v58, v90, v62
	v_pk_mul_f32 v[88:89], v[86:87], v[88:89]
	v_pk_mul_f32 v[112:113], v[78:79], v[112:113]
	v_add_f32_e32 v6, v6, v88
	v_add_f32_e32 v4, v4, v112
	v_add_f32_e32 v6, v6, v89
	v_mul_f32_e32 v104, v50, v77
	v_add_f32_e32 v4, v4, v113
	v_mul_f32_e32 v77, 0xbfb8aa3b, v6
	v_mul_f32_e32 v8, 0xbfb8aa3b, v4
	v_exp_f32_e32 v77, v77
	v_exp_f32_e32 v8, v8
	v_fma_f32 v90, v58, v91, v62
	v_pk_mul_f32 v[88:89], v[86:87], v[120:121]
	v_add_f32_e32 v77, 1.0, v77
	v_add_f32_e32 v88, v90, v88
	v_add_f32_e32 v112, v88, v89
	v_add_f32_e32 v8, 1.0, v8
	v_rcp_f32_e32 v77, v77
	v_mul_f32_e32 v88, 0xbfb8aa3b, v112
	v_rcp_f32_e32 v8, v8
	v_mul_f32_e32 v75, 0xbfb8aa3b, v54
	v_exp_f32_e32 v88, v88
	v_exp_f32_e32 v75, v75
	v_fma_f32 v10, v0, v110, v12
	v_mul_f32_e32 v110, v6, v77
	v_lshlrev_b32_e32 v91, 16, v46
	v_lshlrev_b32_e32 v90, 16, v42
	v_mul_f32_e32 v113, v4, v8
	v_add_f32_e32 v4, 1.0, v88
	v_pk_mov_b32 v[88:89], v[110:111], v[90:91] op_sel:[1,0]
	v_add_f32_e32 v75, 1.0, v75
	v_pk_mul_f32 v[88:89], v[84:85], v[88:89]
	v_rcp_f32_e32 v75, v75
	v_add_f32_e32 v8, v10, v88
	v_fma_f32 v6, v0, v111, v12
	v_add_f32_e32 v8, v8, v89
	v_pk_mul_f32 v[88:89], v[84:85], v[90:91]
	v_mul_f32_e32 v114, v54, v75
	v_add_f32_e32 v6, v6, v88
	v_add_f32_e32 v6, v6, v89
	v_mul_f32_e32 v10, 0xbfb8aa3b, v8
	v_mul_f32_e32 v54, 0xbfb8aa3b, v6
	v_rcp_f32_e32 v4, v4
	v_exp_f32_e32 v10, v10
	v_exp_f32_e32 v54, v54
	v_lshlrev_b32_e32 v88, 16, v43
	v_lshlrev_b32_e32 v89, 16, v47
	v_fma_f32 v50, v2, v116, v14
	v_mul_f32_e32 v115, v112, v4
	v_add_f32_e32 v4, 1.0, v10
	v_add_f32_e32 v10, 1.0, v54
	v_fma_f32 v54, v2, v117, v14
	v_pk_mov_b32 v[116:117], v[116:117], v[88:89] op_sel:[1,0]
	v_rcp_f32_e32 v4, v4
	v_pk_mul_f32 v[116:117], v[82:83], v[116:117]
	v_rcp_f32_e32 v10, v10
	v_add_f32_e32 v50, v50, v116
	v_add_f32_e32 v50, v50, v117
	v_pk_mul_f32 v[116:117], v[82:83], v[88:89]
	v_lshlrev_b32_e32 v119, 16, v64
	v_add_f32_e32 v54, v54, v116
	v_lshlrev_b32_e32 v118, 16, v68
	v_add_f32_e32 v54, v54, v117
	v_mul_f32_e32 v116, v8, v4
	v_mul_f32_e32 v117, v6, v10
	v_fma_f32 v4, v56, v80, v60
	v_fma_f32 v6, v56, v81, v60
	v_pk_mov_b32 v[80:81], v[80:81], v[118:119] op_sel:[1,0]
	v_and_b32_e32 v129, 0xffff0000, v16
	v_pk_mul_f32 v[80:81], v[78:79], v[80:81]
	v_pk_mul_f32 v[78:79], v[78:79], v[118:119]
	v_add_f32_e32 v4, v4, v80
	v_add_f32_e32 v4, v4, v81
	v_add_f32_e32 v6, v6, v78
	v_mul_f32_e32 v8, 0xbfb8aa3b, v4
	v_add_f32_e32 v6, v6, v79
	v_exp_f32_e32 v8, v8
	v_mul_f32_e32 v10, 0xbfb8aa3b, v6
	v_exp_f32_e32 v10, v10
	v_and_b32_e32 v79, 0xffff0000, v28
	v_add_f32_e32 v8, 1.0, v8
	v_rcp_f32_e32 v8, v8
	v_add_f32_e32 v10, 1.0, v10
	v_and_b32_e32 v78, 0xffff0000, v24
	v_and_b32_e32 v128, 0xffff0000, v20
	v_rcp_f32_e32 v10, v10
	v_pk_fma_f32 v[130:131], v[56:57], v[128:129], v[60:61] op_sel:[1,0,1]
	v_pk_mov_b32 v[128:129], v[128:129], v[78:79] op_sel:[1,0]
	v_mul_f32_e32 v118, v4, v8
	v_pk_fma_f32 v[128:129], v[52:53], v[128:129], v[130:131] op_sel:[1,0,0]
	v_mul_f32_e32 v119, v6, v10
	v_pk_fma_f32 v[128:129], v[48:49], v[78:79], v[128:129] op_sel:[1,0,0]
	v_and_b32_e32 v81, 0xffff0000, v36
	v_mul_f32_e32 v4, 0xbfb8aa3b, v128
	v_exp_f32_e32 v4, v4
	v_mul_f32_e32 v6, 0xbfb8aa3b, v129
	v_exp_f32_e32 v6, v6
	v_and_b32_e32 v80, 0xffff0000, v32
	v_pk_fma_f32 v[132:133], v[56:57], v[78:79], v[60:61] op_sel:[1,0,1]
	v_pk_mov_b32 v[78:79], v[78:79], v[80:81] op_sel:[1,0]
	v_add_f32_e32 v4, 1.0, v4
	v_pk_fma_f32 v[78:79], v[52:53], v[78:79], v[132:133] op_sel:[1,0,0]
	v_rcp_f32_e32 v130, v4
	v_add_f32_e32 v4, 1.0, v6
	v_pk_fma_f32 v[132:133], v[48:49], v[80:81], v[78:79] op_sel:[1,0,0]
	v_rcp_f32_e32 v131, v4
	v_mul_f32_e32 v4, 0xbfb8aa3b, v132
	v_exp_f32_e32 v4, v4
	v_mul_f32_e32 v6, 0xbfb8aa3b, v133
	v_exp_f32_e32 v6, v6
	v_and_b32_e32 v123, 0xffff0000, v44
	v_and_b32_e32 v122, 0xffff0000, v40
	v_pk_mul_f32 v[78:79], v[128:129], v[130:131]
	v_pk_fma_f32 v[130:131], v[56:57], v[80:81], v[60:61] op_sel:[1,0,1]
	v_pk_mov_b32 v[80:81], v[80:81], v[122:123] op_sel:[1,0]
	v_add_f32_e32 v4, 1.0, v4
	v_pk_fma_f32 v[80:81], v[52:53], v[80:81], v[130:131] op_sel:[1,0,0]
	v_rcp_f32_e32 v128, v4
	v_add_f32_e32 v4, 1.0, v6
	v_pk_fma_f32 v[130:131], v[48:49], v[122:123], v[80:81] op_sel:[1,0,0]
	v_mul_f32_e32 v75, 0xbfb8aa3b, v50
	v_rcp_f32_e32 v129, v4
	v_mul_f32_e32 v4, 0xbfb8aa3b, v130
	v_exp_f32_e32 v75, v75
	v_exp_f32_e32 v4, v4
	v_mul_f32_e32 v6, 0xbfb8aa3b, v131
	v_exp_f32_e32 v6, v6
	v_and_b32_e32 v125, 0xffff0000, v68
	v_mov_b32_e32 v124, v123
	v_pk_fma_f32 v[56:57], v[56:57], v[122:123], v[60:61] op_sel:[1,0,1]
	v_and_b32_e32 v127, 0xffff0000, v64
	v_mov_b32_e32 v126, v125
	v_pk_fma_f32 v[52:53], v[52:53], v[124:125], v[56:57] op_sel:[1,0,0]
	v_add_f32_e32 v75, 1.0, v75
	v_add_f32_e32 v4, 1.0, v4
	v_pk_fma_f32 v[52:53], v[48:49], v[126:127], v[52:53] op_sel:[1,0,0]
	v_rcp_f32_e32 v75, v75
	v_pk_mul_f32 v[80:81], v[132:133], v[128:129]
	v_rcp_f32_e32 v128, v4
	v_add_f32_e32 v4, 1.0, v6
	v_mul_f32_e32 v6, 0xbfb8aa3b, v52
	v_exp_f32_e32 v6, v6
	v_mul_f32_e32 v8, 0xbfb8aa3b, v53
	v_lshlrev_b32_e32 v48, 16, v69
	v_lshlrev_b32_e32 v49, 16, v65
	v_exp_f32_e32 v8, v8
	v_pk_mov_b32 v[60:61], v[120:121], v[48:49] op_sel:[1,0]
	v_mul_f32_e32 v111, v50, v75
	v_fma_f32 v50, v58, v120, v62
	v_pk_mul_f32 v[60:61], v[86:87], v[60:61]
	v_rcp_f32_e32 v129, v4
	v_add_f32_e32 v4, 1.0, v6
	v_fmac_f32_e32 v62, v58, v121
	v_add_f32_e32 v6, v50, v60
	v_pk_mul_f32 v[48:49], v[86:87], v[48:49]
	v_add_f32_e32 v6, v6, v61
	v_add_f32_e32 v10, v62, v48
	v_rcp_f32_e32 v56, v4
	v_add_f32_e32 v4, 1.0, v8
	v_mul_f32_e32 v8, 0xbfb8aa3b, v6
	v_add_f32_e32 v10, v10, v49
	v_exp_f32_e32 v8, v8
; __device__ __forceinline__ float silu_f(float v) { return v * __builtin_amdgcn_rcpf(1.0f + __expf(-v)); }
; __device__ __forceinline__ void ssd_conv_phase(Frame& F, int j, bool skip_ctx_c) {
;     ...
;         for (int i = 0; i < 10; ++i) { const int tt = tl - 1 + i; raw[i] = (tt >= 0 && tt < T) ? *(const u32x4*)(pre + (size_t)(seq0 + tt) * XBC + c0) : (u32x4){0u, 0u, 0u, 0u}; }
;         float o[8][8];
;         { float pa[8], pb[8], pc[8]; unpack8(raw[0], pa); unpack8(raw[1], pb);
; #pragma unroll
;           for (int i = 0; i < 8; ++i) { unpack8(raw[i + 2], pc);
; #pragma unroll
;               for (int c = 0; c < 8; ++c) o[i][c] = silu_f(bi[c] + w0[c] * pa[c] + w1[c] * pb[c] + w2[c] * pc[c]);
; #pragma unroll
;               for (int c = 0; c < 8; ++c) { pa[c] = pb[c]; pb[c] = pc[c]; } } }
	v_mul_f32_e32 v16, 0xbfb8aa3b, v10
	v_exp_f32_e32 v16, v16
	v_rcp_f32_e32 v57, v4
	v_add_f32_e32 v4, 1.0, v8
	v_rcp_f32_e32 v4, v4
	v_add_f32_e32 v8, 1.0, v16
	v_rcp_f32_e32 v8, v8
	v_and_b32_e32 v29, 0xffff0000, v29
	v_mul_f32_e32 v86, v6, v4
	v_and_b32_e32 v28, 0xffff0000, v25
	v_and_b32_e32 v17, 0xffff0000, v17
	v_and_b32_e32 v16, 0xffff0000, v21
	v_mov_b32_e32 v4, v59
	v_mov_b32_e32 v6, v63
	v_mul_f32_e32 v87, v10, v8
	v_pk_fma_f32 v[20:21], v[4:5], v[16:17], v[6:7] op_sel_hi:[0,1,0]
	v_mov_b32_e32 v8, v55
	v_pk_mov_b32 v[16:17], v[16:17], v[28:29] op_sel:[1,0]
	v_mov_b32_e32 v10, v51
	v_pk_fma_f32 v[16:17], v[8:9], v[16:17], v[20:21] op_sel_hi:[0,1,1]
	v_pk_fma_f32 v[16:17], v[10:11], v[28:29], v[16:17] op_sel_hi:[0,1,1]
	v_mul_f32_e32 v20, 0xbfb8aa3b, v16
	v_mul_f32_e32 v21, 0xbfb8aa3b, v17
	v_and_b32_e32 v37, 0xffff0000, v37
	v_exp_f32_e32 v20, v20
	v_exp_f32_e32 v21, v21
	v_and_b32_e32 v36, 0xffff0000, v33
	v_pk_fma_f32 v[24:25], v[4:5], v[28:29], v[6:7] op_sel_hi:[0,1,0]
	v_pk_mov_b32 v[28:29], v[28:29], v[36:37] op_sel:[1,0]
	v_add_f32_e32 v20, 1.0, v20
	v_pk_fma_f32 v[24:25], v[8:9], v[28:29], v[24:25] op_sel_hi:[0,1,1]
	v_pk_fma_f32 v[24:25], v[10:11], v[36:37], v[24:25] op_sel_hi:[0,1,1]
	v_add_f32_e32 v21, 1.0, v21
	v_mul_f32_e32 v28, 0xbfb8aa3b, v24
	v_mul_f32_e32 v29, 0xbfb8aa3b, v25
	v_rcp_f32_e32 v20, v20
	v_rcp_f32_e32 v21, v21
	v_exp_f32_e32 v28, v28
	v_exp_f32_e32 v29, v29
	v_mul_f32_e32 v77, 0xbfb8aa3b, v54
	v_pk_mul_f32 v[32:33], v[16:17], v[20:21]
	v_add_f32_e32 v16, 1.0, v28
	v_add_f32_e32 v17, 1.0, v29
	v_rcp_f32_e32 v16, v16
	v_rcp_f32_e32 v17, v17
	v_exp_f32_e32 v77, v77
	v_and_b32_e32 v45, 0xffff0000, v45
	v_and_b32_e32 v44, 0xffff0000, v41
	v_and_b32_e32 v41, 0xffff0000, v69
	v_mov_b32_e32 v40, v45
	v_pk_fma_f32 v[20:21], v[4:5], v[36:37], v[6:7] op_sel_hi:[0,1,0]
	v_pk_mov_b32 v[28:29], v[36:37], v[44:45] op_sel:[1,0]
	v_pk_mul_f32 v[36:37], v[24:25], v[16:17]
	v_pk_fma_f32 v[24:25], v[4:5], v[44:45], v[6:7] op_sel_hi:[0,1,0]
	v_pk_mul_f32 v[52:53], v[52:53], v[56:57]
	v_and_b32_e32 v57, 0xffff0000, v65
	v_mov_b32_e32 v56, v41
	v_pk_fma_f32 v[24:25], v[8:9], v[40:41], v[24:25] op_sel_hi:[0,1,1]
	v_pk_fma_f32 v[20:21], v[8:9], v[28:29], v[20:21] op_sel_hi:[0,1,1]
	v_pk_fma_f32 v[24:25], v[10:11], v[56:57], v[24:25] op_sel_hi:[0,1,1]
	v_add_f32_e32 v77, 1.0, v77
	v_pk_fma_f32 v[20:21], v[10:11], v[44:45], v[20:21] op_sel_hi:[0,1,1]
	v_mul_f32_e32 v4, 0xbfb8aa3b, v24
	v_rcp_f32_e32 v77, v77
	v_mul_f32_e32 v28, 0xbfb8aa3b, v20
	v_exp_f32_e32 v4, v4
	v_mul_f32_e32 v6, 0xbfb8aa3b, v25
	v_exp_f32_e32 v28, v28
	v_exp_f32_e32 v6, v6
	v_lshlrev_b32_e32 v41, 16, v66
	v_lshlrev_b32_e32 v40, 16, v70
	v_pk_mov_b32 v[44:45], v[90:91], v[40:41] op_sel:[1,0]
	v_mul_f32_e32 v112, v54, v77
	v_fma_f32 v54, v0, v90, v12
	v_add_f32_e32 v4, 1.0, v4
	v_fma_f32 v0, v0, v91, v12
	v_pk_mul_f32 v[44:45], v[84:85], v[44:45]
	v_pk_mul_f32 v[40:41], v[84:85], v[40:41]
	v_add_f32_e32 v16, 1.0, v28
	v_rcp_f32_e32 v28, v4
	v_add_f32_e32 v4, 1.0, v6
	v_add_f32_e32 v6, v54, v44
	v_add_f32_e32 v0, v0, v40
	v_add_f32_e32 v6, v6, v45
	v_add_f32_e32 v0, v0, v41
	v_mul_f32_e32 v29, 0xbfb8aa3b, v21
	v_mul_f32_e32 v8, 0xbfb8aa3b, v6
	v_mul_f32_e32 v10, 0xbfb8aa3b, v0
	v_exp_f32_e32 v29, v29
	v_exp_f32_e32 v8, v8
	v_exp_f32_e32 v10, v10
	v_and_b32_e32 v51, 0xffff0000, v30
	v_add_f32_e32 v17, 1.0, v29
	v_rcp_f32_e32 v29, v4
	v_add_f32_e32 v4, 1.0, v8
	v_add_f32_e32 v8, 1.0, v10
	v_rcp_f32_e32 v4, v4
	v_rcp_f32_e32 v8, v8
	v_and_b32_e32 v50, 0xffff0000, v26
	v_and_b32_e32 v55, 0xffff0000, v18
	v_mul_f32_e32 v84, v6, v4
	v_mul_f32_e32 v85, v0, v8
	v_and_b32_e32 v54, 0xffff0000, v22
	v_mov_b32_e32 v0, v1
	v_mov_b32_e32 v4, v13
	v_pk_fma_f32 v[12:13], v[0:1], v[54:55], v[4:5] op_sel_hi:[0,1,0]
	v_mov_b32_e32 v6, v5
	v_pk_mov_b32 v[54:55], v[54:55], v[50:51] op_sel:[1,0]
	v_mov_b32_e32 v8, v9
	v_pk_fma_f32 v[12:13], v[6:7], v[54:55], v[12:13] op_sel_hi:[0,1,1]
	v_pk_fma_f32 v[12:13], v[8:9], v[50:51], v[12:13] op_sel_hi:[0,1,1]
	v_mul_f32_e32 v1, 0xbfb8aa3b, v12
	v_exp_f32_e32 v1, v1
	v_mul_f32_e32 v5, 0xbfb8aa3b, v13
	v_exp_f32_e32 v5, v5
	v_pk_mul_f32 v[44:45], v[24:25], v[28:29]
	v_add_f32_e32 v1, 1.0, v1
	v_and_b32_e32 v29, 0xffff0000, v38
	v_and_b32_e32 v28, 0xffff0000, v34
	v_rcp_f32_e32 v54, v1
	v_add_f32_e32 v1, 1.0, v5
	v_pk_fma_f32 v[56:57], v[0:1], v[50:51], v[4:5] op_sel_hi:[0,1,0]
	v_pk_mov_b32 v[50:51], v[50:51], v[28:29] op_sel:[1,0]
	v_rcp_f32_e32 v55, v1
	v_pk_fma_f32 v[50:51], v[6:7], v[50:51], v[56:57] op_sel_hi:[0,1,1]
	v_pk_fma_f32 v[56:57], v[8:9], v[28:29], v[50:51] op_sel_hi:[0,1,1]
	v_mul_f32_e32 v1, 0xbfb8aa3b, v56
	v_exp_f32_e32 v1, v1
	v_mul_f32_e32 v5, 0xbfb8aa3b, v57
	v_rcp_f32_e32 v16, v16
	v_rcp_f32_e32 v17, v17
	v_exp_f32_e32 v5, v5
	v_add_f32_e32 v1, 1.0, v1
	v_pk_mul_f32 v[50:51], v[12:13], v[54:55]
	v_pk_mul_f32 v[40:41], v[20:21], v[16:17]
	v_and_b32_e32 v17, 0xffff0000, v46
	v_and_b32_e32 v16, 0xffff0000, v42
	v_rcp_f32_e32 v12, v1
	v_add_f32_e32 v1, 1.0, v5
	v_pk_fma_f32 v[54:55], v[0:1], v[28:29], v[4:5] op_sel_hi:[0,1,0]
	v_pk_mov_b32 v[28:29], v[28:29], v[16:17] op_sel:[1,0]
	v_rcp_f32_e32 v13, v1
	v_pk_fma_f32 v[28:29], v[6:7], v[28:29], v[54:55] op_sel_hi:[0,1,1]
	v_pk_fma_f32 v[28:29], v[8:9], v[16:17], v[28:29] op_sel_hi:[0,1,1]
	v_mul_f32_e32 v1, 0xbfb8aa3b, v28
	v_mul_f32_e32 v5, 0xbfb8aa3b, v29
	v_exp_f32_e32 v1, v1
	v_exp_f32_e32 v5, v5
	v_and_b32_e32 v21, 0xffff0000, v70
	v_mov_b32_e32 v20, v17
	v_add_f32_e32 v1, 1.0, v1
	v_add_f32_e32 v5, 1.0, v5
	v_pk_mul_f32 v[54:55], v[56:57], v[12:13]
	v_rcp_f32_e32 v12, v1
	v_pk_fma_f32 v[0:1], v[0:1], v[16:17], v[4:5] op_sel_hi:[0,1,0]
	v_and_b32_e32 v25, 0xffff0000, v66
; __device__ __forceinline__ float silu_f(float v) { return v * __builtin_amdgcn_rcpf(1.0f + __expf(-v)); }
; __device__ __forceinline__ u32x4 pack8(const float (&f)[8]) { u32x4 w; w.x = cvt_pk_bf16(f[0], f[1]); w.y = cvt_pk_bf16(f[2], f[3]); w.z = cvt_pk_bf16(f[4], f[5]); w.w = cvt_pk_bf16(f[6], f[7]); return w; }
; __device__ __forceinline__ void ssd_conv_phase(Frame& F, int j, bool skip_ctx_c) {
;     ...
;           for (int i = 0; i < 8; ++i) { unpack8(raw[i + 2], pc);
; #pragma unroll
;               for (int c = 0; c < 8; ++c) o[i][c] = silu_f(bi[c] + w0[c] * pa[c] + w1[c] * pb[c] + w2[c] * pc[c]);
; #pragma unroll
;               for (int c = 0; c < 8; ++c) { pa[c] = pb[c]; pb[c] = pc[c]; } } }
;         if (cb < 64) {
;             bf16_t* dst = (rb < MLAT) ? xst + ((size_t)sb * DI + c0) * LSEQ + tl : xst + (size_t)NB * DI * LSEQ + ((size_t)sb * DI + c0) * LCTX + tl;
; #pragma unroll
;             for (int c = 0; c < 8; ++c) { float t8[8];
; #pragma unroll
;                 for (int i = 0; i < 8; ++i) t8[i] = o[i][c];
;                 *(u32x4*)(dst + (size_t)c * T) = pack8(t8); }
;         } else if (cb < 80) {
;             const int cc = c0 - DI;
; #pragma unroll
;             for (int i = 0; i < 8; ++i) *(u32x4*)(bm + (size_t)(seq0 + tl + i) * GNW + cc) = pack8(o[i]);
;             bf16_t* dst = (rb < MLAT) ? bmt + ((size_t)sb * GNW + cc) * LSEQ + tl : bmt + (size_t)NB * GNW * LSEQ + ((size_t)sb * GNW + cc) * LCTX + tl;
	v_mov_b32_e32 v24, v21
	v_pk_fma_f32 v[0:1], v[6:7], v[20:21], v[0:1] op_sel_hi:[0,1,1]
	v_pk_fma_f32 v[0:1], v[8:9], v[24:25], v[0:1] op_sel_hi:[0,1,1]
	v_mul_f32_e32 v6, 0xbfb8aa3b, v1
	v_lshlrev_b32_e32 v8, 16, v71
	v_lshlrev_b32_e32 v9, 16, v67
	v_exp_f32_e32 v6, v6
	v_pk_mov_b32 v[16:17], v[88:89], v[8:9] op_sel:[1,0]
	v_fma_f32 v75, v2, v88, v14
	v_pk_mul_f32 v[16:17], v[82:83], v[16:17]
	v_fmac_f32_e32 v14, v2, v89
	v_add_f32_e32 v2, v75, v16
	v_add_f32_e32 v2, v2, v17
	v_rcp_f32_e32 v13, v5
	v_add_f32_e32 v5, 1.0, v6
	v_mul_f32_e32 v6, 0xbfb8aa3b, v2
	v_exp_f32_e32 v6, v6
	v_pk_mul_f32 v[8:9], v[82:83], v[8:9]
	v_and_b32_e32 v17, 0xffff0000, v31
	v_and_b32_e32 v16, 0xffff0000, v27
	v_add_f32_e32 v6, 1.0, v6
	v_rcp_f32_e32 v6, v6
	v_and_b32_e32 v19, 0xffff0000, v19
	v_and_b32_e32 v18, 0xffff0000, v23
	v_add_f32_e32 v8, v14, v8
	v_mul_f32_e32 v88, v2, v6
	v_mov_b32_e32 v2, v3
	v_mov_b32_e32 v6, v15
	v_pk_fma_f32 v[14:15], v[2:3], v[18:19], v[6:7] op_sel_hi:[0,1,0]
	v_mov_b32_e32 v10, v7
	v_pk_mov_b32 v[18:19], v[18:19], v[16:17] op_sel:[1,0]
	v_mul_f32_e32 v4, 0xbfb8aa3b, v0
	v_pk_fma_f32 v[14:15], v[10:11], v[18:19], v[14:15] op_sel_hi:[0,1,1]
	v_mov_b32_e32 v18, v11
	v_pk_fma_f32 v[14:15], v[18:19], v[16:17], v[14:15] op_sel_hi:[0,1,1]
	v_mul_f32_e32 v3, 0xbfb8aa3b, v14
	v_exp_f32_e32 v3, v3
	v_mul_f32_e32 v7, 0xbfb8aa3b, v15
	v_exp_f32_e32 v7, v7
	v_pk_mul_f32 v[56:57], v[28:29], v[12:13]
	v_add_f32_e32 v3, 1.0, v3
	v_and_b32_e32 v13, 0xffff0000, v39
	v_and_b32_e32 v12, 0xffff0000, v35
	v_rcp_f32_e32 v20, v3
	v_add_f32_e32 v3, 1.0, v7
	v_exp_f32_e32 v4, v4
	v_pk_fma_f32 v[22:23], v[2:3], v[16:17], v[6:7] op_sel_hi:[0,1,0]
	v_pk_mov_b32 v[16:17], v[16:17], v[12:13] op_sel:[1,0]
	v_rcp_f32_e32 v5, v5
	v_pk_fma_f32 v[16:17], v[10:11], v[16:17], v[22:23] op_sel_hi:[0,1,1]
	v_pk_fma_f32 v[16:17], v[18:19], v[12:13], v[16:17] op_sel_hi:[0,1,1]
	v_mul_f32_e32 v7, 0xbfb8aa3b, v16
	v_add_f32_e32 v4, 1.0, v4
	v_exp_f32_e32 v7, v7
	v_mul_f32_e32 v11, 0xbfb8aa3b, v17
	v_rcp_f32_e32 v4, v4
	v_exp_f32_e32 v11, v11
	v_rcp_f32_e32 v21, v3
	v_add_f32_e32 v3, 1.0, v7
	v_pk_mul_f32 v[58:59], v[0:1], v[4:5]
	v_and_b32_e32 v1, 0xffff0000, v47
	v_and_b32_e32 v0, 0xffff0000, v43
	v_rcp_f32_e32 v22, v3
	v_add_f32_e32 v3, 1.0, v11
	v_add_f32_e32 v8, v8, v9
	v_pk_fma_f32 v[24:25], v[2:3], v[12:13], v[6:7] op_sel_hi:[0,1,0]
	v_pk_mov_b32 v[12:13], v[12:13], v[0:1] op_sel:[1,0]
	v_mul_f32_e32 v9, 0xbfb8aa3b, v8
	v_pk_fma_f32 v[12:13], v[10:11], v[12:13], v[24:25] op_sel_hi:[0,1,1]
	v_exp_f32_e32 v9, v9
	v_pk_fma_f32 v[12:13], v[18:19], v[0:1], v[12:13] op_sel_hi:[0,1,1]
	v_mul_f32_e32 v7, 0xbfb8aa3b, v12
	v_exp_f32_e32 v7, v7
	v_mul_f32_e32 v11, 0xbfb8aa3b, v13
	v_exp_f32_e32 v11, v11
	v_add_f32_e32 v9, 1.0, v9
	v_rcp_f32_e32 v9, v9
	v_rcp_f32_e32 v23, v3
	v_add_f32_e32 v3, 1.0, v7
	v_rcp_f32_e32 v24, v3
	v_add_f32_e32 v3, 1.0, v11
	v_and_b32_e32 v5, 0xffff0000, v71
	v_mov_b32_e32 v4, v1
	v_pk_fma_f32 v[0:1], v[2:3], v[0:1], v[6:7] op_sel_hi:[0,1,0]
	v_mul_f32_e32 v89, v8, v9
	v_and_b32_e32 v9, 0xffff0000, v67
	v_mov_b32_e32 v8, v5
	v_pk_fma_f32 v[0:1], v[10:11], v[4:5], v[0:1] op_sel_hi:[0,1,1]
	v_pk_fma_f32 v[0:1], v[18:19], v[8:9], v[0:1] op_sel_hi:[0,1,1]
	v_mul_f32_e32 v2, 0xbfb8aa3b, v0
	v_mul_f32_e32 v4, 0xbfb8aa3b, v1
	v_exp_f32_e32 v2, v2
	v_exp_f32_e32 v4, v4
	v_rcp_f32_e32 v25, v3
	v_pk_mul_f32 v[48:49], v[130:131], v[128:129]
	v_add_f32_e32 v2, 1.0, v2
	v_add_f32_e32 v3, 1.0, v4
	v_rcp_f32_e32 v2, v2
	v_rcp_f32_e32 v3, v3
	v_pk_mul_f32 v[34:35], v[14:15], v[20:21]
	v_pk_mul_f32 v[38:39], v[16:17], v[22:23]
	v_pk_mul_f32 v[42:43], v[12:13], v[24:25]
	v_pk_mul_f32 v[46:47], v[0:1], v[2:3]
	s_cmp_gt_i32 s15, 63
	s_mov_b64 s[4:5], -1
	s_cbranch_scc0 .LBB0_412
	s_cmpk_lt_u32 s15, 0x50
	v_cvt_pk_bf16_f32 v20, v101, v79
	v_cvt_pk_bf16_f32 v21, v100, v33
	v_cvt_pk_bf16_f32 v22, v99, v51
	v_cvt_pk_bf16_f32 v23, v97, v35
	v_cvt_pk_bf16_f32 v28, v98, v78
	v_cvt_pk_bf16_f32 v29, v96, v32
	v_cvt_pk_bf16_f32 v30, v95, v50
	v_cvt_pk_bf16_f32 v31, v94, v34
	v_ashrrev_i32_e32 v77, 31, v76
	v_or_b32_e32 v82, 1, v76
	v_cvt_pk_bf16_f32 v24, v105, v80
	v_cvt_pk_bf16_f32 v25, v102, v36
	v_cvt_pk_bf16_f32 v26, v108, v54
	v_cvt_pk_bf16_f32 v27, v103, v38
	v_or_b32_e32 v70, 2, v76
	v_cvt_pk_bf16_f32 v16, v106, v81
	v_cvt_pk_bf16_f32 v17, v107, v37
	v_cvt_pk_bf16_f32 v18, v109, v55
	v_cvt_pk_bf16_f32 v19, v104, v39
	v_or_b32_e32 v68, 3, v76
	v_cvt_pk_bf16_f32 v12, v113, v48
	v_cvt_pk_bf16_f32 v13, v110, v40
	v_cvt_pk_bf16_f32 v14, v116, v56
	v_cvt_pk_bf16_f32 v15, v111, v42
	v_or_b32_e32 v66, 4, v76
	v_cvt_pk_bf16_f32 v8, v114, v49
	v_cvt_pk_bf16_f32 v9, v115, v41
	v_cvt_pk_bf16_f32 v10, v117, v57
	v_cvt_pk_bf16_f32 v11, v112, v43
	v_or_b32_e32 v64, 5, v76
	v_cvt_pk_bf16_f32 v4, v118, v52
	v_cvt_pk_bf16_f32 v5, v86, v44
	v_cvt_pk_bf16_f32 v6, v84, v58
	v_cvt_pk_bf16_f32 v7, v88, v46
	v_or_b32_e32 v62, 6, v76
	v_cvt_pk_bf16_f32 v0, v119, v53
	v_cvt_pk_bf16_f32 v1, v87, v45
	v_cvt_pk_bf16_f32 v2, v85, v59
	v_cvt_pk_bf16_f32 v3, v89, v47
	v_or_b32_e32 v60, 7, v76
	s_cbranch_scc1 .LBB0_409
; __device__ __forceinline__ u32x4 pack8(const float (&f)[8]) { u32x4 w; w.x = cvt_pk_bf16(f[0], f[1]); w.y = cvt_pk_bf16(f[2], f[3]); w.z = cvt_pk_bf16(f[4], f[5]); w.w = cvt_pk_bf16(f[6], f[7]); return w; }
; __device__ __forceinline__ void ssd_conv_phase(Frame& F, int j, bool skip_ctx_c) {
;     ...
;         } else if (cb < 80) {
;             const int cc = c0 - DI;
; #pragma unroll
;             for (int i = 0; i < 8; ++i) *(u32x4*)(bm + (size_t)(seq0 + tl + i) * GNW + cc) = pack8(o[i]);
;             bf16_t* dst = (rb < MLAT) ? bmt + ((size_t)sb * GNW + cc) * LSEQ + tl : bmt + (size_t)NB * GNW * LSEQ + ((size_t)sb * GNW + cc) * LCTX + tl;
; #pragma unroll
;             for (int c = 0; c < 8; ++c) { float t8[8];
; #pragma unroll
;                 for (int i = 0; i < 8; ++i) t8[i] = o[i][c];
;                 *(u32x4*)(dst + (size_t)c * T) = pack8(t8); }
;         } else {
;             const int cc = c0 - DI - GNW;
; #pragma unroll
;             for (int i = 0; i < 8; ++i) *(u32x4*)(cm + (size_t)(seq0 + tl + i) * GNW + cc) = pack8(o[i]);
;         }
	v_lshl_add_u64 v[90:91], v[72:73], 1, s[66:67]
	v_lshlrev_b64 v[120:121], 11, v[76:77]
	v_lshl_add_u64 v[120:121], v[90:91], 0, v[120:121]
	s_mov_b32 s4, 0x43efd000
	v_add_co_u32_e32 v120, vcc, s4, v120
	v_ashrrev_i32_e32 v83, 31, v82
	s_nop 0
	v_addc_co_u32_e32 v121, vcc, 0, v121, vcc
	global_store_dwordx4 v[120:121], v[28:31], off offset:2048 sc1
	v_lshlrev_b64 v[120:121], 11, v[82:83]
	v_lshl_add_u64 v[120:121], v[90:91], 0, v[120:121]
	v_add_co_u32_e32 v120, vcc, s4, v120
	v_ashrrev_i32_e32 v71, 31, v70
	s_nop 0
	v_addc_co_u32_e32 v121, vcc, 0, v121, vcc
	global_store_dwordx4 v[120:121], v[20:23], off offset:2048 sc1
	v_lshlrev_b64 v[120:121], 11, v[70:71]
	v_lshl_add_u64 v[120:121], v[90:91], 0, v[120:121]
	v_add_co_u32_e32 v120, vcc, s4, v120
	v_ashrrev_i32_e32 v69, 31, v68
	s_nop 0
	v_addc_co_u32_e32 v121, vcc, 0, v121, vcc
	global_store_dwordx4 v[120:121], v[24:27], off offset:2048 sc1
	v_lshlrev_b64 v[120:121], 11, v[68:69]
	v_lshl_add_u64 v[120:121], v[90:91], 0, v[120:121]
	v_add_co_u32_e32 v120, vcc, s4, v120
	v_ashrrev_i32_e32 v67, 31, v66
	s_nop 0
	v_addc_co_u32_e32 v121, vcc, 0, v121, vcc
	global_store_dwordx4 v[120:121], v[16:19], off offset:2048 sc1
	v_lshlrev_b64 v[120:121], 11, v[66:67]
	v_lshl_add_u64 v[120:121], v[90:91], 0, v[120:121]
	v_add_co_u32_e32 v120, vcc, s4, v120
	v_ashrrev_i32_e32 v65, 31, v64
	s_nop 0
	v_addc_co_u32_e32 v121, vcc, 0, v121, vcc
	global_store_dwordx4 v[120:121], v[12:15], off offset:2048 sc1
	v_lshlrev_b64 v[120:121], 11, v[64:65]
	v_lshl_add_u64 v[120:121], v[90:91], 0, v[120:121]
	v_add_co_u32_e32 v120, vcc, s4, v120
	v_ashrrev_i32_e32 v63, 31, v62
	s_nop 0
	v_addc_co_u32_e32 v121, vcc, 0, v121, vcc
	global_store_dwordx4 v[120:121], v[8:11], off offset:2048 sc1
	v_lshlrev_b64 v[120:121], 11, v[62:63]
	v_lshl_add_u64 v[120:121], v[90:91], 0, v[120:121]
	v_add_co_u32_e32 v120, vcc, s4, v120
	v_ashrrev_i32_e32 v61, 31, v60
	s_nop 0
	v_addc_co_u32_e32 v121, vcc, 0, v121, vcc
	global_store_dwordx4 v[120:121], v[4:7], off offset:2048 sc1
	v_lshlrev_b64 v[120:121], 11, v[60:61]
	v_lshl_add_u64 v[90:91], v[90:91], 0, v[120:121]
	v_add_co_u32_e32 v90, vcc, 0x43efd000, v90
	s_mov_b64 s[4:5], 0
	s_nop 0
	v_addc_co_u32_e32 v91, vcc, 0, v91, vcc
	global_store_dwordx4 v[90:91], v[0:3], off offset:2048 sc1
.LBB0_409:
	s_andn2_b64 vcc, exec, s[4:5]
	s_cbranch_vccnz .LBB0_411
	v_add_u32_e32 v90, 0xfffff000, v72
	v_readlane_b32 s4, v253, 7
	v_ashrrev_i32_e32 v91, 31, v90
	v_readlane_b32 s5, v253, 8
	v_lshlrev_b64 v[76:77], 11, v[76:77]
	v_ashrrev_i32_e32 v83, 31, v82
	v_lshl_add_u64 v[120:121], v[90:91], 1, s[4:5]
	v_lshl_add_u64 v[76:77], v[120:121], 0, v[76:77]
	global_store_dwordx4 v[76:77], v[28:31], off sc1
	v_ashrrev_i32_e32 v71, 31, v70
	s_ashr_i32 s39, s38, 31
	v_lshlrev_b64 v[28:29], 11, v[82:83]
	v_lshl_add_u64 v[28:29], v[120:121], 0, v[28:29]
	global_store_dwordx4 v[28:29], v[20:23], off sc1
	s_and_b64 s[4:5], s[36:37], exec
	v_ashrrev_i32_e32 v69, 31, v68
	v_lshlrev_b64 v[20:21], 11, v[70:71]
	v_lshl_add_u64 v[20:21], v[120:121], 0, v[20:21]
	s_mov_b32 s4, 0x41b00000
	global_store_dwordx4 v[20:21], v[24:27], off sc1
	v_lshlrev_b64 v[20:21], 11, v[68:69]
	s_cselect_b32 s4, s4, 0x43b00000
	v_lshl_add_u64 v[20:21], v[120:121], 0, v[20:21]
	v_ashrrev_i32_e32 v67, 31, v66
	s_add_u32 s15, s66, s4
	global_store_dwordx4 v[20:21], v[16:19], off sc1
	s_addc_u32 s17, s67, 0
	v_ashrrev_i32_e32 v65, 31, v64
	v_lshlrev_b64 v[16:17], 11, v[66:67]
	v_lshl_add_u64 v[16:17], v[120:121], 0, v[16:17]
	s_and_b64 s[4:5], s[36:37], exec
	global_store_dwordx4 v[16:17], v[12:15], off sc1
	s_cselect_b32 s4, 22, 19
	v_ashrrev_i32_e32 v63, 31, v62
	v_lshlrev_b64 v[12:13], 11, v[64:65]
	v_lshl_add_u64 v[12:13], v[120:121], 0, v[12:13]
	s_lshl_b64 s[4:5], s[38:39], s4
	global_store_dwordx4 v[12:13], v[8:11], off sc1
	s_add_u32 s4, s15, s4
	v_ashrrev_i32_e32 v61, 31, v60
	v_lshlrev_b64 v[8:9], 11, v[62:63]
	v_lshl_add_u64 v[8:9], v[120:121], 0, v[8:9]
	s_addc_u32 s5, s17, s5
	global_store_dwordx4 v[8:9], v[4:7], off sc1
	s_and_b64 s[40:41], s[36:37], exec
	s_cselect_b32 s15, 12, 9
	v_lshlrev_b64 v[4:5], 11, v[60:61]
	v_lshl_add_u64 v[4:5], v[120:121], 0, v[4:5]
	global_store_dwordx4 v[4:5], v[0:3], off sc1
	v_ashrrev_i32_e32 v75, 31, v74
	v_readlane_b32 s17, v255, 9
	v_lshlrev_b64 v[0:1], s15, v[90:91]
	v_lshl_add_u64 v[0:1], s[4:5], 0, v[0:1]
	v_lshl_add_u64 v[4:5], v[74:75], 1, v[0:1]
	v_cvt_pk_bf16_f32 v0, v98, v101
	v_cvt_pk_bf16_f32 v1, v105, v106
	v_cvt_pk_bf16_f32 v2, v113, v114
	v_cvt_pk_bf16_f32 v3, v118, v119
	s_lshl_b32 s4, s14, 1
	s_mov_b32 s5, s92
	global_store_dwordx4 v[4:5], v[0:3], off sc1
	v_lshl_add_u64 v[6:7], v[4:5], 0, s[4:5]
	s_lshl_b32 s4, s14, 2
	v_cvt_pk_bf16_f32 v0, v78, v79
	v_cvt_pk_bf16_f32 v1, v80, v81
	v_cvt_pk_bf16_f32 v2, v48, v49
	v_cvt_pk_bf16_f32 v3, v52, v53
	global_store_dwordx4 v[6:7], v[0:3], off sc1
	v_lshl_add_u64 v[6:7], v[4:5], 0, s[4:5]
	s_mul_i32 s4, s14, 6
	v_cvt_pk_bf16_f32 v0, v96, v100
	v_cvt_pk_bf16_f32 v1, v102, v107
	v_cvt_pk_bf16_f32 v2, v110, v115
	v_cvt_pk_bf16_f32 v3, v86, v87
	global_store_dwordx4 v[6:7], v[0:3], off sc1
	v_lshl_add_u64 v[6:7], v[4:5], 0, s[4:5]
	s_lshl_b32 s4, s14, 3
	v_cvt_pk_bf16_f32 v0, v32, v33
	v_cvt_pk_bf16_f32 v1, v36, v37
	v_cvt_pk_bf16_f32 v2, v40, v41
	v_cvt_pk_bf16_f32 v3, v44, v45
	global_store_dwordx4 v[6:7], v[0:3], off sc1
	v_lshl_add_u64 v[6:7], v[4:5], 0, s[4:5]
	s_mul_i32 s4, s14, 10
	v_cvt_pk_bf16_f32 v0, v95, v99
	v_cvt_pk_bf16_f32 v1, v108, v109
	v_cvt_pk_bf16_f32 v2, v116, v117
	v_cvt_pk_bf16_f32 v3, v84, v85
	global_store_dwordx4 v[6:7], v[0:3], off sc1
	v_lshl_add_u64 v[6:7], v[4:5], 0, s[4:5]
	s_mul_i32 s4, s14, 12
	v_cvt_pk_bf16_f32 v0, v50, v51
	v_cvt_pk_bf16_f32 v1, v54, v55
	v_cvt_pk_bf16_f32 v2, v56, v57
	v_cvt_pk_bf16_f32 v3, v58, v59
	global_store_dwordx4 v[6:7], v[0:3], off sc1
	v_lshl_add_u64 v[6:7], v[4:5], 0, s[4:5]
	s_mul_i32 s4, s14, 14
	v_cvt_pk_bf16_f32 v0, v94, v97
	v_cvt_pk_bf16_f32 v1, v103, v104
	v_cvt_pk_bf16_f32 v2, v111, v112
	v_cvt_pk_bf16_f32 v3, v88, v89
	global_store_dwordx4 v[6:7], v[0:3], off sc1
	v_lshl_add_u64 v[4:5], v[4:5], 0, s[4:5]
	s_nop 0
	v_cvt_pk_bf16_f32 v0, v34, v35
	v_cvt_pk_bf16_f32 v1, v38, v39
	v_cvt_pk_bf16_f32 v2, v42, v43
	v_cvt_pk_bf16_f32 v3, v46, v47
	global_store_dwordx4 v[4:5], v[0:3], off sc1

; __device__ __forceinline__ u32x4 pack8(const float (&f)[8]) { u32x4 w; w.x = cvt_pk_bf16(f[0], f[1]); w.y = cvt_pk_bf16(f[2], f[3]); w.z = cvt_pk_bf16(f[4], f[5]); w.w = cvt_pk_bf16(f[6], f[7]); return w; }
; __device__ __forceinline__ void ssd_conv_phase(Frame& F, int j, bool skip_ctx_c) {
;     ...
;         if (cb < 64) {
;             bf16_t* dst = (rb < MLAT) ? xst + ((size_t)sb * DI + c0) * LSEQ + tl : xst + (size_t)NB * DI * LSEQ + ((size_t)sb * DI + c0) * LCTX + tl;
; #pragma unroll
;             for (int c = 0; c < 8; ++c) { float t8[8];
; #pragma unroll
;                 for (int i = 0; i < 8; ++i) t8[i] = o[i][c];
;                 *(u32x4*)(dst + (size_t)c * T) = pack8(t8); }
.LBB0_412:
	s_andn2_b64 vcc, exec, s[4:5]
	s_cbranch_vccnz .LBB0_380
	s_ashr_i32 s39, s38, 31
	s_and_b64 s[4:5], s[36:37], exec
	s_mov_b32 s4, 0x36700000
	s_cselect_b32 s4, s4, 0x3e700000
	s_add_u32 s15, s66, s4
	s_addc_u32 s17, s67, 0
	s_and_b64 s[4:5], s[36:37], exec
	s_cselect_b32 s4, 24, 21
	s_lshl_b64 s[4:5], s[38:39], s4
	s_add_u32 s4, s15, s4
	s_addc_u32 s5, s17, s5
	s_and_b64 s[36:37], s[36:37], exec
	s_cselect_b32 s15, 12, 9
	v_lshlrev_b64 v[0:1], s15, v[72:73]
	v_ashrrev_i32_e32 v75, 31, v74
	v_lshl_add_u64 v[0:1], s[4:5], 0, v[0:1]
	v_lshl_add_u64 v[4:5], v[74:75], 1, v[0:1]
	v_cvt_pk_bf16_f32 v0, v98, v101
	v_cvt_pk_bf16_f32 v1, v105, v106
	v_cvt_pk_bf16_f32 v2, v113, v114
	v_cvt_pk_bf16_f32 v3, v118, v119
	s_lshl_b32 s4, s14, 1
	s_mov_b32 s5, s92
	global_store_dwordx4 v[4:5], v[0:3], off sc1
	v_lshl_add_u64 v[6:7], v[4:5], 0, s[4:5]
	s_lshl_b32 s4, s14, 2
	v_cvt_pk_bf16_f32 v0, v78, v79
	v_cvt_pk_bf16_f32 v1, v80, v81
	v_cvt_pk_bf16_f32 v2, v48, v49
	v_cvt_pk_bf16_f32 v3, v52, v53
	global_store_dwordx4 v[6:7], v[0:3], off sc1
	v_lshl_add_u64 v[6:7], v[4:5], 0, s[4:5]
	s_mul_i32 s4, s14, 6
	v_cvt_pk_bf16_f32 v0, v96, v100
	v_cvt_pk_bf16_f32 v1, v102, v107
	v_cvt_pk_bf16_f32 v2, v110, v115
	v_cvt_pk_bf16_f32 v3, v86, v87
	global_store_dwordx4 v[6:7], v[0:3], off sc1
	v_lshl_add_u64 v[6:7], v[4:5], 0, s[4:5]
	s_lshl_b32 s4, s14, 3
	v_cvt_pk_bf16_f32 v0, v32, v33
	v_cvt_pk_bf16_f32 v1, v36, v37
	v_cvt_pk_bf16_f32 v2, v40, v41
	v_cvt_pk_bf16_f32 v3, v44, v45
	global_store_dwordx4 v[6:7], v[0:3], off sc1
	v_lshl_add_u64 v[6:7], v[4:5], 0, s[4:5]
	s_mul_i32 s4, s14, 10
	v_cvt_pk_bf16_f32 v0, v95, v99
	v_cvt_pk_bf16_f32 v1, v108, v109
	v_cvt_pk_bf16_f32 v2, v116, v117
	v_cvt_pk_bf16_f32 v3, v84, v85
	global_store_dwordx4 v[6:7], v[0:3], off sc1
	v_lshl_add_u64 v[6:7], v[4:5], 0, s[4:5]
	s_mul_i32 s4, s14, 12
	v_cvt_pk_bf16_f32 v0, v50, v51
	v_cvt_pk_bf16_f32 v1, v54, v55
	v_cvt_pk_bf16_f32 v2, v56, v57
	v_cvt_pk_bf16_f32 v3, v58, v59
	global_store_dwordx4 v[6:7], v[0:3], off sc1
	v_lshl_add_u64 v[6:7], v[4:5], 0, s[4:5]
	s_mul_i32 s4, s14, 14
	v_cvt_pk_bf16_f32 v0, v94, v97
	v_cvt_pk_bf16_f32 v1, v103, v104
	v_cvt_pk_bf16_f32 v2, v111, v112
	v_cvt_pk_bf16_f32 v3, v88, v89
	v_readlane_b32 s17, v255, 9
	global_store_dwordx4 v[6:7], v[0:3], off sc1
	v_lshl_add_u64 v[4:5], v[4:5], 0, s[4:5]
	s_nop 0
	v_cvt_pk_bf16_f32 v0, v34, v35
	v_cvt_pk_bf16_f32 v1, v38, v39
	v_cvt_pk_bf16_f32 v2, v42, v43
	v_cvt_pk_bf16_f32 v3, v46, v47
	global_store_dwordx4 v[4:5], v[0:3], off sc1
	s_branch .LBB0_380

; __device__ __forceinline__ float silu_f(float v) { return v * __builtin_amdgcn_rcpf(1.0f + __expf(-v)); }
;     __device__ __forceinline__ const char* a(const pg8::Unit& u) const { return (const char*)ws + aoff + (size_t)u.pm * 256 * K_ * 2 + (u.kq < 0 ? 0 : u.kq * (K_ / 4) * 2); }
;     __device__ __forceinline__ const char* b(const pg8::Unit& u) const { return (const char*)ws + boff + (size_t)u.pn * 256 * K_ * 2 + (u.kq < 0 ? 0 : u.kq * (K_ / 4) * 2); }
;     __device__ __forceinline__ const char* a(const pg8::Unit& u) const { return (const char*)ws + WS_A + (size_t)u.pm * 256 * D * 2; }
;     __device__ __forceinline__ const char* b(const pg8::Unit& u) const { return (const char*)ws + boff + (size_t)u.pn * 256 * D * 2; }
;     __device__ __forceinline__ const char* a(const pg8::Unit& u) const { return (const char*)ws + WS_A + (size_t)u.pm * 256 * D * 2; }
;     __device__ __forceinline__ const char* b(const pg8::Unit& u) const { return (const char*)ws + boff + (size_t)u.pn * 256 * D * 2; }
;     __device__ __forceinline__ const char* a(const pg8::Unit& u) const { return (const char*)ws + WS_W1 + (size_t)(u.pm & 1) * 256 * 256 * 2; }
;     __device__ __forceinline__ const char* b(const pg8::Unit& u) const { return (const char*)ws + WS_A + ((size_t)u.pn * 256 * D + (size_t)(u.pm >> 1) * 256) * 2; }
; __device__ __forceinline__ void ssd_gate_norm_phase(Frame& F, int j, int nrows) {
;     ...
;     for (int r = gw; r < nrows; r += NGW) {
; #pragma unroll 4
;         for (int g = 0; g < 8; ++g) { const size_t off = (size_t)r * DI + g * 512 + lane * 8;
;             float a[8], b[8], zz[8]; unpack8(__builtin_nontemporal_load((const u32x4*)(yf + off)), a); unpack8(__builtin_nontemporal_load((const u32x4*)(yb + off)), b); unpack8(__builtin_nontemporal_load((const u32x4*)(z + off)), zz);
;             float ss = 0.f;
; #pragma unroll
;             for (int c = 0; c < 8; ++c) { a[c] = (a[c] + b[c]) * silu_f(zz[c]); ss += a[c] * a[c]; }
;             const float rs = rsqrtf(wave_sum(ss, lane) * (1.0f / 512.0f) + EPS);
;             const f32x4* gp = (const f32x4*)(ng + g * 512 + lane * 8); const f32x4 g0 = gp[0], g1 = gp[1];
;             a[0] *= rs * g0.x; a[1] *= rs * g0.y; a[2] *= rs * g0.z; a[3] *= rs * g0.w; a[4] *= rs * g1.x; a[5] *= rs * g1.y; a[6] *= rs * g1.z; a[7] *= rs * g1.w;
;             *(u32x4*)(yf + off) = pack8(a); }
.Lgn_row:
	s_add_i32 s5, s4, s72
	s_cmp_ge_i32 s5, s7
	s_cbranch_scc1 .Lgn_last
	s_waitcnt vmcnt(21)
	v_lshlrev_b32_e32 v198, 16, v4
	v_and_b32_e32 v199, 0xffff0000, v4
	v_lshlrev_b32_e32 v206, 16, v8
	v_and_b32_e32 v207, 0xffff0000, v8
	v_lshlrev_b32_e32 v214, 16, v12
	v_and_b32_e32 v215, 0xffff0000, v12
	v_lshlrev_b32_e32 v200, 16, v5
	v_and_b32_e32 v201, 0xffff0000, v5
	v_lshlrev_b32_e32 v208, 16, v9
	v_and_b32_e32 v209, 0xffff0000, v9
	v_lshlrev_b32_e32 v216, 16, v13
	v_and_b32_e32 v217, 0xffff0000, v13
	v_lshlrev_b32_e32 v202, 16, v6
	v_and_b32_e32 v203, 0xffff0000, v6
	v_lshlrev_b32_e32 v210, 16, v10
	v_and_b32_e32 v211, 0xffff0000, v10
	v_lshlrev_b32_e32 v218, 16, v14
	v_and_b32_e32 v219, 0xffff0000, v14
	v_lshlrev_b32_e32 v204, 16, v7
	v_and_b32_e32 v205, 0xffff0000, v7
	v_lshlrev_b32_e32 v212, 16, v11
	v_and_b32_e32 v213, 0xffff0000, v11
	v_lshlrev_b32_e32 v220, 16, v15
	v_and_b32_e32 v221, 0xffff0000, v15
	global_load_dwordx4 v[4:7], v[168:169], off nt
	global_load_dwordx4 v[8:11], v[172:173], off nt
	global_load_dwordx4 v[12:15], v[178:179], off nt
	v_pk_add_f32 v[198:199], v[198:199], v[206:207]
	v_pk_add_f32 v[200:201], v[200:201], v[208:209]
	v_pk_add_f32 v[202:203], v[202:203], v[210:211]
	v_pk_add_f32 v[204:205], v[204:205], v[212:213]
	v_mul_f32_e32 v206, 0xbfb8aa3b, v214
	v_mul_f32_e32 v207, 0xbfb8aa3b, v215
	v_mul_f32_e32 v208, 0xbfb8aa3b, v216
	v_mul_f32_e32 v209, 0xbfb8aa3b, v217
	v_mul_f32_e32 v210, 0xbfb8aa3b, v218
	v_mul_f32_e32 v211, 0xbfb8aa3b, v219
	v_mul_f32_e32 v212, 0xbfb8aa3b, v220
	v_mul_f32_e32 v213, 0xbfb8aa3b, v221
	v_exp_f32_e32 v206, v206
	v_exp_f32_e32 v207, v207
	v_exp_f32_e32 v208, v208
	v_exp_f32_e32 v209, v209
	v_exp_f32_e32 v210, v210
	v_exp_f32_e32 v211, v211
	v_exp_f32_e32 v212, v212
	v_exp_f32_e32 v213, v213
	v_add_f32_e32 v206, 1.0, v206
	v_add_f32_e32 v207, 1.0, v207
	v_add_f32_e32 v208, 1.0, v208
	v_add_f32_e32 v209, 1.0, v209
	v_add_f32_e32 v210, 1.0, v210
	v_add_f32_e32 v211, 1.0, v211
	v_add_f32_e32 v212, 1.0, v212
	v_add_f32_e32 v213, 1.0, v213
	v_rcp_f32_e32 v206, v206
	v_rcp_f32_e32 v207, v207
	v_rcp_f32_e32 v208, v208
	v_rcp_f32_e32 v209, v209
	v_rcp_f32_e32 v210, v210
	v_rcp_f32_e32 v211, v211
	v_rcp_f32_e32 v212, v212
	v_rcp_f32_e32 v213, v213
	s_nop 0
	v_pk_mul_f32 v[206:207], v[206:207], v[214:215]
	v_pk_mul_f32 v[208:209], v[208:209], v[216:217]
	v_pk_mul_f32 v[210:211], v[210:211], v[218:219]
	v_pk_mul_f32 v[212:213], v[212:213], v[220:221]
	v_pk_mul_f32 v[198:199], v[198:199], v[206:207]
	v_pk_mul_f32 v[200:201], v[200:201], v[208:209]
	v_pk_mul_f32 v[202:203], v[202:203], v[210:211]
	v_pk_mul_f32 v[204:205], v[204:205], v[212:213]
	v_pk_mul_f32 v[214:215], v[198:199], v[198:199]
	v_pk_mul_f32 v[216:217], v[200:201], v[200:201]
	v_pk_mul_f32 v[218:219], v[202:203], v[202:203]
	v_pk_mul_f32 v[220:221], v[204:205], v[204:205]
	v_add_f32_e32 v230, v214, v215
	v_add_f32_e32 v230, v216, v230
	v_add_f32_e32 v230, v217, v230
	v_add_f32_e32 v230, v218, v230
	v_add_f32_e32 v230, v219, v230
	v_add_f32_e32 v230, v220, v230
	v_add_f32_e32 v230, v221, v230
	v_mov_b32_e32 v231, v177
	s_nop 0
	v_add_f32_dpp v230, v230, v230 row_shr:1 row_mask:0xf bank_mask:0xf bound_ctrl:1
	s_nop 1
	v_add_f32_dpp v230, v230, v230 row_shr:2 row_mask:0xf bank_mask:0xf bound_ctrl:1
	s_nop 1
	v_add_f32_dpp v230, v230, v230 row_shr:4 row_mask:0xf bank_mask:0xf bound_ctrl:1
	s_nop 1
	v_add_f32_dpp v230, v230, v230 row_shr:8 row_mask:0xf bank_mask:0xf bound_ctrl:1
	s_nop 1
	v_mov_b32_dpp v231, v230 row_bcast:15 row_mask:0xa bank_mask:0xf
	v_add_f32_e32 v230, v230, v231
	v_mov_b32_e32 v231, v177
	s_nop 1
	v_mov_b32_dpp v231, v230 row_bcast:31 row_mask:0xc bank_mask:0xf
	v_add_f32_e32 v230, v230, v231
	s_nop 0
	v_readlane_b32 s6, v230, 63
	s_nop 1
	v_fma_f32 v232, s6, v245, v238
	v_cmp_gt_f32_e32 vcc, s85, v232
	v_mul_f32_e32 v231, 0x4b800000, v232
	s_nop 0
	v_cndmask_b32_e32 v232, v232, v231, vcc
	v_rsq_f32_e32 v232, v232
	s_nop 0
	v_mul_f32_e32 v231, 0x45800000, v232
	v_cndmask_b32_e32 v232, v232, v231, vcc
	v_pk_mul_f32 v[222:223], v[100:101], v[232:233] op_sel_hi:[1,0]
	v_pk_mul_f32 v[224:225], v[102:103], v[232:233] op_sel_hi:[1,0]
	v_pk_mul_f32 v[226:227], v[104:105], v[232:233] op_sel_hi:[1,0]
	v_pk_mul_f32 v[228:229], v[106:107], v[232:233] op_sel_hi:[1,0]
	v_pk_mul_f32 v[222:223], v[198:199], v[222:223]
	v_pk_mul_f32 v[224:225], v[200:201], v[224:225]
	v_pk_mul_f32 v[226:227], v[202:203], v[226:227]
	v_pk_mul_f32 v[228:229], v[204:205], v[228:229]
	v_cvt_pk_bf16_f32 v234, v222, v223
	v_cvt_pk_bf16_f32 v235, v224, v225
	v_cvt_pk_bf16_f32 v236, v226, v227
	v_cvt_pk_bf16_f32 v237, v228, v229
	global_store_dwordx4 v[164:165], v[234:237], off sc1
	s_waitcnt vmcnt(22)
; __device__ __forceinline__ float silu_f(float v) { return v * __builtin_amdgcn_rcpf(1.0f + __expf(-v)); }
;     __device__ __forceinline__ const char* a(const pg8::Unit& u) const { return (const char*)ws + aoff + (size_t)u.pm * 256 * K_ * 2 + (u.kq < 0 ? 0 : u.kq * (K_ / 4) * 2); }
;     __device__ __forceinline__ const char* b(const pg8::Unit& u) const { return (const char*)ws + boff + (size_t)u.pn * 256 * K_ * 2 + (u.kq < 0 ? 0 : u.kq * (K_ / 4) * 2); }
;     __device__ __forceinline__ const char* a(const pg8::Unit& u) const { return (const char*)ws + WS_A + (size_t)u.pm * 256 * D * 2; }
;     __device__ __forceinline__ const char* b(const pg8::Unit& u) const { return (const char*)ws + boff + (size_t)u.pn * 256 * D * 2; }
;     __device__ __forceinline__ const char* a(const pg8::Unit& u) const { return (const char*)ws + WS_A + (size_t)u.pm * 256 * D * 2; }
;     __device__ __forceinline__ const char* b(const pg8::Unit& u) const { return (const char*)ws + boff + (size_t)u.pn * 256 * D * 2; }
;     __device__ __forceinline__ const char* a(const pg8::Unit& u) const { return (const char*)ws + WS_W1 + (size_t)(u.pm & 1) * 256 * 256 * 2; }
;     __device__ __forceinline__ const char* b(const pg8::Unit& u) const { return (const char*)ws + WS_A + ((size_t)u.pn * 256 * D + (size_t)(u.pm >> 1) * 256) * 2; }
; __device__ __forceinline__ void ssd_gate_norm_phase(Frame& F, int j, int nrows) {
;     ...
;     for (int r = gw; r < nrows; r += NGW) {
; #pragma unroll 4
;         for (int g = 0; g < 8; ++g) { const size_t off = (size_t)r * DI + g * 512 + lane * 8;
;             float a[8], b[8], zz[8]; unpack8(__builtin_nontemporal_load((const u32x4*)(yf + off)), a); unpack8(__builtin_nontemporal_load((const u32x4*)(yb + off)), b); unpack8(__builtin_nontemporal_load((const u32x4*)(z + off)), zz);
;             float ss = 0.f;
; #pragma unroll
;             for (int c = 0; c < 8; ++c) { a[c] = (a[c] + b[c]) * silu_f(zz[c]); ss += a[c] * a[c]; }
;             const float rs = rsqrtf(wave_sum(ss, lane) * (1.0f / 512.0f) + EPS);
;             const f32x4* gp = (const f32x4*)(ng + g * 512 + lane * 8); const f32x4 g0 = gp[0], g1 = gp[1];
;             a[0] *= rs * g0.x; a[1] *= rs * g0.y; a[2] *= rs * g0.z; a[3] *= rs * g0.w; a[4] *= rs * g1.x; a[5] *= rs * g1.y; a[6] *= rs * g1.z; a[7] *= rs * g1.w;
;             *(u32x4*)(yf + off) = pack8(a); }
	v_lshlrev_b32_e32 v198, 16, v16
	v_and_b32_e32 v199, 0xffff0000, v16
	v_lshlrev_b32_e32 v206, 16, v20
	v_and_b32_e32 v207, 0xffff0000, v20
	v_lshlrev_b32_e32 v214, 16, v24
	v_and_b32_e32 v215, 0xffff0000, v24
	v_lshlrev_b32_e32 v200, 16, v17
	v_and_b32_e32 v201, 0xffff0000, v17
	v_lshlrev_b32_e32 v208, 16, v21
	v_and_b32_e32 v209, 0xffff0000, v21
	v_lshlrev_b32_e32 v216, 16, v25
	v_and_b32_e32 v217, 0xffff0000, v25
	v_lshlrev_b32_e32 v202, 16, v18
	v_and_b32_e32 v203, 0xffff0000, v18
	v_lshlrev_b32_e32 v210, 16, v22
	v_and_b32_e32 v211, 0xffff0000, v22
	v_lshlrev_b32_e32 v218, 16, v26
	v_and_b32_e32 v219, 0xffff0000, v26
	v_lshlrev_b32_e32 v204, 16, v19
	v_and_b32_e32 v205, 0xffff0000, v19
	v_lshlrev_b32_e32 v212, 16, v23
	v_and_b32_e32 v213, 0xffff0000, v23
	v_lshlrev_b32_e32 v220, 16, v27
	v_and_b32_e32 v221, 0xffff0000, v27
	global_load_dwordx4 v[16:19], v[168:169], off offset:1024 nt
	global_load_dwordx4 v[20:23], v[172:173], off offset:1024 nt
	global_load_dwordx4 v[24:27], v[178:179], off offset:1024 nt
	v_pk_add_f32 v[198:199], v[198:199], v[206:207]
	v_pk_add_f32 v[200:201], v[200:201], v[208:209]
	v_pk_add_f32 v[202:203], v[202:203], v[210:211]
	v_pk_add_f32 v[204:205], v[204:205], v[212:213]
	v_mul_f32_e32 v206, 0xbfb8aa3b, v214
	v_mul_f32_e32 v207, 0xbfb8aa3b, v215
	v_mul_f32_e32 v208, 0xbfb8aa3b, v216
	v_mul_f32_e32 v209, 0xbfb8aa3b, v217
	v_mul_f32_e32 v210, 0xbfb8aa3b, v218
	v_mul_f32_e32 v211, 0xbfb8aa3b, v219
	v_mul_f32_e32 v212, 0xbfb8aa3b, v220
	v_mul_f32_e32 v213, 0xbfb8aa3b, v221
	v_exp_f32_e32 v206, v206
	v_exp_f32_e32 v207, v207
	v_exp_f32_e32 v208, v208
	v_exp_f32_e32 v209, v209
	v_exp_f32_e32 v210, v210
	v_exp_f32_e32 v211, v211
	v_exp_f32_e32 v212, v212
	v_exp_f32_e32 v213, v213
	v_add_f32_e32 v206, 1.0, v206
	v_add_f32_e32 v207, 1.0, v207
	v_add_f32_e32 v208, 1.0, v208
	v_add_f32_e32 v209, 1.0, v209
	v_add_f32_e32 v210, 1.0, v210
	v_add_f32_e32 v211, 1.0, v211
	v_add_f32_e32 v212, 1.0, v212
	v_add_f32_e32 v213, 1.0, v213
	v_rcp_f32_e32 v206, v206
	v_rcp_f32_e32 v207, v207
	v_rcp_f32_e32 v208, v208
	v_rcp_f32_e32 v209, v209
	v_rcp_f32_e32 v210, v210
	v_rcp_f32_e32 v211, v211
	v_rcp_f32_e32 v212, v212
	v_rcp_f32_e32 v213, v213
	s_nop 0
	v_pk_mul_f32 v[206:207], v[206:207], v[214:215]
	v_pk_mul_f32 v[208:209], v[208:209], v[216:217]
	v_pk_mul_f32 v[210:211], v[210:211], v[218:219]
	v_pk_mul_f32 v[212:213], v[212:213], v[220:221]
	v_pk_mul_f32 v[198:199], v[198:199], v[206:207]
	v_pk_mul_f32 v[200:201], v[200:201], v[208:209]
	v_pk_mul_f32 v[202:203], v[202:203], v[210:211]
	v_pk_mul_f32 v[204:205], v[204:205], v[212:213]
	v_pk_mul_f32 v[214:215], v[198:199], v[198:199]
	v_pk_mul_f32 v[216:217], v[200:201], v[200:201]
	v_pk_mul_f32 v[218:219], v[202:203], v[202:203]
	v_pk_mul_f32 v[220:221], v[204:205], v[204:205]
	v_add_f32_e32 v230, v214, v215
	v_add_f32_e32 v230, v216, v230
	v_add_f32_e32 v230, v217, v230
	v_add_f32_e32 v230, v218, v230
	v_add_f32_e32 v230, v219, v230
	v_add_f32_e32 v230, v220, v230
	v_add_f32_e32 v230, v221, v230
	v_mov_b32_e32 v231, v177
	s_nop 0
	v_add_f32_dpp v230, v230, v230 row_shr:1 row_mask:0xf bank_mask:0xf bound_ctrl:1
	s_nop 1
	v_add_f32_dpp v230, v230, v230 row_shr:2 row_mask:0xf bank_mask:0xf bound_ctrl:1
	s_nop 1
	v_add_f32_dpp v230, v230, v230 row_shr:4 row_mask:0xf bank_mask:0xf bound_ctrl:1
	s_nop 1
	v_add_f32_dpp v230, v230, v230 row_shr:8 row_mask:0xf bank_mask:0xf bound_ctrl:1
	s_nop 1
	v_mov_b32_dpp v231, v230 row_bcast:15 row_mask:0xa bank_mask:0xf
	v_add_f32_e32 v230, v230, v231
	v_mov_b32_e32 v231, v177
	s_nop 1
	v_mov_b32_dpp v231, v230 row_bcast:31 row_mask:0xc bank_mask:0xf
	v_add_f32_e32 v230, v230, v231
	s_nop 0
	v_readlane_b32 s6, v230, 63
	s_nop 1
	v_fma_f32 v232, s6, v245, v238
	v_cmp_gt_f32_e32 vcc, s85, v232
	v_mul_f32_e32 v231, 0x4b800000, v232
	s_nop 0
	v_cndmask_b32_e32 v232, v232, v231, vcc
	v_rsq_f32_e32 v232, v232
	s_nop 0
	v_mul_f32_e32 v231, 0x45800000, v232
	v_cndmask_b32_e32 v232, v232, v231, vcc
	v_pk_mul_f32 v[222:223], v[108:109], v[232:233] op_sel_hi:[1,0]
	v_pk_mul_f32 v[224:225], v[110:111], v[232:233] op_sel_hi:[1,0]
	v_pk_mul_f32 v[226:227], v[112:113], v[232:233] op_sel_hi:[1,0]
	v_pk_mul_f32 v[228:229], v[114:115], v[232:233] op_sel_hi:[1,0]
	v_pk_mul_f32 v[222:223], v[198:199], v[222:223]
	v_pk_mul_f32 v[224:225], v[200:201], v[224:225]
	v_pk_mul_f32 v[226:227], v[202:203], v[226:227]
	v_pk_mul_f32 v[228:229], v[204:205], v[228:229]
	v_cvt_pk_bf16_f32 v234, v222, v223
	v_cvt_pk_bf16_f32 v235, v224, v225
	v_cvt_pk_bf16_f32 v236, v226, v227
	v_cvt_pk_bf16_f32 v237, v228, v229
	global_store_dwordx4 v[164:165], v[234:237], off offset:1024 sc1
	s_waitcnt vmcnt(23)
; __device__ __forceinline__ float silu_f(float v) { return v * __builtin_amdgcn_rcpf(1.0f + __expf(-v)); }
;     __device__ __forceinline__ const char* a(const pg8::Unit& u) const { return (const char*)ws + aoff + (size_t)u.pm * 256 * K_ * 2 + (u.kq < 0 ? 0 : u.kq * (K_ / 4) * 2); }
;     __device__ __forceinline__ const char* b(const pg8::Unit& u) const { return (const char*)ws + boff + (size_t)u.pn * 256 * K_ * 2 + (u.kq < 0 ? 0 : u.kq * (K_ / 4) * 2); }
;     __device__ __forceinline__ const char* a(const pg8::Unit& u) const { return (const char*)ws + WS_A + (size_t)u.pm * 256 * D * 2; }
;     __device__ __forceinline__ const char* b(const pg8::Unit& u) const { return (const char*)ws + boff + (size_t)u.pn * 256 * D * 2; }
;     __device__ __forceinline__ const char* a(const pg8::Unit& u) const { return (const char*)ws + WS_A + (size_t)u.pm * 256 * D * 2; }
;     __device__ __forceinline__ const char* b(const pg8::Unit& u) const { return (const char*)ws + boff + (size_t)u.pn * 256 * D * 2; }
;     __device__ __forceinline__ const char* a(const pg8::Unit& u) const { return (const char*)ws + WS_W1 + (size_t)(u.pm & 1) * 256 * 256 * 2; }
;     __device__ __forceinline__ const char* b(const pg8::Unit& u) const { return (const char*)ws + WS_A + ((size_t)u.pn * 256 * D + (size_t)(u.pm >> 1) * 256) * 2; }
; __device__ __forceinline__ void ssd_gate_norm_phase(Frame& F, int j, int nrows) {
;     ...
;     for (int r = gw; r < nrows; r += NGW) {
; #pragma unroll 4
;         for (int g = 0; g < 8; ++g) { const size_t off = (size_t)r * DI + g * 512 + lane * 8;
;             float a[8], b[8], zz[8]; unpack8(__builtin_nontemporal_load((const u32x4*)(yf + off)), a); unpack8(__builtin_nontemporal_load((const u32x4*)(yb + off)), b); unpack8(__builtin_nontemporal_load((const u32x4*)(z + off)), zz);
;             float ss = 0.f;
; #pragma unroll
;             for (int c = 0; c < 8; ++c) { a[c] = (a[c] + b[c]) * silu_f(zz[c]); ss += a[c] * a[c]; }
;             const float rs = rsqrtf(wave_sum(ss, lane) * (1.0f / 512.0f) + EPS);
;             const f32x4* gp = (const f32x4*)(ng + g * 512 + lane * 8); const f32x4 g0 = gp[0], g1 = gp[1];
;             a[0] *= rs * g0.x; a[1] *= rs * g0.y; a[2] *= rs * g0.z; a[3] *= rs * g0.w; a[4] *= rs * g1.x; a[5] *= rs * g1.y; a[6] *= rs * g1.z; a[7] *= rs * g1.w;
;             *(u32x4*)(yf + off) = pack8(a); }
	v_lshlrev_b32_e32 v198, 16, v28
	v_and_b32_e32 v199, 0xffff0000, v28
	v_lshlrev_b32_e32 v206, 16, v32
	v_and_b32_e32 v207, 0xffff0000, v32
	v_lshlrev_b32_e32 v214, 16, v36
	v_and_b32_e32 v215, 0xffff0000, v36
	v_lshlrev_b32_e32 v200, 16, v29
	v_and_b32_e32 v201, 0xffff0000, v29
	v_lshlrev_b32_e32 v208, 16, v33
	v_and_b32_e32 v209, 0xffff0000, v33
	v_lshlrev_b32_e32 v216, 16, v37
	v_and_b32_e32 v217, 0xffff0000, v37
	v_lshlrev_b32_e32 v202, 16, v30
	v_and_b32_e32 v203, 0xffff0000, v30
	v_lshlrev_b32_e32 v210, 16, v34
	v_and_b32_e32 v211, 0xffff0000, v34
	v_lshlrev_b32_e32 v218, 16, v38
	v_and_b32_e32 v219, 0xffff0000, v38
	v_lshlrev_b32_e32 v204, 16, v31
	v_and_b32_e32 v205, 0xffff0000, v31
	v_lshlrev_b32_e32 v212, 16, v35
	v_and_b32_e32 v213, 0xffff0000, v35
	v_lshlrev_b32_e32 v220, 16, v39
	v_and_b32_e32 v221, 0xffff0000, v39
	global_load_dwordx4 v[28:31], v[168:169], off offset:2048 nt
	global_load_dwordx4 v[32:35], v[172:173], off offset:2048 nt
	global_load_dwordx4 v[36:39], v[178:179], off offset:2048 nt
	v_pk_add_f32 v[198:199], v[198:199], v[206:207]
	v_pk_add_f32 v[200:201], v[200:201], v[208:209]
	v_pk_add_f32 v[202:203], v[202:203], v[210:211]
	v_pk_add_f32 v[204:205], v[204:205], v[212:213]
	v_mul_f32_e32 v206, 0xbfb8aa3b, v214
	v_mul_f32_e32 v207, 0xbfb8aa3b, v215
	v_mul_f32_e32 v208, 0xbfb8aa3b, v216
	v_mul_f32_e32 v209, 0xbfb8aa3b, v217
	v_mul_f32_e32 v210, 0xbfb8aa3b, v218
	v_mul_f32_e32 v211, 0xbfb8aa3b, v219
	v_mul_f32_e32 v212, 0xbfb8aa3b, v220
	v_mul_f32_e32 v213, 0xbfb8aa3b, v221
	v_exp_f32_e32 v206, v206
	v_exp_f32_e32 v207, v207
	v_exp_f32_e32 v208, v208
	v_exp_f32_e32 v209, v209
	v_exp_f32_e32 v210, v210
	v_exp_f32_e32 v211, v211
	v_exp_f32_e32 v212, v212
	v_exp_f32_e32 v213, v213
	v_add_f32_e32 v206, 1.0, v206
	v_add_f32_e32 v207, 1.0, v207
	v_add_f32_e32 v208, 1.0, v208
	v_add_f32_e32 v209, 1.0, v209
	v_add_f32_e32 v210, 1.0, v210
	v_add_f32_e32 v211, 1.0, v211
	v_add_f32_e32 v212, 1.0, v212
	v_add_f32_e32 v213, 1.0, v213
	v_rcp_f32_e32 v206, v206
	v_rcp_f32_e32 v207, v207
	v_rcp_f32_e32 v208, v208
	v_rcp_f32_e32 v209, v209
	v_rcp_f32_e32 v210, v210
	v_rcp_f32_e32 v211, v211
	v_rcp_f32_e32 v212, v212
	v_rcp_f32_e32 v213, v213
	s_nop 0
	v_pk_mul_f32 v[206:207], v[206:207], v[214:215]
	v_pk_mul_f32 v[208:209], v[208:209], v[216:217]
	v_pk_mul_f32 v[210:211], v[210:211], v[218:219]
	v_pk_mul_f32 v[212:213], v[212:213], v[220:221]
	v_pk_mul_f32 v[198:199], v[198:199], v[206:207]
	v_pk_mul_f32 v[200:201], v[200:201], v[208:209]
	v_pk_mul_f32 v[202:203], v[202:203], v[210:211]
	v_pk_mul_f32 v[204:205], v[204:205], v[212:213]
	v_pk_mul_f32 v[214:215], v[198:199], v[198:199]
	v_pk_mul_f32 v[216:217], v[200:201], v[200:201]
	v_pk_mul_f32 v[218:219], v[202:203], v[202:203]
	v_pk_mul_f32 v[220:221], v[204:205], v[204:205]
	v_add_f32_e32 v230, v214, v215
	v_add_f32_e32 v230, v216, v230
	v_add_f32_e32 v230, v217, v230
	v_add_f32_e32 v230, v218, v230
	v_add_f32_e32 v230, v219, v230
	v_add_f32_e32 v230, v220, v230
	v_add_f32_e32 v230, v221, v230
	v_mov_b32_e32 v231, v177
	s_nop 0
	v_add_f32_dpp v230, v230, v230 row_shr:1 row_mask:0xf bank_mask:0xf bound_ctrl:1
	s_nop 1
	v_add_f32_dpp v230, v230, v230 row_shr:2 row_mask:0xf bank_mask:0xf bound_ctrl:1
	s_nop 1
	v_add_f32_dpp v230, v230, v230 row_shr:4 row_mask:0xf bank_mask:0xf bound_ctrl:1
	s_nop 1
	v_add_f32_dpp v230, v230, v230 row_shr:8 row_mask:0xf bank_mask:0xf bound_ctrl:1
	s_nop 1
	v_mov_b32_dpp v231, v230 row_bcast:15 row_mask:0xa bank_mask:0xf
	v_add_f32_e32 v230, v230, v231
	v_mov_b32_e32 v231, v177
	s_nop 1
	v_mov_b32_dpp v231, v230 row_bcast:31 row_mask:0xc bank_mask:0xf
	v_add_f32_e32 v230, v230, v231
	s_nop 0
	v_readlane_b32 s6, v230, 63
	s_nop 1
	v_fma_f32 v232, s6, v245, v238
	v_cmp_gt_f32_e32 vcc, s85, v232
	v_mul_f32_e32 v231, 0x4b800000, v232
	s_nop 0
	v_cndmask_b32_e32 v232, v232, v231, vcc
	v_rsq_f32_e32 v232, v232
	s_nop 0
	v_mul_f32_e32 v231, 0x45800000, v232
	v_cndmask_b32_e32 v232, v232, v231, vcc
	v_pk_mul_f32 v[222:223], v[116:117], v[232:233] op_sel_hi:[1,0]
	v_pk_mul_f32 v[224:225], v[118:119], v[232:233] op_sel_hi:[1,0]
	v_pk_mul_f32 v[226:227], v[120:121], v[232:233] op_sel_hi:[1,0]
	v_pk_mul_f32 v[228:229], v[122:123], v[232:233] op_sel_hi:[1,0]
	v_pk_mul_f32 v[222:223], v[198:199], v[222:223]
	v_pk_mul_f32 v[224:225], v[200:201], v[224:225]
	v_pk_mul_f32 v[226:227], v[202:203], v[226:227]
	v_pk_mul_f32 v[228:229], v[204:205], v[228:229]
	v_cvt_pk_bf16_f32 v234, v222, v223
	v_cvt_pk_bf16_f32 v235, v224, v225
	v_cvt_pk_bf16_f32 v236, v226, v227
	v_cvt_pk_bf16_f32 v237, v228, v229
	global_store_dwordx4 v[164:165], v[234:237], off offset:2048 sc1
	s_waitcnt vmcnt(24)
; __device__ __forceinline__ float silu_f(float v) { return v * __builtin_amdgcn_rcpf(1.0f + __expf(-v)); }
;     __device__ __forceinline__ const char* a(const pg8::Unit& u) const { return (const char*)ws + aoff + (size_t)u.pm * 256 * K_ * 2 + (u.kq < 0 ? 0 : u.kq * (K_ / 4) * 2); }
;     __device__ __forceinline__ const char* b(const pg8::Unit& u) const { return (const char*)ws + boff + (size_t)u.pn * 256 * K_ * 2 + (u.kq < 0 ? 0 : u.kq * (K_ / 4) * 2); }
;     __device__ __forceinline__ const char* a(const pg8::Unit& u) const { return (const char*)ws + WS_A + (size_t)u.pm * 256 * D * 2; }
;     __device__ __forceinline__ const char* b(const pg8::Unit& u) const { return (const char*)ws + boff + (size_t)u.pn * 256 * D * 2; }
;     __device__ __forceinline__ const char* a(const pg8::Unit& u) const { return (const char*)ws + WS_A + (size_t)u.pm * 256 * D * 2; }
;     __device__ __forceinline__ const char* b(const pg8::Unit& u) const { return (const char*)ws + boff + (size_t)u.pn * 256 * D * 2; }
;     __device__ __forceinline__ const char* a(const pg8::Unit& u) const { return (const char*)ws + WS_W1 + (size_t)(u.pm & 1) * 256 * 256 * 2; }
;     __device__ __forceinline__ const char* b(const pg8::Unit& u) const { return (const char*)ws + WS_A + ((size_t)u.pn * 256 * D + (size_t)(u.pm >> 1) * 256) * 2; }
; __device__ __forceinline__ void ssd_gate_norm_phase(Frame& F, int j, int nrows) {
;     ...
;     for (int r = gw; r < nrows; r += NGW) {
; #pragma unroll 4
;         for (int g = 0; g < 8; ++g) { const size_t off = (size_t)r * DI + g * 512 + lane * 8;
;             float a[8], b[8], zz[8]; unpack8(__builtin_nontemporal_load((const u32x4*)(yf + off)), a); unpack8(__builtin_nontemporal_load((const u32x4*)(yb + off)), b); unpack8(__builtin_nontemporal_load((const u32x4*)(z + off)), zz);
;             float ss = 0.f;
; #pragma unroll
;             for (int c = 0; c < 8; ++c) { a[c] = (a[c] + b[c]) * silu_f(zz[c]); ss += a[c] * a[c]; }
;             const float rs = rsqrtf(wave_sum(ss, lane) * (1.0f / 512.0f) + EPS);
;             const f32x4* gp = (const f32x4*)(ng + g * 512 + lane * 8); const f32x4 g0 = gp[0], g1 = gp[1];
;             a[0] *= rs * g0.x; a[1] *= rs * g0.y; a[2] *= rs * g0.z; a[3] *= rs * g0.w; a[4] *= rs * g1.x; a[5] *= rs * g1.y; a[6] *= rs * g1.z; a[7] *= rs * g1.w;
;             *(u32x4*)(yf + off) = pack8(a); }
	v_lshlrev_b32_e32 v198, 16, v40
	v_and_b32_e32 v199, 0xffff0000, v40
	v_lshlrev_b32_e32 v206, 16, v44
	v_and_b32_e32 v207, 0xffff0000, v44
	v_lshlrev_b32_e32 v214, 16, v48
	v_and_b32_e32 v215, 0xffff0000, v48
	v_lshlrev_b32_e32 v200, 16, v41
	v_and_b32_e32 v201, 0xffff0000, v41
	v_lshlrev_b32_e32 v208, 16, v45
	v_and_b32_e32 v209, 0xffff0000, v45
	v_lshlrev_b32_e32 v216, 16, v49
	v_and_b32_e32 v217, 0xffff0000, v49
	v_lshlrev_b32_e32 v202, 16, v42
	v_and_b32_e32 v203, 0xffff0000, v42
	v_lshlrev_b32_e32 v210, 16, v46
	v_and_b32_e32 v211, 0xffff0000, v46
	v_lshlrev_b32_e32 v218, 16, v50
	v_and_b32_e32 v219, 0xffff0000, v50
	v_lshlrev_b32_e32 v204, 16, v43
	v_and_b32_e32 v205, 0xffff0000, v43
	v_lshlrev_b32_e32 v212, 16, v47
	v_and_b32_e32 v213, 0xffff0000, v47
	v_lshlrev_b32_e32 v220, 16, v51
	v_and_b32_e32 v221, 0xffff0000, v51
	global_load_dwordx4 v[40:43], v[168:169], off offset:3072 nt
	global_load_dwordx4 v[44:47], v[172:173], off offset:3072 nt
	global_load_dwordx4 v[48:51], v[178:179], off offset:3072 nt
	v_pk_add_f32 v[198:199], v[198:199], v[206:207]
	v_pk_add_f32 v[200:201], v[200:201], v[208:209]
	v_pk_add_f32 v[202:203], v[202:203], v[210:211]
	v_pk_add_f32 v[204:205], v[204:205], v[212:213]
	v_mul_f32_e32 v206, 0xbfb8aa3b, v214
	v_mul_f32_e32 v207, 0xbfb8aa3b, v215
	v_mul_f32_e32 v208, 0xbfb8aa3b, v216
	v_mul_f32_e32 v209, 0xbfb8aa3b, v217
	v_mul_f32_e32 v210, 0xbfb8aa3b, v218
	v_mul_f32_e32 v211, 0xbfb8aa3b, v219
	v_mul_f32_e32 v212, 0xbfb8aa3b, v220
	v_mul_f32_e32 v213, 0xbfb8aa3b, v221
	v_exp_f32_e32 v206, v206
	v_exp_f32_e32 v207, v207
	v_exp_f32_e32 v208, v208
	v_exp_f32_e32 v209, v209
	v_exp_f32_e32 v210, v210
	v_exp_f32_e32 v211, v211
	v_exp_f32_e32 v212, v212
	v_exp_f32_e32 v213, v213
	v_add_f32_e32 v206, 1.0, v206
	v_add_f32_e32 v207, 1.0, v207
	v_add_f32_e32 v208, 1.0, v208
	v_add_f32_e32 v209, 1.0, v209
	v_add_f32_e32 v210, 1.0, v210
	v_add_f32_e32 v211, 1.0, v211
	v_add_f32_e32 v212, 1.0, v212
	v_add_f32_e32 v213, 1.0, v213
	v_rcp_f32_e32 v206, v206
	v_rcp_f32_e32 v207, v207
	v_rcp_f32_e32 v208, v208
	v_rcp_f32_e32 v209, v209
	v_rcp_f32_e32 v210, v210
	v_rcp_f32_e32 v211, v211
	v_rcp_f32_e32 v212, v212
	v_rcp_f32_e32 v213, v213
	s_nop 0
	v_pk_mul_f32 v[206:207], v[206:207], v[214:215]
	v_pk_mul_f32 v[208:209], v[208:209], v[216:217]
	v_pk_mul_f32 v[210:211], v[210:211], v[218:219]
	v_pk_mul_f32 v[212:213], v[212:213], v[220:221]
	v_pk_mul_f32 v[198:199], v[198:199], v[206:207]
	v_pk_mul_f32 v[200:201], v[200:201], v[208:209]
	v_pk_mul_f32 v[202:203], v[202:203], v[210:211]
	v_pk_mul_f32 v[204:205], v[204:205], v[212:213]
	v_pk_mul_f32 v[214:215], v[198:199], v[198:199]
	v_pk_mul_f32 v[216:217], v[200:201], v[200:201]
	v_pk_mul_f32 v[218:219], v[202:203], v[202:203]
	v_pk_mul_f32 v[220:221], v[204:205], v[204:205]
	v_add_f32_e32 v230, v214, v215
	v_add_f32_e32 v230, v216, v230
	v_add_f32_e32 v230, v217, v230
	v_add_f32_e32 v230, v218, v230
	v_add_f32_e32 v230, v219, v230
	v_add_f32_e32 v230, v220, v230
	v_add_f32_e32 v230, v221, v230
	v_mov_b32_e32 v231, v177
	s_nop 0
	v_add_f32_dpp v230, v230, v230 row_shr:1 row_mask:0xf bank_mask:0xf bound_ctrl:1
	s_nop 1
	v_add_f32_dpp v230, v230, v230 row_shr:2 row_mask:0xf bank_mask:0xf bound_ctrl:1
	s_nop 1
	v_add_f32_dpp v230, v230, v230 row_shr:4 row_mask:0xf bank_mask:0xf bound_ctrl:1
	s_nop 1
	v_add_f32_dpp v230, v230, v230 row_shr:8 row_mask:0xf bank_mask:0xf bound_ctrl:1
	s_nop 1
	v_mov_b32_dpp v231, v230 row_bcast:15 row_mask:0xa bank_mask:0xf
	v_add_f32_e32 v230, v230, v231
	v_mov_b32_e32 v231, v177
	s_nop 1
	v_mov_b32_dpp v231, v230 row_bcast:31 row_mask:0xc bank_mask:0xf
	v_add_f32_e32 v230, v230, v231
	s_nop 0
	v_readlane_b32 s6, v230, 63
	s_nop 1
	v_fma_f32 v232, s6, v245, v238
	v_cmp_gt_f32_e32 vcc, s85, v232
	v_mul_f32_e32 v231, 0x4b800000, v232
	s_nop 0
	v_cndmask_b32_e32 v232, v232, v231, vcc
	v_rsq_f32_e32 v232, v232
	s_nop 0
	v_mul_f32_e32 v231, 0x45800000, v232
	v_cndmask_b32_e32 v232, v232, v231, vcc
	v_pk_mul_f32 v[222:223], v[124:125], v[232:233] op_sel_hi:[1,0]
	v_pk_mul_f32 v[224:225], v[126:127], v[232:233] op_sel_hi:[1,0]
	v_pk_mul_f32 v[226:227], v[128:129], v[232:233] op_sel_hi:[1,0]
	v_pk_mul_f32 v[228:229], v[130:131], v[232:233] op_sel_hi:[1,0]
	v_pk_mul_f32 v[222:223], v[198:199], v[222:223]
	v_pk_mul_f32 v[224:225], v[200:201], v[224:225]
	v_pk_mul_f32 v[226:227], v[202:203], v[226:227]
	v_pk_mul_f32 v[228:229], v[204:205], v[228:229]
	v_cvt_pk_bf16_f32 v234, v222, v223
	v_cvt_pk_bf16_f32 v235, v224, v225
	v_cvt_pk_bf16_f32 v236, v226, v227
	v_cvt_pk_bf16_f32 v237, v228, v229
	global_store_dwordx4 v[164:165], v[234:237], off offset:3072 sc1
	s_waitcnt vmcnt(25)
; __device__ __forceinline__ float silu_f(float v) { return v * __builtin_amdgcn_rcpf(1.0f + __expf(-v)); }
;     __device__ __forceinline__ const char* a(const pg8::Unit& u) const { return (const char*)ws + aoff + (size_t)u.pm * 256 * K_ * 2 + (u.kq < 0 ? 0 : u.kq * (K_ / 4) * 2); }
;     __device__ __forceinline__ const char* b(const pg8::Unit& u) const { return (const char*)ws + boff + (size_t)u.pn * 256 * K_ * 2 + (u.kq < 0 ? 0 : u.kq * (K_ / 4) * 2); }
;     __device__ __forceinline__ const char* a(const pg8::Unit& u) const { return (const char*)ws + WS_A + (size_t)u.pm * 256 * D * 2; }
;     __device__ __forceinline__ const char* b(const pg8::Unit& u) const { return (const char*)ws + boff + (size_t)u.pn * 256 * D * 2; }
;     __device__ __forceinline__ const char* a(const pg8::Unit& u) const { return (const char*)ws + WS_A + (size_t)u.pm * 256 * D * 2; }
;     __device__ __forceinline__ const char* b(const pg8::Unit& u) const { return (const char*)ws + boff + (size_t)u.pn * 256 * D * 2; }
;     __device__ __forceinline__ const char* a(const pg8::Unit& u) const { return (const char*)ws + WS_W1 + (size_t)(u.pm & 1) * 256 * 256 * 2; }
;     __device__ __forceinline__ const char* b(const pg8::Unit& u) const { return (const char*)ws + WS_A + ((size_t)u.pn * 256 * D + (size_t)(u.pm >> 1) * 256) * 2; }
; __device__ __forceinline__ void ssd_gate_norm_phase(Frame& F, int j, int nrows) {
;     ...
;     for (int r = gw; r < nrows; r += NGW) {
; #pragma unroll 4
;         for (int g = 0; g < 8; ++g) { const size_t off = (size_t)r * DI + g * 512 + lane * 8;
;             float a[8], b[8], zz[8]; unpack8(__builtin_nontemporal_load((const u32x4*)(yf + off)), a); unpack8(__builtin_nontemporal_load((const u32x4*)(yb + off)), b); unpack8(__builtin_nontemporal_load((const u32x4*)(z + off)), zz);
;             float ss = 0.f;
; #pragma unroll
;             for (int c = 0; c < 8; ++c) { a[c] = (a[c] + b[c]) * silu_f(zz[c]); ss += a[c] * a[c]; }
;             const float rs = rsqrtf(wave_sum(ss, lane) * (1.0f / 512.0f) + EPS);
;             const f32x4* gp = (const f32x4*)(ng + g * 512 + lane * 8); const f32x4 g0 = gp[0], g1 = gp[1];
;             a[0] *= rs * g0.x; a[1] *= rs * g0.y; a[2] *= rs * g0.z; a[3] *= rs * g0.w; a[4] *= rs * g1.x; a[5] *= rs * g1.y; a[6] *= rs * g1.z; a[7] *= rs * g1.w;
;             *(u32x4*)(yf + off) = pack8(a); }
	v_lshlrev_b32_e32 v198, 16, v52
	v_and_b32_e32 v199, 0xffff0000, v52
	v_lshlrev_b32_e32 v206, 16, v56
	v_and_b32_e32 v207, 0xffff0000, v56
	v_lshlrev_b32_e32 v214, 16, v60
	v_and_b32_e32 v215, 0xffff0000, v60
	v_lshlrev_b32_e32 v200, 16, v53
	v_and_b32_e32 v201, 0xffff0000, v53
	v_lshlrev_b32_e32 v208, 16, v57
	v_and_b32_e32 v209, 0xffff0000, v57
	v_lshlrev_b32_e32 v216, 16, v61
	v_and_b32_e32 v217, 0xffff0000, v61
	v_lshlrev_b32_e32 v202, 16, v54
	v_and_b32_e32 v203, 0xffff0000, v54
	v_lshlrev_b32_e32 v210, 16, v58
	v_and_b32_e32 v211, 0xffff0000, v58
	v_lshlrev_b32_e32 v218, 16, v62
	v_and_b32_e32 v219, 0xffff0000, v62
	v_lshlrev_b32_e32 v204, 16, v55
	v_and_b32_e32 v205, 0xffff0000, v55
	v_lshlrev_b32_e32 v212, 16, v59
	v_and_b32_e32 v213, 0xffff0000, v59
	v_lshlrev_b32_e32 v220, 16, v63
	v_and_b32_e32 v221, 0xffff0000, v63
	global_load_dwordx4 v[52:55], v[170:171], off nt
	global_load_dwordx4 v[56:59], v[174:175], off nt
	global_load_dwordx4 v[60:63], v[180:181], off nt
	v_pk_add_f32 v[198:199], v[198:199], v[206:207]
	v_pk_add_f32 v[200:201], v[200:201], v[208:209]
	v_pk_add_f32 v[202:203], v[202:203], v[210:211]
	v_pk_add_f32 v[204:205], v[204:205], v[212:213]
	v_mul_f32_e32 v206, 0xbfb8aa3b, v214
	v_mul_f32_e32 v207, 0xbfb8aa3b, v215
	v_mul_f32_e32 v208, 0xbfb8aa3b, v216
	v_mul_f32_e32 v209, 0xbfb8aa3b, v217
	v_mul_f32_e32 v210, 0xbfb8aa3b, v218
	v_mul_f32_e32 v211, 0xbfb8aa3b, v219
	v_mul_f32_e32 v212, 0xbfb8aa3b, v220
	v_mul_f32_e32 v213, 0xbfb8aa3b, v221
	v_exp_f32_e32 v206, v206
	v_exp_f32_e32 v207, v207
	v_exp_f32_e32 v208, v208
	v_exp_f32_e32 v209, v209
	v_exp_f32_e32 v210, v210
	v_exp_f32_e32 v211, v211
	v_exp_f32_e32 v212, v212
	v_exp_f32_e32 v213, v213
	v_add_f32_e32 v206, 1.0, v206
	v_add_f32_e32 v207, 1.0, v207
	v_add_f32_e32 v208, 1.0, v208
	v_add_f32_e32 v209, 1.0, v209
	v_add_f32_e32 v210, 1.0, v210
	v_add_f32_e32 v211, 1.0, v211
	v_add_f32_e32 v212, 1.0, v212
	v_add_f32_e32 v213, 1.0, v213
	v_rcp_f32_e32 v206, v206
	v_rcp_f32_e32 v207, v207
	v_rcp_f32_e32 v208, v208
	v_rcp_f32_e32 v209, v209
	v_rcp_f32_e32 v210, v210
	v_rcp_f32_e32 v211, v211
	v_rcp_f32_e32 v212, v212
	v_rcp_f32_e32 v213, v213
	s_nop 0
	v_pk_mul_f32 v[206:207], v[206:207], v[214:215]
	v_pk_mul_f32 v[208:209], v[208:209], v[216:217]
	v_pk_mul_f32 v[210:211], v[210:211], v[218:219]
	v_pk_mul_f32 v[212:213], v[212:213], v[220:221]
	v_pk_mul_f32 v[198:199], v[198:199], v[206:207]
	v_pk_mul_f32 v[200:201], v[200:201], v[208:209]
	v_pk_mul_f32 v[202:203], v[202:203], v[210:211]
	v_pk_mul_f32 v[204:205], v[204:205], v[212:213]
	v_pk_mul_f32 v[214:215], v[198:199], v[198:199]
	v_pk_mul_f32 v[216:217], v[200:201], v[200:201]
	v_pk_mul_f32 v[218:219], v[202:203], v[202:203]
	v_pk_mul_f32 v[220:221], v[204:205], v[204:205]
	v_add_f32_e32 v230, v214, v215
	v_add_f32_e32 v230, v216, v230
	v_add_f32_e32 v230, v217, v230
	v_add_f32_e32 v230, v218, v230
	v_add_f32_e32 v230, v219, v230
	v_add_f32_e32 v230, v220, v230
	v_add_f32_e32 v230, v221, v230
	v_mov_b32_e32 v231, v177
	s_nop 0
	v_add_f32_dpp v230, v230, v230 row_shr:1 row_mask:0xf bank_mask:0xf bound_ctrl:1
	s_nop 1
	v_add_f32_dpp v230, v230, v230 row_shr:2 row_mask:0xf bank_mask:0xf bound_ctrl:1
	s_nop 1
	v_add_f32_dpp v230, v230, v230 row_shr:4 row_mask:0xf bank_mask:0xf bound_ctrl:1
	s_nop 1
	v_add_f32_dpp v230, v230, v230 row_shr:8 row_mask:0xf bank_mask:0xf bound_ctrl:1
	s_nop 1
	v_mov_b32_dpp v231, v230 row_bcast:15 row_mask:0xa bank_mask:0xf
	v_add_f32_e32 v230, v230, v231
	v_mov_b32_e32 v231, v177
	s_nop 1
	v_mov_b32_dpp v231, v230 row_bcast:31 row_mask:0xc bank_mask:0xf
	v_add_f32_e32 v230, v230, v231
	s_nop 0
	v_readlane_b32 s6, v230, 63
	s_nop 1
	v_fma_f32 v232, s6, v245, v238
	v_cmp_gt_f32_e32 vcc, s85, v232
	v_mul_f32_e32 v231, 0x4b800000, v232
	s_nop 0
	v_cndmask_b32_e32 v232, v232, v231, vcc
	v_rsq_f32_e32 v232, v232
	s_nop 0
	v_mul_f32_e32 v231, 0x45800000, v232
	v_cndmask_b32_e32 v232, v232, v231, vcc
	v_pk_mul_f32 v[222:223], v[132:133], v[232:233] op_sel_hi:[1,0]
	v_pk_mul_f32 v[224:225], v[134:135], v[232:233] op_sel_hi:[1,0]
	v_pk_mul_f32 v[226:227], v[136:137], v[232:233] op_sel_hi:[1,0]
	v_pk_mul_f32 v[228:229], v[138:139], v[232:233] op_sel_hi:[1,0]
	v_pk_mul_f32 v[222:223], v[198:199], v[222:223]
	v_pk_mul_f32 v[224:225], v[200:201], v[224:225]
	v_pk_mul_f32 v[226:227], v[202:203], v[226:227]
	v_pk_mul_f32 v[228:229], v[204:205], v[228:229]
	v_cvt_pk_bf16_f32 v234, v222, v223
	v_cvt_pk_bf16_f32 v235, v224, v225
	v_cvt_pk_bf16_f32 v236, v226, v227
	v_cvt_pk_bf16_f32 v237, v228, v229
	global_store_dwordx4 v[166:167], v[234:237], off sc1
	s_waitcnt vmcnt(26)
; __device__ __forceinline__ float silu_f(float v) { return v * __builtin_amdgcn_rcpf(1.0f + __expf(-v)); }
;     __device__ __forceinline__ const char* a(const pg8::Unit& u) const { return (const char*)ws + aoff + (size_t)u.pm * 256 * K_ * 2 + (u.kq < 0 ? 0 : u.kq * (K_ / 4) * 2); }
;     __device__ __forceinline__ const char* b(const pg8::Unit& u) const { return (const char*)ws + boff + (size_t)u.pn * 256 * K_ * 2 + (u.kq < 0 ? 0 : u.kq * (K_ / 4) * 2); }
;     __device__ __forceinline__ const char* a(const pg8::Unit& u) const { return (const char*)ws + WS_A + (size_t)u.pm * 256 * D * 2; }
;     __device__ __forceinline__ const char* b(const pg8::Unit& u) const { return (const char*)ws + boff + (size_t)u.pn * 256 * D * 2; }
;     __device__ __forceinline__ const char* a(const pg8::Unit& u) const { return (const char*)ws + WS_A + (size_t)u.pm * 256 * D * 2; }
;     __device__ __forceinline__ const char* b(const pg8::Unit& u) const { return (const char*)ws + boff + (size_t)u.pn * 256 * D * 2; }
;     __device__ __forceinline__ const char* a(const pg8::Unit& u) const { return (const char*)ws + WS_W1 + (size_t)(u.pm & 1) * 256 * 256 * 2; }
;     __device__ __forceinline__ const char* b(const pg8::Unit& u) const { return (const char*)ws + WS_A + ((size_t)u.pn * 256 * D + (size_t)(u.pm >> 1) * 256) * 2; }
; __device__ __forceinline__ void ssd_gate_norm_phase(Frame& F, int j, int nrows) {
;     ...
;     for (int r = gw; r < nrows; r += NGW) {
; #pragma unroll 4
;         for (int g = 0; g < 8; ++g) { const size_t off = (size_t)r * DI + g * 512 + lane * 8;
;             float a[8], b[8], zz[8]; unpack8(__builtin_nontemporal_load((const u32x4*)(yf + off)), a); unpack8(__builtin_nontemporal_load((const u32x4*)(yb + off)), b); unpack8(__builtin_nontemporal_load((const u32x4*)(z + off)), zz);
;             float ss = 0.f;
; #pragma unroll
;             for (int c = 0; c < 8; ++c) { a[c] = (a[c] + b[c]) * silu_f(zz[c]); ss += a[c] * a[c]; }
;             const float rs = rsqrtf(wave_sum(ss, lane) * (1.0f / 512.0f) + EPS);
;             const f32x4* gp = (const f32x4*)(ng + g * 512 + lane * 8); const f32x4 g0 = gp[0], g1 = gp[1];
;             a[0] *= rs * g0.x; a[1] *= rs * g0.y; a[2] *= rs * g0.z; a[3] *= rs * g0.w; a[4] *= rs * g1.x; a[5] *= rs * g1.y; a[6] *= rs * g1.z; a[7] *= rs * g1.w;
;             *(u32x4*)(yf + off) = pack8(a); }
	v_lshlrev_b32_e32 v198, 16, v64
	v_and_b32_e32 v199, 0xffff0000, v64
	v_lshlrev_b32_e32 v206, 16, v68
	v_and_b32_e32 v207, 0xffff0000, v68
	v_lshlrev_b32_e32 v214, 16, v72
	v_and_b32_e32 v215, 0xffff0000, v72
	v_lshlrev_b32_e32 v200, 16, v65
	v_and_b32_e32 v201, 0xffff0000, v65
	v_lshlrev_b32_e32 v208, 16, v69
	v_and_b32_e32 v209, 0xffff0000, v69
	v_lshlrev_b32_e32 v216, 16, v73
	v_and_b32_e32 v217, 0xffff0000, v73
	v_lshlrev_b32_e32 v202, 16, v66
	v_and_b32_e32 v203, 0xffff0000, v66
	v_lshlrev_b32_e32 v210, 16, v70
	v_and_b32_e32 v211, 0xffff0000, v70
	v_lshlrev_b32_e32 v218, 16, v74
	v_and_b32_e32 v219, 0xffff0000, v74
	v_lshlrev_b32_e32 v204, 16, v67
	v_and_b32_e32 v205, 0xffff0000, v67
	v_lshlrev_b32_e32 v212, 16, v71
	v_and_b32_e32 v213, 0xffff0000, v71
	v_lshlrev_b32_e32 v220, 16, v75
	v_and_b32_e32 v221, 0xffff0000, v75
	global_load_dwordx4 v[64:67], v[170:171], off offset:1024 nt
	global_load_dwordx4 v[68:71], v[174:175], off offset:1024 nt
	global_load_dwordx4 v[72:75], v[180:181], off offset:1024 nt
	v_pk_add_f32 v[198:199], v[198:199], v[206:207]
	v_pk_add_f32 v[200:201], v[200:201], v[208:209]
	v_pk_add_f32 v[202:203], v[202:203], v[210:211]
	v_pk_add_f32 v[204:205], v[204:205], v[212:213]
	v_mul_f32_e32 v206, 0xbfb8aa3b, v214
	v_mul_f32_e32 v207, 0xbfb8aa3b, v215
	v_mul_f32_e32 v208, 0xbfb8aa3b, v216
	v_mul_f32_e32 v209, 0xbfb8aa3b, v217
	v_mul_f32_e32 v210, 0xbfb8aa3b, v218
	v_mul_f32_e32 v211, 0xbfb8aa3b, v219
	v_mul_f32_e32 v212, 0xbfb8aa3b, v220
	v_mul_f32_e32 v213, 0xbfb8aa3b, v221
	v_exp_f32_e32 v206, v206
	v_exp_f32_e32 v207, v207
	v_exp_f32_e32 v208, v208
	v_exp_f32_e32 v209, v209
	v_exp_f32_e32 v210, v210
	v_exp_f32_e32 v211, v211
	v_exp_f32_e32 v212, v212
	v_exp_f32_e32 v213, v213
	v_add_f32_e32 v206, 1.0, v206
	v_add_f32_e32 v207, 1.0, v207
	v_add_f32_e32 v208, 1.0, v208
	v_add_f32_e32 v209, 1.0, v209
	v_add_f32_e32 v210, 1.0, v210
	v_add_f32_e32 v211, 1.0, v211
	v_add_f32_e32 v212, 1.0, v212
	v_add_f32_e32 v213, 1.0, v213
	v_rcp_f32_e32 v206, v206
	v_rcp_f32_e32 v207, v207
	v_rcp_f32_e32 v208, v208
	v_rcp_f32_e32 v209, v209
	v_rcp_f32_e32 v210, v210
	v_rcp_f32_e32 v211, v211
	v_rcp_f32_e32 v212, v212
	v_rcp_f32_e32 v213, v213
	s_nop 0
	v_pk_mul_f32 v[206:207], v[206:207], v[214:215]
	v_pk_mul_f32 v[208:209], v[208:209], v[216:217]
	v_pk_mul_f32 v[210:211], v[210:211], v[218:219]
	v_pk_mul_f32 v[212:213], v[212:213], v[220:221]
	v_pk_mul_f32 v[198:199], v[198:199], v[206:207]
	v_pk_mul_f32 v[200:201], v[200:201], v[208:209]
	v_pk_mul_f32 v[202:203], v[202:203], v[210:211]
	v_pk_mul_f32 v[204:205], v[204:205], v[212:213]
	v_pk_mul_f32 v[214:215], v[198:199], v[198:199]
	v_pk_mul_f32 v[216:217], v[200:201], v[200:201]
	v_pk_mul_f32 v[218:219], v[202:203], v[202:203]
	v_pk_mul_f32 v[220:221], v[204:205], v[204:205]
	v_add_f32_e32 v230, v214, v215
	v_add_f32_e32 v230, v216, v230
	v_add_f32_e32 v230, v217, v230
	v_add_f32_e32 v230, v218, v230
	v_add_f32_e32 v230, v219, v230
	v_add_f32_e32 v230, v220, v230
	v_add_f32_e32 v230, v221, v230
	v_mov_b32_e32 v231, v177
	s_nop 0
	v_add_f32_dpp v230, v230, v230 row_shr:1 row_mask:0xf bank_mask:0xf bound_ctrl:1
	s_nop 1
	v_add_f32_dpp v230, v230, v230 row_shr:2 row_mask:0xf bank_mask:0xf bound_ctrl:1
	s_nop 1
	v_add_f32_dpp v230, v230, v230 row_shr:4 row_mask:0xf bank_mask:0xf bound_ctrl:1
	s_nop 1
	v_add_f32_dpp v230, v230, v230 row_shr:8 row_mask:0xf bank_mask:0xf bound_ctrl:1
	s_nop 1
	v_mov_b32_dpp v231, v230 row_bcast:15 row_mask:0xa bank_mask:0xf
	v_add_f32_e32 v230, v230, v231
	v_mov_b32_e32 v231, v177
	s_nop 1
	v_mov_b32_dpp v231, v230 row_bcast:31 row_mask:0xc bank_mask:0xf
	v_add_f32_e32 v230, v230, v231
	s_nop 0
	v_readlane_b32 s6, v230, 63
	s_nop 1
	v_fma_f32 v232, s6, v245, v238
	v_cmp_gt_f32_e32 vcc, s85, v232
	v_mul_f32_e32 v231, 0x4b800000, v232
	s_nop 0
	v_cndmask_b32_e32 v232, v232, v231, vcc
	v_rsq_f32_e32 v232, v232
	s_nop 0
	v_mul_f32_e32 v231, 0x45800000, v232
	v_cndmask_b32_e32 v232, v232, v231, vcc
	v_pk_mul_f32 v[222:223], v[140:141], v[232:233] op_sel_hi:[1,0]
	v_pk_mul_f32 v[224:225], v[142:143], v[232:233] op_sel_hi:[1,0]
	v_pk_mul_f32 v[226:227], v[144:145], v[232:233] op_sel_hi:[1,0]
	v_pk_mul_f32 v[228:229], v[146:147], v[232:233] op_sel_hi:[1,0]
	v_pk_mul_f32 v[222:223], v[198:199], v[222:223]
	v_pk_mul_f32 v[224:225], v[200:201], v[224:225]
	v_pk_mul_f32 v[226:227], v[202:203], v[226:227]
	v_pk_mul_f32 v[228:229], v[204:205], v[228:229]
	v_cvt_pk_bf16_f32 v234, v222, v223
	v_cvt_pk_bf16_f32 v235, v224, v225
	v_cvt_pk_bf16_f32 v236, v226, v227
	v_cvt_pk_bf16_f32 v237, v228, v229
	global_store_dwordx4 v[166:167], v[234:237], off offset:1024 sc1
	s_waitcnt vmcnt(27)
; __device__ __forceinline__ float silu_f(float v) { return v * __builtin_amdgcn_rcpf(1.0f + __expf(-v)); }
;     __device__ __forceinline__ const char* a(const pg8::Unit& u) const { return (const char*)ws + aoff + (size_t)u.pm * 256 * K_ * 2 + (u.kq < 0 ? 0 : u.kq * (K_ / 4) * 2); }
;     __device__ __forceinline__ const char* b(const pg8::Unit& u) const { return (const char*)ws + boff + (size_t)u.pn * 256 * K_ * 2 + (u.kq < 0 ? 0 : u.kq * (K_ / 4) * 2); }
;     __device__ __forceinline__ const char* a(const pg8::Unit& u) const { return (const char*)ws + WS_A + (size_t)u.pm * 256 * D * 2; }
;     __device__ __forceinline__ const char* b(const pg8::Unit& u) const { return (const char*)ws + boff + (size_t)u.pn * 256 * D * 2; }
;     __device__ __forceinline__ const char* a(const pg8::Unit& u) const { return (const char*)ws + WS_A + (size_t)u.pm * 256 * D * 2; }
;     __device__ __forceinline__ const char* b(const pg8::Unit& u) const { return (const char*)ws + boff + (size_t)u.pn * 256 * D * 2; }
;     __device__ __forceinline__ const char* a(const pg8::Unit& u) const { return (const char*)ws + WS_W1 + (size_t)(u.pm & 1) * 256 * 256 * 2; }
;     __device__ __forceinline__ const char* b(const pg8::Unit& u) const { return (const char*)ws + WS_A + ((size_t)u.pn * 256 * D + (size_t)(u.pm >> 1) * 256) * 2; }
; __device__ __forceinline__ void ssd_gate_norm_phase(Frame& F, int j, int nrows) {
;     ...
;     for (int r = gw; r < nrows; r += NGW) {
; #pragma unroll 4
;         for (int g = 0; g < 8; ++g) { const size_t off = (size_t)r * DI + g * 512 + lane * 8;
;             float a[8], b[8], zz[8]; unpack8(__builtin_nontemporal_load((const u32x4*)(yf + off)), a); unpack8(__builtin_nontemporal_load((const u32x4*)(yb + off)), b); unpack8(__builtin_nontemporal_load((const u32x4*)(z + off)), zz);
;             float ss = 0.f;
; #pragma unroll
;             for (int c = 0; c < 8; ++c) { a[c] = (a[c] + b[c]) * silu_f(zz[c]); ss += a[c] * a[c]; }
;             const float rs = rsqrtf(wave_sum(ss, lane) * (1.0f / 512.0f) + EPS);
;             const f32x4* gp = (const f32x4*)(ng + g * 512 + lane * 8); const f32x4 g0 = gp[0], g1 = gp[1];
;             a[0] *= rs * g0.x; a[1] *= rs * g0.y; a[2] *= rs * g0.z; a[3] *= rs * g0.w; a[4] *= rs * g1.x; a[5] *= rs * g1.y; a[6] *= rs * g1.z; a[7] *= rs * g1.w;
;             *(u32x4*)(yf + off) = pack8(a); }
	v_lshlrev_b32_e32 v198, 16, v76
	v_and_b32_e32 v199, 0xffff0000, v76
	v_lshlrev_b32_e32 v206, 16, v80
	v_and_b32_e32 v207, 0xffff0000, v80
	v_lshlrev_b32_e32 v214, 16, v84
	v_and_b32_e32 v215, 0xffff0000, v84
	v_lshlrev_b32_e32 v200, 16, v77
	v_and_b32_e32 v201, 0xffff0000, v77
	v_lshlrev_b32_e32 v208, 16, v81
	v_and_b32_e32 v209, 0xffff0000, v81
	v_lshlrev_b32_e32 v216, 16, v85
	v_and_b32_e32 v217, 0xffff0000, v85
	v_lshlrev_b32_e32 v202, 16, v78
	v_and_b32_e32 v203, 0xffff0000, v78
	v_lshlrev_b32_e32 v210, 16, v82
	v_and_b32_e32 v211, 0xffff0000, v82
	v_lshlrev_b32_e32 v218, 16, v86
	v_and_b32_e32 v219, 0xffff0000, v86
	v_lshlrev_b32_e32 v204, 16, v79
	v_and_b32_e32 v205, 0xffff0000, v79
	v_lshlrev_b32_e32 v212, 16, v83
	v_and_b32_e32 v213, 0xffff0000, v83
	v_lshlrev_b32_e32 v220, 16, v87
	v_and_b32_e32 v221, 0xffff0000, v87
	global_load_dwordx4 v[76:79], v[170:171], off offset:2048 nt
	global_load_dwordx4 v[80:83], v[174:175], off offset:2048 nt
	global_load_dwordx4 v[84:87], v[180:181], off offset:2048 nt
	v_pk_add_f32 v[198:199], v[198:199], v[206:207]
	v_pk_add_f32 v[200:201], v[200:201], v[208:209]
	v_pk_add_f32 v[202:203], v[202:203], v[210:211]
	v_pk_add_f32 v[204:205], v[204:205], v[212:213]
	v_mul_f32_e32 v206, 0xbfb8aa3b, v214
	v_mul_f32_e32 v207, 0xbfb8aa3b, v215
	v_mul_f32_e32 v208, 0xbfb8aa3b, v216
	v_mul_f32_e32 v209, 0xbfb8aa3b, v217
	v_mul_f32_e32 v210, 0xbfb8aa3b, v218
	v_mul_f32_e32 v211, 0xbfb8aa3b, v219
	v_mul_f32_e32 v212, 0xbfb8aa3b, v220
	v_mul_f32_e32 v213, 0xbfb8aa3b, v221
	v_exp_f32_e32 v206, v206
	v_exp_f32_e32 v207, v207
	v_exp_f32_e32 v208, v208
	v_exp_f32_e32 v209, v209
	v_exp_f32_e32 v210, v210
	v_exp_f32_e32 v211, v211
	v_exp_f32_e32 v212, v212
	v_exp_f32_e32 v213, v213
	v_add_f32_e32 v206, 1.0, v206
	v_add_f32_e32 v207, 1.0, v207
	v_add_f32_e32 v208, 1.0, v208
	v_add_f32_e32 v209, 1.0, v209
	v_add_f32_e32 v210, 1.0, v210
	v_add_f32_e32 v211, 1.0, v211
	v_add_f32_e32 v212, 1.0, v212
	v_add_f32_e32 v213, 1.0, v213
	v_rcp_f32_e32 v206, v206
	v_rcp_f32_e32 v207, v207
	v_rcp_f32_e32 v208, v208
	v_rcp_f32_e32 v209, v209
	v_rcp_f32_e32 v210, v210
	v_rcp_f32_e32 v211, v211
	v_rcp_f32_e32 v212, v212
	v_rcp_f32_e32 v213, v213
	s_nop 0
	v_pk_mul_f32 v[206:207], v[206:207], v[214:215]
	v_pk_mul_f32 v[208:209], v[208:209], v[216:217]
	v_pk_mul_f32 v[210:211], v[210:211], v[218:219]
	v_pk_mul_f32 v[212:213], v[212:213], v[220:221]
	v_pk_mul_f32 v[198:199], v[198:199], v[206:207]
	v_pk_mul_f32 v[200:201], v[200:201], v[208:209]
	v_pk_mul_f32 v[202:203], v[202:203], v[210:211]
	v_pk_mul_f32 v[204:205], v[204:205], v[212:213]
	v_pk_mul_f32 v[214:215], v[198:199], v[198:199]
	v_pk_mul_f32 v[216:217], v[200:201], v[200:201]
	v_pk_mul_f32 v[218:219], v[202:203], v[202:203]
	v_pk_mul_f32 v[220:221], v[204:205], v[204:205]
	v_add_f32_e32 v230, v214, v215
	v_add_f32_e32 v230, v216, v230
	v_add_f32_e32 v230, v217, v230
	v_add_f32_e32 v230, v218, v230
	v_add_f32_e32 v230, v219, v230
	v_add_f32_e32 v230, v220, v230
	v_add_f32_e32 v230, v221, v230
	v_mov_b32_e32 v231, v177
	s_nop 0
	v_add_f32_dpp v230, v230, v230 row_shr:1 row_mask:0xf bank_mask:0xf bound_ctrl:1
	s_nop 1
	v_add_f32_dpp v230, v230, v230 row_shr:2 row_mask:0xf bank_mask:0xf bound_ctrl:1
	s_nop 1
	v_add_f32_dpp v230, v230, v230 row_shr:4 row_mask:0xf bank_mask:0xf bound_ctrl:1
	s_nop 1
	v_add_f32_dpp v230, v230, v230 row_shr:8 row_mask:0xf bank_mask:0xf bound_ctrl:1
	s_nop 1
	v_mov_b32_dpp v231, v230 row_bcast:15 row_mask:0xa bank_mask:0xf
	v_add_f32_e32 v230, v230, v231
	v_mov_b32_e32 v231, v177
	s_nop 1
	v_mov_b32_dpp v231, v230 row_bcast:31 row_mask:0xc bank_mask:0xf
	v_add_f32_e32 v230, v230, v231
	s_nop 0
	v_readlane_b32 s6, v230, 63
	s_nop 1
	v_fma_f32 v232, s6, v245, v238
	v_cmp_gt_f32_e32 vcc, s85, v232
	v_mul_f32_e32 v231, 0x4b800000, v232
	s_nop 0
	v_cndmask_b32_e32 v232, v232, v231, vcc
	v_rsq_f32_e32 v232, v232
	s_nop 0
	v_mul_f32_e32 v231, 0x45800000, v232
	v_cndmask_b32_e32 v232, v232, v231, vcc
	v_pk_mul_f32 v[222:223], v[148:149], v[232:233] op_sel_hi:[1,0]
	v_pk_mul_f32 v[224:225], v[150:151], v[232:233] op_sel_hi:[1,0]
	v_pk_mul_f32 v[226:227], v[152:153], v[232:233] op_sel_hi:[1,0]
	v_pk_mul_f32 v[228:229], v[154:155], v[232:233] op_sel_hi:[1,0]
	v_pk_mul_f32 v[222:223], v[198:199], v[222:223]
	v_pk_mul_f32 v[224:225], v[200:201], v[224:225]
	v_pk_mul_f32 v[226:227], v[202:203], v[226:227]
	v_pk_mul_f32 v[228:229], v[204:205], v[228:229]
	v_cvt_pk_bf16_f32 v234, v222, v223
	v_cvt_pk_bf16_f32 v235, v224, v225
	v_cvt_pk_bf16_f32 v236, v226, v227
	v_cvt_pk_bf16_f32 v237, v228, v229
	global_store_dwordx4 v[166:167], v[234:237], off offset:2048 sc1
	s_waitcnt vmcnt(28)
; __device__ __forceinline__ float silu_f(float v) { return v * __builtin_amdgcn_rcpf(1.0f + __expf(-v)); }
;     __device__ __forceinline__ const char* a(const pg8::Unit& u) const { return (const char*)ws + aoff + (size_t)u.pm * 256 * K_ * 2 + (u.kq < 0 ? 0 : u.kq * (K_ / 4) * 2); }
;     __device__ __forceinline__ const char* b(const pg8::Unit& u) const { return (const char*)ws + boff + (size_t)u.pn * 256 * K_ * 2 + (u.kq < 0 ? 0 : u.kq * (K_ / 4) * 2); }
;     __device__ __forceinline__ const char* a(const pg8::Unit& u) const { return (const char*)ws + WS_A + (size_t)u.pm * 256 * D * 2; }
;     __device__ __forceinline__ const char* b(const pg8::Unit& u) const { return (const char*)ws + boff + (size_t)u.pn * 256 * D * 2; }
;     __device__ __forceinline__ const char* a(const pg8::Unit& u) const { return (const char*)ws + WS_A + (size_t)u.pm * 256 * D * 2; }
;     __device__ __forceinline__ const char* b(const pg8::Unit& u) const { return (const char*)ws + boff + (size_t)u.pn * 256 * D * 2; }
;     __device__ __forceinline__ const char* a(const pg8::Unit& u) const { return (const char*)ws + WS_W1 + (size_t)(u.pm & 1) * 256 * 256 * 2; }
;     __device__ __forceinline__ const char* b(const pg8::Unit& u) const { return (const char*)ws + WS_A + ((size_t)u.pn * 256 * D + (size_t)(u.pm >> 1) * 256) * 2; }
; __device__ __forceinline__ void ssd_gate_norm_phase(Frame& F, int j, int nrows) {
;     ...
;     for (int r = gw; r < nrows; r += NGW) {
; #pragma unroll 4
;         for (int g = 0; g < 8; ++g) { const size_t off = (size_t)r * DI + g * 512 + lane * 8;
;             float a[8], b[8], zz[8]; unpack8(__builtin_nontemporal_load((const u32x4*)(yf + off)), a); unpack8(__builtin_nontemporal_load((const u32x4*)(yb + off)), b); unpack8(__builtin_nontemporal_load((const u32x4*)(z + off)), zz);
;             float ss = 0.f;
; #pragma unroll
;             for (int c = 0; c < 8; ++c) { a[c] = (a[c] + b[c]) * silu_f(zz[c]); ss += a[c] * a[c]; }
;             const float rs = rsqrtf(wave_sum(ss, lane) * (1.0f / 512.0f) + EPS);
;             const f32x4* gp = (const f32x4*)(ng + g * 512 + lane * 8); const f32x4 g0 = gp[0], g1 = gp[1];
;             a[0] *= rs * g0.x; a[1] *= rs * g0.y; a[2] *= rs * g0.z; a[3] *= rs * g0.w; a[4] *= rs * g1.x; a[5] *= rs * g1.y; a[6] *= rs * g1.z; a[7] *= rs * g1.w;
;             *(u32x4*)(yf + off) = pack8(a); }
	v_lshlrev_b32_e32 v198, 16, v88
	v_and_b32_e32 v199, 0xffff0000, v88
	v_lshlrev_b32_e32 v206, 16, v92
	v_and_b32_e32 v207, 0xffff0000, v92
	v_lshlrev_b32_e32 v214, 16, v96
	v_and_b32_e32 v215, 0xffff0000, v96
	v_lshlrev_b32_e32 v200, 16, v89
	v_and_b32_e32 v201, 0xffff0000, v89
	v_lshlrev_b32_e32 v208, 16, v93
	v_and_b32_e32 v209, 0xffff0000, v93
	v_lshlrev_b32_e32 v216, 16, v97
	v_and_b32_e32 v217, 0xffff0000, v97
	v_lshlrev_b32_e32 v202, 16, v90
	v_and_b32_e32 v203, 0xffff0000, v90
	v_lshlrev_b32_e32 v210, 16, v94
	v_and_b32_e32 v211, 0xffff0000, v94
	v_lshlrev_b32_e32 v218, 16, v98
	v_and_b32_e32 v219, 0xffff0000, v98
	v_lshlrev_b32_e32 v204, 16, v91
	v_and_b32_e32 v205, 0xffff0000, v91
	v_lshlrev_b32_e32 v212, 16, v95
	v_and_b32_e32 v213, 0xffff0000, v95
	v_lshlrev_b32_e32 v220, 16, v99
	v_and_b32_e32 v221, 0xffff0000, v99
	global_load_dwordx4 v[88:91], v[170:171], off offset:3072 nt
	global_load_dwordx4 v[92:95], v[174:175], off offset:3072 nt
	global_load_dwordx4 v[96:99], v[180:181], off offset:3072 nt
	v_pk_add_f32 v[198:199], v[198:199], v[206:207]
	v_pk_add_f32 v[200:201], v[200:201], v[208:209]
	v_pk_add_f32 v[202:203], v[202:203], v[210:211]
	v_pk_add_f32 v[204:205], v[204:205], v[212:213]
	v_mul_f32_e32 v206, 0xbfb8aa3b, v214
	v_mul_f32_e32 v207, 0xbfb8aa3b, v215
	v_mul_f32_e32 v208, 0xbfb8aa3b, v216
	v_mul_f32_e32 v209, 0xbfb8aa3b, v217
	v_mul_f32_e32 v210, 0xbfb8aa3b, v218
	v_mul_f32_e32 v211, 0xbfb8aa3b, v219
	v_mul_f32_e32 v212, 0xbfb8aa3b, v220
	v_mul_f32_e32 v213, 0xbfb8aa3b, v221
	v_exp_f32_e32 v206, v206
	v_exp_f32_e32 v207, v207
	v_exp_f32_e32 v208, v208
	v_exp_f32_e32 v209, v209
	v_exp_f32_e32 v210, v210
	v_exp_f32_e32 v211, v211
	v_exp_f32_e32 v212, v212
	v_exp_f32_e32 v213, v213
	v_add_f32_e32 v206, 1.0, v206
	v_add_f32_e32 v207, 1.0, v207
	v_add_f32_e32 v208, 1.0, v208
	v_add_f32_e32 v209, 1.0, v209
	v_add_f32_e32 v210, 1.0, v210
	v_add_f32_e32 v211, 1.0, v211
	v_add_f32_e32 v212, 1.0, v212
	v_add_f32_e32 v213, 1.0, v213
	v_rcp_f32_e32 v206, v206
	v_rcp_f32_e32 v207, v207
	v_rcp_f32_e32 v208, v208
	v_rcp_f32_e32 v209, v209
	v_rcp_f32_e32 v210, v210
	v_rcp_f32_e32 v211, v211
	v_rcp_f32_e32 v212, v212
	v_rcp_f32_e32 v213, v213
	s_nop 0
	v_pk_mul_f32 v[206:207], v[206:207], v[214:215]
	v_pk_mul_f32 v[208:209], v[208:209], v[216:217]
	v_pk_mul_f32 v[210:211], v[210:211], v[218:219]
	v_pk_mul_f32 v[212:213], v[212:213], v[220:221]
	v_pk_mul_f32 v[198:199], v[198:199], v[206:207]
	v_pk_mul_f32 v[200:201], v[200:201], v[208:209]
	v_pk_mul_f32 v[202:203], v[202:203], v[210:211]
	v_pk_mul_f32 v[204:205], v[204:205], v[212:213]
	v_pk_mul_f32 v[214:215], v[198:199], v[198:199]
	v_pk_mul_f32 v[216:217], v[200:201], v[200:201]
	v_pk_mul_f32 v[218:219], v[202:203], v[202:203]
	v_pk_mul_f32 v[220:221], v[204:205], v[204:205]
	v_add_f32_e32 v230, v214, v215
	v_add_f32_e32 v230, v216, v230
	v_add_f32_e32 v230, v217, v230
	v_add_f32_e32 v230, v218, v230
	v_add_f32_e32 v230, v219, v230
	v_add_f32_e32 v230, v220, v230
	v_add_f32_e32 v230, v221, v230
	v_mov_b32_e32 v231, v177
	s_nop 0
	v_add_f32_dpp v230, v230, v230 row_shr:1 row_mask:0xf bank_mask:0xf bound_ctrl:1
	s_nop 1
	v_add_f32_dpp v230, v230, v230 row_shr:2 row_mask:0xf bank_mask:0xf bound_ctrl:1
	s_nop 1
	v_add_f32_dpp v230, v230, v230 row_shr:4 row_mask:0xf bank_mask:0xf bound_ctrl:1
	s_nop 1
	v_add_f32_dpp v230, v230, v230 row_shr:8 row_mask:0xf bank_mask:0xf bound_ctrl:1
	s_nop 1
	v_mov_b32_dpp v231, v230 row_bcast:15 row_mask:0xa bank_mask:0xf
	v_add_f32_e32 v230, v230, v231
	v_mov_b32_e32 v231, v177
	s_nop 1
	v_mov_b32_dpp v231, v230 row_bcast:31 row_mask:0xc bank_mask:0xf
	v_add_f32_e32 v230, v230, v231
	s_nop 0
	v_readlane_b32 s6, v230, 63
	s_nop 1
	v_fma_f32 v232, s6, v245, v238
	v_cmp_gt_f32_e32 vcc, s85, v232
	v_mul_f32_e32 v231, 0x4b800000, v232
	s_nop 0
	v_cndmask_b32_e32 v232, v232, v231, vcc
	v_rsq_f32_e32 v232, v232
	s_nop 0
	v_mul_f32_e32 v231, 0x45800000, v232
	v_cndmask_b32_e32 v232, v232, v231, vcc
	v_pk_mul_f32 v[222:223], v[156:157], v[232:233] op_sel_hi:[1,0]
	v_pk_mul_f32 v[224:225], v[158:159], v[232:233] op_sel_hi:[1,0]
	v_pk_mul_f32 v[226:227], v[160:161], v[232:233] op_sel_hi:[1,0]
	v_pk_mul_f32 v[228:229], v[162:163], v[232:233] op_sel_hi:[1,0]
	v_pk_mul_f32 v[222:223], v[198:199], v[222:223]
	v_pk_mul_f32 v[224:225], v[200:201], v[224:225]
	v_pk_mul_f32 v[226:227], v[202:203], v[226:227]
	v_pk_mul_f32 v[228:229], v[204:205], v[228:229]
	v_cvt_pk_bf16_f32 v234, v222, v223
	v_cvt_pk_bf16_f32 v235, v224, v225
	v_cvt_pk_bf16_f32 v236, v226, v227
	v_cvt_pk_bf16_f32 v237, v228, v229
	global_store_dwordx4 v[166:167], v[234:237], off offset:3072 sc1
	v_mov_b32_e32 v164, v168
	v_mov_b32_e32 v165, v169
	v_mov_b32_e32 v166, v170
	v_mov_b32_e32 v167, v171
	v_lshl_add_u64 v[168:169], v[168:169], 0, s[0:1]
	v_lshl_add_u64 v[170:171], v[170:171], 0, s[0:1]
	v_lshl_add_u64 v[172:173], v[172:173], 0, s[0:1]
	v_lshl_add_u64 v[174:175], v[174:175], 0, s[0:1]
	v_lshl_add_u64 v[178:179], v[178:179], 0, s[0:1]
	v_lshl_add_u64 v[180:181], v[180:181], 0, s[0:1]
	s_mov_b32 s4, s5
	s_branch .Lgn_row
; __device__ __forceinline__ float silu_f(float v) { return v * __builtin_amdgcn_rcpf(1.0f + __expf(-v)); }
;     __device__ __forceinline__ const char* a(const pg8::Unit& u) const { return (const char*)ws + aoff + (size_t)u.pm * 256 * K_ * 2 + (u.kq < 0 ? 0 : u.kq * (K_ / 4) * 2); }
;     __device__ __forceinline__ const char* b(const pg8::Unit& u) const { return (const char*)ws + boff + (size_t)u.pn * 256 * K_ * 2 + (u.kq < 0 ? 0 : u.kq * (K_ / 4) * 2); }
;     __device__ __forceinline__ const char* a(const pg8::Unit& u) const { return (const char*)ws + WS_A + (size_t)u.pm * 256 * D * 2; }
;     __device__ __forceinline__ const char* b(const pg8::Unit& u) const { return (const char*)ws + boff + (size_t)u.pn * 256 * D * 2; }
;     __device__ __forceinline__ const char* a(const pg8::Unit& u) const { return (const char*)ws + WS_A + (size_t)u.pm * 256 * D * 2; }
;     __device__ __forceinline__ const char* b(const pg8::Unit& u) const { return (const char*)ws + boff + (size_t)u.pn * 256 * D * 2; }
;     __device__ __forceinline__ const char* a(const pg8::Unit& u) const { return (const char*)ws + WS_W1 + (size_t)(u.pm & 1) * 256 * 256 * 2; }
;     __device__ __forceinline__ const char* b(const pg8::Unit& u) const { return (const char*)ws + WS_A + ((size_t)u.pn * 256 * D + (size_t)(u.pm >> 1) * 256) * 2; }
; __device__ __forceinline__ void ssd_gate_norm_phase(Frame& F, int j, int nrows) {
;     ...
;         for (int g = 0; g < 8; ++g) { const size_t off = (size_t)r * DI + g * 512 + lane * 8;
;             float a[8], b[8], zz[8]; unpack8(__builtin_nontemporal_load((const u32x4*)(yf + off)), a); unpack8(__builtin_nontemporal_load((const u32x4*)(yb + off)), b); unpack8(__builtin_nontemporal_load((const u32x4*)(z + off)), zz);
;             float ss = 0.f;
; #pragma unroll
;             for (int c = 0; c < 8; ++c) { a[c] = (a[c] + b[c]) * silu_f(zz[c]); ss += a[c] * a[c]; }
;             const float rs = rsqrtf(wave_sum(ss, lane) * (1.0f / 512.0f) + EPS);
;             const f32x4* gp = (const f32x4*)(ng + g * 512 + lane * 8); const f32x4 g0 = gp[0], g1 = gp[1];
;             a[0] *= rs * g0.x; a[1] *= rs * g0.y; a[2] *= rs * g0.z; a[3] *= rs * g0.w; a[4] *= rs * g1.x; a[5] *= rs * g1.y; a[6] *= rs * g1.z; a[7] *= rs * g1.w;
;             *(u32x4*)(yf + off) = pack8(a); }
.Lgn_last:
	s_waitcnt vmcnt(21)
	v_lshlrev_b32_e32 v198, 16, v4
	v_and_b32_e32 v199, 0xffff0000, v4
	v_lshlrev_b32_e32 v206, 16, v8
	v_and_b32_e32 v207, 0xffff0000, v8
	v_lshlrev_b32_e32 v214, 16, v12
	v_and_b32_e32 v215, 0xffff0000, v12
	v_lshlrev_b32_e32 v200, 16, v5
	v_and_b32_e32 v201, 0xffff0000, v5
	v_lshlrev_b32_e32 v208, 16, v9
	v_and_b32_e32 v209, 0xffff0000, v9
	v_lshlrev_b32_e32 v216, 16, v13
	v_and_b32_e32 v217, 0xffff0000, v13
	v_lshlrev_b32_e32 v202, 16, v6
	v_and_b32_e32 v203, 0xffff0000, v6
	v_lshlrev_b32_e32 v210, 16, v10
	v_and_b32_e32 v211, 0xffff0000, v10
	v_lshlrev_b32_e32 v218, 16, v14
	v_and_b32_e32 v219, 0xffff0000, v14
	v_lshlrev_b32_e32 v204, 16, v7
	v_and_b32_e32 v205, 0xffff0000, v7
	v_lshlrev_b32_e32 v212, 16, v11
	v_and_b32_e32 v213, 0xffff0000, v11
	v_lshlrev_b32_e32 v220, 16, v15
	v_and_b32_e32 v221, 0xffff0000, v15
	v_pk_add_f32 v[198:199], v[198:199], v[206:207]
	v_pk_add_f32 v[200:201], v[200:201], v[208:209]
	v_pk_add_f32 v[202:203], v[202:203], v[210:211]
	v_pk_add_f32 v[204:205], v[204:205], v[212:213]
	v_mul_f32_e32 v206, 0xbfb8aa3b, v214
	v_mul_f32_e32 v207, 0xbfb8aa3b, v215
	v_mul_f32_e32 v208, 0xbfb8aa3b, v216
	v_mul_f32_e32 v209, 0xbfb8aa3b, v217
	v_mul_f32_e32 v210, 0xbfb8aa3b, v218
	v_mul_f32_e32 v211, 0xbfb8aa3b, v219
	v_mul_f32_e32 v212, 0xbfb8aa3b, v220
	v_mul_f32_e32 v213, 0xbfb8aa3b, v221
	v_exp_f32_e32 v206, v206
	v_exp_f32_e32 v207, v207
	v_exp_f32_e32 v208, v208
	v_exp_f32_e32 v209, v209
	v_exp_f32_e32 v210, v210
	v_exp_f32_e32 v211, v211
	v_exp_f32_e32 v212, v212
	v_exp_f32_e32 v213, v213
	v_add_f32_e32 v206, 1.0, v206
	v_add_f32_e32 v207, 1.0, v207
	v_add_f32_e32 v208, 1.0, v208
	v_add_f32_e32 v209, 1.0, v209
	v_add_f32_e32 v210, 1.0, v210
	v_add_f32_e32 v211, 1.0, v211
	v_add_f32_e32 v212, 1.0, v212
	v_add_f32_e32 v213, 1.0, v213
	v_rcp_f32_e32 v206, v206
	v_rcp_f32_e32 v207, v207
	v_rcp_f32_e32 v208, v208
	v_rcp_f32_e32 v209, v209
	v_rcp_f32_e32 v210, v210
	v_rcp_f32_e32 v211, v211
	v_rcp_f32_e32 v212, v212
	v_rcp_f32_e32 v213, v213
	s_nop 0
	v_pk_mul_f32 v[206:207], v[206:207], v[214:215]
	v_pk_mul_f32 v[208:209], v[208:209], v[216:217]
	v_pk_mul_f32 v[210:211], v[210:211], v[218:219]
	v_pk_mul_f32 v[212:213], v[212:213], v[220:221]
	v_pk_mul_f32 v[198:199], v[198:199], v[206:207]
	v_pk_mul_f32 v[200:201], v[200:201], v[208:209]
	v_pk_mul_f32 v[202:203], v[202:203], v[210:211]
	v_pk_mul_f32 v[204:205], v[204:205], v[212:213]
	v_pk_mul_f32 v[214:215], v[198:199], v[198:199]
	v_pk_mul_f32 v[216:217], v[200:201], v[200:201]
	v_pk_mul_f32 v[218:219], v[202:203], v[202:203]
	v_pk_mul_f32 v[220:221], v[204:205], v[204:205]
	v_add_f32_e32 v230, v214, v215
	v_add_f32_e32 v230, v216, v230
	v_add_f32_e32 v230, v217, v230
	v_add_f32_e32 v230, v218, v230
	v_add_f32_e32 v230, v219, v230
	v_add_f32_e32 v230, v220, v230
	v_add_f32_e32 v230, v221, v230
	v_mov_b32_e32 v231, v177
	s_nop 0
	v_add_f32_dpp v230, v230, v230 row_shr:1 row_mask:0xf bank_mask:0xf bound_ctrl:1
	s_nop 1
	v_add_f32_dpp v230, v230, v230 row_shr:2 row_mask:0xf bank_mask:0xf bound_ctrl:1
	s_nop 1
	v_add_f32_dpp v230, v230, v230 row_shr:4 row_mask:0xf bank_mask:0xf bound_ctrl:1
	s_nop 1
	v_add_f32_dpp v230, v230, v230 row_shr:8 row_mask:0xf bank_mask:0xf bound_ctrl:1
	s_nop 1
	v_mov_b32_dpp v231, v230 row_bcast:15 row_mask:0xa bank_mask:0xf
	v_add_f32_e32 v230, v230, v231
	v_mov_b32_e32 v231, v177
	s_nop 1
	v_mov_b32_dpp v231, v230 row_bcast:31 row_mask:0xc bank_mask:0xf
	v_add_f32_e32 v230, v230, v231
	s_nop 0
	v_readlane_b32 s6, v230, 63
	s_nop 1
	v_fma_f32 v232, s6, v245, v238
	v_cmp_gt_f32_e32 vcc, s85, v232
	v_mul_f32_e32 v231, 0x4b800000, v232
	s_nop 0
	v_cndmask_b32_e32 v232, v232, v231, vcc
	v_rsq_f32_e32 v232, v232
	s_nop 0
	v_mul_f32_e32 v231, 0x45800000, v232
	v_cndmask_b32_e32 v232, v232, v231, vcc
	v_pk_mul_f32 v[222:223], v[100:101], v[232:233] op_sel_hi:[1,0]
	v_pk_mul_f32 v[224:225], v[102:103], v[232:233] op_sel_hi:[1,0]
	v_pk_mul_f32 v[226:227], v[104:105], v[232:233] op_sel_hi:[1,0]
	v_pk_mul_f32 v[228:229], v[106:107], v[232:233] op_sel_hi:[1,0]
	v_pk_mul_f32 v[222:223], v[198:199], v[222:223]
	v_pk_mul_f32 v[224:225], v[200:201], v[224:225]
	v_pk_mul_f32 v[226:227], v[202:203], v[226:227]
	v_pk_mul_f32 v[228:229], v[204:205], v[228:229]
	v_cvt_pk_bf16_f32 v234, v222, v223
	v_cvt_pk_bf16_f32 v235, v224, v225
	v_cvt_pk_bf16_f32 v236, v226, v227
	v_cvt_pk_bf16_f32 v237, v228, v229
	global_store_dwordx4 v[164:165], v[234:237], off sc1
	s_waitcnt vmcnt(19)
; __device__ __forceinline__ float silu_f(float v) { return v * __builtin_amdgcn_rcpf(1.0f + __expf(-v)); }
;     __device__ __forceinline__ const char* a(const pg8::Unit& u) const { return (const char*)ws + aoff + (size_t)u.pm * 256 * K_ * 2 + (u.kq < 0 ? 0 : u.kq * (K_ / 4) * 2); }
;     __device__ __forceinline__ const char* b(const pg8::Unit& u) const { return (const char*)ws + boff + (size_t)u.pn * 256 * K_ * 2 + (u.kq < 0 ? 0 : u.kq * (K_ / 4) * 2); }
;     __device__ __forceinline__ const char* a(const pg8::Unit& u) const { return (const char*)ws + WS_A + (size_t)u.pm * 256 * D * 2; }
;     __device__ __forceinline__ const char* b(const pg8::Unit& u) const { return (const char*)ws + boff + (size_t)u.pn * 256 * D * 2; }
;     __device__ __forceinline__ const char* a(const pg8::Unit& u) const { return (const char*)ws + WS_A + (size_t)u.pm * 256 * D * 2; }
;     __device__ __forceinline__ const char* b(const pg8::Unit& u) const { return (const char*)ws + boff + (size_t)u.pn * 256 * D * 2; }
;     __device__ __forceinline__ const char* a(const pg8::Unit& u) const { return (const char*)ws + WS_W1 + (size_t)(u.pm & 1) * 256 * 256 * 2; }
;     __device__ __forceinline__ const char* b(const pg8::Unit& u) const { return (const char*)ws + WS_A + ((size_t)u.pn * 256 * D + (size_t)(u.pm >> 1) * 256) * 2; }
; __device__ __forceinline__ void ssd_gate_norm_phase(Frame& F, int j, int nrows) {
;     ...
;         for (int g = 0; g < 8; ++g) { const size_t off = (size_t)r * DI + g * 512 + lane * 8;
;             float a[8], b[8], zz[8]; unpack8(__builtin_nontemporal_load((const u32x4*)(yf + off)), a); unpack8(__builtin_nontemporal_load((const u32x4*)(yb + off)), b); unpack8(__builtin_nontemporal_load((const u32x4*)(z + off)), zz);
;             float ss = 0.f;
; #pragma unroll
;             for (int c = 0; c < 8; ++c) { a[c] = (a[c] + b[c]) * silu_f(zz[c]); ss += a[c] * a[c]; }
;             const float rs = rsqrtf(wave_sum(ss, lane) * (1.0f / 512.0f) + EPS);
;             const f32x4* gp = (const f32x4*)(ng + g * 512 + lane * 8); const f32x4 g0 = gp[0], g1 = gp[1];
;             a[0] *= rs * g0.x; a[1] *= rs * g0.y; a[2] *= rs * g0.z; a[3] *= rs * g0.w; a[4] *= rs * g1.x; a[5] *= rs * g1.y; a[6] *= rs * g1.z; a[7] *= rs * g1.w;
;             *(u32x4*)(yf + off) = pack8(a); }
	v_lshlrev_b32_e32 v198, 16, v16
	v_and_b32_e32 v199, 0xffff0000, v16
	v_lshlrev_b32_e32 v206, 16, v20
	v_and_b32_e32 v207, 0xffff0000, v20
	v_lshlrev_b32_e32 v214, 16, v24
	v_and_b32_e32 v215, 0xffff0000, v24
	v_lshlrev_b32_e32 v200, 16, v17
	v_and_b32_e32 v201, 0xffff0000, v17
	v_lshlrev_b32_e32 v208, 16, v21
	v_and_b32_e32 v209, 0xffff0000, v21
	v_lshlrev_b32_e32 v216, 16, v25
	v_and_b32_e32 v217, 0xffff0000, v25
	v_lshlrev_b32_e32 v202, 16, v18
	v_and_b32_e32 v203, 0xffff0000, v18
	v_lshlrev_b32_e32 v210, 16, v22
	v_and_b32_e32 v211, 0xffff0000, v22
	v_lshlrev_b32_e32 v218, 16, v26
	v_and_b32_e32 v219, 0xffff0000, v26
	v_lshlrev_b32_e32 v204, 16, v19
	v_and_b32_e32 v205, 0xffff0000, v19
	v_lshlrev_b32_e32 v212, 16, v23
	v_and_b32_e32 v213, 0xffff0000, v23
	v_lshlrev_b32_e32 v220, 16, v27
	v_and_b32_e32 v221, 0xffff0000, v27
	v_pk_add_f32 v[198:199], v[198:199], v[206:207]
	v_pk_add_f32 v[200:201], v[200:201], v[208:209]
	v_pk_add_f32 v[202:203], v[202:203], v[210:211]
	v_pk_add_f32 v[204:205], v[204:205], v[212:213]
	v_mul_f32_e32 v206, 0xbfb8aa3b, v214
	v_mul_f32_e32 v207, 0xbfb8aa3b, v215
	v_mul_f32_e32 v208, 0xbfb8aa3b, v216
	v_mul_f32_e32 v209, 0xbfb8aa3b, v217
	v_mul_f32_e32 v210, 0xbfb8aa3b, v218
	v_mul_f32_e32 v211, 0xbfb8aa3b, v219
	v_mul_f32_e32 v212, 0xbfb8aa3b, v220
	v_mul_f32_e32 v213, 0xbfb8aa3b, v221
	v_exp_f32_e32 v206, v206
	v_exp_f32_e32 v207, v207
	v_exp_f32_e32 v208, v208
	v_exp_f32_e32 v209, v209
	v_exp_f32_e32 v210, v210
	v_exp_f32_e32 v211, v211
	v_exp_f32_e32 v212, v212
	v_exp_f32_e32 v213, v213
	v_add_f32_e32 v206, 1.0, v206
	v_add_f32_e32 v207, 1.0, v207
	v_add_f32_e32 v208, 1.0, v208
	v_add_f32_e32 v209, 1.0, v209
	v_add_f32_e32 v210, 1.0, v210
	v_add_f32_e32 v211, 1.0, v211
	v_add_f32_e32 v212, 1.0, v212
	v_add_f32_e32 v213, 1.0, v213
	v_rcp_f32_e32 v206, v206
	v_rcp_f32_e32 v207, v207
	v_rcp_f32_e32 v208, v208
	v_rcp_f32_e32 v209, v209
	v_rcp_f32_e32 v210, v210
	v_rcp_f32_e32 v211, v211
	v_rcp_f32_e32 v212, v212
	v_rcp_f32_e32 v213, v213
	s_nop 0
	v_pk_mul_f32 v[206:207], v[206:207], v[214:215]
	v_pk_mul_f32 v[208:209], v[208:209], v[216:217]
	v_pk_mul_f32 v[210:211], v[210:211], v[218:219]
	v_pk_mul_f32 v[212:213], v[212:213], v[220:221]
	v_pk_mul_f32 v[198:199], v[198:199], v[206:207]
	v_pk_mul_f32 v[200:201], v[200:201], v[208:209]
	v_pk_mul_f32 v[202:203], v[202:203], v[210:211]
	v_pk_mul_f32 v[204:205], v[204:205], v[212:213]
	v_pk_mul_f32 v[214:215], v[198:199], v[198:199]
	v_pk_mul_f32 v[216:217], v[200:201], v[200:201]
	v_pk_mul_f32 v[218:219], v[202:203], v[202:203]
	v_pk_mul_f32 v[220:221], v[204:205], v[204:205]
	v_add_f32_e32 v230, v214, v215
	v_add_f32_e32 v230, v216, v230
	v_add_f32_e32 v230, v217, v230
	v_add_f32_e32 v230, v218, v230
	v_add_f32_e32 v230, v219, v230
	v_add_f32_e32 v230, v220, v230
	v_add_f32_e32 v230, v221, v230
	v_mov_b32_e32 v231, v177
	s_nop 0
	v_add_f32_dpp v230, v230, v230 row_shr:1 row_mask:0xf bank_mask:0xf bound_ctrl:1
	s_nop 1
	v_add_f32_dpp v230, v230, v230 row_shr:2 row_mask:0xf bank_mask:0xf bound_ctrl:1
	s_nop 1
	v_add_f32_dpp v230, v230, v230 row_shr:4 row_mask:0xf bank_mask:0xf bound_ctrl:1
	s_nop 1
	v_add_f32_dpp v230, v230, v230 row_shr:8 row_mask:0xf bank_mask:0xf bound_ctrl:1
	s_nop 1
	v_mov_b32_dpp v231, v230 row_bcast:15 row_mask:0xa bank_mask:0xf
	v_add_f32_e32 v230, v230, v231
	v_mov_b32_e32 v231, v177
	s_nop 1
	v_mov_b32_dpp v231, v230 row_bcast:31 row_mask:0xc bank_mask:0xf
	v_add_f32_e32 v230, v230, v231
	s_nop 0
	v_readlane_b32 s6, v230, 63
	s_nop 1
	v_fma_f32 v232, s6, v245, v238
	v_cmp_gt_f32_e32 vcc, s85, v232
	v_mul_f32_e32 v231, 0x4b800000, v232
	s_nop 0
	v_cndmask_b32_e32 v232, v232, v231, vcc
	v_rsq_f32_e32 v232, v232
	s_nop 0
	v_mul_f32_e32 v231, 0x45800000, v232
	v_cndmask_b32_e32 v232, v232, v231, vcc
	v_pk_mul_f32 v[222:223], v[108:109], v[232:233] op_sel_hi:[1,0]
	v_pk_mul_f32 v[224:225], v[110:111], v[232:233] op_sel_hi:[1,0]
	v_pk_mul_f32 v[226:227], v[112:113], v[232:233] op_sel_hi:[1,0]
	v_pk_mul_f32 v[228:229], v[114:115], v[232:233] op_sel_hi:[1,0]
	v_pk_mul_f32 v[222:223], v[198:199], v[222:223]
	v_pk_mul_f32 v[224:225], v[200:201], v[224:225]
	v_pk_mul_f32 v[226:227], v[202:203], v[226:227]
	v_pk_mul_f32 v[228:229], v[204:205], v[228:229]
	v_cvt_pk_bf16_f32 v234, v222, v223
	v_cvt_pk_bf16_f32 v235, v224, v225
	v_cvt_pk_bf16_f32 v236, v226, v227
	v_cvt_pk_bf16_f32 v237, v228, v229
	global_store_dwordx4 v[164:165], v[234:237], off offset:1024 sc1
	s_waitcnt vmcnt(17)
; __device__ __forceinline__ float silu_f(float v) { return v * __builtin_amdgcn_rcpf(1.0f + __expf(-v)); }
;     __device__ __forceinline__ const char* a(const pg8::Unit& u) const { return (const char*)ws + aoff + (size_t)u.pm * 256 * K_ * 2 + (u.kq < 0 ? 0 : u.kq * (K_ / 4) * 2); }
;     __device__ __forceinline__ const char* b(const pg8::Unit& u) const { return (const char*)ws + boff + (size_t)u.pn * 256 * K_ * 2 + (u.kq < 0 ? 0 : u.kq * (K_ / 4) * 2); }
;     __device__ __forceinline__ const char* a(const pg8::Unit& u) const { return (const char*)ws + WS_A + (size_t)u.pm * 256 * D * 2; }
;     __device__ __forceinline__ const char* b(const pg8::Unit& u) const { return (const char*)ws + boff + (size_t)u.pn * 256 * D * 2; }
;     __device__ __forceinline__ const char* a(const pg8::Unit& u) const { return (const char*)ws + WS_A + (size_t)u.pm * 256 * D * 2; }
;     __device__ __forceinline__ const char* b(const pg8::Unit& u) const { return (const char*)ws + boff + (size_t)u.pn * 256 * D * 2; }
;     __device__ __forceinline__ const char* a(const pg8::Unit& u) const { return (const char*)ws + WS_W1 + (size_t)(u.pm & 1) * 256 * 256 * 2; }
;     __device__ __forceinline__ const char* b(const pg8::Unit& u) const { return (const char*)ws + WS_A + ((size_t)u.pn * 256 * D + (size_t)(u.pm >> 1) * 256) * 2; }
; __device__ __forceinline__ void ssd_gate_norm_phase(Frame& F, int j, int nrows) {
;     ...
;         for (int g = 0; g < 8; ++g) { const size_t off = (size_t)r * DI + g * 512 + lane * 8;
;             float a[8], b[8], zz[8]; unpack8(__builtin_nontemporal_load((const u32x4*)(yf + off)), a); unpack8(__builtin_nontemporal_load((const u32x4*)(yb + off)), b); unpack8(__builtin_nontemporal_load((const u32x4*)(z + off)), zz);
;             float ss = 0.f;
; #pragma unroll
;             for (int c = 0; c < 8; ++c) { a[c] = (a[c] + b[c]) * silu_f(zz[c]); ss += a[c] * a[c]; }
;             const float rs = rsqrtf(wave_sum(ss, lane) * (1.0f / 512.0f) + EPS);
;             const f32x4* gp = (const f32x4*)(ng + g * 512 + lane * 8); const f32x4 g0 = gp[0], g1 = gp[1];
;             a[0] *= rs * g0.x; a[1] *= rs * g0.y; a[2] *= rs * g0.z; a[3] *= rs * g0.w; a[4] *= rs * g1.x; a[5] *= rs * g1.y; a[6] *= rs * g1.z; a[7] *= rs * g1.w;
;             *(u32x4*)(yf + off) = pack8(a); }
	v_lshlrev_b32_e32 v198, 16, v28
	v_and_b32_e32 v199, 0xffff0000, v28
	v_lshlrev_b32_e32 v206, 16, v32
	v_and_b32_e32 v207, 0xffff0000, v32
	v_lshlrev_b32_e32 v214, 16, v36
	v_and_b32_e32 v215, 0xffff0000, v36
	v_lshlrev_b32_e32 v200, 16, v29
	v_and_b32_e32 v201, 0xffff0000, v29
	v_lshlrev_b32_e32 v208, 16, v33
	v_and_b32_e32 v209, 0xffff0000, v33
	v_lshlrev_b32_e32 v216, 16, v37
	v_and_b32_e32 v217, 0xffff0000, v37
	v_lshlrev_b32_e32 v202, 16, v30
	v_and_b32_e32 v203, 0xffff0000, v30
	v_lshlrev_b32_e32 v210, 16, v34
	v_and_b32_e32 v211, 0xffff0000, v34
	v_lshlrev_b32_e32 v218, 16, v38
	v_and_b32_e32 v219, 0xffff0000, v38
	v_lshlrev_b32_e32 v204, 16, v31
	v_and_b32_e32 v205, 0xffff0000, v31
	v_lshlrev_b32_e32 v212, 16, v35
	v_and_b32_e32 v213, 0xffff0000, v35
	v_lshlrev_b32_e32 v220, 16, v39
	v_and_b32_e32 v221, 0xffff0000, v39
	v_pk_add_f32 v[198:199], v[198:199], v[206:207]
	v_pk_add_f32 v[200:201], v[200:201], v[208:209]
	v_pk_add_f32 v[202:203], v[202:203], v[210:211]
	v_pk_add_f32 v[204:205], v[204:205], v[212:213]
	v_mul_f32_e32 v206, 0xbfb8aa3b, v214
	v_mul_f32_e32 v207, 0xbfb8aa3b, v215
	v_mul_f32_e32 v208, 0xbfb8aa3b, v216
	v_mul_f32_e32 v209, 0xbfb8aa3b, v217
	v_mul_f32_e32 v210, 0xbfb8aa3b, v218
	v_mul_f32_e32 v211, 0xbfb8aa3b, v219
	v_mul_f32_e32 v212, 0xbfb8aa3b, v220
	v_mul_f32_e32 v213, 0xbfb8aa3b, v221
	v_exp_f32_e32 v206, v206
	v_exp_f32_e32 v207, v207
	v_exp_f32_e32 v208, v208
	v_exp_f32_e32 v209, v209
	v_exp_f32_e32 v210, v210
	v_exp_f32_e32 v211, v211
	v_exp_f32_e32 v212, v212
	v_exp_f32_e32 v213, v213
	v_add_f32_e32 v206, 1.0, v206
	v_add_f32_e32 v207, 1.0, v207
	v_add_f32_e32 v208, 1.0, v208
	v_add_f32_e32 v209, 1.0, v209
	v_add_f32_e32 v210, 1.0, v210
	v_add_f32_e32 v211, 1.0, v211
	v_add_f32_e32 v212, 1.0, v212
	v_add_f32_e32 v213, 1.0, v213
	v_rcp_f32_e32 v206, v206
	v_rcp_f32_e32 v207, v207
	v_rcp_f32_e32 v208, v208
	v_rcp_f32_e32 v209, v209
	v_rcp_f32_e32 v210, v210
	v_rcp_f32_e32 v211, v211
	v_rcp_f32_e32 v212, v212
	v_rcp_f32_e32 v213, v213
	s_nop 0
	v_pk_mul_f32 v[206:207], v[206:207], v[214:215]
	v_pk_mul_f32 v[208:209], v[208:209], v[216:217]
	v_pk_mul_f32 v[210:211], v[210:211], v[218:219]
	v_pk_mul_f32 v[212:213], v[212:213], v[220:221]
	v_pk_mul_f32 v[198:199], v[198:199], v[206:207]
	v_pk_mul_f32 v[200:201], v[200:201], v[208:209]
	v_pk_mul_f32 v[202:203], v[202:203], v[210:211]
	v_pk_mul_f32 v[204:205], v[204:205], v[212:213]
	v_pk_mul_f32 v[214:215], v[198:199], v[198:199]
	v_pk_mul_f32 v[216:217], v[200:201], v[200:201]
	v_pk_mul_f32 v[218:219], v[202:203], v[202:203]
	v_pk_mul_f32 v[220:221], v[204:205], v[204:205]
	v_add_f32_e32 v230, v214, v215
	v_add_f32_e32 v230, v216, v230
	v_add_f32_e32 v230, v217, v230
	v_add_f32_e32 v230, v218, v230
	v_add_f32_e32 v230, v219, v230
	v_add_f32_e32 v230, v220, v230
	v_add_f32_e32 v230, v221, v230
	v_mov_b32_e32 v231, v177
	s_nop 0
	v_add_f32_dpp v230, v230, v230 row_shr:1 row_mask:0xf bank_mask:0xf bound_ctrl:1
	s_nop 1
	v_add_f32_dpp v230, v230, v230 row_shr:2 row_mask:0xf bank_mask:0xf bound_ctrl:1
	s_nop 1
	v_add_f32_dpp v230, v230, v230 row_shr:4 row_mask:0xf bank_mask:0xf bound_ctrl:1
	s_nop 1
	v_add_f32_dpp v230, v230, v230 row_shr:8 row_mask:0xf bank_mask:0xf bound_ctrl:1
	s_nop 1
	v_mov_b32_dpp v231, v230 row_bcast:15 row_mask:0xa bank_mask:0xf
	v_add_f32_e32 v230, v230, v231
	v_mov_b32_e32 v231, v177
	s_nop 1
	v_mov_b32_dpp v231, v230 row_bcast:31 row_mask:0xc bank_mask:0xf
	v_add_f32_e32 v230, v230, v231
	s_nop 0
	v_readlane_b32 s6, v230, 63
	s_nop 1
	v_fma_f32 v232, s6, v245, v238
	v_cmp_gt_f32_e32 vcc, s85, v232
	v_mul_f32_e32 v231, 0x4b800000, v232
	s_nop 0
	v_cndmask_b32_e32 v232, v232, v231, vcc
	v_rsq_f32_e32 v232, v232
	s_nop 0
	v_mul_f32_e32 v231, 0x45800000, v232
	v_cndmask_b32_e32 v232, v232, v231, vcc
	v_pk_mul_f32 v[222:223], v[116:117], v[232:233] op_sel_hi:[1,0]
	v_pk_mul_f32 v[224:225], v[118:119], v[232:233] op_sel_hi:[1,0]
	v_pk_mul_f32 v[226:227], v[120:121], v[232:233] op_sel_hi:[1,0]
	v_pk_mul_f32 v[228:229], v[122:123], v[232:233] op_sel_hi:[1,0]
	v_pk_mul_f32 v[222:223], v[198:199], v[222:223]
	v_pk_mul_f32 v[224:225], v[200:201], v[224:225]
	v_pk_mul_f32 v[226:227], v[202:203], v[226:227]
	v_pk_mul_f32 v[228:229], v[204:205], v[228:229]
	v_cvt_pk_bf16_f32 v234, v222, v223
	v_cvt_pk_bf16_f32 v235, v224, v225
	v_cvt_pk_bf16_f32 v236, v226, v227
	v_cvt_pk_bf16_f32 v237, v228, v229
	global_store_dwordx4 v[164:165], v[234:237], off offset:2048 sc1
	s_waitcnt vmcnt(15)
; __device__ __forceinline__ float silu_f(float v) { return v * __builtin_amdgcn_rcpf(1.0f + __expf(-v)); }
;     __device__ __forceinline__ const char* a(const pg8::Unit& u) const { return (const char*)ws + aoff + (size_t)u.pm * 256 * K_ * 2 + (u.kq < 0 ? 0 : u.kq * (K_ / 4) * 2); }
;     __device__ __forceinline__ const char* b(const pg8::Unit& u) const { return (const char*)ws + boff + (size_t)u.pn * 256 * K_ * 2 + (u.kq < 0 ? 0 : u.kq * (K_ / 4) * 2); }
;     __device__ __forceinline__ const char* a(const pg8::Unit& u) const { return (const char*)ws + WS_A + (size_t)u.pm * 256 * D * 2; }
;     __device__ __forceinline__ const char* b(const pg8::Unit& u) const { return (const char*)ws + boff + (size_t)u.pn * 256 * D * 2; }
;     __device__ __forceinline__ const char* a(const pg8::Unit& u) const { return (const char*)ws + WS_A + (size_t)u.pm * 256 * D * 2; }
;     __device__ __forceinline__ const char* b(const pg8::Unit& u) const { return (const char*)ws + boff + (size_t)u.pn * 256 * D * 2; }
;     __device__ __forceinline__ const char* a(const pg8::Unit& u) const { return (const char*)ws + WS_W1 + (size_t)(u.pm & 1) * 256 * 256 * 2; }
;     __device__ __forceinline__ const char* b(const pg8::Unit& u) const { return (const char*)ws + WS_A + ((size_t)u.pn * 256 * D + (size_t)(u.pm >> 1) * 256) * 2; }
; __device__ __forceinline__ void ssd_gate_norm_phase(Frame& F, int j, int nrows) {
;     ...
;         for (int g = 0; g < 8; ++g) { const size_t off = (size_t)r * DI + g * 512 + lane * 8;
;             float a[8], b[8], zz[8]; unpack8(__builtin_nontemporal_load((const u32x4*)(yf + off)), a); unpack8(__builtin_nontemporal_load((const u32x4*)(yb + off)), b); unpack8(__builtin_nontemporal_load((const u32x4*)(z + off)), zz);
;             float ss = 0.f;
; #pragma unroll
;             for (int c = 0; c < 8; ++c) { a[c] = (a[c] + b[c]) * silu_f(zz[c]); ss += a[c] * a[c]; }
;             const float rs = rsqrtf(wave_sum(ss, lane) * (1.0f / 512.0f) + EPS);
;             const f32x4* gp = (const f32x4*)(ng + g * 512 + lane * 8); const f32x4 g0 = gp[0], g1 = gp[1];
;             a[0] *= rs * g0.x; a[1] *= rs * g0.y; a[2] *= rs * g0.z; a[3] *= rs * g0.w; a[4] *= rs * g1.x; a[5] *= rs * g1.y; a[6] *= rs * g1.z; a[7] *= rs * g1.w;
;             *(u32x4*)(yf + off) = pack8(a); }
	v_lshlrev_b32_e32 v198, 16, v40
	v_and_b32_e32 v199, 0xffff0000, v40
	v_lshlrev_b32_e32 v206, 16, v44
	v_and_b32_e32 v207, 0xffff0000, v44
	v_lshlrev_b32_e32 v214, 16, v48
	v_and_b32_e32 v215, 0xffff0000, v48
	v_lshlrev_b32_e32 v200, 16, v41
	v_and_b32_e32 v201, 0xffff0000, v41
	v_lshlrev_b32_e32 v208, 16, v45
	v_and_b32_e32 v209, 0xffff0000, v45
	v_lshlrev_b32_e32 v216, 16, v49
	v_and_b32_e32 v217, 0xffff0000, v49
	v_lshlrev_b32_e32 v202, 16, v42
	v_and_b32_e32 v203, 0xffff0000, v42
	v_lshlrev_b32_e32 v210, 16, v46
	v_and_b32_e32 v211, 0xffff0000, v46
	v_lshlrev_b32_e32 v218, 16, v50
	v_and_b32_e32 v219, 0xffff0000, v50
	v_lshlrev_b32_e32 v204, 16, v43
	v_and_b32_e32 v205, 0xffff0000, v43
	v_lshlrev_b32_e32 v212, 16, v47
	v_and_b32_e32 v213, 0xffff0000, v47
	v_lshlrev_b32_e32 v220, 16, v51
	v_and_b32_e32 v221, 0xffff0000, v51
	v_pk_add_f32 v[198:199], v[198:199], v[206:207]
	v_pk_add_f32 v[200:201], v[200:201], v[208:209]
	v_pk_add_f32 v[202:203], v[202:203], v[210:211]
	v_pk_add_f32 v[204:205], v[204:205], v[212:213]
	v_mul_f32_e32 v206, 0xbfb8aa3b, v214
	v_mul_f32_e32 v207, 0xbfb8aa3b, v215
	v_mul_f32_e32 v208, 0xbfb8aa3b, v216
	v_mul_f32_e32 v209, 0xbfb8aa3b, v217
	v_mul_f32_e32 v210, 0xbfb8aa3b, v218
	v_mul_f32_e32 v211, 0xbfb8aa3b, v219
	v_mul_f32_e32 v212, 0xbfb8aa3b, v220
	v_mul_f32_e32 v213, 0xbfb8aa3b, v221
	v_exp_f32_e32 v206, v206
	v_exp_f32_e32 v207, v207
	v_exp_f32_e32 v208, v208
	v_exp_f32_e32 v209, v209
	v_exp_f32_e32 v210, v210
	v_exp_f32_e32 v211, v211
	v_exp_f32_e32 v212, v212
	v_exp_f32_e32 v213, v213
	v_add_f32_e32 v206, 1.0, v206
	v_add_f32_e32 v207, 1.0, v207
	v_add_f32_e32 v208, 1.0, v208
	v_add_f32_e32 v209, 1.0, v209
	v_add_f32_e32 v210, 1.0, v210
	v_add_f32_e32 v211, 1.0, v211
	v_add_f32_e32 v212, 1.0, v212
	v_add_f32_e32 v213, 1.0, v213
	v_rcp_f32_e32 v206, v206
	v_rcp_f32_e32 v207, v207
	v_rcp_f32_e32 v208, v208
	v_rcp_f32_e32 v209, v209
	v_rcp_f32_e32 v210, v210
	v_rcp_f32_e32 v211, v211
	v_rcp_f32_e32 v212, v212
	v_rcp_f32_e32 v213, v213
	s_nop 0
	v_pk_mul_f32 v[206:207], v[206:207], v[214:215]
	v_pk_mul_f32 v[208:209], v[208:209], v[216:217]
	v_pk_mul_f32 v[210:211], v[210:211], v[218:219]
	v_pk_mul_f32 v[212:213], v[212:213], v[220:221]
	v_pk_mul_f32 v[198:199], v[198:199], v[206:207]
	v_pk_mul_f32 v[200:201], v[200:201], v[208:209]
	v_pk_mul_f32 v[202:203], v[202:203], v[210:211]
	v_pk_mul_f32 v[204:205], v[204:205], v[212:213]
	v_pk_mul_f32 v[214:215], v[198:199], v[198:199]
	v_pk_mul_f32 v[216:217], v[200:201], v[200:201]
	v_pk_mul_f32 v[218:219], v[202:203], v[202:203]
	v_pk_mul_f32 v[220:221], v[204:205], v[204:205]
	v_add_f32_e32 v230, v214, v215
	v_add_f32_e32 v230, v216, v230
	v_add_f32_e32 v230, v217, v230
	v_add_f32_e32 v230, v218, v230
	v_add_f32_e32 v230, v219, v230
	v_add_f32_e32 v230, v220, v230
	v_add_f32_e32 v230, v221, v230
	v_mov_b32_e32 v231, v177
	s_nop 0
	v_add_f32_dpp v230, v230, v230 row_shr:1 row_mask:0xf bank_mask:0xf bound_ctrl:1
	s_nop 1
	v_add_f32_dpp v230, v230, v230 row_shr:2 row_mask:0xf bank_mask:0xf bound_ctrl:1
	s_nop 1
	v_add_f32_dpp v230, v230, v230 row_shr:4 row_mask:0xf bank_mask:0xf bound_ctrl:1
	s_nop 1
	v_add_f32_dpp v230, v230, v230 row_shr:8 row_mask:0xf bank_mask:0xf bound_ctrl:1
	s_nop 1
	v_mov_b32_dpp v231, v230 row_bcast:15 row_mask:0xa bank_mask:0xf
	v_add_f32_e32 v230, v230, v231
	v_mov_b32_e32 v231, v177
	s_nop 1
	v_mov_b32_dpp v231, v230 row_bcast:31 row_mask:0xc bank_mask:0xf
	v_add_f32_e32 v230, v230, v231
	s_nop 0
	v_readlane_b32 s6, v230, 63
	s_nop 1
	v_fma_f32 v232, s6, v245, v238
	v_cmp_gt_f32_e32 vcc, s85, v232
	v_mul_f32_e32 v231, 0x4b800000, v232
	s_nop 0
	v_cndmask_b32_e32 v232, v232, v231, vcc
	v_rsq_f32_e32 v232, v232
	s_nop 0
	v_mul_f32_e32 v231, 0x45800000, v232
	v_cndmask_b32_e32 v232, v232, v231, vcc
	v_pk_mul_f32 v[222:223], v[124:125], v[232:233] op_sel_hi:[1,0]
	v_pk_mul_f32 v[224:225], v[126:127], v[232:233] op_sel_hi:[1,0]
	v_pk_mul_f32 v[226:227], v[128:129], v[232:233] op_sel_hi:[1,0]
	v_pk_mul_f32 v[228:229], v[130:131], v[232:233] op_sel_hi:[1,0]
	v_pk_mul_f32 v[222:223], v[198:199], v[222:223]
	v_pk_mul_f32 v[224:225], v[200:201], v[224:225]
	v_pk_mul_f32 v[226:227], v[202:203], v[226:227]
	v_pk_mul_f32 v[228:229], v[204:205], v[228:229]
	v_cvt_pk_bf16_f32 v234, v222, v223
	v_cvt_pk_bf16_f32 v235, v224, v225
	v_cvt_pk_bf16_f32 v236, v226, v227
	v_cvt_pk_bf16_f32 v237, v228, v229
	global_store_dwordx4 v[164:165], v[234:237], off offset:3072 sc1
	s_waitcnt vmcnt(13)
; __device__ __forceinline__ float silu_f(float v) { return v * __builtin_amdgcn_rcpf(1.0f + __expf(-v)); }
;     __device__ __forceinline__ const char* a(const pg8::Unit& u) const { return (const char*)ws + aoff + (size_t)u.pm * 256 * K_ * 2 + (u.kq < 0 ? 0 : u.kq * (K_ / 4) * 2); }
;     __device__ __forceinline__ const char* b(const pg8::Unit& u) const { return (const char*)ws + boff + (size_t)u.pn * 256 * K_ * 2 + (u.kq < 0 ? 0 : u.kq * (K_ / 4) * 2); }
;     __device__ __forceinline__ const char* a(const pg8::Unit& u) const { return (const char*)ws + WS_A + (size_t)u.pm * 256 * D * 2; }
;     __device__ __forceinline__ const char* b(const pg8::Unit& u) const { return (const char*)ws + boff + (size_t)u.pn * 256 * D * 2; }
;     __device__ __forceinline__ const char* a(const pg8::Unit& u) const { return (const char*)ws + WS_A + (size_t)u.pm * 256 * D * 2; }
;     __device__ __forceinline__ const char* b(const pg8::Unit& u) const { return (const char*)ws + boff + (size_t)u.pn * 256 * D * 2; }
;     __device__ __forceinline__ const char* a(const pg8::Unit& u) const { return (const char*)ws + WS_W1 + (size_t)(u.pm & 1) * 256 * 256 * 2; }
;     __device__ __forceinline__ const char* b(const pg8::Unit& u) const { return (const char*)ws + WS_A + ((size_t)u.pn * 256 * D + (size_t)(u.pm >> 1) * 256) * 2; }
; __device__ __forceinline__ void ssd_gate_norm_phase(Frame& F, int j, int nrows) {
;     ...
;         for (int g = 0; g < 8; ++g) { const size_t off = (size_t)r * DI + g * 512 + lane * 8;
;             float a[8], b[8], zz[8]; unpack8(__builtin_nontemporal_load((const u32x4*)(yf + off)), a); unpack8(__builtin_nontemporal_load((const u32x4*)(yb + off)), b); unpack8(__builtin_nontemporal_load((const u32x4*)(z + off)), zz);
;             float ss = 0.f;
; #pragma unroll
;             for (int c = 0; c < 8; ++c) { a[c] = (a[c] + b[c]) * silu_f(zz[c]); ss += a[c] * a[c]; }
;             const float rs = rsqrtf(wave_sum(ss, lane) * (1.0f / 512.0f) + EPS);
;             const f32x4* gp = (const f32x4*)(ng + g * 512 + lane * 8); const f32x4 g0 = gp[0], g1 = gp[1];
;             a[0] *= rs * g0.x; a[1] *= rs * g0.y; a[2] *= rs * g0.z; a[3] *= rs * g0.w; a[4] *= rs * g1.x; a[5] *= rs * g1.y; a[6] *= rs * g1.z; a[7] *= rs * g1.w;
;             *(u32x4*)(yf + off) = pack8(a); }
	v_lshlrev_b32_e32 v198, 16, v52
	v_and_b32_e32 v199, 0xffff0000, v52
	v_lshlrev_b32_e32 v206, 16, v56
	v_and_b32_e32 v207, 0xffff0000, v56
	v_lshlrev_b32_e32 v214, 16, v60
	v_and_b32_e32 v215, 0xffff0000, v60
	v_lshlrev_b32_e32 v200, 16, v53
	v_and_b32_e32 v201, 0xffff0000, v53
	v_lshlrev_b32_e32 v208, 16, v57
	v_and_b32_e32 v209, 0xffff0000, v57
	v_lshlrev_b32_e32 v216, 16, v61
	v_and_b32_e32 v217, 0xffff0000, v61
	v_lshlrev_b32_e32 v202, 16, v54
	v_and_b32_e32 v203, 0xffff0000, v54
	v_lshlrev_b32_e32 v210, 16, v58
	v_and_b32_e32 v211, 0xffff0000, v58
	v_lshlrev_b32_e32 v218, 16, v62
	v_and_b32_e32 v219, 0xffff0000, v62
	v_lshlrev_b32_e32 v204, 16, v55
	v_and_b32_e32 v205, 0xffff0000, v55
	v_lshlrev_b32_e32 v212, 16, v59
	v_and_b32_e32 v213, 0xffff0000, v59
	v_lshlrev_b32_e32 v220, 16, v63
	v_and_b32_e32 v221, 0xffff0000, v63
	v_pk_add_f32 v[198:199], v[198:199], v[206:207]
	v_pk_add_f32 v[200:201], v[200:201], v[208:209]
	v_pk_add_f32 v[202:203], v[202:203], v[210:211]
	v_pk_add_f32 v[204:205], v[204:205], v[212:213]
	v_mul_f32_e32 v206, 0xbfb8aa3b, v214
	v_mul_f32_e32 v207, 0xbfb8aa3b, v215
	v_mul_f32_e32 v208, 0xbfb8aa3b, v216
	v_mul_f32_e32 v209, 0xbfb8aa3b, v217
	v_mul_f32_e32 v210, 0xbfb8aa3b, v218
	v_mul_f32_e32 v211, 0xbfb8aa3b, v219
	v_mul_f32_e32 v212, 0xbfb8aa3b, v220
	v_mul_f32_e32 v213, 0xbfb8aa3b, v221
	v_exp_f32_e32 v206, v206
	v_exp_f32_e32 v207, v207
	v_exp_f32_e32 v208, v208
	v_exp_f32_e32 v209, v209
	v_exp_f32_e32 v210, v210
	v_exp_f32_e32 v211, v211
	v_exp_f32_e32 v212, v212
	v_exp_f32_e32 v213, v213
	v_add_f32_e32 v206, 1.0, v206
	v_add_f32_e32 v207, 1.0, v207
	v_add_f32_e32 v208, 1.0, v208
	v_add_f32_e32 v209, 1.0, v209
	v_add_f32_e32 v210, 1.0, v210
	v_add_f32_e32 v211, 1.0, v211
	v_add_f32_e32 v212, 1.0, v212
	v_add_f32_e32 v213, 1.0, v213
	v_rcp_f32_e32 v206, v206
	v_rcp_f32_e32 v207, v207
	v_rcp_f32_e32 v208, v208
	v_rcp_f32_e32 v209, v209
	v_rcp_f32_e32 v210, v210
	v_rcp_f32_e32 v211, v211
	v_rcp_f32_e32 v212, v212
	v_rcp_f32_e32 v213, v213
	s_nop 0
	v_pk_mul_f32 v[206:207], v[206:207], v[214:215]
	v_pk_mul_f32 v[208:209], v[208:209], v[216:217]
	v_pk_mul_f32 v[210:211], v[210:211], v[218:219]
	v_pk_mul_f32 v[212:213], v[212:213], v[220:221]
	v_pk_mul_f32 v[198:199], v[198:199], v[206:207]
	v_pk_mul_f32 v[200:201], v[200:201], v[208:209]
	v_pk_mul_f32 v[202:203], v[202:203], v[210:211]
	v_pk_mul_f32 v[204:205], v[204:205], v[212:213]
	v_pk_mul_f32 v[214:215], v[198:199], v[198:199]
	v_pk_mul_f32 v[216:217], v[200:201], v[200:201]
	v_pk_mul_f32 v[218:219], v[202:203], v[202:203]
	v_pk_mul_f32 v[220:221], v[204:205], v[204:205]
	v_add_f32_e32 v230, v214, v215
	v_add_f32_e32 v230, v216, v230
	v_add_f32_e32 v230, v217, v230
	v_add_f32_e32 v230, v218, v230
	v_add_f32_e32 v230, v219, v230
	v_add_f32_e32 v230, v220, v230
	v_add_f32_e32 v230, v221, v230
	v_mov_b32_e32 v231, v177
	s_nop 0
	v_add_f32_dpp v230, v230, v230 row_shr:1 row_mask:0xf bank_mask:0xf bound_ctrl:1
	s_nop 1
	v_add_f32_dpp v230, v230, v230 row_shr:2 row_mask:0xf bank_mask:0xf bound_ctrl:1
	s_nop 1
	v_add_f32_dpp v230, v230, v230 row_shr:4 row_mask:0xf bank_mask:0xf bound_ctrl:1
	s_nop 1
	v_add_f32_dpp v230, v230, v230 row_shr:8 row_mask:0xf bank_mask:0xf bound_ctrl:1
	s_nop 1
	v_mov_b32_dpp v231, v230 row_bcast:15 row_mask:0xa bank_mask:0xf
	v_add_f32_e32 v230, v230, v231
	v_mov_b32_e32 v231, v177
	s_nop 1
	v_mov_b32_dpp v231, v230 row_bcast:31 row_mask:0xc bank_mask:0xf
	v_add_f32_e32 v230, v230, v231
	s_nop 0
	v_readlane_b32 s6, v230, 63
	s_nop 1
	v_fma_f32 v232, s6, v245, v238
	v_cmp_gt_f32_e32 vcc, s85, v232
	v_mul_f32_e32 v231, 0x4b800000, v232
	s_nop 0
	v_cndmask_b32_e32 v232, v232, v231, vcc
	v_rsq_f32_e32 v232, v232
	s_nop 0
	v_mul_f32_e32 v231, 0x45800000, v232
	v_cndmask_b32_e32 v232, v232, v231, vcc
	v_pk_mul_f32 v[222:223], v[132:133], v[232:233] op_sel_hi:[1,0]
	v_pk_mul_f32 v[224:225], v[134:135], v[232:233] op_sel_hi:[1,0]
	v_pk_mul_f32 v[226:227], v[136:137], v[232:233] op_sel_hi:[1,0]
	v_pk_mul_f32 v[228:229], v[138:139], v[232:233] op_sel_hi:[1,0]
	v_pk_mul_f32 v[222:223], v[198:199], v[222:223]
	v_pk_mul_f32 v[224:225], v[200:201], v[224:225]
	v_pk_mul_f32 v[226:227], v[202:203], v[226:227]
	v_pk_mul_f32 v[228:229], v[204:205], v[228:229]
	v_cvt_pk_bf16_f32 v234, v222, v223
	v_cvt_pk_bf16_f32 v235, v224, v225
	v_cvt_pk_bf16_f32 v236, v226, v227
	v_cvt_pk_bf16_f32 v237, v228, v229
	global_store_dwordx4 v[166:167], v[234:237], off sc1
	s_waitcnt vmcnt(11)
; __device__ __forceinline__ float silu_f(float v) { return v * __builtin_amdgcn_rcpf(1.0f + __expf(-v)); }
;     __device__ __forceinline__ const char* a(const pg8::Unit& u) const { return (const char*)ws + aoff + (size_t)u.pm * 256 * K_ * 2 + (u.kq < 0 ? 0 : u.kq * (K_ / 4) * 2); }
;     __device__ __forceinline__ const char* b(const pg8::Unit& u) const { return (const char*)ws + boff + (size_t)u.pn * 256 * K_ * 2 + (u.kq < 0 ? 0 : u.kq * (K_ / 4) * 2); }
;     __device__ __forceinline__ const char* a(const pg8::Unit& u) const { return (const char*)ws + WS_A + (size_t)u.pm * 256 * D * 2; }
;     __device__ __forceinline__ const char* b(const pg8::Unit& u) const { return (const char*)ws + boff + (size_t)u.pn * 256 * D * 2; }
;     __device__ __forceinline__ const char* a(const pg8::Unit& u) const { return (const char*)ws + WS_A + (size_t)u.pm * 256 * D * 2; }
;     __device__ __forceinline__ const char* b(const pg8::Unit& u) const { return (const char*)ws + boff + (size_t)u.pn * 256 * D * 2; }
;     __device__ __forceinline__ const char* a(const pg8::Unit& u) const { return (const char*)ws + WS_W1 + (size_t)(u.pm & 1) * 256 * 256 * 2; }
;     __device__ __forceinline__ const char* b(const pg8::Unit& u) const { return (const char*)ws + WS_A + ((size_t)u.pn * 256 * D + (size_t)(u.pm >> 1) * 256) * 2; }
; __device__ __forceinline__ void ssd_gate_norm_phase(Frame& F, int j, int nrows) {
;     ...
;         for (int g = 0; g < 8; ++g) { const size_t off = (size_t)r * DI + g * 512 + lane * 8;
;             float a[8], b[8], zz[8]; unpack8(__builtin_nontemporal_load((const u32x4*)(yf + off)), a); unpack8(__builtin_nontemporal_load((const u32x4*)(yb + off)), b); unpack8(__builtin_nontemporal_load((const u32x4*)(z + off)), zz);
;             float ss = 0.f;
; #pragma unroll
;             for (int c = 0; c < 8; ++c) { a[c] = (a[c] + b[c]) * silu_f(zz[c]); ss += a[c] * a[c]; }
;             const float rs = rsqrtf(wave_sum(ss, lane) * (1.0f / 512.0f) + EPS);
;             const f32x4* gp = (const f32x4*)(ng + g * 512 + lane * 8); const f32x4 g0 = gp[0], g1 = gp[1];
;             a[0] *= rs * g0.x; a[1] *= rs * g0.y; a[2] *= rs * g0.z; a[3] *= rs * g0.w; a[4] *= rs * g1.x; a[5] *= rs * g1.y; a[6] *= rs * g1.z; a[7] *= rs * g1.w;
;             *(u32x4*)(yf + off) = pack8(a); }
	v_lshlrev_b32_e32 v198, 16, v64
	v_and_b32_e32 v199, 0xffff0000, v64
	v_lshlrev_b32_e32 v206, 16, v68
	v_and_b32_e32 v207, 0xffff0000, v68
	v_lshlrev_b32_e32 v214, 16, v72
	v_and_b32_e32 v215, 0xffff0000, v72
	v_lshlrev_b32_e32 v200, 16, v65
	v_and_b32_e32 v201, 0xffff0000, v65
	v_lshlrev_b32_e32 v208, 16, v69
	v_and_b32_e32 v209, 0xffff0000, v69
	v_lshlrev_b32_e32 v216, 16, v73
	v_and_b32_e32 v217, 0xffff0000, v73
	v_lshlrev_b32_e32 v202, 16, v66
	v_and_b32_e32 v203, 0xffff0000, v66
	v_lshlrev_b32_e32 v210, 16, v70
	v_and_b32_e32 v211, 0xffff0000, v70
	v_lshlrev_b32_e32 v218, 16, v74
	v_and_b32_e32 v219, 0xffff0000, v74
	v_lshlrev_b32_e32 v204, 16, v67
	v_and_b32_e32 v205, 0xffff0000, v67
	v_lshlrev_b32_e32 v212, 16, v71
	v_and_b32_e32 v213, 0xffff0000, v71
	v_lshlrev_b32_e32 v220, 16, v75
	v_and_b32_e32 v221, 0xffff0000, v75
	v_pk_add_f32 v[198:199], v[198:199], v[206:207]
	v_pk_add_f32 v[200:201], v[200:201], v[208:209]
	v_pk_add_f32 v[202:203], v[202:203], v[210:211]
	v_pk_add_f32 v[204:205], v[204:205], v[212:213]
	v_mul_f32_e32 v206, 0xbfb8aa3b, v214
	v_mul_f32_e32 v207, 0xbfb8aa3b, v215
	v_mul_f32_e32 v208, 0xbfb8aa3b, v216
	v_mul_f32_e32 v209, 0xbfb8aa3b, v217
	v_mul_f32_e32 v210, 0xbfb8aa3b, v218
	v_mul_f32_e32 v211, 0xbfb8aa3b, v219
	v_mul_f32_e32 v212, 0xbfb8aa3b, v220
	v_mul_f32_e32 v213, 0xbfb8aa3b, v221
	v_exp_f32_e32 v206, v206
	v_exp_f32_e32 v207, v207
	v_exp_f32_e32 v208, v208
	v_exp_f32_e32 v209, v209
	v_exp_f32_e32 v210, v210
	v_exp_f32_e32 v211, v211
	v_exp_f32_e32 v212, v212
	v_exp_f32_e32 v213, v213
	v_add_f32_e32 v206, 1.0, v206
	v_add_f32_e32 v207, 1.0, v207
	v_add_f32_e32 v208, 1.0, v208
	v_add_f32_e32 v209, 1.0, v209
	v_add_f32_e32 v210, 1.0, v210
	v_add_f32_e32 v211, 1.0, v211
	v_add_f32_e32 v212, 1.0, v212
	v_add_f32_e32 v213, 1.0, v213
	v_rcp_f32_e32 v206, v206
	v_rcp_f32_e32 v207, v207
	v_rcp_f32_e32 v208, v208
	v_rcp_f32_e32 v209, v209
	v_rcp_f32_e32 v210, v210
	v_rcp_f32_e32 v211, v211
	v_rcp_f32_e32 v212, v212
	v_rcp_f32_e32 v213, v213
	s_nop 0
	v_pk_mul_f32 v[206:207], v[206:207], v[214:215]
	v_pk_mul_f32 v[208:209], v[208:209], v[216:217]
	v_pk_mul_f32 v[210:211], v[210:211], v[218:219]
	v_pk_mul_f32 v[212:213], v[212:213], v[220:221]
	v_pk_mul_f32 v[198:199], v[198:199], v[206:207]
	v_pk_mul_f32 v[200:201], v[200:201], v[208:209]
	v_pk_mul_f32 v[202:203], v[202:203], v[210:211]
	v_pk_mul_f32 v[204:205], v[204:205], v[212:213]
	v_pk_mul_f32 v[214:215], v[198:199], v[198:199]
	v_pk_mul_f32 v[216:217], v[200:201], v[200:201]
	v_pk_mul_f32 v[218:219], v[202:203], v[202:203]
	v_pk_mul_f32 v[220:221], v[204:205], v[204:205]
	v_add_f32_e32 v230, v214, v215
	v_add_f32_e32 v230, v216, v230
	v_add_f32_e32 v230, v217, v230
	v_add_f32_e32 v230, v218, v230
	v_add_f32_e32 v230, v219, v230
	v_add_f32_e32 v230, v220, v230
	v_add_f32_e32 v230, v221, v230
	v_mov_b32_e32 v231, v177
	s_nop 0
	v_add_f32_dpp v230, v230, v230 row_shr:1 row_mask:0xf bank_mask:0xf bound_ctrl:1
	s_nop 1
	v_add_f32_dpp v230, v230, v230 row_shr:2 row_mask:0xf bank_mask:0xf bound_ctrl:1
	s_nop 1
	v_add_f32_dpp v230, v230, v230 row_shr:4 row_mask:0xf bank_mask:0xf bound_ctrl:1
	s_nop 1
	v_add_f32_dpp v230, v230, v230 row_shr:8 row_mask:0xf bank_mask:0xf bound_ctrl:1
	s_nop 1
	v_mov_b32_dpp v231, v230 row_bcast:15 row_mask:0xa bank_mask:0xf
	v_add_f32_e32 v230, v230, v231
	v_mov_b32_e32 v231, v177
	s_nop 1
	v_mov_b32_dpp v231, v230 row_bcast:31 row_mask:0xc bank_mask:0xf
	v_add_f32_e32 v230, v230, v231
	s_nop 0
	v_readlane_b32 s6, v230, 63
	s_nop 1
	v_fma_f32 v232, s6, v245, v238
	v_cmp_gt_f32_e32 vcc, s85, v232
	v_mul_f32_e32 v231, 0x4b800000, v232
	s_nop 0
	v_cndmask_b32_e32 v232, v232, v231, vcc
	v_rsq_f32_e32 v232, v232
	s_nop 0
	v_mul_f32_e32 v231, 0x45800000, v232
	v_cndmask_b32_e32 v232, v232, v231, vcc
	v_pk_mul_f32 v[222:223], v[140:141], v[232:233] op_sel_hi:[1,0]
	v_pk_mul_f32 v[224:225], v[142:143], v[232:233] op_sel_hi:[1,0]
	v_pk_mul_f32 v[226:227], v[144:145], v[232:233] op_sel_hi:[1,0]
	v_pk_mul_f32 v[228:229], v[146:147], v[232:233] op_sel_hi:[1,0]
	v_pk_mul_f32 v[222:223], v[198:199], v[222:223]
	v_pk_mul_f32 v[224:225], v[200:201], v[224:225]
	v_pk_mul_f32 v[226:227], v[202:203], v[226:227]
	v_pk_mul_f32 v[228:229], v[204:205], v[228:229]
	v_cvt_pk_bf16_f32 v234, v222, v223
	v_cvt_pk_bf16_f32 v235, v224, v225
	v_cvt_pk_bf16_f32 v236, v226, v227
	v_cvt_pk_bf16_f32 v237, v228, v229
	global_store_dwordx4 v[166:167], v[234:237], off offset:1024 sc1
	s_waitcnt vmcnt(9)
; __device__ __forceinline__ float silu_f(float v) { return v * __builtin_amdgcn_rcpf(1.0f + __expf(-v)); }
;     __device__ __forceinline__ const char* a(const pg8::Unit& u) const { return (const char*)ws + aoff + (size_t)u.pm * 256 * K_ * 2 + (u.kq < 0 ? 0 : u.kq * (K_ / 4) * 2); }
;     __device__ __forceinline__ const char* b(const pg8::Unit& u) const { return (const char*)ws + boff + (size_t)u.pn * 256 * K_ * 2 + (u.kq < 0 ? 0 : u.kq * (K_ / 4) * 2); }
;     __device__ __forceinline__ const char* a(const pg8::Unit& u) const { return (const char*)ws + WS_A + (size_t)u.pm * 256 * D * 2; }
;     __device__ __forceinline__ const char* b(const pg8::Unit& u) const { return (const char*)ws + boff + (size_t)u.pn * 256 * D * 2; }
;     __device__ __forceinline__ const char* a(const pg8::Unit& u) const { return (const char*)ws + WS_A + (size_t)u.pm * 256 * D * 2; }
;     __device__ __forceinline__ const char* b(const pg8::Unit& u) const { return (const char*)ws + boff + (size_t)u.pn * 256 * D * 2; }
;     __device__ __forceinline__ const char* a(const pg8::Unit& u) const { return (const char*)ws + WS_W1 + (size_t)(u.pm & 1) * 256 * 256 * 2; }
;     __device__ __forceinline__ const char* b(const pg8::Unit& u) const { return (const char*)ws + WS_A + ((size_t)u.pn * 256 * D + (size_t)(u.pm >> 1) * 256) * 2; }
; __device__ __forceinline__ void ssd_gate_norm_phase(Frame& F, int j, int nrows) {
;     ...
;         for (int g = 0; g < 8; ++g) { const size_t off = (size_t)r * DI + g * 512 + lane * 8;
;             float a[8], b[8], zz[8]; unpack8(__builtin_nontemporal_load((const u32x4*)(yf + off)), a); unpack8(__builtin_nontemporal_load((const u32x4*)(yb + off)), b); unpack8(__builtin_nontemporal_load((const u32x4*)(z + off)), zz);
;             float ss = 0.f;
; #pragma unroll
;             for (int c = 0; c < 8; ++c) { a[c] = (a[c] + b[c]) * silu_f(zz[c]); ss += a[c] * a[c]; }
;             const float rs = rsqrtf(wave_sum(ss, lane) * (1.0f / 512.0f) + EPS);
;             const f32x4* gp = (const f32x4*)(ng + g * 512 + lane * 8); const f32x4 g0 = gp[0], g1 = gp[1];
;             a[0] *= rs * g0.x; a[1] *= rs * g0.y; a[2] *= rs * g0.z; a[3] *= rs * g0.w; a[4] *= rs * g1.x; a[5] *= rs * g1.y; a[6] *= rs * g1.z; a[7] *= rs * g1.w;
;             *(u32x4*)(yf + off) = pack8(a); }
	v_lshlrev_b32_e32 v198, 16, v76
	v_and_b32_e32 v199, 0xffff0000, v76
	v_lshlrev_b32_e32 v206, 16, v80
	v_and_b32_e32 v207, 0xffff0000, v80
	v_lshlrev_b32_e32 v214, 16, v84
	v_and_b32_e32 v215, 0xffff0000, v84
	v_lshlrev_b32_e32 v200, 16, v77
	v_and_b32_e32 v201, 0xffff0000, v77
	v_lshlrev_b32_e32 v208, 16, v81
	v_and_b32_e32 v209, 0xffff0000, v81
	v_lshlrev_b32_e32 v216, 16, v85
	v_and_b32_e32 v217, 0xffff0000, v85
	v_lshlrev_b32_e32 v202, 16, v78
	v_and_b32_e32 v203, 0xffff0000, v78
	v_lshlrev_b32_e32 v210, 16, v82
	v_and_b32_e32 v211, 0xffff0000, v82
	v_lshlrev_b32_e32 v218, 16, v86
	v_and_b32_e32 v219, 0xffff0000, v86
	v_lshlrev_b32_e32 v204, 16, v79
	v_and_b32_e32 v205, 0xffff0000, v79
	v_lshlrev_b32_e32 v212, 16, v83
	v_and_b32_e32 v213, 0xffff0000, v83
	v_lshlrev_b32_e32 v220, 16, v87
	v_and_b32_e32 v221, 0xffff0000, v87
	v_pk_add_f32 v[198:199], v[198:199], v[206:207]
	v_pk_add_f32 v[200:201], v[200:201], v[208:209]
	v_pk_add_f32 v[202:203], v[202:203], v[210:211]
	v_pk_add_f32 v[204:205], v[204:205], v[212:213]
	v_mul_f32_e32 v206, 0xbfb8aa3b, v214
	v_mul_f32_e32 v207, 0xbfb8aa3b, v215
	v_mul_f32_e32 v208, 0xbfb8aa3b, v216
	v_mul_f32_e32 v209, 0xbfb8aa3b, v217
	v_mul_f32_e32 v210, 0xbfb8aa3b, v218
	v_mul_f32_e32 v211, 0xbfb8aa3b, v219
	v_mul_f32_e32 v212, 0xbfb8aa3b, v220
	v_mul_f32_e32 v213, 0xbfb8aa3b, v221
	v_exp_f32_e32 v206, v206
	v_exp_f32_e32 v207, v207
	v_exp_f32_e32 v208, v208
	v_exp_f32_e32 v209, v209
	v_exp_f32_e32 v210, v210
	v_exp_f32_e32 v211, v211
	v_exp_f32_e32 v212, v212
	v_exp_f32_e32 v213, v213
	v_add_f32_e32 v206, 1.0, v206
	v_add_f32_e32 v207, 1.0, v207
	v_add_f32_e32 v208, 1.0, v208
	v_add_f32_e32 v209, 1.0, v209
	v_add_f32_e32 v210, 1.0, v210
	v_add_f32_e32 v211, 1.0, v211
	v_add_f32_e32 v212, 1.0, v212
	v_add_f32_e32 v213, 1.0, v213
	v_rcp_f32_e32 v206, v206
	v_rcp_f32_e32 v207, v207
	v_rcp_f32_e32 v208, v208
	v_rcp_f32_e32 v209, v209
	v_rcp_f32_e32 v210, v210
	v_rcp_f32_e32 v211, v211
	v_rcp_f32_e32 v212, v212
	v_rcp_f32_e32 v213, v213
	s_nop 0
	v_pk_mul_f32 v[206:207], v[206:207], v[214:215]
	v_pk_mul_f32 v[208:209], v[208:209], v[216:217]
	v_pk_mul_f32 v[210:211], v[210:211], v[218:219]
	v_pk_mul_f32 v[212:213], v[212:213], v[220:221]
	v_pk_mul_f32 v[198:199], v[198:199], v[206:207]
	v_pk_mul_f32 v[200:201], v[200:201], v[208:209]
	v_pk_mul_f32 v[202:203], v[202:203], v[210:211]
	v_pk_mul_f32 v[204:205], v[204:205], v[212:213]
	v_pk_mul_f32 v[214:215], v[198:199], v[198:199]
	v_pk_mul_f32 v[216:217], v[200:201], v[200:201]
	v_pk_mul_f32 v[218:219], v[202:203], v[202:203]
	v_pk_mul_f32 v[220:221], v[204:205], v[204:205]
	v_add_f32_e32 v230, v214, v215
	v_add_f32_e32 v230, v216, v230
	v_add_f32_e32 v230, v217, v230
	v_add_f32_e32 v230, v218, v230
	v_add_f32_e32 v230, v219, v230
	v_add_f32_e32 v230, v220, v230
	v_add_f32_e32 v230, v221, v230
	v_mov_b32_e32 v231, v177
	s_nop 0
	v_add_f32_dpp v230, v230, v230 row_shr:1 row_mask:0xf bank_mask:0xf bound_ctrl:1
	s_nop 1
	v_add_f32_dpp v230, v230, v230 row_shr:2 row_mask:0xf bank_mask:0xf bound_ctrl:1
	s_nop 1
	v_add_f32_dpp v230, v230, v230 row_shr:4 row_mask:0xf bank_mask:0xf bound_ctrl:1
	s_nop 1
	v_add_f32_dpp v230, v230, v230 row_shr:8 row_mask:0xf bank_mask:0xf bound_ctrl:1
	s_nop 1
	v_mov_b32_dpp v231, v230 row_bcast:15 row_mask:0xa bank_mask:0xf
	v_add_f32_e32 v230, v230, v231
	v_mov_b32_e32 v231, v177
	s_nop 1
	v_mov_b32_dpp v231, v230 row_bcast:31 row_mask:0xc bank_mask:0xf
	v_add_f32_e32 v230, v230, v231
	s_nop 0
	v_readlane_b32 s6, v230, 63
	s_nop 1
	v_fma_f32 v232, s6, v245, v238
	v_cmp_gt_f32_e32 vcc, s85, v232
	v_mul_f32_e32 v231, 0x4b800000, v232
	s_nop 0
	v_cndmask_b32_e32 v232, v232, v231, vcc
	v_rsq_f32_e32 v232, v232
	s_nop 0
	v_mul_f32_e32 v231, 0x45800000, v232
	v_cndmask_b32_e32 v232, v232, v231, vcc
	v_pk_mul_f32 v[222:223], v[148:149], v[232:233] op_sel_hi:[1,0]
	v_pk_mul_f32 v[224:225], v[150:151], v[232:233] op_sel_hi:[1,0]
	v_pk_mul_f32 v[226:227], v[152:153], v[232:233] op_sel_hi:[1,0]
	v_pk_mul_f32 v[228:229], v[154:155], v[232:233] op_sel_hi:[1,0]
	v_pk_mul_f32 v[222:223], v[198:199], v[222:223]
	v_pk_mul_f32 v[224:225], v[200:201], v[224:225]
	v_pk_mul_f32 v[226:227], v[202:203], v[226:227]
	v_pk_mul_f32 v[228:229], v[204:205], v[228:229]
	v_cvt_pk_bf16_f32 v234, v222, v223
	v_cvt_pk_bf16_f32 v235, v224, v225
	v_cvt_pk_bf16_f32 v236, v226, v227
	v_cvt_pk_bf16_f32 v237, v228, v229
	global_store_dwordx4 v[166:167], v[234:237], off offset:2048 sc1
	s_waitcnt vmcnt(7)
; __device__ __forceinline__ float silu_f(float v) { return v * __builtin_amdgcn_rcpf(1.0f + __expf(-v)); }
;     __device__ __forceinline__ const char* a(const pg8::Unit& u) const { return (const char*)ws + aoff + (size_t)u.pm * 256 * K_ * 2 + (u.kq < 0 ? 0 : u.kq * (K_ / 4) * 2); }
;     __device__ __forceinline__ const char* b(const pg8::Unit& u) const { return (const char*)ws + boff + (size_t)u.pn * 256 * K_ * 2 + (u.kq < 0 ? 0 : u.kq * (K_ / 4) * 2); }
;     __device__ __forceinline__ const char* a(const pg8::Unit& u) const { return (const char*)ws + WS_A + (size_t)u.pm * 256 * D * 2; }
;     __device__ __forceinline__ const char* b(const pg8::Unit& u) const { return (const char*)ws + boff + (size_t)u.pn * 256 * D * 2; }
;     __device__ __forceinline__ const char* a(const pg8::Unit& u) const { return (const char*)ws + WS_A + (size_t)u.pm * 256 * D * 2; }
;     __device__ __forceinline__ const char* b(const pg8::Unit& u) const { return (const char*)ws + boff + (size_t)u.pn * 256 * D * 2; }
;     __device__ __forceinline__ const char* a(const pg8::Unit& u) const { return (const char*)ws + WS_W1 + (size_t)(u.pm & 1) * 256 * 256 * 2; }
;     __device__ __forceinline__ const char* b(const pg8::Unit& u) const { return (const char*)ws + WS_A + ((size_t)u.pn * 256 * D + (size_t)(u.pm >> 1) * 256) * 2; }
; __device__ __forceinline__ void ssd_gate_norm_phase(Frame& F, int j, int nrows) {
;     ...
;         for (int g = 0; g < 8; ++g) { const size_t off = (size_t)r * DI + g * 512 + lane * 8;
;             float a[8], b[8], zz[8]; unpack8(__builtin_nontemporal_load((const u32x4*)(yf + off)), a); unpack8(__builtin_nontemporal_load((const u32x4*)(yb + off)), b); unpack8(__builtin_nontemporal_load((const u32x4*)(z + off)), zz);
;             float ss = 0.f;
; #pragma unroll
;             for (int c = 0; c < 8; ++c) { a[c] = (a[c] + b[c]) * silu_f(zz[c]); ss += a[c] * a[c]; }
;             const float rs = rsqrtf(wave_sum(ss, lane) * (1.0f / 512.0f) + EPS);
;             const f32x4* gp = (const f32x4*)(ng + g * 512 + lane * 8); const f32x4 g0 = gp[0], g1 = gp[1];
;             a[0] *= rs * g0.x; a[1] *= rs * g0.y; a[2] *= rs * g0.z; a[3] *= rs * g0.w; a[4] *= rs * g1.x; a[5] *= rs * g1.y; a[6] *= rs * g1.z; a[7] *= rs * g1.w;
;             *(u32x4*)(yf + off) = pack8(a); }
	v_lshlrev_b32_e32 v198, 16, v88
	v_and_b32_e32 v199, 0xffff0000, v88
	v_lshlrev_b32_e32 v206, 16, v92
	v_and_b32_e32 v207, 0xffff0000, v92
	v_lshlrev_b32_e32 v214, 16, v96
	v_and_b32_e32 v215, 0xffff0000, v96
	v_lshlrev_b32_e32 v200, 16, v89
	v_and_b32_e32 v201, 0xffff0000, v89
	v_lshlrev_b32_e32 v208, 16, v93
	v_and_b32_e32 v209, 0xffff0000, v93
	v_lshlrev_b32_e32 v216, 16, v97
	v_and_b32_e32 v217, 0xffff0000, v97
	v_lshlrev_b32_e32 v202, 16, v90
	v_and_b32_e32 v203, 0xffff0000, v90
	v_lshlrev_b32_e32 v210, 16, v94
	v_and_b32_e32 v211, 0xffff0000, v94
	v_lshlrev_b32_e32 v218, 16, v98
	v_and_b32_e32 v219, 0xffff0000, v98
	v_lshlrev_b32_e32 v204, 16, v91
	v_and_b32_e32 v205, 0xffff0000, v91
	v_lshlrev_b32_e32 v212, 16, v95
	v_and_b32_e32 v213, 0xffff0000, v95
	v_lshlrev_b32_e32 v220, 16, v99
	v_and_b32_e32 v221, 0xffff0000, v99
	v_pk_add_f32 v[198:199], v[198:199], v[206:207]
	v_pk_add_f32 v[200:201], v[200:201], v[208:209]
	v_pk_add_f32 v[202:203], v[202:203], v[210:211]
	v_pk_add_f32 v[204:205], v[204:205], v[212:213]
	v_mul_f32_e32 v206, 0xbfb8aa3b, v214
	v_mul_f32_e32 v207, 0xbfb8aa3b, v215
	v_mul_f32_e32 v208, 0xbfb8aa3b, v216
	v_mul_f32_e32 v209, 0xbfb8aa3b, v217
	v_mul_f32_e32 v210, 0xbfb8aa3b, v218
	v_mul_f32_e32 v211, 0xbfb8aa3b, v219
	v_mul_f32_e32 v212, 0xbfb8aa3b, v220
	v_mul_f32_e32 v213, 0xbfb8aa3b, v221
	v_exp_f32_e32 v206, v206
	v_exp_f32_e32 v207, v207
	v_exp_f32_e32 v208, v208
	v_exp_f32_e32 v209, v209
	v_exp_f32_e32 v210, v210
	v_exp_f32_e32 v211, v211
	v_exp_f32_e32 v212, v212
	v_exp_f32_e32 v213, v213
	v_add_f32_e32 v206, 1.0, v206
	v_add_f32_e32 v207, 1.0, v207
	v_add_f32_e32 v208, 1.0, v208
	v_add_f32_e32 v209, 1.0, v209
	v_add_f32_e32 v210, 1.0, v210
	v_add_f32_e32 v211, 1.0, v211
	v_add_f32_e32 v212, 1.0, v212
	v_add_f32_e32 v213, 1.0, v213
	v_rcp_f32_e32 v206, v206
	v_rcp_f32_e32 v207, v207
	v_rcp_f32_e32 v208, v208
	v_rcp_f32_e32 v209, v209
	v_rcp_f32_e32 v210, v210
	v_rcp_f32_e32 v211, v211
	v_rcp_f32_e32 v212, v212
	v_rcp_f32_e32 v213, v213
	s_nop 0
	v_pk_mul_f32 v[206:207], v[206:207], v[214:215]
	v_pk_mul_f32 v[208:209], v[208:209], v[216:217]
	v_pk_mul_f32 v[210:211], v[210:211], v[218:219]
	v_pk_mul_f32 v[212:213], v[212:213], v[220:221]
	v_pk_mul_f32 v[198:199], v[198:199], v[206:207]
	v_pk_mul_f32 v[200:201], v[200:201], v[208:209]
	v_pk_mul_f32 v[202:203], v[202:203], v[210:211]
	v_pk_mul_f32 v[204:205], v[204:205], v[212:213]
	v_pk_mul_f32 v[214:215], v[198:199], v[198:199]
	v_pk_mul_f32 v[216:217], v[200:201], v[200:201]
	v_pk_mul_f32 v[218:219], v[202:203], v[202:203]
	v_pk_mul_f32 v[220:221], v[204:205], v[204:205]
	v_add_f32_e32 v230, v214, v215
	v_add_f32_e32 v230, v216, v230
	v_add_f32_e32 v230, v217, v230
	v_add_f32_e32 v230, v218, v230
	v_add_f32_e32 v230, v219, v230
	v_add_f32_e32 v230, v220, v230
	v_add_f32_e32 v230, v221, v230
	v_mov_b32_e32 v231, v177
	s_nop 0
	v_add_f32_dpp v230, v230, v230 row_shr:1 row_mask:0xf bank_mask:0xf bound_ctrl:1
	s_nop 1
	v_add_f32_dpp v230, v230, v230 row_shr:2 row_mask:0xf bank_mask:0xf bound_ctrl:1
	s_nop 1
	v_add_f32_dpp v230, v230, v230 row_shr:4 row_mask:0xf bank_mask:0xf bound_ctrl:1
	s_nop 1
	v_add_f32_dpp v230, v230, v230 row_shr:8 row_mask:0xf bank_mask:0xf bound_ctrl:1
	s_nop 1
	v_mov_b32_dpp v231, v230 row_bcast:15 row_mask:0xa bank_mask:0xf
	v_add_f32_e32 v230, v230, v231
	v_mov_b32_e32 v231, v177
	s_nop 1
	v_mov_b32_dpp v231, v230 row_bcast:31 row_mask:0xc bank_mask:0xf
	v_add_f32_e32 v230, v230, v231
	s_nop 0
	v_readlane_b32 s6, v230, 63
	s_nop 1
	v_fma_f32 v232, s6, v245, v238
	v_cmp_gt_f32_e32 vcc, s85, v232
	v_mul_f32_e32 v231, 0x4b800000, v232
	s_nop 0
	v_cndmask_b32_e32 v232, v232, v231, vcc
	v_rsq_f32_e32 v232, v232
	s_nop 0
	v_mul_f32_e32 v231, 0x45800000, v232
	v_cndmask_b32_e32 v232, v232, v231, vcc
	v_pk_mul_f32 v[222:223], v[156:157], v[232:233] op_sel_hi:[1,0]
	v_pk_mul_f32 v[224:225], v[158:159], v[232:233] op_sel_hi:[1,0]
	v_pk_mul_f32 v[226:227], v[160:161], v[232:233] op_sel_hi:[1,0]
	v_pk_mul_f32 v[228:229], v[162:163], v[232:233] op_sel_hi:[1,0]
	v_pk_mul_f32 v[222:223], v[198:199], v[222:223]
	v_pk_mul_f32 v[224:225], v[200:201], v[224:225]
	v_pk_mul_f32 v[226:227], v[202:203], v[226:227]
	v_pk_mul_f32 v[228:229], v[204:205], v[228:229]
	v_cvt_pk_bf16_f32 v234, v222, v223
	v_cvt_pk_bf16_f32 v235, v224, v225
	v_cvt_pk_bf16_f32 v236, v226, v227
	v_cvt_pk_bf16_f32 v237, v228, v229
	global_store_dwordx4 v[166:167], v[234:237], off offset:3072 sc1

; #define PG8_STAGE(bufoff, gbase, voff) do { _Pragma("unroll") for (int _i = 0; _i < 2; ++_i) \
;         __builtin_amdgcn_global_load_lds((const unsigned*)((const char*)(gbase) + (voff)[_i]), (LAS unsigned*)(lds + (bufoff) + ldsw + _i * 8192), 16, 0, 0); } while (0)
; #define PG8_LDA(dst, b, h) do { _Pragma("unroll") for (int m = 0; m < 4; ++m) _Pragma("unroll") for (int k = 0; k < 2; ++k) dst[m][k] = *(const LAS bf16x8*)(lds + PG8_SA(b, h) + aoff + m * 2048 + k * 1024); } while (0)
; #define PG8_LDB(dst, b, h) do { _Pragma("unroll") for (int n = 0; n < 2; ++n) _Pragma("unroll") for (int k = 0; k < 2; ++k) dst[n][k] = *(const LAS bf16x8*)(lds + PG8_SB(b, h) + boff + n * 2048 + k * 1024); } while (0)
; #define PG8_WAIT_V(n) asm volatile("s_waitcnt vmcnt(" #n ")" ::: "memory")
; #define PG8_BAR __builtin_amdgcn_s_barrier()
; #define PG8_SCHED __builtin_amdgcn_sched_barrier(0)
;     __device__ __forceinline__ const char* a(const pg8::Unit& u) const { return (const char*)ws + aoff + (size_t)u.pm * 256 * K_ * 2 + (u.kq < 0 ? 0 : u.kq * (K_ / 4) * 2); }
;     __device__ __forceinline__ const char* b(const pg8::Unit& u) const { return (const char*)ws + boff + (size_t)u.pn * 256 * K_ * 2 + (u.kq < 0 ? 0 : u.kq * (K_ / 4) * 2); }
;     __device__ __forceinline__ const char* a(const pg8::Unit& u) const { return (const char*)ws + WS_A + (size_t)u.pm * 256 * D * 2; }
;     __device__ __forceinline__ const char* b(const pg8::Unit& u) const { return (const char*)ws + boff + (size_t)u.pn * 256 * D * 2; }
; template <class Epi, class Sched, bool ALIGN_EPI>
; __device__ __forceinline__ void gemm_phase(LAS unsigned char* lds, const int wid, const int lda_, const int ldb_, const int K_, const Sched& S, const Epi& E) {
;     ...
;     const char* cA = S.a(cur); const char* cB = S.b(cur);
;     PG8_STAGE(PG8_SB(0, 0), cB, voffB); PG8_STAGE(PG8_SB(0, 1), cB + hstepB, voffB); PG8_STAGE(PG8_SA(0, 0), cA, voffA); PG8_STAGE(PG8_SA(0, 1), cA + hstepA, voffA);
;     if (wr == 1) PG8_BAR;
;     PG8_WAIT_V(2); PG8_BAR;
;     PG8_STAGE(PG8_SB(1, 0), cB + kstep, voffB); PG8_STAGE(PG8_SA(1, 0), cA + kstep, voffA); PG8_STAGE(PG8_SB(1, 1), cB + hstepB + kstep, voffB);
;     PG8_WAIT_V(6); PG8_BAR;
;     ...
;             PG8_LDB(B0, 0, 0); PG8_LDB(B1, 0, 1); PG8_SCHED; PG8_LDA(At, 0, 0); PG8_STAGE(PG8_SA(1, 1), a1 + hstepA, voffA);
.LBB0_659:
	v_mov_b32_e32 v133, v177
	v_lshl_add_u64 v[12:13], s[4:5], 0, v[176:177]
	v_lshl_add_u64 v[14:15], s[4:5], 0, v[132:133]
	v_and_b32_e32 v7, 15, v6
	v_readlane_b32 s4, v252, 46
	v_and_b32_e32 v23, 48, v6
	v_ashrrev_i32_e32 v21, 6, v6
	v_or_b32_e32 v134, s4, v7
	v_lshlrev_b32_e32 v22, 6, v134
	s_movk_i32 s4, 0x3c0
	v_and_or_b32 v22, v22, s4, v23
	v_readlane_b32 s4, v252, 47
	v_ashrrev_i32_e32 v20, 1, v6
	v_lshlrev_b32_e32 v6, 2, v6
	v_lshl_add_u32 v24, v21, 10, s4
	v_readlane_b32 s4, v252, 49
	v_lshl_add_u64 v[8:9], s[96:97], 0, v[176:177]
	v_lshl_or_b32 v7, v7, 6, v23
	v_add_lshl_u32 v21, v21, s4, 10
	v_and_b32_e32 v6, 32, v6
	v_lshl_add_u64 v[10:11], s[96:97], 0, v[132:133]
	v_mov_b32_e32 v129, v177
	v_bitop3_b32 v135, v7, v21, v6 bitop3:0xde
	v_lshl_add_u64 v[6:7], v[8:9], 0, s[24:25]
	s_add_i32 m0, s16, 0x18000
	v_lshl_add_u64 v[16:17], s[94:95], 0, v[128:129]
	v_mov_b32_e32 v131, v177
	s_waitcnt vmcnt(2)
	s_barrier
	global_load_lds_dwordx4 v[6:7], off
	v_lshl_add_u64 v[6:7], v[10:11], 0, s[24:25]
	s_add_i32 m0, s16, 0x1a000
	s_add_i32 s72, s16, 0x8000
	v_lshl_add_u64 v[18:19], s[94:95], 0, v[130:131]
	global_load_lds_dwordx4 v[6:7], off
	v_lshl_add_u64 v[6:7], v[16:17], 0, s[24:25]
	s_mov_b32 m0, s72
	s_add_i32 s73, s16, 0xa000
	global_load_lds_dwordx4 v[6:7], off
	v_lshl_add_u64 v[6:7], v[18:19], 0, s[24:25]
	s_mov_b32 m0, s73
	v_add_u32_e32 v0, v2, v0
	global_load_lds_dwordx4 v[6:7], off
	v_lshl_add_u64 v[6:7], v[12:13], 0, s[24:25]
	s_add_i32 m0, s16, 0x1c000
	v_lshlrev_b32_e32 v25, 2, v134
	global_load_lds_dwordx4 v[6:7], off
	v_lshl_add_u64 v[6:7], v[14:15], 0, s[24:25]
	s_add_i32 m0, s16, 0x1e000
	v_add_lshl_u32 v0, v0, v1, 1
	global_load_lds_dwordx4 v[6:7], off
	v_mov_b32_e32 v1, v177
	v_and_b32_e32 v20, -8, v20
	v_and_b32_e32 v25, 32, v25
	s_waitcnt vmcnt(6)
	v_readlane_b32 s4, v252, 48
	v_lshl_add_u64 v[152:153], s[10:11], 0, v[0:1]
	v_add_u32_e32 v0, v5, v3
	v_bitop3_b32 v22, v22, v24, v25 bitop3:0xde
	v_add_u32_e32 v136, s4, v20
	v_add_lshl_u32 v0, v0, v4, 1
	v_ashrrev_i32_e32 v137, 31, v136
	v_or_b32_e32 v138, 16, v134
	v_or_b32_e32 v140, 32, v134
	v_or_b32_e32 v142, 48, v134
	v_add_u32_e32 v144, 0x80, v134
	v_add_u32_e32 v146, 0x90, v134
	v_add_u32_e32 v148, 0xa0, v134
	v_add_u32_e32 v150, 0xb0, v134
	v_lshl_add_u64 v[154:155], s[10:11], 0, v[0:1]
	s_mov_b32 s74, 0
	v_add_u32_e32 v139, 0, v22
	s_barrier
	v_add_u32_e32 v141, 0x10000, v135
	ds_read_b128 v[160:163], v141 offset:1024
	ds_read_b128 v[164:167], v141 offset:2048
	ds_read_b128 v[168:171], v141 offset:3072
	v_add_u32_e32 v141, 0x14000, v135
	ds_read_b128 v[172:175], v141
	ds_read_b128 v[180:183], v141 offset:1024
	ds_read_b128 v[184:187], v141 offset:2048
	ds_read_b128 v[188:191], v141 offset:3072
	ds_read_b128 v[192:195], v139
	ds_read_b128 v[196:199], v139 offset:1024
	ds_read_b128 v[200:203], v139 offset:2048
	ds_read_b128 v[204:207], v139 offset:3072
	ds_read_b128 v[208:211], v139 offset:4096
	ds_read_b128 v[212:215], v139 offset:5120
	ds_read_b128 v[216:219], v139 offset:6144
	ds_read_b128 v[220:223], v139 offset:7168
	s_branch .LBB0_661

; #define PG8_STAGE(bufoff, gbase, voff) do { _Pragma("unroll") for (int _i = 0; _i < 2; ++_i) \
;         __builtin_amdgcn_global_load_lds((const unsigned*)((const char*)(gbase) + (voff)[_i]), (LAS unsigned*)(lds + (bufoff) + ldsw + _i * 8192), 16, 0, 0); } while (0)
; #define PG8_LDA(dst, b, h) do { _Pragma("unroll") for (int m = 0; m < 4; ++m) _Pragma("unroll") for (int k = 0; k < 2; ++k) dst[m][k] = *(const LAS bf16x8*)(lds + PG8_SA(b, h) + aoff + m * 2048 + k * 1024); } while (0)
; #define PG8_LDB(dst, b, h) do { _Pragma("unroll") for (int n = 0; n < 2; ++n) _Pragma("unroll") for (int k = 0; k < 2; ++k) dst[n][k] = *(const LAS bf16x8*)(lds + PG8_SB(b, h) + boff + n * 2048 + k * 1024); } while (0)
; #define PG8_MMA(ai, bj, At, Bt) do { __builtin_amdgcn_s_setprio(1); _Pragma("unroll") for (int m = 0; m < 4; ++m) _Pragma("unroll") for (int n = 0; n < 2; ++n) _Pragma("unroll") for (int k = 0; k < 2; ++k) \
;         acc[ai][bj][m][n] = __builtin_amdgcn_mfma_f32_16x16x32_bf16(Bt[n][k], At[m][k], acc[ai][bj][m][n], 0, 0, 0); __builtin_amdgcn_s_setprio(0); } while (0)
; #define PG8_WAIT_V(n) asm volatile("s_waitcnt vmcnt(" #n ")" ::: "memory")
; #define PG8_WAIT_L(n) asm volatile("s_waitcnt lgkmcnt(" #n ")" ::: "memory")
; #define PG8_BAR __builtin_amdgcn_s_barrier()
; #define PG8_SCHED __builtin_amdgcn_sched_barrier(0)
; template <class Epi, class Sched, bool ALIGN_EPI>
; __device__ __forceinline__ void gemm_phase(LAS unsigned char* lds, const int wid, const int lda_, const int ldb_, const int K_, const Sched& S, const Epi& E) {
;     ...
;         const bool has_next = S.next(ui + 1, nxt);
;         const int nt = S.nt(cur);
;         const char* nA = has_next ? S.a(nxt) : cA; const char* nB = has_next ? S.b(nxt) : cB;
; #pragma unroll 1
;         for (int t = 0; t < nt; t += 2) {
;             const bool last = (t == nt - 2);
;             const char* a1 = cA + (size_t)(t + 1) * kstep;
;             const char* a2 = last ? nA : cA + (size_t)(t + 2) * kstep; const char* b2 = last ? nB : cB + (size_t)(t + 2) * kstep;
;             const char* a3 = a2 + kstep; const char* b3 = b2 + kstep;
;             PG8_LDB(B0, 0, 0); PG8_LDB(B1, 0, 1); PG8_SCHED; PG8_LDA(At, 0, 0); PG8_STAGE(PG8_SA(1, 1), a1 + hstepA, voffA);
;             PG8_WAIT_V(8); PG8_WAIT_L(0); PG8_BAR; PG8_MMA(0, 0, At, B0); PG8_MMA(0, 1, At, B1); PG8_BAR; PG8_SCHED;
.LBB0_670:
	s_xor_b64 s[44:45], s[4:5], -1
	s_cmp_gt_i32 s38, -1
	s_cselect_b64 s[50:51], -1, 0
	s_cmp_lt_i32 s38, 0
	s_cselect_b32 s35, 64, 16
	s_max_i32 s17, s75, 0
	s_ashr_i32 s43, s42, 31
	s_lshl_b32 s17, s17, 11
	s_lshl_b64 s[46:47], s[42:43], 21
	v_readlane_b32 s48, v252, 62
	v_readlane_b32 s49, v252, 63
	s_add_u32 s27, s48, s46
	s_addc_u32 s37, s49, s47
	s_add_u32 s46, s27, s17
	s_addc_u32 s47, s37, 0
	s_and_b64 s[48:49], s[4:5], exec
	s_cselect_b32 s37, s47, s95
	s_cselect_b32 s39, s46, s94
	s_ashr_i32 s41, s40, 31
	s_lshl_b64 s[48:49], s[40:41], 21
	s_add_u32 s27, s6, s48
	s_addc_u32 s41, s7, s49
	s_add_u32 s48, s27, s17
	s_addc_u32 s49, s41, 0
	s_and_b64 s[4:5], s[4:5], exec
	s_cselect_b32 s4, s49, s97
	s_cselect_b32 s5, s48, s96
	s_add_i32 s41, s35, -2
	s_add_u32 s94, s94, 0x80
	s_addc_u32 s95, s95, 0
	s_add_u32 s43, s96, 0x100
	s_mov_b32 s77, 0
	s_addc_u32 s76, s97, 0
	s_add_i32 s78, s77, 2
	s_add_u32 s17, s94, 0x80
	s_addc_u32 s27, s95, 0
	s_add_i32 s79, 0, 0x10000
	s_cmp_eq_u32 s41, s77
	s_cselect_b32 s97, s37, s27
	s_cselect_b32 s96, s39, s17
	v_add_u32_e32 v141, 0x10000, v135
	ds_read_b128 v[156:159], v141
	s_cselect_b32 s81, s4, s76
	s_cselect_b32 s80, s5, s43
	s_add_i32 s17, 0, 0x14000
	v_lshl_add_u64 v[224:225], s[94:95], 0, v[152:153]
	s_add_i32 m0, s16, 0xc000
	global_load_lds_dwordx4 v[224:225], off
	v_lshl_add_u64 v[224:225], s[94:95], 0, v[154:155]
	s_add_i32 m0, s16, 0xe000
	s_nop 0
	global_load_lds_dwordx4 v[224:225], off
	s_waitcnt vmcnt(8)
	s_waitcnt lgkmcnt(0)
	s_barrier
	s_setprio 1
	s_waitcnt lgkmcnt(0)
	v_mfma_f32_16x16x32_bf16 v[124:127], v[156:159], v[192:195], 0
	v_mfma_f32_16x16x32_bf16 v[120:123], v[164:167], v[192:195], 0
	v_mfma_f32_16x16x32_bf16 v[116:119], v[156:159], v[200:203], 0
	v_mfma_f32_16x16x32_bf16 v[112:115], v[164:167], v[200:203], 0
	v_mfma_f32_16x16x32_bf16 v[100:103], v[156:159], v[208:211], 0
	v_mfma_f32_16x16x32_bf16 v[96:99], v[164:167], v[208:211], 0
	v_mfma_f32_16x16x32_bf16 v[84:87], v[156:159], v[216:219], 0
	v_mfma_f32_16x16x32_bf16 v[80:83], v[164:167], v[216:219], 0
	v_mfma_f32_16x16x32_bf16 v[124:127], v[160:163], v[196:199], v[124:127]
	v_mfma_f32_16x16x32_bf16 v[120:123], v[168:171], v[196:199], v[120:123]
	v_mfma_f32_16x16x32_bf16 v[116:119], v[160:163], v[204:207], v[116:119]
	v_mfma_f32_16x16x32_bf16 v[112:115], v[168:171], v[204:207], v[112:115]
	v_mfma_f32_16x16x32_bf16 v[100:103], v[160:163], v[212:215], v[100:103]
	v_mfma_f32_16x16x32_bf16 v[96:99], v[168:171], v[212:215], v[96:99]
	v_mfma_f32_16x16x32_bf16 v[84:87], v[160:163], v[220:223], v[84:87]
	v_mfma_f32_16x16x32_bf16 v[80:83], v[168:171], v[220:223], v[80:83]
	s_setprio 0
	s_setprio 1
	v_mfma_f32_16x16x32_bf16 v[108:111], v[172:175], v[192:195], 0
	v_mfma_f32_16x16x32_bf16 v[104:107], v[184:187], v[192:195], 0
	v_mfma_f32_16x16x32_bf16 v[92:95], v[172:175], v[200:203], 0
	v_mfma_f32_16x16x32_bf16 v[88:91], v[184:187], v[200:203], 0
	v_mfma_f32_16x16x32_bf16 v[76:79], v[172:175], v[208:211], 0
	v_mfma_f32_16x16x32_bf16 v[72:75], v[184:187], v[208:211], 0
	v_mfma_f32_16x16x32_bf16 v[68:71], v[172:175], v[216:219], 0
	v_mfma_f32_16x16x32_bf16 v[64:67], v[184:187], v[216:219], 0
	v_mfma_f32_16x16x32_bf16 v[108:111], v[180:183], v[196:199], v[108:111]
	v_mfma_f32_16x16x32_bf16 v[104:107], v[188:191], v[196:199], v[104:107]
	v_mfma_f32_16x16x32_bf16 v[92:95], v[180:183], v[204:207], v[92:95]
	v_mfma_f32_16x16x32_bf16 v[88:91], v[188:191], v[204:207], v[88:91]
	v_mfma_f32_16x16x32_bf16 v[76:79], v[180:183], v[212:215], v[76:79]
	v_mfma_f32_16x16x32_bf16 v[72:75], v[188:191], v[212:215], v[72:75]
	v_mfma_f32_16x16x32_bf16 v[68:71], v[180:183], v[220:223], v[68:71]
	v_mfma_f32_16x16x32_bf16 v[64:67], v[188:191], v[220:223], v[64:67]
	s_setprio 0
	s_barrier
; #define PG8_STAGE(bufoff, gbase, voff) do { _Pragma("unroll") for (int _i = 0; _i < 2; ++_i) \
;         __builtin_amdgcn_global_load_lds((const unsigned*)((const char*)(gbase) + (voff)[_i]), (LAS unsigned*)(lds + (bufoff) + ldsw + _i * 8192), 16, 0, 0); } while (0)
; #define PG8_LDA(dst, b, h) do { _Pragma("unroll") for (int m = 0; m < 4; ++m) _Pragma("unroll") for (int k = 0; k < 2; ++k) dst[m][k] = *(const LAS bf16x8*)(lds + PG8_SA(b, h) + aoff + m * 2048 + k * 1024); } while (0)
; #define PG8_MMA(ai, bj, At, Bt) do { __builtin_amdgcn_s_setprio(1); _Pragma("unroll") for (int m = 0; m < 4; ++m) _Pragma("unroll") for (int n = 0; n < 2; ++n) _Pragma("unroll") for (int k = 0; k < 2; ++k) \
;         acc[ai][bj][m][n] = __builtin_amdgcn_mfma_f32_16x16x32_bf16(Bt[n][k], At[m][k], acc[ai][bj][m][n], 0, 0, 0); __builtin_amdgcn_s_setprio(0); } while (0)
; #define PG8_WAIT_V(n) asm volatile("s_waitcnt vmcnt(" #n ")" ::: "memory")
; #define PG8_WAIT_L(n) asm volatile("s_waitcnt lgkmcnt(" #n ")" ::: "memory")
; #define PG8_BAR __builtin_amdgcn_s_barrier()
; #define PG8_SCHED __builtin_amdgcn_sched_barrier(0)
; template <class Epi, class Sched, bool ALIGN_EPI>
; __device__ __forceinline__ void gemm_phase(LAS unsigned char* lds, const int wid, const int lda_, const int ldb_, const int K_, const Sched& S, const Epi& E) {
;     ...
;             PG8_LDA(At, 0, 1); PG8_STAGE(PG8_SB(0, 0), b2, voffB); PG8_STAGE(PG8_SB(0, 1), b2 + hstepB, voffB); PG8_STAGE(PG8_SA(0, 0), a2, voffA);
;             PG8_WAIT_V(8); PG8_WAIT_L(0); PG8_BAR; PG8_MMA(1, 0, At, B0); PG8_MMA(1, 1, At, B1); PG8_BAR; PG8_SCHED;
	s_add_i32 s27, s79, s3
	v_lshl_add_u64 v[224:225], s[80:81], 0, v[176:177]
	s_mov_b32 m0, s27
	ds_read_b128 v[192:195], v139 offset:16384
	ds_read_b128 v[196:199], v139 offset:17408
	ds_read_b128 v[200:203], v139 offset:18432
	ds_read_b128 v[204:207], v139 offset:19456
	ds_read_b128 v[208:211], v139 offset:20480
	ds_read_b128 v[212:215], v139 offset:21504
	ds_read_b128 v[216:219], v139 offset:22528
	ds_read_b128 v[220:223], v139 offset:23552
	global_load_lds_dwordx4 v[224:225], off
	s_add_i32 m0, s27, 0x2000
	v_lshl_add_u64 v[226:227], s[80:81], 0, v[132:133]
	s_add_u32 s80, s80, s30
	s_addc_u32 s81, s81, s31
	s_add_i32 s17, s17, s3
	global_load_lds_dwordx4 v[226:227], off
	v_lshl_add_u64 v[228:229], s[80:81], 0, v[176:177]
	s_mov_b32 m0, s17
	v_lshl_add_u64 v[230:231], s[80:81], 0, v[132:133]
	global_load_lds_dwordx4 v[228:229], off
	s_add_i32 m0, s17, 0x2000
	v_lshl_add_u64 v[232:233], s[96:97], 0, v[128:129]
	global_load_lds_dwordx4 v[230:231], off
	s_mov_b32 m0, s16
	v_lshl_add_u64 v[234:235], s[96:97], 0, v[130:131]
	global_load_lds_dwordx4 v[232:233], off
	s_mov_b32 m0, s14
	s_nop 0
	global_load_lds_dwordx4 v[234:235], off
	s_waitcnt vmcnt(8)
	s_waitcnt lgkmcnt(0)
	s_barrier
	s_setprio 1
	s_waitcnt lgkmcnt(0)
	v_mfma_f32_16x16x32_bf16 v[60:63], v[156:159], v[192:195], 0
	v_mfma_f32_16x16x32_bf16 v[56:59], v[164:167], v[192:195], 0
	v_mfma_f32_16x16x32_bf16 v[52:55], v[156:159], v[200:203], 0
	v_mfma_f32_16x16x32_bf16 v[48:51], v[164:167], v[200:203], 0
	v_mfma_f32_16x16x32_bf16 v[36:39], v[156:159], v[208:211], 0
	v_mfma_f32_16x16x32_bf16 v[32:35], v[164:167], v[208:211], 0
	v_mfma_f32_16x16x32_bf16 v[20:23], v[156:159], v[216:219], 0
	v_mfma_f32_16x16x32_bf16 v[16:19], v[164:167], v[216:219], 0
	v_mfma_f32_16x16x32_bf16 v[60:63], v[160:163], v[196:199], v[60:63]
	v_mfma_f32_16x16x32_bf16 v[56:59], v[168:171], v[196:199], v[56:59]
	v_mfma_f32_16x16x32_bf16 v[52:55], v[160:163], v[204:207], v[52:55]
	v_mfma_f32_16x16x32_bf16 v[48:51], v[168:171], v[204:207], v[48:51]
	v_mfma_f32_16x16x32_bf16 v[36:39], v[160:163], v[212:215], v[36:39]
	v_mfma_f32_16x16x32_bf16 v[32:35], v[168:171], v[212:215], v[32:35]
	v_mfma_f32_16x16x32_bf16 v[20:23], v[160:163], v[220:223], v[20:23]
	v_mfma_f32_16x16x32_bf16 v[16:19], v[168:171], v[220:223], v[16:19]
	s_setprio 0
	s_setprio 1
	v_mfma_f32_16x16x32_bf16 v[44:47], v[172:175], v[192:195], 0
	v_mfma_f32_16x16x32_bf16 v[40:43], v[184:187], v[192:195], 0
	v_mfma_f32_16x16x32_bf16 v[28:31], v[172:175], v[200:203], 0
	v_mfma_f32_16x16x32_bf16 v[24:27], v[184:187], v[200:203], 0
	v_mfma_f32_16x16x32_bf16 v[12:15], v[172:175], v[208:211], 0
	v_mfma_f32_16x16x32_bf16 v[8:11], v[184:187], v[208:211], 0
	v_mfma_f32_16x16x32_bf16 v[4:7], v[172:175], v[216:219], 0
	v_mfma_f32_16x16x32_bf16 v[0:3], v[184:187], v[216:219], 0
	v_mfma_f32_16x16x32_bf16 v[44:47], v[180:183], v[196:199], v[44:47]
	v_mfma_f32_16x16x32_bf16 v[40:43], v[188:191], v[196:199], v[40:43]
	v_mfma_f32_16x16x32_bf16 v[28:31], v[180:183], v[204:207], v[28:31]
	v_mfma_f32_16x16x32_bf16 v[24:27], v[188:191], v[204:207], v[24:27]
	v_mfma_f32_16x16x32_bf16 v[12:15], v[180:183], v[212:215], v[12:15]
	v_mfma_f32_16x16x32_bf16 v[8:11], v[188:191], v[212:215], v[8:11]
	v_mfma_f32_16x16x32_bf16 v[4:7], v[180:183], v[220:223], v[4:7]
	v_mfma_f32_16x16x32_bf16 v[0:3], v[188:191], v[220:223], v[0:3]
	s_setprio 0
	s_barrier
	s_branch .Lgemm_join_671

; #define PG8_STAGE(bufoff, gbase, voff) do { _Pragma("unroll") for (int _i = 0; _i < 2; ++_i) \
;         __builtin_amdgcn_global_load_lds((const unsigned*)((const char*)(gbase) + (voff)[_i]), (LAS unsigned*)(lds + (bufoff) + ldsw + _i * 8192), 16, 0, 0); } while (0)
; #define PG8_LDA(dst, b, h) do { _Pragma("unroll") for (int m = 0; m < 4; ++m) _Pragma("unroll") for (int k = 0; k < 2; ++k) dst[m][k] = *(const LAS bf16x8*)(lds + PG8_SA(b, h) + aoff + m * 2048 + k * 1024); } while (0)
; #define PG8_LDB(dst, b, h) do { _Pragma("unroll") for (int n = 0; n < 2; ++n) _Pragma("unroll") for (int k = 0; k < 2; ++k) dst[n][k] = *(const LAS bf16x8*)(lds + PG8_SB(b, h) + boff + n * 2048 + k * 1024); } while (0)
; #define PG8_MMA(ai, bj, At, Bt) do { __builtin_amdgcn_s_setprio(1); _Pragma("unroll") for (int m = 0; m < 4; ++m) _Pragma("unroll") for (int n = 0; n < 2; ++n) _Pragma("unroll") for (int k = 0; k < 2; ++k) \
;         acc[ai][bj][m][n] = __builtin_amdgcn_mfma_f32_16x16x32_bf16(Bt[n][k], At[m][k], acc[ai][bj][m][n], 0, 0, 0); __builtin_amdgcn_s_setprio(0); } while (0)
; #define PG8_WAIT_V(n) asm volatile("s_waitcnt vmcnt(" #n ")" ::: "memory")
; #define PG8_WAIT_L(n) asm volatile("s_waitcnt lgkmcnt(" #n ")" ::: "memory")
; #define PG8_BAR __builtin_amdgcn_s_barrier()
; #define PG8_SCHED __builtin_amdgcn_sched_barrier(0)
; template <class Epi, class Sched, bool ALIGN_EPI>
; __device__ __forceinline__ void gemm_phase(LAS unsigned char* lds, const int wid, const int lda_, const int ldb_, const int K_, const Sched& S, const Epi& E) {
;     ...
;             PG8_LDB(B0, 1, 0); PG8_LDB(B1, 1, 1); PG8_SCHED; PG8_LDA(At, 1, 0); PG8_STAGE(PG8_SA(0, 1), a2 + hstepA, voffA);
;             PG8_WAIT_V(8); PG8_WAIT_L(0); PG8_BAR; PG8_MMA(0, 0, At, B0); PG8_MMA(0, 1, At, B1); PG8_BAR; PG8_SCHED;
;             PG8_LDA(At, 1, 1); PG8_STAGE(PG8_SB(1, 0), b3, voffB); PG8_STAGE(PG8_SB(1, 1), b3 + hstepB, voffB); PG8_STAGE(PG8_SA(1, 0), a3, voffA);
;             PG8_WAIT_V(8); PG8_WAIT_L(0); PG8_BAR; PG8_MMA(1, 0, At, B0); PG8_MMA(1, 1, At, B1); PG8_BAR; PG8_SCHED;
.Lgemm_join_671:
	s_add_i32 s17, 0, 0x18000
	v_add_u32_e32 v141, s17, v135
	s_add_i32 s27, 0, 0x1c000
	ds_read_b128 v[156:159], v141
	ds_read_b128 v[160:163], v141 offset:1024
	ds_read_b128 v[164:167], v141 offset:2048
	ds_read_b128 v[168:171], v141 offset:3072
	v_add_u32_e32 v141, s27, v135
	ds_read_b128 v[172:175], v141
	ds_read_b128 v[180:183], v141 offset:1024
	ds_read_b128 v[184:187], v141 offset:2048
	ds_read_b128 v[188:191], v141 offset:3072
	s_add_u32 s80, s96, s10
	s_addc_u32 s81, s97, s11
	s_mov_b32 m0, s15
	v_lshl_add_u64 v[236:237], s[80:81], 0, v[128:129]
	ds_read_b128 v[192:195], v139 offset:32768
	ds_read_b128 v[196:199], v139 offset:33792
	ds_read_b128 v[200:203], v139 offset:34816
	ds_read_b128 v[204:207], v139 offset:35840
	ds_read_b128 v[208:211], v139 offset:36864
	ds_read_b128 v[212:215], v139 offset:37888
	ds_read_b128 v[216:219], v139 offset:38912
	ds_read_b128 v[220:223], v139 offset:39936
	global_load_lds_dwordx4 v[236:237], off
	v_lshl_add_u64 v[236:237], s[80:81], 0, v[130:131]
	s_mov_b32 m0, s26
	s_nop 0
	global_load_lds_dwordx4 v[236:237], off
	s_waitcnt vmcnt(8)
	s_waitcnt lgkmcnt(0)
	s_barrier
	s_setprio 1
	s_waitcnt lgkmcnt(0)
	v_mfma_f32_16x16x32_bf16 v[124:127], v[156:159], v[192:195], v[124:127]
	v_mfma_f32_16x16x32_bf16 v[120:123], v[164:167], v[192:195], v[120:123]
	v_mfma_f32_16x16x32_bf16 v[116:119], v[156:159], v[200:203], v[116:119]
	v_mfma_f32_16x16x32_bf16 v[112:115], v[164:167], v[200:203], v[112:115]
	v_mfma_f32_16x16x32_bf16 v[100:103], v[156:159], v[208:211], v[100:103]
	v_mfma_f32_16x16x32_bf16 v[96:99], v[164:167], v[208:211], v[96:99]
	v_mfma_f32_16x16x32_bf16 v[84:87], v[156:159], v[216:219], v[84:87]
	v_mfma_f32_16x16x32_bf16 v[80:83], v[164:167], v[216:219], v[80:83]
	v_mfma_f32_16x16x32_bf16 v[124:127], v[160:163], v[196:199], v[124:127]
	v_mfma_f32_16x16x32_bf16 v[120:123], v[168:171], v[196:199], v[120:123]
	v_mfma_f32_16x16x32_bf16 v[116:119], v[160:163], v[204:207], v[116:119]
	v_mfma_f32_16x16x32_bf16 v[112:115], v[168:171], v[204:207], v[112:115]
	v_mfma_f32_16x16x32_bf16 v[100:103], v[160:163], v[212:215], v[100:103]
	v_mfma_f32_16x16x32_bf16 v[96:99], v[168:171], v[212:215], v[96:99]
	v_mfma_f32_16x16x32_bf16 v[84:87], v[160:163], v[220:223], v[84:87]
	v_mfma_f32_16x16x32_bf16 v[80:83], v[168:171], v[220:223], v[80:83]
	s_setprio 0
	s_setprio 1
	v_mfma_f32_16x16x32_bf16 v[108:111], v[172:175], v[192:195], v[108:111]
	v_mfma_f32_16x16x32_bf16 v[104:107], v[184:187], v[192:195], v[104:107]
	v_mfma_f32_16x16x32_bf16 v[92:95], v[172:175], v[200:203], v[92:95]
	v_mfma_f32_16x16x32_bf16 v[88:91], v[184:187], v[200:203], v[88:91]
	v_mfma_f32_16x16x32_bf16 v[76:79], v[172:175], v[208:211], v[76:79]
	v_mfma_f32_16x16x32_bf16 v[72:75], v[184:187], v[208:211], v[72:75]
	v_mfma_f32_16x16x32_bf16 v[68:71], v[172:175], v[216:219], v[68:71]
	v_mfma_f32_16x16x32_bf16 v[64:67], v[184:187], v[216:219], v[64:67]
	v_mfma_f32_16x16x32_bf16 v[108:111], v[180:183], v[196:199], v[108:111]
	v_mfma_f32_16x16x32_bf16 v[104:107], v[188:191], v[196:199], v[104:107]
	v_mfma_f32_16x16x32_bf16 v[92:95], v[180:183], v[204:207], v[92:95]
	v_mfma_f32_16x16x32_bf16 v[88:91], v[188:191], v[204:207], v[88:91]
	v_mfma_f32_16x16x32_bf16 v[76:79], v[180:183], v[212:215], v[76:79]
	v_mfma_f32_16x16x32_bf16 v[72:75], v[188:191], v[212:215], v[72:75]
	v_mfma_f32_16x16x32_bf16 v[68:71], v[180:183], v[220:223], v[68:71]
	v_mfma_f32_16x16x32_bf16 v[64:67], v[188:191], v[220:223], v[64:67]
	s_setprio 0
	s_barrier
	s_add_i32 s17, s17, s3
	v_lshl_add_u64 v[224:225], v[224:225], 0, s[24:25]
	s_mov_b32 m0, s17
	ds_read_b128 v[192:195], v139 offset:49152
	ds_read_b128 v[196:199], v139 offset:50176
	ds_read_b128 v[200:203], v139 offset:51200
	ds_read_b128 v[204:207], v139 offset:52224
	ds_read_b128 v[208:211], v139 offset:53248
	ds_read_b128 v[212:215], v139 offset:54272
	ds_read_b128 v[216:219], v139 offset:55296
	ds_read_b128 v[220:223], v139 offset:56320
	global_load_lds_dwordx4 v[224:225], off
	v_lshl_add_u64 v[224:225], v[226:227], 0, s[24:25]
	s_add_i32 m0, s17, 0x2000
	s_add_i32 s17, s27, s3
	global_load_lds_dwordx4 v[224:225], off
	v_lshl_add_u64 v[224:225], v[228:229], 0, s[24:25]
	s_mov_b32 m0, s17
	s_nop 0
	global_load_lds_dwordx4 v[224:225], off
	v_lshl_add_u64 v[224:225], v[230:231], 0, s[24:25]
	s_add_i32 m0, s17, 0x2000
	s_nop 0
	global_load_lds_dwordx4 v[224:225], off
	v_lshl_add_u64 v[224:225], v[232:233], 0, s[24:25]
	s_mov_b32 m0, s72
	s_nop 0
	global_load_lds_dwordx4 v[224:225], off
	v_lshl_add_u64 v[224:225], v[234:235], 0, s[24:25]
	s_mov_b32 m0, s73
	s_nop 0
	global_load_lds_dwordx4 v[224:225], off
	s_waitcnt vmcnt(8)
	s_waitcnt lgkmcnt(0)
	s_barrier
; #define PG8_STAGE(bufoff, gbase, voff) do { _Pragma("unroll") for (int _i = 0; _i < 2; ++_i) \
;         __builtin_amdgcn_global_load_lds((const unsigned*)((const char*)(gbase) + (voff)[_i]), (LAS unsigned*)(lds + (bufoff) + ldsw + _i * 8192), 16, 0, 0); } while (0)
; #define PG8_LDA(dst, b, h) do { _Pragma("unroll") for (int m = 0; m < 4; ++m) _Pragma("unroll") for (int k = 0; k < 2; ++k) dst[m][k] = *(const LAS bf16x8*)(lds + PG8_SA(b, h) + aoff + m * 2048 + k * 1024); } while (0)
; #define PG8_WAIT_V(n) asm volatile("s_waitcnt vmcnt(" #n ")" ::: "memory")
; #define PG8_WAIT_L(n) asm volatile("s_waitcnt lgkmcnt(" #n ")" ::: "memory")
; template <class Epi, class Sched, bool ALIGN_EPI>
; __device__ __forceinline__ void gemm_phase(LAS unsigned char* lds, const int wid, const int lda_, const int ldb_, const int K_, const Sched& S, const Epi& E) {
;     ...
;         for (int t = 0; t < nt; t += 2) {
;             const bool last = (t == nt - 2);
;             const char* a1 = cA + (size_t)(t + 1) * kstep;
;             const char* a2 = last ? nA : cA + (size_t)(t + 2) * kstep; const char* b2 = last ? nB : cB + (size_t)(t + 2) * kstep;
;             const char* a3 = a2 + kstep; const char* b3 = b2 + kstep;
;             PG8_LDB(B0, 0, 0); PG8_LDB(B1, 0, 1); PG8_SCHED; PG8_LDA(At, 0, 0); PG8_STAGE(PG8_SA(1, 1), a1 + hstepA, voffA);
;             PG8_WAIT_V(8); PG8_WAIT_L(0); PG8_BAR; PG8_MMA(0, 0, At, B0); PG8_MMA(0, 1, At, B1); PG8_BAR; PG8_SCHED;
;             PG8_LDA(At, 0, 1); PG8_STAGE(PG8_SB(0, 0), b2, voffB); PG8_STAGE(PG8_SB(0, 1), b2 + hstepB, voffB); PG8_STAGE(PG8_SA(0, 0), a2, voffA);
;             PG8_WAIT_V(8); PG8_WAIT_L(0); PG8_BAR; PG8_MMA(1, 0, At, B0); PG8_MMA(1, 1, At, B1); PG8_BAR; PG8_SCHED;
;             PG8_LDB(B0, 1, 0); PG8_LDB(B1, 1, 1); PG8_SCHED; PG8_LDA(At, 1, 0); PG8_STAGE(PG8_SA(0, 1), a2 + hstepA, voffA);
;             PG8_WAIT_V(8); PG8_WAIT_L(0); PG8_BAR; PG8_MMA(0, 0, At, B0); PG8_MMA(0, 1, At, B1); PG8_BAR; PG8_SCHED;
;             PG8_LDA(At, 1, 1); PG8_STAGE(PG8_SB(1, 0), b3, voffB); PG8_STAGE(PG8_SB(1, 1), b3 + hstepB, voffB); PG8_STAGE(PG8_SA(1, 0), a3, voffA);
;             PG8_WAIT_V(8); PG8_WAIT_L(0); PG8_BAR; PG8_MMA(1, 0, At, B0); PG8_MMA(1, 1, At, B1); PG8_BAR; PG8_SCHED;
;         }
;         if constexpr (ALIGN_EPI) { if (wr == 0) PG8_BAR; }
;         E(acc, cur, S, wr, wc, fr, fq);
;         if (!has_next) break;
	s_setprio 1
	s_waitcnt lgkmcnt(0)
	v_mfma_f32_16x16x32_bf16 v[60:63], v[156:159], v[192:195], v[60:63]
	v_mfma_f32_16x16x32_bf16 v[56:59], v[164:167], v[192:195], v[56:59]
	v_mfma_f32_16x16x32_bf16 v[52:55], v[156:159], v[200:203], v[52:55]
	v_mfma_f32_16x16x32_bf16 v[48:51], v[164:167], v[200:203], v[48:51]
	v_mfma_f32_16x16x32_bf16 v[36:39], v[156:159], v[208:211], v[36:39]
	v_mfma_f32_16x16x32_bf16 v[32:35], v[164:167], v[208:211], v[32:35]
	v_mfma_f32_16x16x32_bf16 v[20:23], v[156:159], v[216:219], v[20:23]
	v_mfma_f32_16x16x32_bf16 v[16:19], v[164:167], v[216:219], v[16:19]
	v_mfma_f32_16x16x32_bf16 v[60:63], v[160:163], v[196:199], v[60:63]
	v_mfma_f32_16x16x32_bf16 v[56:59], v[168:171], v[196:199], v[56:59]
	v_mfma_f32_16x16x32_bf16 v[52:55], v[160:163], v[204:207], v[52:55]
	v_mfma_f32_16x16x32_bf16 v[48:51], v[168:171], v[204:207], v[48:51]
	v_mfma_f32_16x16x32_bf16 v[36:39], v[160:163], v[212:215], v[36:39]
	v_mfma_f32_16x16x32_bf16 v[32:35], v[168:171], v[212:215], v[32:35]
	v_mfma_f32_16x16x32_bf16 v[20:23], v[160:163], v[220:223], v[20:23]
	v_mfma_f32_16x16x32_bf16 v[16:19], v[168:171], v[220:223], v[16:19]
	s_setprio 0
	s_setprio 1
	v_mfma_f32_16x16x32_bf16 v[44:47], v[172:175], v[192:195], v[44:47]
	v_mfma_f32_16x16x32_bf16 v[40:43], v[184:187], v[192:195], v[40:43]
	v_mfma_f32_16x16x32_bf16 v[28:31], v[172:175], v[200:203], v[28:31]
	v_mfma_f32_16x16x32_bf16 v[24:27], v[184:187], v[200:203], v[24:27]
	v_mfma_f32_16x16x32_bf16 v[12:15], v[172:175], v[208:211], v[12:15]
	v_mfma_f32_16x16x32_bf16 v[8:11], v[184:187], v[208:211], v[8:11]
	v_mfma_f32_16x16x32_bf16 v[4:7], v[172:175], v[216:219], v[4:7]
	v_mfma_f32_16x16x32_bf16 v[0:3], v[184:187], v[216:219], v[0:3]
	v_mfma_f32_16x16x32_bf16 v[44:47], v[180:183], v[196:199], v[44:47]
	v_mfma_f32_16x16x32_bf16 v[40:43], v[188:191], v[196:199], v[40:43]
	v_mfma_f32_16x16x32_bf16 v[28:31], v[180:183], v[204:207], v[28:31]
	v_mfma_f32_16x16x32_bf16 v[24:27], v[188:191], v[204:207], v[24:27]
	v_mfma_f32_16x16x32_bf16 v[12:15], v[180:183], v[212:215], v[12:15]
	v_mfma_f32_16x16x32_bf16 v[8:11], v[188:191], v[212:215], v[8:11]
	v_mfma_f32_16x16x32_bf16 v[4:7], v[180:183], v[220:223], v[4:7]
	v_mfma_f32_16x16x32_bf16 v[0:3], v[188:191], v[220:223], v[0:3]
	s_setprio 0
	s_barrier
	s_add_u32 s94, s94, 0x100
	s_addc_u32 s95, s95, 0
	s_add_u32 s43, s43, 0x100
	s_addc_u32 s76, s76, 0
	s_cmp_ge_u32 s78, s35
	s_mov_b32 s77, s78
	s_cbranch_scc0 .LBB0_671
	s_setprio 2
	v_add_u32_e32 v141, 0x10000, v135
	ds_read_b128 v[160:163], v141 offset:1024
	ds_read_b128 v[164:167], v141 offset:2048
	ds_read_b128 v[168:171], v141 offset:3072
	v_add_u32_e32 v141, 0x14000, v135
	ds_read_b128 v[172:175], v141
	ds_read_b128 v[180:183], v141 offset:1024
	ds_read_b128 v[184:187], v141 offset:2048
	ds_read_b128 v[188:191], v141 offset:3072
	ds_read_b128 v[192:195], v139
	ds_read_b128 v[196:199], v139 offset:1024
	ds_read_b128 v[200:203], v139 offset:2048
	ds_read_b128 v[204:207], v139 offset:3072
	ds_read_b128 v[208:211], v139 offset:4096
	ds_read_b128 v[212:215], v139 offset:5120
	ds_read_b128 v[216:219], v139 offset:6144
	ds_read_b128 v[220:223], v139 offset:7168
	s_mov_b64 s[94:95], -1
	s_and_b64 vcc, exec, s[50:51]
	s_cbranch_vccz .LBB0_674
	s_mov_b32 s39, s92
	s_ashr_i32 s35, s34, 31
	s_ashr_i32 s37, s36, 31
	s_lshl_b64 s[4:5], s[34:35], 20
	s_lshl_b64 s[50:51], s[36:37], 9
	s_lshl_b64 s[38:39], s[38:39], 23
	v_readlane_b32 s76, v251, 28
	v_readlane_b32 s77, v251, 29
	s_add_u32 s17, s76, s50
	s_addc_u32 s27, s77, s51
	s_add_u32 s17, s17, s38
	s_addc_u32 s27, s27, s39
	s_add_u32 s4, s17, s4
	s_addc_u32 s5, s27, s5
	s_add_u32 s4, s4, 0xfc000000
	s_addc_u32 s5, s5, -1
	s_mov_b64 s[94:95], 0

; #define PG8_STAGE(bufoff, gbase, voff) do { _Pragma("unroll") for (int _i = 0; _i < 2; ++_i) \
;         __builtin_amdgcn_global_load_lds((const unsigned*)((const char*)(gbase) + (voff)[_i]), (LAS unsigned*)(lds + (bufoff) + ldsw + _i * 8192), 16, 0, 0); } while (0)
; #define PG8_LDA(dst, b, h) do { _Pragma("unroll") for (int m = 0; m < 4; ++m) _Pragma("unroll") for (int k = 0; k < 2; ++k) dst[m][k] = *(const LAS bf16x8*)(lds + PG8_SA(b, h) + aoff + m * 2048 + k * 1024); } while (0)
; #define PG8_LDB(dst, b, h) do { _Pragma("unroll") for (int n = 0; n < 2; ++n) _Pragma("unroll") for (int k = 0; k < 2; ++k) dst[n][k] = *(const LAS bf16x8*)(lds + PG8_SB(b, h) + boff + n * 2048 + k * 1024); } while (0)
; #define PG8_WAIT_V(n) asm volatile("s_waitcnt vmcnt(" #n ")" ::: "memory")
; #define PG8_BAR __builtin_amdgcn_s_barrier()
; #define PG8_SCHED __builtin_amdgcn_sched_barrier(0)
;     __device__ __forceinline__ const char* a(const pg8::Unit& u) const { return (const char*)ws + aoff + (size_t)u.pm * 256 * K_ * 2 + (u.kq < 0 ? 0 : u.kq * (K_ / 4) * 2); }
;     __device__ __forceinline__ const char* b(const pg8::Unit& u) const { return (const char*)ws + boff + (size_t)u.pn * 256 * K_ * 2 + (u.kq < 0 ? 0 : u.kq * (K_ / 4) * 2); }
;     __device__ __forceinline__ const char* a(const pg8::Unit& u) const { return (const char*)ws + WS_A + (size_t)u.pm * 256 * D * 2; }
;     __device__ __forceinline__ const char* b(const pg8::Unit& u) const { return (const char*)ws + boff + (size_t)u.pn * 256 * D * 2; }
; template <class Epi, class Sched, bool ALIGN_EPI>
; __device__ __forceinline__ void gemm_phase(LAS unsigned char* lds, const int wid, const int lda_, const int ldb_, const int K_, const Sched& S, const Epi& E) {
;     ...
;     const char* cA = S.a(cur); const char* cB = S.b(cur);
;     PG8_STAGE(PG8_SB(0, 0), cB, voffB); PG8_STAGE(PG8_SB(0, 1), cB + hstepB, voffB); PG8_STAGE(PG8_SA(0, 0), cA, voffA); PG8_STAGE(PG8_SA(0, 1), cA + hstepA, voffA);
;     if (wr == 1) PG8_BAR;
;     PG8_WAIT_V(2); PG8_BAR;
;     PG8_STAGE(PG8_SB(1, 0), cB + kstep, voffB); PG8_STAGE(PG8_SA(1, 0), cA + kstep, voffA); PG8_STAGE(PG8_SB(1, 1), cB + hstepB + kstep, voffB);
;     PG8_WAIT_V(6); PG8_BAR;
;     ...
;             PG8_LDB(B0, 0, 0); PG8_LDB(B1, 0, 1); PG8_SCHED; PG8_LDA(At, 0, 0); PG8_STAGE(PG8_SA(1, 1), a1 + hstepA, voffA);
.LBB0_867:
	v_mov_b32_e32 v133, v177
	v_lshl_add_u64 v[12:13], s[4:5], 0, v[176:177]
	v_lshl_add_u64 v[14:15], s[4:5], 0, v[132:133]
	v_and_b32_e32 v7, 15, v6
	v_readlane_b32 s4, v252, 46
	v_and_b32_e32 v23, 48, v6
	v_readlane_b32 s48, v254, 10
	v_or_b32_e32 v134, s4, v7
	v_lshlrev_b32_e32 v22, 6, v134
	s_movk_i32 s4, 0x3c0
	v_ashrrev_i32_e32 v21, 6, v6
	v_and_or_b32 v22, v22, s4, v23
	v_readlane_b32 s4, v252, 47
	v_readlane_b32 s49, v254, 11
	v_ashrrev_i32_e32 v20, 1, v6
	v_lshl_add_u32 v24, v21, 10, s4
	v_readlane_b32 s4, v252, 49
	v_lshlrev_b32_e32 v6, 2, v6
	v_lshl_add_u64 v[8:9], s[48:49], 0, v[176:177]
	v_readlane_b32 s46, v254, 12
	v_lshl_or_b32 v7, v7, 6, v23
	v_add_lshl_u32 v21, v21, s4, 10
	v_and_b32_e32 v6, 32, v6
	v_lshl_add_u64 v[10:11], s[48:49], 0, v[132:133]
	v_mov_b32_e32 v129, v177
	v_readlane_b32 s47, v254, 13
	v_bitop3_b32 v135, v7, v21, v6 bitop3:0xde
	v_lshl_add_u64 v[6:7], v[8:9], 0, s[24:25]
	s_add_i32 m0, s16, 0x18000
	v_lshl_add_u64 v[16:17], s[46:47], 0, v[128:129]
	v_mov_b32_e32 v131, v177
	s_waitcnt vmcnt(2)
	s_barrier
	global_load_lds_dwordx4 v[6:7], off
	v_lshl_add_u64 v[6:7], v[10:11], 0, s[24:25]
	s_add_i32 m0, s16, 0x1a000
	s_add_i32 s15, s16, 0x8000
	v_lshl_add_u64 v[18:19], s[46:47], 0, v[130:131]
	global_load_lds_dwordx4 v[6:7], off
	v_lshl_add_u64 v[6:7], v[16:17], 0, s[24:25]
	s_mov_b32 m0, s15
	s_add_i32 s26, s16, 0xa000
	global_load_lds_dwordx4 v[6:7], off
	v_lshl_add_u64 v[6:7], v[18:19], 0, s[24:25]
	s_mov_b32 m0, s26
	v_lshlrev_b32_e32 v25, 2, v134
	global_load_lds_dwordx4 v[6:7], off
	v_lshl_add_u64 v[6:7], v[12:13], 0, s[24:25]
	s_add_i32 m0, s16, 0x1c000
	v_and_b32_e32 v20, -8, v20
	global_load_lds_dwordx4 v[6:7], off
	v_lshl_add_u64 v[6:7], v[14:15], 0, s[24:25]
	s_add_i32 m0, s16, 0x1e000
	v_and_b32_e32 v25, 32, v25
	global_load_lds_dwordx4 v[6:7], off
	s_waitcnt vmcnt(6)
	v_readlane_b32 s4, v252, 48
	v_add_u32_e32 v3, v5, v3
	v_add_u32_e32 v0, v2, v0
	v_readlane_b32 s40, v254, 4
	v_bitop3_b32 v22, v22, v24, v25 bitop3:0xde
	v_add_u32_e32 v136, s4, v20
	v_add_lshl_u32 v4, v3, v4, 1
	v_mov_b32_e32 v5, v177
	v_add_lshl_u32 v0, v0, v1, 1
	v_mov_b32_e32 v1, v177
	v_readlane_b32 s41, v254, 5
	v_readlane_b32 s4, v254, 8
	v_ashrrev_i32_e32 v137, 31, v136
	v_or_b32_e32 v138, 16, v134
	v_or_b32_e32 v140, 32, v134
	v_or_b32_e32 v142, 48, v134
	v_add_u32_e32 v144, 0x80, v134
	v_add_u32_e32 v146, 0x90, v134
	v_add_u32_e32 v148, 0xa0, v134
	v_add_u32_e32 v150, 0xb0, v134
	v_lshl_add_u64 v[152:153], s[0:1], 0, v[4:5]
	v_lshl_add_u64 v[154:155], s[0:1], 0, v[0:1]
	s_mov_b32 s72, 0
	v_add_u32_e32 v139, 0, v22
	s_mov_b32 s41, s4
	s_barrier
	v_readlane_b32 s5, v254, 9
	v_add_u32_e32 v141, 0x10000, v135
	ds_read_b128 v[160:163], v141
	ds_read_b128 v[164:167], v141 offset:1024
	ds_read_b128 v[168:171], v141 offset:2048
	ds_read_b128 v[172:175], v141 offset:3072
	v_add_u32_e32 v141, 0x14000, v135
	ds_read_b128 v[180:183], v141
	ds_read_b128 v[184:187], v141 offset:1024
	ds_read_b128 v[188:191], v141 offset:2048
	ds_read_b128 v[192:195], v141 offset:3072
	ds_read_b128 v[196:199], v139
	ds_read_b128 v[200:203], v139 offset:1024
	ds_read_b128 v[204:207], v139 offset:2048
	ds_read_b128 v[208:211], v139 offset:3072
	ds_read_b128 v[212:215], v139 offset:4096
	ds_read_b128 v[216:219], v139 offset:5120
	ds_read_b128 v[220:223], v139 offset:6144
	ds_read_b128 v[224:227], v139 offset:7168

; #define PG8_STAGE(bufoff, gbase, voff) do { _Pragma("unroll") for (int _i = 0; _i < 2; ++_i) \
;         __builtin_amdgcn_global_load_lds((const unsigned*)((const char*)(gbase) + (voff)[_i]), (LAS unsigned*)(lds + (bufoff) + ldsw + _i * 8192), 16, 0, 0); } while (0)
; #define PG8_LDA(dst, b, h) do { _Pragma("unroll") for (int m = 0; m < 4; ++m) _Pragma("unroll") for (int k = 0; k < 2; ++k) dst[m][k] = *(const LAS bf16x8*)(lds + PG8_SA(b, h) + aoff + m * 2048 + k * 1024); } while (0)
; #define PG8_LDB(dst, b, h) do { _Pragma("unroll") for (int n = 0; n < 2; ++n) _Pragma("unroll") for (int k = 0; k < 2; ++k) dst[n][k] = *(const LAS bf16x8*)(lds + PG8_SB(b, h) + boff + n * 2048 + k * 1024); } while (0)
; #define PG8_MMA(ai, bj, At, Bt) do { __builtin_amdgcn_s_setprio(1); _Pragma("unroll") for (int m = 0; m < 4; ++m) _Pragma("unroll") for (int n = 0; n < 2; ++n) _Pragma("unroll") for (int k = 0; k < 2; ++k) \
;         acc[ai][bj][m][n] = __builtin_amdgcn_mfma_f32_16x16x32_bf16(Bt[n][k], At[m][k], acc[ai][bj][m][n], 0, 0, 0); __builtin_amdgcn_s_setprio(0); } while (0)
; template <class Epi, class Sched, bool ALIGN_EPI>
; __device__ __forceinline__ void gemm_phase(LAS unsigned char* lds, const int wid, const int lda_, const int ldb_, const int K_, const Sched& S, const Epi& E) {
;     ...
;         const bool has_next = S.next(ui + 1, nxt);
;         const int nt = S.nt(cur);
;         const char* nA = has_next ? S.a(nxt) : cA; const char* nB = has_next ? S.b(nxt) : cB;
; #pragma unroll 1
;         for (int t = 0; t < nt; t += 2) {
;             const bool last = (t == nt - 2);
;             const char* a1 = cA + (size_t)(t + 1) * kstep;
;             const char* a2 = last ? nA : cA + (size_t)(t + 2) * kstep; const char* b2 = last ? nB : cB + (size_t)(t + 2) * kstep;
;             const char* a3 = a2 + kstep; const char* b3 = b2 + kstep;
;             PG8_LDB(B0, 0, 0); PG8_LDB(B1, 0, 1); PG8_SCHED; PG8_LDA(At, 0, 0); PG8_STAGE(PG8_SA(1, 1), a1 + hstepA, voffA);
;             PG8_WAIT_V(8); PG8_WAIT_L(0); PG8_BAR; PG8_MMA(0, 0, At, B0); PG8_MMA(0, 1, At, B1); PG8_BAR; PG8_SCHED;
;             PG8_LDA(At, 0, 1); PG8_STAGE(PG8_SB(0, 0), b2, voffB); PG8_STAGE(PG8_SB(0, 1), b2 + hstepB, voffB); PG8_STAGE(PG8_SA(0, 0), a2, voffA);
;             PG8_WAIT_V(8); PG8_WAIT_L(0); PG8_BAR; PG8_MMA(1, 0, At, B0); PG8_MMA(1, 1, At, B1); PG8_BAR; PG8_SCHED;
.LBB0_882:
	s_and_b64 s[4:5], s[4:5], exec
	s_cselect_b32 s4, s27, 0x380000
	s_add_u32 s44, s66, s4
	s_addc_u32 s45, s67, 0
	s_and_b64 s[4:5], s[50:51], exec
	s_cselect_b32 s4, s45, s47
	s_cselect_b32 s5, s44, s46
	s_add_u32 s42, s46, 0x80
	s_addc_u32 s43, s47, 0
	s_add_u32 s31, s48, 0x100
	v_lshl_add_u64 v[156:157], s[42:43], 0, v[152:153]
	v_lshl_add_u64 v[158:159], s[42:43], 0, v[154:155]
	s_addc_u32 s35, s49, 0
	s_mov_b32 s73, -2
	s_mov_b64 s[48:49], 0
	s_add_u32 s17, s46, s48
	s_addc_u32 s27, s47, s49
	s_add_u32 s17, s17, 0x100
	s_addc_u32 s27, s27, 0
	s_add_u32 s42, s31, s48
	s_addc_u32 s43, s35, s49
	s_add_i32 s74, 0, 0x10000
	s_cmpk_eq_i32 s48, 0x300
	s_cselect_b32 s51, s4, s27
	s_cselect_b32 s50, s5, s17
	s_cselect_b32 s43, s39, s43
	s_cselect_b32 s42, s38, s42
	s_add_i32 s17, 0, 0x14000
	v_lshl_add_u64 v[228:229], v[158:159], 0, s[48:49]
	s_add_i32 m0, s16, 0xc000
	global_load_lds_dwordx4 v[228:229], off
	v_lshl_add_u64 v[228:229], v[156:157], 0, s[48:49]
	s_add_i32 m0, s16, 0xe000
	s_nop 0
	global_load_lds_dwordx4 v[228:229], off
	s_waitcnt vmcnt(8)
	s_waitcnt lgkmcnt(0)
	s_barrier
	s_setprio 1
	s_waitcnt lgkmcnt(0)
	v_mfma_f32_16x16x32_bf16 v[124:127], v[160:163], v[196:199], 0
	v_mfma_f32_16x16x32_bf16 v[120:123], v[168:171], v[196:199], 0
	v_mfma_f32_16x16x32_bf16 v[116:119], v[160:163], v[204:207], 0
	v_mfma_f32_16x16x32_bf16 v[112:115], v[168:171], v[204:207], 0
	v_mfma_f32_16x16x32_bf16 v[100:103], v[160:163], v[212:215], 0
	v_mfma_f32_16x16x32_bf16 v[96:99], v[168:171], v[212:215], 0
	v_mfma_f32_16x16x32_bf16 v[84:87], v[160:163], v[220:223], 0
	v_mfma_f32_16x16x32_bf16 v[80:83], v[168:171], v[220:223], 0
	v_mfma_f32_16x16x32_bf16 v[124:127], v[164:167], v[200:203], v[124:127]
	v_mfma_f32_16x16x32_bf16 v[120:123], v[172:175], v[200:203], v[120:123]
	v_mfma_f32_16x16x32_bf16 v[116:119], v[164:167], v[208:211], v[116:119]
	v_mfma_f32_16x16x32_bf16 v[112:115], v[172:175], v[208:211], v[112:115]
	v_mfma_f32_16x16x32_bf16 v[100:103], v[164:167], v[216:219], v[100:103]
	v_mfma_f32_16x16x32_bf16 v[96:99], v[172:175], v[216:219], v[96:99]
	v_mfma_f32_16x16x32_bf16 v[84:87], v[164:167], v[224:227], v[84:87]
	v_mfma_f32_16x16x32_bf16 v[80:83], v[172:175], v[224:227], v[80:83]
	s_setprio 0
	s_setprio 1
	v_mfma_f32_16x16x32_bf16 v[108:111], v[180:183], v[196:199], 0
	v_mfma_f32_16x16x32_bf16 v[104:107], v[188:191], v[196:199], 0
	v_mfma_f32_16x16x32_bf16 v[92:95], v[180:183], v[204:207], 0
	v_mfma_f32_16x16x32_bf16 v[88:91], v[188:191], v[204:207], 0
	v_mfma_f32_16x16x32_bf16 v[76:79], v[180:183], v[212:215], 0
	v_mfma_f32_16x16x32_bf16 v[72:75], v[188:191], v[212:215], 0
	v_mfma_f32_16x16x32_bf16 v[68:71], v[180:183], v[220:223], 0
	v_mfma_f32_16x16x32_bf16 v[64:67], v[188:191], v[220:223], 0
	v_mfma_f32_16x16x32_bf16 v[108:111], v[184:187], v[200:203], v[108:111]
	v_mfma_f32_16x16x32_bf16 v[104:107], v[192:195], v[200:203], v[104:107]
	v_mfma_f32_16x16x32_bf16 v[92:95], v[184:187], v[208:211], v[92:95]
	v_mfma_f32_16x16x32_bf16 v[88:91], v[192:195], v[208:211], v[88:91]
	v_mfma_f32_16x16x32_bf16 v[76:79], v[184:187], v[216:219], v[76:79]
	v_mfma_f32_16x16x32_bf16 v[72:75], v[192:195], v[216:219], v[72:75]
	v_mfma_f32_16x16x32_bf16 v[68:71], v[184:187], v[224:227], v[68:71]
	v_mfma_f32_16x16x32_bf16 v[64:67], v[192:195], v[224:227], v[64:67]
	s_setprio 0
	s_barrier
	s_add_i32 s27, s74, s3
	v_lshl_add_u64 v[228:229], s[42:43], 0, v[176:177]
	s_mov_b32 m0, s27
	ds_read_b128 v[196:199], v139 offset:16384
	ds_read_b128 v[200:203], v139 offset:17408
	ds_read_b128 v[204:207], v139 offset:18432
	ds_read_b128 v[208:211], v139 offset:19456
	ds_read_b128 v[212:215], v139 offset:20480
	ds_read_b128 v[216:219], v139 offset:21504
	ds_read_b128 v[220:223], v139 offset:22528
	ds_read_b128 v[224:227], v139 offset:23552
	global_load_lds_dwordx4 v[228:229], off
	s_add_i32 m0, s27, 0x2000
	v_lshl_add_u64 v[230:231], s[42:43], 0, v[132:133]
	s_add_u32 s42, s42, s10
	s_addc_u32 s43, s43, s11
	s_add_i32 s17, s17, s3
	global_load_lds_dwordx4 v[230:231], off
	v_lshl_add_u64 v[232:233], s[42:43], 0, v[176:177]
	s_mov_b32 m0, s17
	v_lshl_add_u64 v[234:235], s[42:43], 0, v[132:133]
	global_load_lds_dwordx4 v[232:233], off
	s_add_i32 m0, s17, 0x2000
	v_lshl_add_u64 v[236:237], s[50:51], 0, v[128:129]
	global_load_lds_dwordx4 v[234:235], off
	s_mov_b32 m0, s16
	v_lshl_add_u64 v[246:247], s[50:51], 0, v[130:131]
	global_load_lds_dwordx4 v[236:237], off
	s_mov_b32 m0, s6
	s_nop 0
	global_load_lds_dwordx4 v[246:247], off
	s_waitcnt vmcnt(8)
	s_waitcnt lgkmcnt(0)
	s_barrier
	s_setprio 1
	s_waitcnt lgkmcnt(0)
	v_mfma_f32_16x16x32_bf16 v[60:63], v[160:163], v[196:199], 0
	v_mfma_f32_16x16x32_bf16 v[56:59], v[168:171], v[196:199], 0
	v_mfma_f32_16x16x32_bf16 v[52:55], v[160:163], v[204:207], 0
	v_mfma_f32_16x16x32_bf16 v[48:51], v[168:171], v[204:207], 0
	v_mfma_f32_16x16x32_bf16 v[36:39], v[160:163], v[212:215], 0
	v_mfma_f32_16x16x32_bf16 v[32:35], v[168:171], v[212:215], 0
	v_mfma_f32_16x16x32_bf16 v[20:23], v[160:163], v[220:223], 0
	v_mfma_f32_16x16x32_bf16 v[16:19], v[168:171], v[220:223], 0
	v_mfma_f32_16x16x32_bf16 v[60:63], v[164:167], v[200:203], v[60:63]
	v_mfma_f32_16x16x32_bf16 v[56:59], v[172:175], v[200:203], v[56:59]
	v_mfma_f32_16x16x32_bf16 v[52:55], v[164:167], v[208:211], v[52:55]
	v_mfma_f32_16x16x32_bf16 v[48:51], v[172:175], v[208:211], v[48:51]
	v_mfma_f32_16x16x32_bf16 v[36:39], v[164:167], v[216:219], v[36:39]
	v_mfma_f32_16x16x32_bf16 v[32:35], v[172:175], v[216:219], v[32:35]
	v_mfma_f32_16x16x32_bf16 v[20:23], v[164:167], v[224:227], v[20:23]
	v_mfma_f32_16x16x32_bf16 v[16:19], v[172:175], v[224:227], v[16:19]
	s_setprio 0
	s_setprio 1
	v_mfma_f32_16x16x32_bf16 v[44:47], v[180:183], v[196:199], 0
	v_mfma_f32_16x16x32_bf16 v[40:43], v[188:191], v[196:199], 0
	v_mfma_f32_16x16x32_bf16 v[28:31], v[180:183], v[204:207], 0
	v_mfma_f32_16x16x32_bf16 v[24:27], v[188:191], v[204:207], 0
	v_mfma_f32_16x16x32_bf16 v[12:15], v[180:183], v[212:215], 0
	v_mfma_f32_16x16x32_bf16 v[8:11], v[188:191], v[212:215], 0
	v_mfma_f32_16x16x32_bf16 v[4:7], v[180:183], v[220:223], 0
	v_mfma_f32_16x16x32_bf16 v[0:3], v[188:191], v[220:223], 0
	v_mfma_f32_16x16x32_bf16 v[44:47], v[184:187], v[200:203], v[44:47]
	v_mfma_f32_16x16x32_bf16 v[40:43], v[192:195], v[200:203], v[40:43]
	v_mfma_f32_16x16x32_bf16 v[28:31], v[184:187], v[208:211], v[28:31]
	v_mfma_f32_16x16x32_bf16 v[24:27], v[192:195], v[208:211], v[24:27]
	v_mfma_f32_16x16x32_bf16 v[12:15], v[184:187], v[216:219], v[12:15]
	v_mfma_f32_16x16x32_bf16 v[8:11], v[192:195], v[216:219], v[8:11]
	v_mfma_f32_16x16x32_bf16 v[4:7], v[184:187], v[224:227], v[4:7]
	v_mfma_f32_16x16x32_bf16 v[0:3], v[192:195], v[224:227], v[0:3]
	s_setprio 0
	s_barrier
	s_branch .Lgemm_join_883

; #define PG8_STAGE(bufoff, gbase, voff) do { _Pragma("unroll") for (int _i = 0; _i < 2; ++_i) \
;         __builtin_amdgcn_global_load_lds((const unsigned*)((const char*)(gbase) + (voff)[_i]), (LAS unsigned*)(lds + (bufoff) + ldsw + _i * 8192), 16, 0, 0); } while (0)
; #define PG8_LDA(dst, b, h) do { _Pragma("unroll") for (int m = 0; m < 4; ++m) _Pragma("unroll") for (int k = 0; k < 2; ++k) dst[m][k] = *(const LAS bf16x8*)(lds + PG8_SA(b, h) + aoff + m * 2048 + k * 1024); } while (0)
; #define PG8_LDB(dst, b, h) do { _Pragma("unroll") for (int n = 0; n < 2; ++n) _Pragma("unroll") for (int k = 0; k < 2; ++k) dst[n][k] = *(const LAS bf16x8*)(lds + PG8_SB(b, h) + boff + n * 2048 + k * 1024); } while (0)
; #define PG8_MMA(ai, bj, At, Bt) do { __builtin_amdgcn_s_setprio(1); _Pragma("unroll") for (int m = 0; m < 4; ++m) _Pragma("unroll") for (int n = 0; n < 2; ++n) _Pragma("unroll") for (int k = 0; k < 2; ++k) \
;         acc[ai][bj][m][n] = __builtin_amdgcn_mfma_f32_16x16x32_bf16(Bt[n][k], At[m][k], acc[ai][bj][m][n], 0, 0, 0); __builtin_amdgcn_s_setprio(0); } while (0)
; #define PG8_WAIT_V(n) asm volatile("s_waitcnt vmcnt(" #n ")" ::: "memory")
; #define PG8_WAIT_L(n) asm volatile("s_waitcnt lgkmcnt(" #n ")" ::: "memory")
; #define PG8_BAR __builtin_amdgcn_s_barrier()
; #define PG8_SCHED __builtin_amdgcn_sched_barrier(0)
; template <class Epi, class Sched, bool ALIGN_EPI>
; __device__ __forceinline__ void gemm_phase(LAS unsigned char* lds, const int wid, const int lda_, const int ldb_, const int K_, const Sched& S, const Epi& E) {
;     ...
;             PG8_LDB(B0, 1, 0); PG8_LDB(B1, 1, 1); PG8_SCHED; PG8_LDA(At, 1, 0); PG8_STAGE(PG8_SA(0, 1), a2 + hstepA, voffA);
;             PG8_WAIT_V(8); PG8_WAIT_L(0); PG8_BAR; PG8_MMA(0, 0, At, B0); PG8_MMA(0, 1, At, B1); PG8_BAR; PG8_SCHED;
;             PG8_LDA(At, 1, 1); PG8_STAGE(PG8_SB(1, 0), b3, voffB); PG8_STAGE(PG8_SB(1, 1), b3 + hstepB, voffB); PG8_STAGE(PG8_SA(1, 0), a3, voffA);
;             PG8_WAIT_V(8); PG8_WAIT_L(0); PG8_BAR; PG8_MMA(1, 0, At, B0); PG8_MMA(1, 1, At, B1); PG8_BAR; PG8_SCHED;
.Lgemm_join_883:
	s_add_i32 s17, 0, 0x18000
	v_add_u32_e32 v141, s17, v135
	s_add_i32 s27, 0, 0x1c000
	ds_read_b128 v[160:163], v141
	ds_read_b128 v[164:167], v141 offset:1024
	ds_read_b128 v[168:171], v141 offset:2048
	ds_read_b128 v[172:175], v141 offset:3072
	v_add_u32_e32 v141, s27, v135
	ds_read_b128 v[180:183], v141
	ds_read_b128 v[184:187], v141 offset:1024
	ds_read_b128 v[188:191], v141 offset:2048
	ds_read_b128 v[192:195], v141 offset:3072
	s_add_u32 s42, s50, s0
	s_addc_u32 s43, s51, s1
	s_mov_b32 m0, s7
	v_lshl_add_u64 v[248:249], s[42:43], 0, v[128:129]
	ds_read_b128 v[196:199], v139 offset:32768
	ds_read_b128 v[200:203], v139 offset:33792
	ds_read_b128 v[204:207], v139 offset:34816
	ds_read_b128 v[208:211], v139 offset:35840
	ds_read_b128 v[212:215], v139 offset:36864
	ds_read_b128 v[216:219], v139 offset:37888
	ds_read_b128 v[220:223], v139 offset:38912
	ds_read_b128 v[224:227], v139 offset:39936
	global_load_lds_dwordx4 v[248:249], off
	v_lshl_add_u64 v[248:249], s[42:43], 0, v[130:131]
	s_mov_b32 m0, s14
	s_nop 0
	global_load_lds_dwordx4 v[248:249], off
	s_waitcnt vmcnt(8)
	s_waitcnt lgkmcnt(0)
	s_barrier
	s_setprio 1
	s_waitcnt lgkmcnt(0)
	v_mfma_f32_16x16x32_bf16 v[124:127], v[160:163], v[196:199], v[124:127]
	v_mfma_f32_16x16x32_bf16 v[120:123], v[168:171], v[196:199], v[120:123]
	v_mfma_f32_16x16x32_bf16 v[116:119], v[160:163], v[204:207], v[116:119]
	v_mfma_f32_16x16x32_bf16 v[112:115], v[168:171], v[204:207], v[112:115]
	v_mfma_f32_16x16x32_bf16 v[100:103], v[160:163], v[212:215], v[100:103]
	v_mfma_f32_16x16x32_bf16 v[96:99], v[168:171], v[212:215], v[96:99]
	v_mfma_f32_16x16x32_bf16 v[84:87], v[160:163], v[220:223], v[84:87]
	v_mfma_f32_16x16x32_bf16 v[80:83], v[168:171], v[220:223], v[80:83]
	v_mfma_f32_16x16x32_bf16 v[124:127], v[164:167], v[200:203], v[124:127]
	v_mfma_f32_16x16x32_bf16 v[120:123], v[172:175], v[200:203], v[120:123]
	v_mfma_f32_16x16x32_bf16 v[116:119], v[164:167], v[208:211], v[116:119]
	v_mfma_f32_16x16x32_bf16 v[112:115], v[172:175], v[208:211], v[112:115]
	v_mfma_f32_16x16x32_bf16 v[100:103], v[164:167], v[216:219], v[100:103]
	v_mfma_f32_16x16x32_bf16 v[96:99], v[172:175], v[216:219], v[96:99]
	v_mfma_f32_16x16x32_bf16 v[84:87], v[164:167], v[224:227], v[84:87]
	v_mfma_f32_16x16x32_bf16 v[80:83], v[172:175], v[224:227], v[80:83]
	s_setprio 0
	s_setprio 1
	v_mfma_f32_16x16x32_bf16 v[108:111], v[180:183], v[196:199], v[108:111]
	v_mfma_f32_16x16x32_bf16 v[104:107], v[188:191], v[196:199], v[104:107]
	v_mfma_f32_16x16x32_bf16 v[92:95], v[180:183], v[204:207], v[92:95]
	v_mfma_f32_16x16x32_bf16 v[88:91], v[188:191], v[204:207], v[88:91]
	v_mfma_f32_16x16x32_bf16 v[76:79], v[180:183], v[212:215], v[76:79]
	v_mfma_f32_16x16x32_bf16 v[72:75], v[188:191], v[212:215], v[72:75]
	v_mfma_f32_16x16x32_bf16 v[68:71], v[180:183], v[220:223], v[68:71]
	v_mfma_f32_16x16x32_bf16 v[64:67], v[188:191], v[220:223], v[64:67]
	v_mfma_f32_16x16x32_bf16 v[108:111], v[184:187], v[200:203], v[108:111]
	v_mfma_f32_16x16x32_bf16 v[104:107], v[192:195], v[200:203], v[104:107]
	v_mfma_f32_16x16x32_bf16 v[92:95], v[184:187], v[208:211], v[92:95]
	v_mfma_f32_16x16x32_bf16 v[88:91], v[192:195], v[208:211], v[88:91]
	v_mfma_f32_16x16x32_bf16 v[76:79], v[184:187], v[216:219], v[76:79]
	v_mfma_f32_16x16x32_bf16 v[72:75], v[192:195], v[216:219], v[72:75]
	v_mfma_f32_16x16x32_bf16 v[68:71], v[184:187], v[224:227], v[68:71]
	v_mfma_f32_16x16x32_bf16 v[64:67], v[192:195], v[224:227], v[64:67]
	s_setprio 0
	s_barrier
	s_add_i32 s17, s17, s3
	v_lshl_add_u64 v[228:229], v[228:229], 0, s[24:25]
	s_mov_b32 m0, s17
	ds_read_b128 v[196:199], v139 offset:49152
	ds_read_b128 v[200:203], v139 offset:50176
	ds_read_b128 v[204:207], v139 offset:51200
	ds_read_b128 v[208:211], v139 offset:52224
	ds_read_b128 v[212:215], v139 offset:53248
	ds_read_b128 v[216:219], v139 offset:54272
	ds_read_b128 v[220:223], v139 offset:55296
	ds_read_b128 v[224:227], v139 offset:56320
	global_load_lds_dwordx4 v[228:229], off
	v_lshl_add_u64 v[228:229], v[230:231], 0, s[24:25]
	s_add_i32 m0, s17, 0x2000
	s_add_i32 s17, s27, s3
	global_load_lds_dwordx4 v[228:229], off
	v_lshl_add_u64 v[228:229], v[232:233], 0, s[24:25]
	s_mov_b32 m0, s17
	s_nop 0
	global_load_lds_dwordx4 v[228:229], off
	v_lshl_add_u64 v[228:229], v[234:235], 0, s[24:25]
	s_add_i32 m0, s17, 0x2000
	s_nop 0
	global_load_lds_dwordx4 v[228:229], off
	v_lshl_add_u64 v[228:229], v[236:237], 0, s[24:25]
	s_mov_b32 m0, s15
	s_nop 0
	global_load_lds_dwordx4 v[228:229], off
	v_lshl_add_u64 v[228:229], v[246:247], 0, s[24:25]
	s_mov_b32 m0, s26
	s_nop 0
	global_load_lds_dwordx4 v[228:229], off
	s_waitcnt vmcnt(8)
	s_waitcnt lgkmcnt(0)
	s_barrier
; #define PG8_MMA(ai, bj, At, Bt) do { __builtin_amdgcn_s_setprio(1); _Pragma("unroll") for (int m = 0; m < 4; ++m) _Pragma("unroll") for (int n = 0; n < 2; ++n) _Pragma("unroll") for (int k = 0; k < 2; ++k) \
;         acc[ai][bj][m][n] = __builtin_amdgcn_mfma_f32_16x16x32_bf16(Bt[n][k], At[m][k], acc[ai][bj][m][n], 0, 0, 0); __builtin_amdgcn_s_setprio(0); } while (0)
; #define PG8_WAIT_V(n) asm volatile("s_waitcnt vmcnt(" #n ")" ::: "memory")
; #define PG8_WAIT_L(n) asm volatile("s_waitcnt lgkmcnt(" #n ")" ::: "memory")
; #define PG8_BAR __builtin_amdgcn_s_barrier()
; #define PG8_SCHED __builtin_amdgcn_sched_barrier(0)
; template <class Epi, class Sched, bool ALIGN_EPI>
; __device__ __forceinline__ void gemm_phase(LAS unsigned char* lds, const int wid, const int lda_, const int ldb_, const int K_, const Sched& S, const Epi& E) {
;     ...
;             PG8_WAIT_V(8); PG8_WAIT_L(0); PG8_BAR; PG8_MMA(1, 0, At, B0); PG8_MMA(1, 1, At, B1); PG8_BAR; PG8_SCHED;
;         }
	s_setprio 1
	s_waitcnt lgkmcnt(0)
	v_mfma_f32_16x16x32_bf16 v[60:63], v[160:163], v[196:199], v[60:63]
	v_mfma_f32_16x16x32_bf16 v[56:59], v[168:171], v[196:199], v[56:59]
	v_mfma_f32_16x16x32_bf16 v[52:55], v[160:163], v[204:207], v[52:55]
	v_mfma_f32_16x16x32_bf16 v[48:51], v[168:171], v[204:207], v[48:51]
	v_mfma_f32_16x16x32_bf16 v[36:39], v[160:163], v[212:215], v[36:39]
	v_mfma_f32_16x16x32_bf16 v[32:35], v[168:171], v[212:215], v[32:35]
	v_mfma_f32_16x16x32_bf16 v[20:23], v[160:163], v[220:223], v[20:23]
	v_mfma_f32_16x16x32_bf16 v[16:19], v[168:171], v[220:223], v[16:19]
	v_mfma_f32_16x16x32_bf16 v[60:63], v[164:167], v[200:203], v[60:63]
	v_mfma_f32_16x16x32_bf16 v[56:59], v[172:175], v[200:203], v[56:59]
	v_mfma_f32_16x16x32_bf16 v[52:55], v[164:167], v[208:211], v[52:55]
	v_mfma_f32_16x16x32_bf16 v[48:51], v[172:175], v[208:211], v[48:51]
	v_mfma_f32_16x16x32_bf16 v[36:39], v[164:167], v[216:219], v[36:39]
	v_mfma_f32_16x16x32_bf16 v[32:35], v[172:175], v[216:219], v[32:35]
	v_mfma_f32_16x16x32_bf16 v[20:23], v[164:167], v[224:227], v[20:23]
	v_mfma_f32_16x16x32_bf16 v[16:19], v[172:175], v[224:227], v[16:19]
	s_setprio 0
	s_setprio 1
	v_mfma_f32_16x16x32_bf16 v[44:47], v[180:183], v[196:199], v[44:47]
	v_mfma_f32_16x16x32_bf16 v[40:43], v[188:191], v[196:199], v[40:43]
	v_mfma_f32_16x16x32_bf16 v[28:31], v[180:183], v[204:207], v[28:31]
	v_mfma_f32_16x16x32_bf16 v[24:27], v[188:191], v[204:207], v[24:27]
	v_mfma_f32_16x16x32_bf16 v[12:15], v[180:183], v[212:215], v[12:15]
	v_mfma_f32_16x16x32_bf16 v[8:11], v[188:191], v[212:215], v[8:11]
	v_mfma_f32_16x16x32_bf16 v[4:7], v[180:183], v[220:223], v[4:7]
	v_mfma_f32_16x16x32_bf16 v[0:3], v[188:191], v[220:223], v[0:3]
	v_mfma_f32_16x16x32_bf16 v[44:47], v[184:187], v[200:203], v[44:47]
	v_mfma_f32_16x16x32_bf16 v[40:43], v[192:195], v[200:203], v[40:43]
	v_mfma_f32_16x16x32_bf16 v[28:31], v[184:187], v[208:211], v[28:31]
	v_mfma_f32_16x16x32_bf16 v[24:27], v[192:195], v[208:211], v[24:27]
	v_mfma_f32_16x16x32_bf16 v[12:15], v[184:187], v[216:219], v[12:15]
	v_mfma_f32_16x16x32_bf16 v[8:11], v[192:195], v[216:219], v[8:11]
	v_mfma_f32_16x16x32_bf16 v[4:7], v[184:187], v[224:227], v[4:7]
	v_mfma_f32_16x16x32_bf16 v[0:3], v[192:195], v[224:227], v[0:3]
	s_setprio 0
	s_barrier
	s_add_i32 s73, s73, 2
	s_add_u32 s48, s48, 0x100
	s_addc_u32 s49, s49, 0
	s_cmp_gt_u32 s73, 5
	s_cbranch_scc0 .LBB0_883
; __device__ __forceinline__ unsigned cvt_pk_bf16(float lo, float hi) { const f32x2 v = {lo, hi}; return __builtin_bit_cast(unsigned, __builtin_convertvector(v, bf16x2_t)); }
; #define PG8_STAGE(bufoff, gbase, voff) do { _Pragma("unroll") for (int _i = 0; _i < 2; ++_i) \
;         __builtin_amdgcn_global_load_lds((const unsigned*)((const char*)(gbase) + (voff)[_i]), (LAS unsigned*)(lds + (bufoff) + ldsw + _i * 8192), 16, 0, 0); } while (0)
; #define PG8_LDA(dst, b, h) do { _Pragma("unroll") for (int m = 0; m < 4; ++m) _Pragma("unroll") for (int k = 0; k < 2; ++k) dst[m][k] = *(const LAS bf16x8*)(lds + PG8_SA(b, h) + aoff + m * 2048 + k * 1024); } while (0)
; #define PG8_LDB(dst, b, h) do { _Pragma("unroll") for (int n = 0; n < 2; ++n) _Pragma("unroll") for (int k = 0; k < 2; ++k) dst[n][k] = *(const LAS bf16x8*)(lds + PG8_SB(b, h) + boff + n * 2048 + k * 1024); } while (0)
; #define PG8_SCHED __builtin_amdgcn_sched_barrier(0)
;     template <class Sched> __device__ __forceinline__ void operator()(const f32x4 (&acc)[2][2][4][2], const Unit& u, const Sched& S, int wr, int wc, int fr, int fq) const {
;         const int rl0 = wr * 64 + fr, cl0 = wc * 32 + 8 * fq;
;         char* uo; int ldo, kind; S.out(u, uo, ldo, kind);
;         asm volatile("" : "+s"(ldo));
;         if (kind == 0) {
;             bf16_t* base = (bf16_t*)uo;
; #pragma unroll
;             for (int ai = 0; ai < 2; ++ai)
; #pragma unroll
;                 for (int m = 0; m < 4; ++m) { bf16_t* rowp = base + (size_t)(rl0 + ai * HALF + m * 16) * ldo + cl0;
; #pragma unroll
;                     for (int bj = 0; bj < 2; ++bj) { const f32x4 v0 = acc[ai][bj][m][0], v1 = acc[ai][bj][m][1];
;                         u32x4 w; w.x = cvt_pk_bf16(v0[0], v0[1]); w.y = cvt_pk_bf16(v0[2], v0[3]); w.z = cvt_pk_bf16(v1[0], v1[1]); w.w = cvt_pk_bf16(v1[2], v1[3]);
;                         *(u32x4*)(rowp + bj * HALF) = w; } }
; template <class Epi, class Sched, bool ALIGN_EPI>
; __device__ __forceinline__ void gemm_phase(LAS unsigned char* lds, const int wid, const int lda_, const int ldb_, const int K_, const Sched& S, const Epi& E) {
;     ...
;             PG8_LDB(B0, 0, 0); PG8_LDB(B1, 0, 1); PG8_SCHED; PG8_LDA(At, 0, 0); PG8_STAGE(PG8_SA(1, 1), a1 + hstepA, voffA);
	s_setprio 2
	v_add_u32_e32 v141, 0x10000, v135
	ds_read_b128 v[160:163], v141
	ds_read_b128 v[164:167], v141 offset:1024
	ds_read_b128 v[168:171], v141 offset:2048
	ds_read_b128 v[172:175], v141 offset:3072
	v_add_u32_e32 v141, 0x14000, v135
	ds_read_b128 v[180:183], v141
	ds_read_b128 v[184:187], v141 offset:1024
	ds_read_b128 v[188:191], v141 offset:2048
	ds_read_b128 v[192:195], v141 offset:3072
	ds_read_b128 v[196:199], v139
	ds_read_b128 v[200:203], v139 offset:1024
	ds_read_b128 v[204:207], v139 offset:2048
	ds_read_b128 v[208:211], v139 offset:3072
	ds_read_b128 v[212:215], v139 offset:4096
	ds_read_b128 v[216:219], v139 offset:5120
	ds_read_b128 v[220:223], v139 offset:6144
	ds_read_b128 v[224:227], v139 offset:7168
	s_lshl_b32 s4, s41, 8
	s_and_b32 s5, s4, 0xfffff800
	s_and_b32 s17, s41, 7
	s_or_b32 s17, s5, s17
	s_ashr_i32 s5, s17, 31
	s_cmp_lt_i32 s41, 64
	s_cselect_b32 s4, s17, s4
	s_movk_i32 s17, 0x800
	s_cselect_b32 s5, s5, 0
	s_cselect_b32 s17, 0x4000, s17
	s_ashr_i32 s41, s40, 31
	s_lshl_b64 s[40:41], s[40:41], 9
	s_lshl_b64 s[4:5], s[4:5], 12
	v_readlane_b32 s27, v254, 19
	s_add_u32 s4, s27, s4
	v_readlane_b32 s27, v254, 20
	s_addc_u32 s5, s27, s5
	s_add_u32 s4, s4, s40
	s_addc_u32 s5, s5, s41
	v_lshl_add_u64 v[156:157], v[136:137], 1, s[4:5]
	v_mad_i64_i32 v[158:159], s[4:5], s17, v134, 0
	v_lshl_add_u64 v[158:159], v[158:159], 1, v[156:157]
	v_cvt_pk_bf16_f32 v108, v108, v109
	v_cvt_pk_bf16_f32 v109, v110, v111
	v_cvt_pk_bf16_f32 v110, v104, v105
	v_cvt_pk_bf16_f32 v111, v106, v107
	v_mad_i64_i32 v[104:105], s[4:5], s17, v138, 0
	v_cvt_pk_bf16_f32 v124, v124, v125
	v_cvt_pk_bf16_f32 v125, v126, v127
	v_cvt_pk_bf16_f32 v126, v120, v121
	v_cvt_pk_bf16_f32 v127, v122, v123
	global_store_dwordx4 v[158:159], v[108:111], off offset:256
	v_cvt_pk_bf16_f32 v92, v92, v93
	v_cvt_pk_bf16_f32 v93, v94, v95
	v_lshl_add_u64 v[108:109], v[104:105], 1, v[156:157]
	v_cvt_pk_bf16_f32 v94, v88, v89
	v_cvt_pk_bf16_f32 v95, v90, v91
	v_mad_i64_i32 v[88:89], s[4:5], s17, v140, 0
	global_store_dwordx4 v[158:159], v[124:127], off
	v_cvt_pk_bf16_f32 v104, v116, v117
	v_cvt_pk_bf16_f32 v105, v118, v119
	v_cvt_pk_bf16_f32 v106, v112, v113
	v_cvt_pk_bf16_f32 v107, v114, v115
	global_store_dwordx4 v[108:109], v[92:95], off offset:256
	v_cvt_pk_bf16_f32 v76, v76, v77
	v_cvt_pk_bf16_f32 v77, v78, v79
	v_lshl_add_u64 v[92:93], v[88:89], 1, v[156:157]
	v_cvt_pk_bf16_f32 v78, v72, v73
	v_cvt_pk_bf16_f32 v79, v74, v75
	v_mad_i64_i32 v[72:73], s[4:5], s17, v142, 0
	v_cvt_pk_bf16_f32 v68, v68, v69
	v_cvt_pk_bf16_f32 v69, v70, v71
	v_cvt_pk_bf16_f32 v70, v64, v65
	v_mad_i64_i32 v[64:65], s[4:5], s17, v144, 0
	global_store_dwordx4 v[108:109], v[104:107], off
	v_cvt_pk_bf16_f32 v88, v100, v101
	v_cvt_pk_bf16_f32 v89, v102, v103
	v_cvt_pk_bf16_f32 v90, v96, v97
	v_cvt_pk_bf16_f32 v91, v98, v99
	global_store_dwordx4 v[92:93], v[76:79], off offset:256
	v_cvt_pk_bf16_f32 v74, v80, v81
	v_cvt_pk_bf16_f32 v75, v82, v83
	v_lshl_add_u64 v[76:77], v[72:73], 1, v[156:157]
	v_cvt_pk_bf16_f32 v72, v84, v85
	v_cvt_pk_bf16_f32 v73, v86, v87
	v_cvt_pk_bf16_f32 v71, v66, v67
	v_lshl_add_u64 v[64:65], v[64:65], 1, v[156:157]
	v_cvt_pk_bf16_f32 v44, v44, v45
	v_cvt_pk_bf16_f32 v45, v46, v47
	v_cvt_pk_bf16_f32 v46, v40, v41
	v_cvt_pk_bf16_f32 v47, v42, v43
	v_mad_i64_i32 v[40:41], s[4:5], s17, v146, 0
	global_store_dwordx4 v[92:93], v[88:91], off
	global_store_dwordx4 v[76:77], v[72:75], off
	global_store_dwordx4 v[76:77], v[68:71], off offset:256
	v_cvt_pk_bf16_f32 v60, v60, v61
	v_cvt_pk_bf16_f32 v61, v62, v63
	v_cvt_pk_bf16_f32 v62, v56, v57
	v_cvt_pk_bf16_f32 v63, v58, v59
	global_store_dwordx4 v[64:65], v[44:47], off offset:256
	v_cvt_pk_bf16_f32 v28, v28, v29
	v_cvt_pk_bf16_f32 v29, v30, v31
	v_lshl_add_u64 v[44:45], v[40:41], 1, v[156:157]
	v_cvt_pk_bf16_f32 v30, v24, v25
	v_cvt_pk_bf16_f32 v31, v26, v27
	v_mad_i64_i32 v[24:25], s[4:5], s17, v148, 0
	global_store_dwordx4 v[64:65], v[60:63], off
	v_cvt_pk_bf16_f32 v40, v52, v53
	v_cvt_pk_bf16_f32 v41, v54, v55
	v_cvt_pk_bf16_f32 v42, v48, v49
	v_cvt_pk_bf16_f32 v43, v50, v51
	global_store_dwordx4 v[44:45], v[28:31], off offset:256
	v_cvt_pk_bf16_f32 v12, v12, v13
	v_cvt_pk_bf16_f32 v13, v14, v15
	v_lshl_add_u64 v[28:29], v[24:25], 1, v[156:157]
	v_cvt_pk_bf16_f32 v14, v8, v9
	v_cvt_pk_bf16_f32 v15, v10, v11
	v_mad_i64_i32 v[8:9], s[4:5], s17, v150, 0
	global_store_dwordx4 v[44:45], v[40:43], off
	v_cvt_pk_bf16_f32 v24, v36, v37
	v_cvt_pk_bf16_f32 v25, v38, v39
	v_cvt_pk_bf16_f32 v26, v32, v33
	v_cvt_pk_bf16_f32 v27, v34, v35
	global_store_dwordx4 v[28:29], v[12:15], off offset:256
	v_cvt_pk_bf16_f32 v10, v16, v17
	v_cvt_pk_bf16_f32 v11, v18, v19
	v_lshl_add_u64 v[12:13], v[8:9], 1, v[156:157]
	v_cvt_pk_bf16_f32 v8, v20, v21
	v_cvt_pk_bf16_f32 v9, v22, v23
	v_cvt_pk_bf16_f32 v4, v4, v5
	v_cvt_pk_bf16_f32 v5, v6, v7
	v_cvt_pk_bf16_f32 v6, v0, v1
	v_cvt_pk_bf16_f32 v7, v2, v3
	s_and_b64 vcc, exec, s[36:37]
	s_mov_b32 s40, s30
	s_mov_b32 s41, s34
	s_mov_b64 s[48:49], s[38:39]
	s_mov_b64 s[46:47], s[44:45]
	global_store_dwordx4 v[28:29], v[24:27], off
	global_store_dwordx4 v[12:13], v[8:11], off
	global_store_dwordx4 v[12:13], v[4:7], off offset:256
	s_cbranch_vccz .LBB0_868
	v_readlane_b32 s0, v253, 1
	s_waitcnt vmcnt(0)
	v_readlane_b32 s1, v253, 2
	v_readlane_b32 s72, v255, 28
	s_andn2_b64 vcc, exec, s[0:1]
	v_readlane_b32 s73, v255, 29
	s_cbranch_vccnz .LBB0_887
	s_barrier

; __device__ __forceinline__ int fresh_lane() { int l; asm volatile("v_mbcnt_lo_u32_b32 %0, -1, 0\n\tv_mbcnt_hi_u32_b32 %0, -1, %0" : "=v"(l)); return l; }
; #define PG8_STAGE(bufoff, gbase, voff) do { _Pragma("unroll") for (int _i = 0; _i < 2; ++_i) \
;         __builtin_amdgcn_global_load_lds((const unsigned*)((const char*)(gbase) + (voff)[_i]), (LAS unsigned*)(lds + (bufoff) + ldsw + _i * 8192), 16, 0, 0); } while (0)
; #define PG8_WAIT_V(n) asm volatile("s_waitcnt vmcnt(" #n ")" ::: "memory")
; #define PG8_BAR __builtin_amdgcn_s_barrier()
; template <class Epi, class Sched, bool ALIGN_EPI>
; __device__ __forceinline__ void gemm_phase(LAS unsigned char* lds, const int wid, const int lda_, const int ldb_, const int K_, const Sched& S, const Epi& E) {
;     ...
;     const int lane = fresh_lane(), tid = wid * 64 + lane;
;     const int wr = wid >> 2, wc = wid & 3, fr = lane & 15, fq = lane >> 4;
;     unsigned voffA[2], voffB[2];
; #pragma unroll
;     for (int i = 0; i < 2; ++i) { int R, C; stage_rc(tid * 16 + i * 8192, R, C); const int Rb = Epi::PERM ? ((R & ~31) + perm32(R & 31)) : R;
;         voffA[i] = (unsigned)(R * lda + C) * 2u; voffB[i] = (unsigned)(Rb * ldb + C) * 2u; }
;     const size_t kstep = (size_t)(BK * 2);
;     const size_t hstepA = (size_t)HALF * lda * 2, hstepB = (size_t)HALF * ldb * 2;
;     const unsigned ldsw = (unsigned)wid * 1024u;
;     const int aoff = lds_byte(wr * 64 + fr, fq * 8), boff = lds_byte(wc * 32 + fr, fq * 8);
;     ...
;     Unit cur, nxt; int ui = 0;
;     if (!S.next(0, cur)) return;
;     f32x4 acc[2][2][4][2];
; #pragma unroll
;     for (int a = 0; a < 2; ++a)
; #pragma unroll
;         for (int b = 0; b < 2; ++b)
; #pragma unroll
;             for (int m = 0; m < 4; ++m)
; #pragma unroll
;                 for (int n = 0; n < 2; ++n) acc[a][b][m][n] = (f32x4){0.f, 0.f, 0.f, 0.f};
;     bf16x8 At[4][2], B0[2][2], B1[2][2];
;     const char* cA = S.a(cur); const char* cB = S.b(cur);
;     PG8_STAGE(PG8_SB(0, 0), cB, voffB); PG8_STAGE(PG8_SB(0, 1), cB + hstepB, voffB); PG8_STAGE(PG8_SA(0, 0), cA, voffA); PG8_STAGE(PG8_SA(0, 1), cA + hstepA, voffA);
;     if (wr == 1) PG8_BAR;
;     PG8_WAIT_V(2); PG8_BAR;
;     PG8_STAGE(PG8_SB(1, 0), cB + kstep, voffB); PG8_STAGE(PG8_SA(1, 0), cA + kstep, voffA); PG8_STAGE(PG8_SB(1, 1), cB + hstepB + kstep, voffB);
;     PG8_WAIT_V(6); PG8_BAR;
.LBB0_950:
	v_mov_b32_e32 v129, v177
	v_lshl_add_u64 v[12:13], s[4:5], 0, v[176:177]
	v_lshl_add_u64 v[14:15], s[4:5], 0, v[128:129]
	v_and_b32_e32 v7, 15, v6
	v_readlane_b32 s4, v252, 46
	v_and_b32_e32 v23, 48, v6
	v_ashrrev_i32_e32 v21, 6, v6
	v_or_b32_e32 v134, s4, v7
	v_lshlrev_b32_e32 v22, 6, v134
	s_movk_i32 s4, 0x3c0
	v_and_or_b32 v22, v22, s4, v23
	v_readlane_b32 s4, v252, 47
	v_ashrrev_i32_e32 v20, 1, v6
	v_lshlrev_b32_e32 v6, 2, v6
	v_lshl_add_u32 v24, v21, 10, s4
	v_readlane_b32 s4, v252, 49
	v_lshl_add_u64 v[8:9], s[96:97], 0, v[176:177]
	v_readlane_b32 s94, v254, 26
	v_lshl_or_b32 v7, v7, 6, v23
	v_add_lshl_u32 v21, v21, s4, 10
	v_and_b32_e32 v6, 32, v6
	v_lshl_add_u64 v[10:11], s[96:97], 0, v[128:129]
	v_mov_b32_e32 v133, v177
	v_readlane_b32 s95, v254, 27
	v_bitop3_b32 v135, v7, v21, v6 bitop3:0xde
	v_lshl_add_u64 v[6:7], v[8:9], 0, s[24:25]
	s_add_i32 m0, s16, 0x18000
	v_lshl_add_u64 v[16:17], s[94:95], 0, v[132:133]
	v_mov_b32_e32 v131, v177
	s_waitcnt vmcnt(2)
	s_barrier
	global_load_lds_dwordx4 v[6:7], off
	v_lshl_add_u64 v[6:7], v[10:11], 0, s[24:25]
	s_add_i32 m0, s16, 0x1a000
	s_add_i32 s72, s16, 0x8000
	v_lshl_add_u64 v[18:19], s[94:95], 0, v[130:131]
	global_load_lds_dwordx4 v[6:7], off
	v_lshl_add_u64 v[6:7], v[16:17], 0, s[24:25]
	s_mov_b32 m0, s72
	s_add_i32 s73, s16, 0xa000
	global_load_lds_dwordx4 v[6:7], off
	v_lshl_add_u64 v[6:7], v[18:19], 0, s[24:25]
	s_mov_b32 m0, s73
	v_lshlrev_b32_e32 v25, 2, v134
	global_load_lds_dwordx4 v[6:7], off
	v_lshl_add_u64 v[6:7], v[12:13], 0, s[24:25]
	s_add_i32 m0, s16, 0x1c000
	v_and_b32_e32 v20, -8, v20
	global_load_lds_dwordx4 v[6:7], off
	v_lshl_add_u64 v[6:7], v[14:15], 0, s[24:25]
	s_add_i32 m0, s16, 0x1e000
	v_and_b32_e32 v25, 32, v25
	global_load_lds_dwordx4 v[6:7], off
	s_waitcnt vmcnt(6)
	v_readlane_b32 s4, v252, 48
	v_add_u32_e32 v3, v5, v3
	v_add_u32_e32 v0, v2, v0
	v_bitop3_b32 v22, v22, v24, v25 bitop3:0xde
	v_add_u32_e32 v136, s4, v20
	v_add_lshl_u32 v4, v3, v4, 1
	v_mov_b32_e32 v5, v177
	v_add_lshl_u32 v0, v0, v1, 1
	v_mov_b32_e32 v1, v177
	v_readlane_b32 s4, v254, 16
	v_ashrrev_i32_e32 v137, 31, v136
	v_or_b32_e32 v138, 16, v134
	v_or_b32_e32 v140, 32, v134
	v_or_b32_e32 v142, 48, v134
	v_add_u32_e32 v144, 0x80, v134
	v_add_u32_e32 v146, 0x90, v134
	v_add_u32_e32 v148, 0xa0, v134
	v_add_u32_e32 v150, 0xb0, v134
	v_lshl_add_u64 v[152:153], s[0:1], 0, v[4:5]
	v_lshl_add_u64 v[154:155], s[0:1], 0, v[0:1]
	s_mov_b32 s74, 0
	v_add_u32_e32 v139, 0, v22
	s_mov_b32 s48, s4
	v_readlane_b32 s44, v254, 21
	v_readlane_b32 s46, v254, 17
	s_barrier
	v_readlane_b32 s45, v254, 22
	v_readlane_b32 s47, v254, 18
	v_add_u32_e32 v141, 0x10000, v135
	ds_read_b128 v[160:163], v141 offset:1024
	ds_read_b128 v[164:167], v141 offset:2048
	ds_read_b128 v[168:171], v141 offset:3072
	v_add_u32_e32 v141, 0x14000, v135
	ds_read_b128 v[172:175], v141
	ds_read_b128 v[180:183], v141 offset:1024
	ds_read_b128 v[184:187], v141 offset:2048
	ds_read_b128 v[188:191], v141 offset:3072
	ds_read_b128 v[192:195], v139
	ds_read_b128 v[196:199], v139 offset:1024
	ds_read_b128 v[200:203], v139 offset:2048
	ds_read_b128 v[204:207], v139 offset:3072
	ds_read_b128 v[208:211], v139 offset:4096
	ds_read_b128 v[212:215], v139 offset:5120
	ds_read_b128 v[216:219], v139 offset:6144
	ds_read_b128 v[220:223], v139 offset:7168
	s_branch .LBB0_952

; #define PG8_STAGE(bufoff, gbase, voff) do { _Pragma("unroll") for (int _i = 0; _i < 2; ++_i) \
;         __builtin_amdgcn_global_load_lds((const unsigned*)((const char*)(gbase) + (voff)[_i]), (LAS unsigned*)(lds + (bufoff) + ldsw + _i * 8192), 16, 0, 0); } while (0)
; #define PG8_LDA(dst, b, h) do { _Pragma("unroll") for (int m = 0; m < 4; ++m) _Pragma("unroll") for (int k = 0; k < 2; ++k) dst[m][k] = *(const LAS bf16x8*)(lds + PG8_SA(b, h) + aoff + m * 2048 + k * 1024); } while (0)
; #define PG8_LDB(dst, b, h) do { _Pragma("unroll") for (int n = 0; n < 2; ++n) _Pragma("unroll") for (int k = 0; k < 2; ++k) dst[n][k] = *(const LAS bf16x8*)(lds + PG8_SB(b, h) + boff + n * 2048 + k * 1024); } while (0)
; #define PG8_MMA(ai, bj, At, Bt) do { __builtin_amdgcn_s_setprio(1); _Pragma("unroll") for (int m = 0; m < 4; ++m) _Pragma("unroll") for (int n = 0; n < 2; ++n) _Pragma("unroll") for (int k = 0; k < 2; ++k) \
;         acc[ai][bj][m][n] = __builtin_amdgcn_mfma_f32_16x16x32_bf16(Bt[n][k], At[m][k], acc[ai][bj][m][n], 0, 0, 0); __builtin_amdgcn_s_setprio(0); } while (0)
; #define PG8_WAIT_V(n) asm volatile("s_waitcnt vmcnt(" #n ")" ::: "memory")
; #define PG8_WAIT_L(n) asm volatile("s_waitcnt lgkmcnt(" #n ")" ::: "memory")
; #define PG8_BAR __builtin_amdgcn_s_barrier()
; #define PG8_SCHED __builtin_amdgcn_sched_barrier(0)
; template <class Epi, class Sched, bool ALIGN_EPI>
; __device__ __forceinline__ void gemm_phase(LAS unsigned char* lds, const int wid, const int lda_, const int ldb_, const int K_, const Sched& S, const Epi& E) {
;     ...
;         const bool has_next = S.next(ui + 1, nxt);
;         const int nt = S.nt(cur);
;         const char* nA = has_next ? S.a(nxt) : cA; const char* nB = has_next ? S.b(nxt) : cB;
; #pragma unroll 1
;         for (int t = 0; t < nt; t += 2) {
;             const bool last = (t == nt - 2);
;             const char* a1 = cA + (size_t)(t + 1) * kstep;
;             const char* a2 = last ? nA : cA + (size_t)(t + 2) * kstep; const char* b2 = last ? nB : cB + (size_t)(t + 2) * kstep;
;             const char* a3 = a2 + kstep; const char* b3 = b2 + kstep;
;             PG8_LDB(B0, 0, 0); PG8_LDB(B1, 0, 1); PG8_SCHED; PG8_LDA(At, 0, 0); PG8_STAGE(PG8_SA(1, 1), a1 + hstepA, voffA);
;             PG8_WAIT_V(8); PG8_WAIT_L(0); PG8_BAR; PG8_MMA(0, 0, At, B0); PG8_MMA(0, 1, At, B1); PG8_BAR; PG8_SCHED;
.LBB0_961:
	s_xor_b64 s[36:37], s[4:5], -1
	s_cmp_gt_i32 s48, -1
	s_cselect_b64 s[50:51], -1, 0
	s_cmp_lt_i32 s48, 0
	s_cselect_b32 s45, 32, 8
	s_max_i32 s17, s75, 0
	s_ashr_i32 s35, s34, 31
	s_lshl_b32 s17, s17, 10
	s_lshl_b64 s[38:39], s[34:35], 20
	v_readlane_b32 s27, v254, 19
	s_add_u32 s27, s27, s38
	v_readlane_b32 s31, v254, 20
	s_addc_u32 s31, s31, s39
	s_add_u32 s38, s27, s17
	s_addc_u32 s39, s31, 0
	s_and_b64 s[40:41], s[4:5], exec
	s_cselect_b32 s35, s39, s95
	s_cselect_b32 s47, s38, s94
	s_ashr_i32 s31, s30, 31
	s_lshl_b64 s[40:41], s[30:31], 20
	s_add_u32 s27, s6, s40
	s_addc_u32 s31, s7, s41
	s_add_u32 s40, s27, s17
	s_addc_u32 s41, s31, 0
	s_and_b64 s[4:5], s[4:5], exec
	s_cselect_b32 s4, s41, s97
	s_cselect_b32 s5, s40, s96
	s_add_i32 s31, s45, -2
	s_add_u32 s94, s94, 0x80
	s_addc_u32 s95, s95, 0
	s_add_u32 s49, s96, 0x100
	s_mov_b32 s77, 0
	s_addc_u32 s76, s97, 0
	s_add_i32 s78, s77, 2
	s_add_u32 s17, s94, 0x80
	s_addc_u32 s27, s95, 0
	s_add_i32 s79, 0, 0x10000
	s_cmp_eq_u32 s31, s77
	s_cselect_b32 s97, s35, s27
	s_cselect_b32 s96, s47, s17
	v_add_u32_e32 v141, 0x10000, v135
	ds_read_b128 v[156:159], v141
	s_cselect_b32 s43, s4, s76
	s_cselect_b32 s42, s5, s49
	s_add_i32 s17, 0, 0x14000
	v_lshl_add_u64 v[224:225], s[94:95], 0, v[152:153]
	s_add_i32 m0, s16, 0xc000
	global_load_lds_dwordx4 v[224:225], off
	v_lshl_add_u64 v[224:225], s[94:95], 0, v[154:155]
	s_add_i32 m0, s16, 0xe000
	s_nop 0
	global_load_lds_dwordx4 v[224:225], off
	s_waitcnt vmcnt(8)
	s_waitcnt lgkmcnt(0)
	s_barrier
	s_setprio 1
	s_waitcnt lgkmcnt(0)
	v_mfma_f32_16x16x32_bf16 v[124:127], v[156:159], v[192:195], 0
	v_mfma_f32_16x16x32_bf16 v[120:123], v[164:167], v[192:195], 0
	v_mfma_f32_16x16x32_bf16 v[116:119], v[156:159], v[200:203], 0
	v_mfma_f32_16x16x32_bf16 v[112:115], v[164:167], v[200:203], 0
	v_mfma_f32_16x16x32_bf16 v[100:103], v[156:159], v[208:211], 0
	v_mfma_f32_16x16x32_bf16 v[96:99], v[164:167], v[208:211], 0
	v_mfma_f32_16x16x32_bf16 v[84:87], v[156:159], v[216:219], 0
	v_mfma_f32_16x16x32_bf16 v[80:83], v[164:167], v[216:219], 0
	v_mfma_f32_16x16x32_bf16 v[124:127], v[160:163], v[196:199], v[124:127]
	v_mfma_f32_16x16x32_bf16 v[120:123], v[168:171], v[196:199], v[120:123]
	v_mfma_f32_16x16x32_bf16 v[116:119], v[160:163], v[204:207], v[116:119]
	v_mfma_f32_16x16x32_bf16 v[112:115], v[168:171], v[204:207], v[112:115]
	v_mfma_f32_16x16x32_bf16 v[100:103], v[160:163], v[212:215], v[100:103]
	v_mfma_f32_16x16x32_bf16 v[96:99], v[168:171], v[212:215], v[96:99]
	v_mfma_f32_16x16x32_bf16 v[84:87], v[160:163], v[220:223], v[84:87]
	v_mfma_f32_16x16x32_bf16 v[80:83], v[168:171], v[220:223], v[80:83]
	s_setprio 0
	s_setprio 1
	v_mfma_f32_16x16x32_bf16 v[108:111], v[172:175], v[192:195], 0
	v_mfma_f32_16x16x32_bf16 v[104:107], v[184:187], v[192:195], 0
	v_mfma_f32_16x16x32_bf16 v[92:95], v[172:175], v[200:203], 0
	v_mfma_f32_16x16x32_bf16 v[88:91], v[184:187], v[200:203], 0
	v_mfma_f32_16x16x32_bf16 v[76:79], v[172:175], v[208:211], 0
	v_mfma_f32_16x16x32_bf16 v[72:75], v[184:187], v[208:211], 0
	v_mfma_f32_16x16x32_bf16 v[68:71], v[172:175], v[216:219], 0
	v_mfma_f32_16x16x32_bf16 v[64:67], v[184:187], v[216:219], 0
	v_mfma_f32_16x16x32_bf16 v[108:111], v[180:183], v[196:199], v[108:111]
	v_mfma_f32_16x16x32_bf16 v[104:107], v[188:191], v[196:199], v[104:107]
	v_mfma_f32_16x16x32_bf16 v[92:95], v[180:183], v[204:207], v[92:95]
	v_mfma_f32_16x16x32_bf16 v[88:91], v[188:191], v[204:207], v[88:91]
	v_mfma_f32_16x16x32_bf16 v[76:79], v[180:183], v[212:215], v[76:79]
	v_mfma_f32_16x16x32_bf16 v[72:75], v[188:191], v[212:215], v[72:75]
	v_mfma_f32_16x16x32_bf16 v[68:71], v[180:183], v[220:223], v[68:71]
	v_mfma_f32_16x16x32_bf16 v[64:67], v[188:191], v[220:223], v[64:67]
	s_setprio 0
	s_barrier
; #define PG8_STAGE(bufoff, gbase, voff) do { _Pragma("unroll") for (int _i = 0; _i < 2; ++_i) \
;         __builtin_amdgcn_global_load_lds((const unsigned*)((const char*)(gbase) + (voff)[_i]), (LAS unsigned*)(lds + (bufoff) + ldsw + _i * 8192), 16, 0, 0); } while (0)
; #define PG8_LDA(dst, b, h) do { _Pragma("unroll") for (int m = 0; m < 4; ++m) _Pragma("unroll") for (int k = 0; k < 2; ++k) dst[m][k] = *(const LAS bf16x8*)(lds + PG8_SA(b, h) + aoff + m * 2048 + k * 1024); } while (0)
; #define PG8_MMA(ai, bj, At, Bt) do { __builtin_amdgcn_s_setprio(1); _Pragma("unroll") for (int m = 0; m < 4; ++m) _Pragma("unroll") for (int n = 0; n < 2; ++n) _Pragma("unroll") for (int k = 0; k < 2; ++k) \
;         acc[ai][bj][m][n] = __builtin_amdgcn_mfma_f32_16x16x32_bf16(Bt[n][k], At[m][k], acc[ai][bj][m][n], 0, 0, 0); __builtin_amdgcn_s_setprio(0); } while (0)
; #define PG8_WAIT_V(n) asm volatile("s_waitcnt vmcnt(" #n ")" ::: "memory")
; #define PG8_WAIT_L(n) asm volatile("s_waitcnt lgkmcnt(" #n ")" ::: "memory")
; #define PG8_BAR __builtin_amdgcn_s_barrier()
; #define PG8_SCHED __builtin_amdgcn_sched_barrier(0)
; template <class Epi, class Sched, bool ALIGN_EPI>
; __device__ __forceinline__ void gemm_phase(LAS unsigned char* lds, const int wid, const int lda_, const int ldb_, const int K_, const Sched& S, const Epi& E) {
;     ...
;             PG8_LDA(At, 0, 1); PG8_STAGE(PG8_SB(0, 0), b2, voffB); PG8_STAGE(PG8_SB(0, 1), b2 + hstepB, voffB); PG8_STAGE(PG8_SA(0, 0), a2, voffA);
;             PG8_WAIT_V(8); PG8_WAIT_L(0); PG8_BAR; PG8_MMA(1, 0, At, B0); PG8_MMA(1, 1, At, B1); PG8_BAR; PG8_SCHED;
	s_add_i32 s27, s79, s3
	v_lshl_add_u64 v[224:225], s[42:43], 0, v[176:177]
	s_mov_b32 m0, s27
	ds_read_b128 v[192:195], v139 offset:16384
	ds_read_b128 v[196:199], v139 offset:17408
	ds_read_b128 v[200:203], v139 offset:18432
	ds_read_b128 v[204:207], v139 offset:19456
	ds_read_b128 v[208:211], v139 offset:20480
	ds_read_b128 v[212:215], v139 offset:21504
	ds_read_b128 v[216:219], v139 offset:22528
	ds_read_b128 v[220:223], v139 offset:23552
	global_load_lds_dwordx4 v[224:225], off
	s_add_i32 m0, s27, 0x2000
	v_lshl_add_u64 v[226:227], s[42:43], 0, v[128:129]
	s_add_u32 s42, s42, s10
	s_addc_u32 s43, s43, s11
	s_add_i32 s17, s17, s3
	global_load_lds_dwordx4 v[226:227], off
	v_lshl_add_u64 v[228:229], s[42:43], 0, v[176:177]
	s_mov_b32 m0, s17
	v_lshl_add_u64 v[230:231], s[42:43], 0, v[128:129]
	global_load_lds_dwordx4 v[228:229], off
	s_add_i32 m0, s17, 0x2000
	v_lshl_add_u64 v[232:233], s[96:97], 0, v[132:133]
	global_load_lds_dwordx4 v[230:231], off
	s_mov_b32 m0, s16
	v_lshl_add_u64 v[234:235], s[96:97], 0, v[130:131]
	global_load_lds_dwordx4 v[232:233], off
	s_mov_b32 m0, s14
	s_nop 0
	global_load_lds_dwordx4 v[234:235], off
	s_waitcnt vmcnt(8)
	s_waitcnt lgkmcnt(0)
	s_barrier
	s_setprio 1
	s_waitcnt lgkmcnt(0)
	v_mfma_f32_16x16x32_bf16 v[60:63], v[156:159], v[192:195], 0
	v_mfma_f32_16x16x32_bf16 v[56:59], v[164:167], v[192:195], 0
	v_mfma_f32_16x16x32_bf16 v[52:55], v[156:159], v[200:203], 0
	v_mfma_f32_16x16x32_bf16 v[48:51], v[164:167], v[200:203], 0
	v_mfma_f32_16x16x32_bf16 v[36:39], v[156:159], v[208:211], 0
	v_mfma_f32_16x16x32_bf16 v[32:35], v[164:167], v[208:211], 0
	v_mfma_f32_16x16x32_bf16 v[20:23], v[156:159], v[216:219], 0
	v_mfma_f32_16x16x32_bf16 v[16:19], v[164:167], v[216:219], 0
	v_mfma_f32_16x16x32_bf16 v[60:63], v[160:163], v[196:199], v[60:63]
	v_mfma_f32_16x16x32_bf16 v[56:59], v[168:171], v[196:199], v[56:59]
	v_mfma_f32_16x16x32_bf16 v[52:55], v[160:163], v[204:207], v[52:55]
	v_mfma_f32_16x16x32_bf16 v[48:51], v[168:171], v[204:207], v[48:51]
	v_mfma_f32_16x16x32_bf16 v[36:39], v[160:163], v[212:215], v[36:39]
	v_mfma_f32_16x16x32_bf16 v[32:35], v[168:171], v[212:215], v[32:35]
	v_mfma_f32_16x16x32_bf16 v[20:23], v[160:163], v[220:223], v[20:23]
	v_mfma_f32_16x16x32_bf16 v[16:19], v[168:171], v[220:223], v[16:19]
	s_setprio 0
	s_setprio 1
	v_mfma_f32_16x16x32_bf16 v[44:47], v[172:175], v[192:195], 0
	v_mfma_f32_16x16x32_bf16 v[40:43], v[184:187], v[192:195], 0
	v_mfma_f32_16x16x32_bf16 v[28:31], v[172:175], v[200:203], 0
	v_mfma_f32_16x16x32_bf16 v[24:27], v[184:187], v[200:203], 0
	v_mfma_f32_16x16x32_bf16 v[12:15], v[172:175], v[208:211], 0
	v_mfma_f32_16x16x32_bf16 v[8:11], v[184:187], v[208:211], 0
	v_mfma_f32_16x16x32_bf16 v[4:7], v[172:175], v[216:219], 0
	v_mfma_f32_16x16x32_bf16 v[0:3], v[184:187], v[216:219], 0
	v_mfma_f32_16x16x32_bf16 v[44:47], v[180:183], v[196:199], v[44:47]
	v_mfma_f32_16x16x32_bf16 v[40:43], v[188:191], v[196:199], v[40:43]
	v_mfma_f32_16x16x32_bf16 v[28:31], v[180:183], v[204:207], v[28:31]
	v_mfma_f32_16x16x32_bf16 v[24:27], v[188:191], v[204:207], v[24:27]
	v_mfma_f32_16x16x32_bf16 v[12:15], v[180:183], v[212:215], v[12:15]
	v_mfma_f32_16x16x32_bf16 v[8:11], v[188:191], v[212:215], v[8:11]
	v_mfma_f32_16x16x32_bf16 v[4:7], v[180:183], v[220:223], v[4:7]
	v_mfma_f32_16x16x32_bf16 v[0:3], v[188:191], v[220:223], v[0:3]
	s_setprio 0
	s_barrier
	s_branch .Lgemm_join_962

; #define PG8_STAGE(bufoff, gbase, voff) do { _Pragma("unroll") for (int _i = 0; _i < 2; ++_i) \
;         __builtin_amdgcn_global_load_lds((const unsigned*)((const char*)(gbase) + (voff)[_i]), (LAS unsigned*)(lds + (bufoff) + ldsw + _i * 8192), 16, 0, 0); } while (0)
; #define PG8_LDA(dst, b, h) do { _Pragma("unroll") for (int m = 0; m < 4; ++m) _Pragma("unroll") for (int k = 0; k < 2; ++k) dst[m][k] = *(const LAS bf16x8*)(lds + PG8_SA(b, h) + aoff + m * 2048 + k * 1024); } while (0)
; #define PG8_LDB(dst, b, h) do { _Pragma("unroll") for (int n = 0; n < 2; ++n) _Pragma("unroll") for (int k = 0; k < 2; ++k) dst[n][k] = *(const LAS bf16x8*)(lds + PG8_SB(b, h) + boff + n * 2048 + k * 1024); } while (0)
; #define PG8_MMA(ai, bj, At, Bt) do { __builtin_amdgcn_s_setprio(1); _Pragma("unroll") for (int m = 0; m < 4; ++m) _Pragma("unroll") for (int n = 0; n < 2; ++n) _Pragma("unroll") for (int k = 0; k < 2; ++k) \
;         acc[ai][bj][m][n] = __builtin_amdgcn_mfma_f32_16x16x32_bf16(Bt[n][k], At[m][k], acc[ai][bj][m][n], 0, 0, 0); __builtin_amdgcn_s_setprio(0); } while (0)
; #define PG8_WAIT_V(n) asm volatile("s_waitcnt vmcnt(" #n ")" ::: "memory")
; #define PG8_WAIT_L(n) asm volatile("s_waitcnt lgkmcnt(" #n ")" ::: "memory")
; #define PG8_BAR __builtin_amdgcn_s_barrier()
; #define PG8_SCHED __builtin_amdgcn_sched_barrier(0)
; template <class Epi, class Sched, bool ALIGN_EPI>
; __device__ __forceinline__ void gemm_phase(LAS unsigned char* lds, const int wid, const int lda_, const int ldb_, const int K_, const Sched& S, const Epi& E) {
;     ...
;             PG8_LDB(B0, 1, 0); PG8_LDB(B1, 1, 1); PG8_SCHED; PG8_LDA(At, 1, 0); PG8_STAGE(PG8_SA(0, 1), a2 + hstepA, voffA);
;             PG8_WAIT_V(8); PG8_WAIT_L(0); PG8_BAR; PG8_MMA(0, 0, At, B0); PG8_MMA(0, 1, At, B1); PG8_BAR; PG8_SCHED;
;             PG8_LDA(At, 1, 1); PG8_STAGE(PG8_SB(1, 0), b3, voffB); PG8_STAGE(PG8_SB(1, 1), b3 + hstepB, voffB); PG8_STAGE(PG8_SA(1, 0), a3, voffA);
;             PG8_WAIT_V(8); PG8_WAIT_L(0); PG8_BAR; PG8_MMA(1, 0, At, B0); PG8_MMA(1, 1, At, B1); PG8_BAR; PG8_SCHED;
.Lgemm_join_962:
	s_add_i32 s17, 0, 0x18000
	v_add_u32_e32 v141, s17, v135
	s_add_i32 s27, 0, 0x1c000
	ds_read_b128 v[156:159], v141
	ds_read_b128 v[160:163], v141 offset:1024
	ds_read_b128 v[164:167], v141 offset:2048
	ds_read_b128 v[168:171], v141 offset:3072
	v_add_u32_e32 v141, s27, v135
	ds_read_b128 v[172:175], v141
	ds_read_b128 v[180:183], v141 offset:1024
	ds_read_b128 v[184:187], v141 offset:2048
	ds_read_b128 v[188:191], v141 offset:3072
	s_add_u32 s42, s96, s0
	s_addc_u32 s43, s97, s1
	s_mov_b32 m0, s15
	v_lshl_add_u64 v[236:237], s[42:43], 0, v[132:133]
	ds_read_b128 v[192:195], v139 offset:32768
	ds_read_b128 v[196:199], v139 offset:33792
	ds_read_b128 v[200:203], v139 offset:34816
	ds_read_b128 v[204:207], v139 offset:35840
	ds_read_b128 v[208:211], v139 offset:36864
	ds_read_b128 v[212:215], v139 offset:37888
	ds_read_b128 v[216:219], v139 offset:38912
	ds_read_b128 v[220:223], v139 offset:39936
	global_load_lds_dwordx4 v[236:237], off
	v_lshl_add_u64 v[236:237], s[42:43], 0, v[130:131]
	s_mov_b32 m0, s26
	s_nop 0
	global_load_lds_dwordx4 v[236:237], off
	s_waitcnt vmcnt(8)
	s_waitcnt lgkmcnt(0)
	s_barrier
	s_setprio 1
	s_waitcnt lgkmcnt(0)
	v_mfma_f32_16x16x32_bf16 v[124:127], v[156:159], v[192:195], v[124:127]
	v_mfma_f32_16x16x32_bf16 v[120:123], v[164:167], v[192:195], v[120:123]
	v_mfma_f32_16x16x32_bf16 v[116:119], v[156:159], v[200:203], v[116:119]
	v_mfma_f32_16x16x32_bf16 v[112:115], v[164:167], v[200:203], v[112:115]
	v_mfma_f32_16x16x32_bf16 v[100:103], v[156:159], v[208:211], v[100:103]
	v_mfma_f32_16x16x32_bf16 v[96:99], v[164:167], v[208:211], v[96:99]
	v_mfma_f32_16x16x32_bf16 v[84:87], v[156:159], v[216:219], v[84:87]
	v_mfma_f32_16x16x32_bf16 v[80:83], v[164:167], v[216:219], v[80:83]
	v_mfma_f32_16x16x32_bf16 v[124:127], v[160:163], v[196:199], v[124:127]
	v_mfma_f32_16x16x32_bf16 v[120:123], v[168:171], v[196:199], v[120:123]
	v_mfma_f32_16x16x32_bf16 v[116:119], v[160:163], v[204:207], v[116:119]
	v_mfma_f32_16x16x32_bf16 v[112:115], v[168:171], v[204:207], v[112:115]
	v_mfma_f32_16x16x32_bf16 v[100:103], v[160:163], v[212:215], v[100:103]
	v_mfma_f32_16x16x32_bf16 v[96:99], v[168:171], v[212:215], v[96:99]
	v_mfma_f32_16x16x32_bf16 v[84:87], v[160:163], v[220:223], v[84:87]
	v_mfma_f32_16x16x32_bf16 v[80:83], v[168:171], v[220:223], v[80:83]
	s_setprio 0
	s_setprio 1
	v_mfma_f32_16x16x32_bf16 v[108:111], v[172:175], v[192:195], v[108:111]
	v_mfma_f32_16x16x32_bf16 v[104:107], v[184:187], v[192:195], v[104:107]
	v_mfma_f32_16x16x32_bf16 v[92:95], v[172:175], v[200:203], v[92:95]
	v_mfma_f32_16x16x32_bf16 v[88:91], v[184:187], v[200:203], v[88:91]
	v_mfma_f32_16x16x32_bf16 v[76:79], v[172:175], v[208:211], v[76:79]
	v_mfma_f32_16x16x32_bf16 v[72:75], v[184:187], v[208:211], v[72:75]
	v_mfma_f32_16x16x32_bf16 v[68:71], v[172:175], v[216:219], v[68:71]
	v_mfma_f32_16x16x32_bf16 v[64:67], v[184:187], v[216:219], v[64:67]
	v_mfma_f32_16x16x32_bf16 v[108:111], v[180:183], v[196:199], v[108:111]
	v_mfma_f32_16x16x32_bf16 v[104:107], v[188:191], v[196:199], v[104:107]
	v_mfma_f32_16x16x32_bf16 v[92:95], v[180:183], v[204:207], v[92:95]
	v_mfma_f32_16x16x32_bf16 v[88:91], v[188:191], v[204:207], v[88:91]
	v_mfma_f32_16x16x32_bf16 v[76:79], v[180:183], v[212:215], v[76:79]
	v_mfma_f32_16x16x32_bf16 v[72:75], v[188:191], v[212:215], v[72:75]
	v_mfma_f32_16x16x32_bf16 v[68:71], v[180:183], v[220:223], v[68:71]
	v_mfma_f32_16x16x32_bf16 v[64:67], v[188:191], v[220:223], v[64:67]
	s_setprio 0
	s_barrier
	s_add_i32 s17, s17, s3
	v_lshl_add_u64 v[224:225], v[224:225], 0, s[24:25]
	s_mov_b32 m0, s17
	ds_read_b128 v[192:195], v139 offset:49152
	ds_read_b128 v[196:199], v139 offset:50176
	ds_read_b128 v[200:203], v139 offset:51200
	ds_read_b128 v[204:207], v139 offset:52224
	ds_read_b128 v[208:211], v139 offset:53248
	ds_read_b128 v[212:215], v139 offset:54272
	ds_read_b128 v[216:219], v139 offset:55296
	ds_read_b128 v[220:223], v139 offset:56320
	global_load_lds_dwordx4 v[224:225], off
	v_lshl_add_u64 v[224:225], v[226:227], 0, s[24:25]
	s_add_i32 m0, s17, 0x2000
	s_add_i32 s17, s27, s3
	global_load_lds_dwordx4 v[224:225], off
	v_lshl_add_u64 v[224:225], v[228:229], 0, s[24:25]
	s_mov_b32 m0, s17
	s_nop 0
	global_load_lds_dwordx4 v[224:225], off
	v_lshl_add_u64 v[224:225], v[230:231], 0, s[24:25]
	s_add_i32 m0, s17, 0x2000
	s_nop 0
	global_load_lds_dwordx4 v[224:225], off
	v_lshl_add_u64 v[224:225], v[232:233], 0, s[24:25]
	s_mov_b32 m0, s72
	s_nop 0
	global_load_lds_dwordx4 v[224:225], off
	v_lshl_add_u64 v[224:225], v[234:235], 0, s[24:25]
	s_mov_b32 m0, s73
	s_nop 0
	global_load_lds_dwordx4 v[224:225], off
	s_waitcnt vmcnt(8)
	s_waitcnt lgkmcnt(0)
	s_barrier
; #define PG8_STAGE(bufoff, gbase, voff) do { _Pragma("unroll") for (int _i = 0; _i < 2; ++_i) \
;         __builtin_amdgcn_global_load_lds((const unsigned*)((const char*)(gbase) + (voff)[_i]), (LAS unsigned*)(lds + (bufoff) + ldsw + _i * 8192), 16, 0, 0); } while (0)
; #define PG8_LDA(dst, b, h) do { _Pragma("unroll") for (int m = 0; m < 4; ++m) _Pragma("unroll") for (int k = 0; k < 2; ++k) dst[m][k] = *(const LAS bf16x8*)(lds + PG8_SA(b, h) + aoff + m * 2048 + k * 1024); } while (0)
; #define PG8_LDB(dst, b, h) do { _Pragma("unroll") for (int n = 0; n < 2; ++n) _Pragma("unroll") for (int k = 0; k < 2; ++k) dst[n][k] = *(const LAS bf16x8*)(lds + PG8_SB(b, h) + boff + n * 2048 + k * 1024); } while (0)
; #define PG8_WAIT_V(n) asm volatile("s_waitcnt vmcnt(" #n ")" ::: "memory")
; #define PG8_WAIT_L(n) asm volatile("s_waitcnt lgkmcnt(" #n ")" ::: "memory")
; #define PG8_BAR __builtin_amdgcn_s_barrier()
; #define PG8_SCHED __builtin_amdgcn_sched_barrier(0)
; template <class Epi, class Sched, bool ALIGN_EPI>
; __device__ __forceinline__ void gemm_phase(LAS unsigned char* lds, const int wid, const int lda_, const int ldb_, const int K_, const Sched& S, const Epi& E) {
;     ...
;             PG8_LDB(B0, 0, 0); PG8_LDB(B1, 0, 1); PG8_SCHED; PG8_LDA(At, 0, 0); PG8_STAGE(PG8_SA(1, 1), a1 + hstepA, voffA);
;             PG8_WAIT_V(8); PG8_WAIT_L(0); PG8_BAR; PG8_MMA(0, 0, At, B0); PG8_MMA(0, 1, At, B1); PG8_BAR; PG8_SCHED;
;             PG8_LDA(At, 0, 1); PG8_STAGE(PG8_SB(0, 0), b2, voffB); PG8_STAGE(PG8_SB(0, 1), b2 + hstepB, voffB); PG8_STAGE(PG8_SA(0, 0), a2, voffA);
;             PG8_WAIT_V(8); PG8_WAIT_L(0); PG8_BAR; PG8_MMA(1, 0, At, B0); PG8_MMA(1, 1, At, B1); PG8_BAR; PG8_SCHED;
;             PG8_LDB(B0, 1, 0); PG8_LDB(B1, 1, 1); PG8_SCHED; PG8_LDA(At, 1, 0); PG8_STAGE(PG8_SA(0, 1), a2 + hstepA, voffA);
;             PG8_WAIT_V(8); PG8_WAIT_L(0); PG8_BAR; PG8_MMA(0, 0, At, B0); PG8_MMA(0, 1, At, B1); PG8_BAR; PG8_SCHED;
;             PG8_LDA(At, 1, 1); PG8_STAGE(PG8_SB(1, 0), b3, voffB); PG8_STAGE(PG8_SB(1, 1), b3 + hstepB, voffB); PG8_STAGE(PG8_SA(1, 0), a3, voffA);
;             PG8_WAIT_V(8); PG8_WAIT_L(0); PG8_BAR; PG8_MMA(1, 0, At, B0); PG8_MMA(1, 1, At, B1); PG8_BAR; PG8_SCHED;
;         }
;         if constexpr (ALIGN_EPI) { if (wr == 0) PG8_BAR; }
;         E(acc, cur, S, wr, wc, fr, fq);
	s_setprio 1
	s_waitcnt lgkmcnt(0)
	v_mfma_f32_16x16x32_bf16 v[60:63], v[156:159], v[192:195], v[60:63]
	v_mfma_f32_16x16x32_bf16 v[56:59], v[164:167], v[192:195], v[56:59]
	v_mfma_f32_16x16x32_bf16 v[52:55], v[156:159], v[200:203], v[52:55]
	v_mfma_f32_16x16x32_bf16 v[48:51], v[164:167], v[200:203], v[48:51]
	v_mfma_f32_16x16x32_bf16 v[36:39], v[156:159], v[208:211], v[36:39]
	v_mfma_f32_16x16x32_bf16 v[32:35], v[164:167], v[208:211], v[32:35]
	v_mfma_f32_16x16x32_bf16 v[20:23], v[156:159], v[216:219], v[20:23]
	v_mfma_f32_16x16x32_bf16 v[16:19], v[164:167], v[216:219], v[16:19]
	v_mfma_f32_16x16x32_bf16 v[60:63], v[160:163], v[196:199], v[60:63]
	v_mfma_f32_16x16x32_bf16 v[56:59], v[168:171], v[196:199], v[56:59]
	v_mfma_f32_16x16x32_bf16 v[52:55], v[160:163], v[204:207], v[52:55]
	v_mfma_f32_16x16x32_bf16 v[48:51], v[168:171], v[204:207], v[48:51]
	v_mfma_f32_16x16x32_bf16 v[36:39], v[160:163], v[212:215], v[36:39]
	v_mfma_f32_16x16x32_bf16 v[32:35], v[168:171], v[212:215], v[32:35]
	v_mfma_f32_16x16x32_bf16 v[20:23], v[160:163], v[220:223], v[20:23]
	v_mfma_f32_16x16x32_bf16 v[16:19], v[168:171], v[220:223], v[16:19]
	s_setprio 0
	s_setprio 1
	v_mfma_f32_16x16x32_bf16 v[44:47], v[172:175], v[192:195], v[44:47]
	v_mfma_f32_16x16x32_bf16 v[40:43], v[184:187], v[192:195], v[40:43]
	v_mfma_f32_16x16x32_bf16 v[28:31], v[172:175], v[200:203], v[28:31]
	v_mfma_f32_16x16x32_bf16 v[24:27], v[184:187], v[200:203], v[24:27]
	v_mfma_f32_16x16x32_bf16 v[12:15], v[172:175], v[208:211], v[12:15]
	v_mfma_f32_16x16x32_bf16 v[8:11], v[184:187], v[208:211], v[8:11]
	v_mfma_f32_16x16x32_bf16 v[4:7], v[172:175], v[216:219], v[4:7]
	v_mfma_f32_16x16x32_bf16 v[0:3], v[184:187], v[216:219], v[0:3]
	v_mfma_f32_16x16x32_bf16 v[44:47], v[180:183], v[196:199], v[44:47]
	v_mfma_f32_16x16x32_bf16 v[40:43], v[188:191], v[196:199], v[40:43]
	v_mfma_f32_16x16x32_bf16 v[28:31], v[180:183], v[204:207], v[28:31]
	v_mfma_f32_16x16x32_bf16 v[24:27], v[188:191], v[204:207], v[24:27]
	v_mfma_f32_16x16x32_bf16 v[12:15], v[180:183], v[212:215], v[12:15]
	v_mfma_f32_16x16x32_bf16 v[8:11], v[188:191], v[212:215], v[8:11]
	v_mfma_f32_16x16x32_bf16 v[4:7], v[180:183], v[220:223], v[4:7]
	v_mfma_f32_16x16x32_bf16 v[0:3], v[188:191], v[220:223], v[0:3]
	s_setprio 0
	s_barrier
	s_add_u32 s94, s94, 0x100
	s_addc_u32 s95, s95, 0
	s_add_u32 s49, s49, 0x100
	s_addc_u32 s76, s76, 0
	s_cmp_ge_u32 s78, s45
	s_mov_b32 s77, s78
	s_cbranch_scc0 .LBB0_962
	s_setprio 2
	v_add_u32_e32 v141, 0x10000, v135
	ds_read_b128 v[160:163], v141 offset:1024
	ds_read_b128 v[164:167], v141 offset:2048
	ds_read_b128 v[168:171], v141 offset:3072
	v_add_u32_e32 v141, 0x14000, v135
	ds_read_b128 v[172:175], v141
	ds_read_b128 v[180:183], v141 offset:1024
	ds_read_b128 v[184:187], v141 offset:2048
	ds_read_b128 v[188:191], v141 offset:3072
	ds_read_b128 v[192:195], v139
	ds_read_b128 v[196:199], v139 offset:1024
	ds_read_b128 v[200:203], v139 offset:2048
	ds_read_b128 v[204:207], v139 offset:3072
	ds_read_b128 v[208:211], v139 offset:4096
	ds_read_b128 v[212:215], v139 offset:5120
	ds_read_b128 v[216:219], v139 offset:6144
	ds_read_b128 v[220:223], v139 offset:7168
	s_mov_b64 s[94:95], -1
	s_and_b64 vcc, exec, s[50:51]
	s_cbranch_vccz .LBB0_965
	s_mov_b32 s49, s92
	s_ashr_i32 s47, s46, 31
	s_ashr_i32 s45, s44, 31
	s_lshl_b64 s[4:5], s[46:47], 20
	s_lshl_b64 s[42:43], s[44:45], 9
	s_lshl_b64 s[48:49], s[48:49], 23
	v_readlane_b32 s50, v251, 28
	v_readlane_b32 s51, v251, 29
	s_add_u32 s17, s50, s42
	s_addc_u32 s27, s51, s43
	s_add_u32 s17, s17, s48
	s_addc_u32 s27, s27, s49
	s_add_u32 s4, s17, s4
	s_addc_u32 s5, s27, s5
	s_add_u32 s4, s4, 0xfc000000
	s_addc_u32 s5, s5, -1
	s_mov_b64 s[94:95], 0

; __device__ __forceinline__ unsigned cvt_pk_bf16(float lo, float hi) { const f32x2 v = {lo, hi}; return __builtin_bit_cast(unsigned, __builtin_convertvector(v, bf16x2_t)); }
; __device__ __forceinline__ void norm_mod_phase(Frame& F, int L, const float* gvec, int sh_chunk, int nrows, const float* pg, const float* pg2, const float* xlat, const float* xctx) {
;     ...
; #pragma unroll
;         for (int j = 0; j < 8; ++j) ss += (v[j].x * v[j].x + v[j].y * v[j].y) + (v[j].z * v[j].z + v[j].w * v[j].w);
;         const float rstd = rsqrtf(wave_sum(ss, lane) * (1.0f / D) + EPS);
;         u32x2* o = (u32x2*)(A + (size_t)r * D) + lane;
; #pragma unroll
;         for (int j = 0; j < 8; ++j) { const f32x4 y = v[j] * rstd * vq[64 * j] + vq[64 * j + D / 4];
;             u32x2 w; w.x = cvt_pk_bf16(y.x, y.y); w.y = cvt_pk_bf16(y.z, y.w); o[64 * j] = w; }
.LBB0_1041:
	v_pk_mul_f32 v[16:17], v[34:35], v[34:35]
	v_pk_mul_f32 v[20:21], v[38:39], v[38:39]
	v_pk_mul_f32 v[24:25], v[36:37], v[36:37]
	v_pk_mul_f32 v[28:29], v[32:33], v[32:33]
	v_pk_mul_f32 v[8:9], v[42:43], v[42:43]
	v_pk_mul_f32 v[12:13], v[40:41], v[40:41]
	v_mov_b32_e32 v138, v28
	v_mov_b32_e32 v139, v24
	v_mov_b32_e32 v24, v29
	v_mov_b32_e32 v28, v16
	v_mov_b32_e32 v29, v20
	v_mov_b32_e32 v20, v17
	v_pk_add_f32 v[16:17], v[28:29], v[20:21]
	v_pk_mov_b32 v[20:21], v[12:13], v[8:9] op_sel:[1,0]
	v_mov_b32_e32 v13, v9
	v_pk_add_f32 v[8:9], v[20:21], v[12:13]
	v_pk_add_f32 v[24:25], v[138:139], v[24:25]
	v_pk_add_f32 v[8:9], v[8:9], v[8:9] op_sel_hi:[0,1]
	v_mul_f32_e32 v8, v44, v44
	v_pk_add_f32 v[16:17], v[24:25], v[16:17]
	v_pk_fma_f32 v[12:13], v[44:45], v[44:45], v[8:9] op_sel_hi:[1,1,0]
	v_mul_f32_e32 v8, v46, v46
	v_pk_add_f32 v[16:17], v[16:17], v[16:17] op_sel_hi:[0,1]
	v_pk_fma_f32 v[20:21], v[46:47], v[46:47], v[8:9] op_sel_hi:[1,1,0]
	v_mul_f32_e32 v12, v48, v48
	v_mul_f32_e32 v20, v49, v49
	v_mul_f32_e32 v8, v50, v50
	v_mul_f32_e32 v16, v51, v51
	v_pk_mul_f32 v[0:1], v[54:55], v[54:55]
	v_pk_mul_f32 v[4:5], v[52:53], v[52:53]
	v_pk_add_f32 v[12:13], v[12:13], v[20:21]
	v_pk_add_f32 v[8:9], v[8:9], v[16:17]
	s_add_i32 s41, s41, 8
	v_pk_add_f32 v[8:9], v[12:13], v[8:9]
	v_pk_mov_b32 v[12:13], v[4:5], v[0:1] op_sel:[1,0]
	v_mov_b32_e32 v5, v1
	v_pk_add_f32 v[0:1], v[12:13], v[4:5]
	v_pk_add_f32 v[8:9], v[8:9], v[8:9] op_sel_hi:[0,1]
	v_pk_add_f32 v[0:1], v[0:1], v[0:1] op_sel_hi:[0,1]
	v_mul_f32_e32 v0, v56, v56
	v_pk_fma_f32 v[4:5], v[56:57], v[56:57], v[0:1] op_sel_hi:[1,1,0]
	v_mul_f32_e32 v0, v58, v58
	v_pk_fma_f32 v[12:13], v[58:59], v[58:59], v[0:1] op_sel_hi:[1,1,0]
	v_mul_f32_e32 v4, v60, v60
	v_mul_f32_e32 v12, v61, v61
	v_mul_f32_e32 v0, v62, v62
	v_mul_f32_e32 v8, v63, v63
	v_pk_add_f32 v[4:5], v[4:5], v[12:13]
	v_pk_add_f32 v[0:1], v[0:1], v[8:9]
	s_nop 0
	v_pk_add_f32 v[0:1], v[4:5], v[0:1]
	s_nop 0
	v_add_f32_e32 v0, v0, v1
	v_mov_b32_e32 v1, v177
	s_nop 0
	v_add_f32_dpp v0, v0, v0 row_shr:1 row_mask:0xf bank_mask:0xf bound_ctrl:1
	s_nop 1
	v_add_f32_dpp v0, v0, v0 row_shr:2 row_mask:0xf bank_mask:0xf bound_ctrl:1
	s_nop 1
	v_add_f32_dpp v0, v0, v0 row_shr:4 row_mask:0xf bank_mask:0xf bound_ctrl:1
	s_nop 1
	v_add_f32_dpp v0, v0, v0 row_shr:8 row_mask:0xf bank_mask:0xf bound_ctrl:1
	s_nop 1
	v_mov_b32_dpp v1, v0 row_bcast:15 row_mask:0xa bank_mask:0xf
	v_add_f32_e32 v0, v0, v1
	v_mov_b32_e32 v1, v177
	s_nop 1
	v_mov_b32_dpp v1, v0 row_bcast:31 row_mask:0xc bank_mask:0xf
	v_add_f32_e32 v0, v0, v1
	s_nop 0
	v_readlane_b32 s1, v0, 63
	s_nop 1
	v_fma_f32 v0, s1, v241, v238
	v_cmp_gt_f32_e32 vcc, s85, v0
	v_mul_f32_e32 v1, 0x4b800000, v0
	s_ashr_i32 s1, s0, 31
	v_cndmask_b32_e32 v0, v0, v1, vcc
	v_rsq_f32_e32 v0, v0
	s_lshl_b64 s[0:1], s[0:1], 12
	s_cmp_lt_i32 s41, s6
	v_mul_f32_e32 v1, 0x45800000, v0
	v_cndmask_b32_e32 v4, v0, v1, vcc
	v_pk_mul_f32 v[8:9], v[32:33], v[4:5] op_sel_hi:[1,0]
	v_pk_mul_f32 v[12:13], v[34:35], v[4:5] op_sel_hi:[1,0]
	ds_read_b128 v[32:35], v157
	ds_read_b128 v[138:141], v157 offset:8192
	v_lshl_add_u64 v[0:1], v[66:67], 0, s[0:1]
	s_waitcnt lgkmcnt(0)
	v_pk_fma_f32 v[12:13], v[34:35], v[12:13], v[140:141]
	v_pk_fma_f32 v[8:9], v[32:33], v[8:9], v[138:139]
	s_nop 0
	v_cvt_pk_bf16_f32 v8, v8, v9
	v_cvt_pk_bf16_f32 v9, v12, v13
	global_store_dwordx2 v[0:1], v[8:9], off sc1
	v_pk_mul_f32 v[8:9], v[36:37], v[4:5] op_sel_hi:[1,0]
	v_pk_mul_f32 v[12:13], v[38:39], v[4:5] op_sel_hi:[1,0]
	ds_read_b128 v[32:35], v157 offset:1024
	ds_read_b128 v[36:39], v157 offset:9216
	s_waitcnt lgkmcnt(0)
	v_pk_fma_f32 v[12:13], v[34:35], v[12:13], v[38:39]
	v_pk_fma_f32 v[8:9], v[32:33], v[8:9], v[36:37]
	s_nop 0
	v_cvt_pk_bf16_f32 v8, v8, v9
	v_cvt_pk_bf16_f32 v9, v12, v13
	global_store_dwordx2 v[0:1], v[8:9], off offset:512 sc1
	ds_read_b128 v[32:35], v157 offset:2048
	ds_read_b128 v[36:39], v157 offset:10240
	v_pk_mul_f32 v[8:9], v[40:41], v[4:5] op_sel_hi:[1,0]
	v_pk_mul_f32 v[12:13], v[42:43], v[4:5] op_sel_hi:[1,0]
	v_mov_b32_e32 v40, v31
	v_mov_b32_e32 v41, v27
	s_waitcnt lgkmcnt(0)
	v_pk_fma_f32 v[12:13], v[34:35], v[12:13], v[38:39]
	v_pk_fma_f32 v[8:9], v[32:33], v[8:9], v[36:37]
	v_mov_b32_e32 v42, v23
	v_cvt_pk_bf16_f32 v8, v8, v9
	v_cvt_pk_bf16_f32 v9, v12, v13
	global_store_dwordx2 v[0:1], v[8:9], off offset:1024 sc1
	ds_read_b128 v[32:35], v157 offset:3072
	ds_read_b128 v[36:39], v157 offset:11264
	v_pk_mul_f32 v[8:9], v[44:45], v[4:5] op_sel_hi:[1,0]
	v_pk_mul_f32 v[12:13], v[46:47], v[4:5] op_sel_hi:[1,0]
	v_mov_b32_e32 v43, v19
	v_mov_b32_e32 v44, v15
	s_waitcnt lgkmcnt(0)
	v_pk_fma_f32 v[12:13], v[12:13], v[34:35], v[38:39]
	v_pk_fma_f32 v[8:9], v[8:9], v[32:33], v[36:37]
	v_mov_b32_e32 v45, v11
	v_cvt_pk_bf16_f32 v8, v8, v9
	v_cvt_pk_bf16_f32 v9, v12, v13
	global_store_dwordx2 v[0:1], v[8:9], off offset:1536 sc1
	ds_read_b128 v[32:35], v157 offset:4096
	ds_read_b128 v[36:39], v157 offset:12288
	v_pk_mul_f32 v[8:9], v[48:49], v[4:5] op_sel_hi:[1,0]
	v_pk_mul_f32 v[12:13], v[50:51], v[4:5] op_sel_hi:[1,0]
	v_mov_b32_e32 v46, v7
	v_mov_b32_e32 v47, v3
	s_waitcnt lgkmcnt(0)
	v_pk_fma_f32 v[12:13], v[12:13], v[34:35], v[38:39]
	v_pk_fma_f32 v[8:9], v[8:9], v[32:33], v[36:37]
	s_nop 0
	v_cvt_pk_bf16_f32 v8, v8, v9
	v_cvt_pk_bf16_f32 v9, v12, v13
	global_store_dwordx2 v[0:1], v[8:9], off offset:2048 sc1
	ds_read_b128 v[32:35], v157 offset:5120
	ds_read_b128 v[36:39], v157 offset:13312
	v_pk_mul_f32 v[8:9], v[52:53], v[4:5] op_sel_hi:[1,0]
	v_pk_mul_f32 v[12:13], v[54:55], v[4:5] op_sel_hi:[1,0]
	s_waitcnt lgkmcnt(0)
	v_pk_fma_f32 v[8:9], v[8:9], v[32:33], v[36:37]
	v_pk_fma_f32 v[12:13], v[12:13], v[34:35], v[38:39]
	v_cvt_pk_bf16_f32 v8, v8, v9
	v_cvt_pk_bf16_f32 v9, v12, v13
	global_store_dwordx2 v[0:1], v[8:9], off offset:2560 sc1
	ds_read_b128 v[32:35], v157 offset:6144
	ds_read_b128 v[36:39], v157 offset:14336
	v_pk_mul_f32 v[8:9], v[56:57], v[4:5] op_sel_hi:[1,0]
	v_pk_mul_f32 v[12:13], v[58:59], v[4:5] op_sel_hi:[1,0]
	s_waitcnt lgkmcnt(0)
	v_pk_fma_f32 v[8:9], v[8:9], v[32:33], v[36:37]
	v_pk_fma_f32 v[12:13], v[12:13], v[34:35], v[38:39]
	v_cvt_pk_bf16_f32 v8, v8, v9
	v_cvt_pk_bf16_f32 v9, v12, v13
	global_store_dwordx2 v[0:1], v[8:9], off offset:3072 sc1
	ds_read_b128 v[32:35], v157 offset:7168
	ds_read_b128 v[36:39], v157 offset:15360
	v_pk_mul_f32 v[8:9], v[60:61], v[4:5] op_sel_hi:[1,0]
	v_pk_mul_f32 v[4:5], v[62:63], v[4:5] op_sel_hi:[1,0]
	s_waitcnt lgkmcnt(0)
	v_pk_fma_f32 v[8:9], v[8:9], v[32:33], v[36:37]
	v_pk_fma_f32 v[4:5], v[4:5], v[34:35], v[38:39]
	v_cvt_pk_bf16_f32 v8, v8, v9
	v_cvt_pk_bf16_f32 v9, v4, v5
	v_mov_b32_e32 v32, v30
	v_mov_b32_e32 v33, v26
	v_mov_b32_e32 v34, v22
	v_mov_b32_e32 v35, v18
	v_mov_b32_e32 v36, v14
	v_mov_b32_e32 v37, v10
	v_mov_b32_e32 v38, v6
	v_mov_b32_e32 v39, v2
	global_store_dwordx2 v[0:1], v[8:9], off offset:3584 sc1
	s_cbranch_scc0 .LBB0_1058

; #define LAS __attribute__((address_space(3)))
; __device__ __forceinline__ unsigned cvt_pk_bf16(float lo, float hi) { const f32x2 v = {lo, hi}; return __builtin_bit_cast(unsigned, __builtin_convertvector(v, bf16x2_t)); }
; __device__ __forceinline__ float bf_lo(unsigned u) { return __uint_as_float(u << 16); }
; __device__ __forceinline__ float bf_hi(unsigned u) { return __uint_as_float(u & 0xffff0000u); }
; __device__ __forceinline__ void norm_mod_phase(Frame& F, int L, const float* gvec, int sh_chunk, int nrows, const float* pg, const float* pg2, const float* xlat, const float* xctx) {
;     ...
;         if (hc) {
;             const LAS f32x4* gq = vq + 2 * (D / 4); u32x2* xw_ = (u32x2*)((bf16_t*)(F.ws + WS_XC) + (size_t)(r - MLAT) * D) + lane;
; #pragma unroll
;             for (int j = 0; j < 8; ++j) { f32x4 p = {0.f, 0.f, 0.f, 0.f};
; #pragma unroll
;                 for (int q = 0; q < 4; ++q) { const u32x2 w = aux[q][j]; p += (f32x4){bf_lo(w.x), bf_hi(w.x), bf_lo(w.y), bf_hi(w.y)}; }
;                 v[j] += gq[64 * j] * p; u32x2 w; w.x = cvt_pk_bf16(v[j].x, v[j].y); w.y = cvt_pk_bf16(v[j].z, v[j].w); xw_[64 * j] = w; }
.LBB0_1052:
	s_and_b64 vcc, exec, s[36:37]
	s_cbranch_vccnz .LBB0_1041
	v_pk_add_f32 v[154:155], v[154:155], 0 op_sel_hi:[1,0]
	v_pk_add_f32 v[152:153], v[152:153], 0 op_sel_hi:[1,0]
	v_lshlrev_b32_e32 v158, 16, v88
	v_and_b32_e32 v159, 0xffff0000, v88
	v_lshlrev_b32_e32 v160, 16, v89
	v_and_b32_e32 v161, 0xffff0000, v89
	v_pk_add_f32 v[152:153], v[152:153], v[158:159]
	v_pk_add_f32 v[154:155], v[154:155], v[160:161]
	v_lshlrev_b32_e32 v158, 16, v116
	v_and_b32_e32 v159, 0xffff0000, v116
	v_lshlrev_b32_e32 v160, 16, v117
	v_and_b32_e32 v161, 0xffff0000, v117
	v_pk_add_f32 v[154:155], v[154:155], v[160:161]
	v_pk_add_f32 v[152:153], v[152:153], v[158:159]
	v_lshlrev_b32_e32 v158, 16, v136
	v_and_b32_e32 v159, 0xffff0000, v136
	v_lshlrev_b32_e32 v160, 16, v137
	v_and_b32_e32 v161, 0xffff0000, v137
	v_pk_add_f32 v[158:159], v[152:153], v[158:159]
	v_pk_add_f32 v[160:161], v[154:155], v[160:161]
	ds_read_b128 v[152:155], v157 offset:16384
	s_add_i32 s4, s0, 0xffffc000
	s_mov_b32 s5, s92
	s_lshl_b64 s[4:5], s[4:5], 12
	v_lshl_add_u64 v[0:1], v[72:73], 0, s[4:5]
	s_waitcnt lgkmcnt(0)
	v_pk_fma_f32 v[34:35], v[160:161], v[154:155], v[34:35]
	v_pk_fma_f32 v[32:33], v[158:159], v[152:153], v[32:33]
	v_cvt_pk_bf16_f32 v153, v34, v35
	v_cvt_pk_bf16_f32 v152, v32, v33
	global_store_dwordx2 v[0:1], v[152:153], off sc1
	v_pk_add_f32 v[150:151], v[150:151], 0 op_sel_hi:[1,0]
	v_pk_add_f32 v[148:149], v[148:149], 0 op_sel_hi:[1,0]
	v_lshlrev_b32_e32 v152, 16, v86
	v_and_b32_e32 v153, 0xffff0000, v86
	v_lshlrev_b32_e32 v154, 16, v87
	v_and_b32_e32 v155, 0xffff0000, v87
	v_pk_add_f32 v[148:149], v[148:149], v[152:153]
	v_pk_add_f32 v[150:151], v[150:151], v[154:155]
	v_lshlrev_b32_e32 v152, 16, v114
	v_and_b32_e32 v153, 0xffff0000, v114
	v_lshlrev_b32_e32 v154, 16, v115
	v_and_b32_e32 v155, 0xffff0000, v115
	v_pk_add_f32 v[150:151], v[150:151], v[154:155]
	v_pk_add_f32 v[148:149], v[148:149], v[152:153]
	v_lshlrev_b32_e32 v152, 16, v134
	v_and_b32_e32 v153, 0xffff0000, v134
	v_lshlrev_b32_e32 v154, 16, v135
	v_and_b32_e32 v155, 0xffff0000, v135
	v_pk_add_f32 v[152:153], v[148:149], v[152:153]
	v_pk_add_f32 v[154:155], v[150:151], v[154:155]
	ds_read_b128 v[148:151], v157 offset:17408
	v_pk_add_f32 v[146:147], v[146:147], 0 op_sel_hi:[1,0]
	v_pk_add_f32 v[144:145], v[144:145], 0 op_sel_hi:[1,0]
	v_pk_add_f32 v[142:143], v[142:143], 0 op_sel_hi:[1,0]
	v_pk_add_f32 v[140:141], v[140:141], 0 op_sel_hi:[1,0]
	s_waitcnt lgkmcnt(0)
	v_pk_fma_f32 v[38:39], v[154:155], v[150:151], v[38:39]
	v_pk_fma_f32 v[36:37], v[152:153], v[148:149], v[36:37]
	v_cvt_pk_bf16_f32 v149, v38, v39
	v_cvt_pk_bf16_f32 v148, v36, v37
	global_store_dwordx2 v[0:1], v[148:149], off offset:512 sc1
	v_lshlrev_b32_e32 v148, 16, v84
	v_and_b32_e32 v149, 0xffff0000, v84
	v_lshlrev_b32_e32 v150, 16, v85
	v_and_b32_e32 v151, 0xffff0000, v85
	v_pk_add_f32 v[144:145], v[144:145], v[148:149]
	v_pk_add_f32 v[146:147], v[146:147], v[150:151]
	v_lshlrev_b32_e32 v148, 16, v112
	v_and_b32_e32 v149, 0xffff0000, v112
	v_lshlrev_b32_e32 v150, 16, v113
	v_and_b32_e32 v151, 0xffff0000, v113
	v_pk_add_f32 v[146:147], v[146:147], v[150:151]
	v_pk_add_f32 v[144:145], v[144:145], v[148:149]
	v_lshlrev_b32_e32 v148, 16, v132
	v_and_b32_e32 v149, 0xffff0000, v132
	v_lshlrev_b32_e32 v150, 16, v133
	v_and_b32_e32 v151, 0xffff0000, v133
	v_pk_add_f32 v[148:149], v[144:145], v[148:149]
	v_pk_add_f32 v[150:151], v[146:147], v[150:151]
	ds_read_b128 v[144:147], v157 offset:18432
	v_pk_add_f32 v[138:139], v[138:139], 0 op_sel_hi:[1,0]
	v_pk_add_f32 v[28:29], v[28:29], 0 op_sel_hi:[1,0]
	v_pk_add_f32 v[24:25], v[24:25], 0 op_sel_hi:[1,0]
	v_pk_add_f32 v[20:21], v[20:21], 0 op_sel_hi:[1,0]
	s_waitcnt lgkmcnt(0)
	v_pk_fma_f32 v[42:43], v[150:151], v[146:147], v[42:43]
	v_pk_fma_f32 v[40:41], v[148:149], v[144:145], v[40:41]
	v_cvt_pk_bf16_f32 v145, v42, v43
	v_cvt_pk_bf16_f32 v144, v40, v41
	global_store_dwordx2 v[0:1], v[144:145], off offset:1024 sc1
	v_lshlrev_b32_e32 v144, 16, v82
	v_and_b32_e32 v145, 0xffff0000, v82
	v_lshlrev_b32_e32 v146, 16, v83
	v_and_b32_e32 v147, 0xffff0000, v83
	v_pk_add_f32 v[140:141], v[140:141], v[144:145]
	v_pk_add_f32 v[142:143], v[142:143], v[146:147]
	v_lshlrev_b32_e32 v144, 16, v110
	v_and_b32_e32 v145, 0xffff0000, v110
	v_lshlrev_b32_e32 v146, 16, v111
	v_and_b32_e32 v147, 0xffff0000, v111
	v_pk_add_f32 v[142:143], v[142:143], v[146:147]
	v_pk_add_f32 v[140:141], v[140:141], v[144:145]
	v_lshlrev_b32_e32 v144, 16, v130
	v_and_b32_e32 v145, 0xffff0000, v130
	v_lshlrev_b32_e32 v146, 16, v131
	v_and_b32_e32 v147, 0xffff0000, v131
	v_pk_add_f32 v[144:145], v[140:141], v[144:145]
	v_pk_add_f32 v[146:147], v[142:143], v[146:147]
	ds_read_b128 v[140:143], v157 offset:19456
	v_pk_add_f32 v[16:17], v[16:17], 0 op_sel_hi:[1,0]
	v_pk_add_f32 v[12:13], v[12:13], 0 op_sel_hi:[1,0]
	v_pk_add_f32 v[8:9], v[8:9], 0 op_sel_hi:[1,0]
	v_pk_add_f32 v[4:5], v[4:5], 0 op_sel_hi:[1,0]
	s_waitcnt lgkmcnt(0)
; #define LAS __attribute__((address_space(3)))
; __device__ __forceinline__ unsigned cvt_pk_bf16(float lo, float hi) { const f32x2 v = {lo, hi}; return __builtin_bit_cast(unsigned, __builtin_convertvector(v, bf16x2_t)); }
; __device__ __forceinline__ float bf_lo(unsigned u) { return __uint_as_float(u << 16); }
; __device__ __forceinline__ float bf_hi(unsigned u) { return __uint_as_float(u & 0xffff0000u); }
; __device__ __forceinline__ void norm_mod_phase(Frame& F, int L, const float* gvec, int sh_chunk, int nrows, const float* pg, const float* pg2, const float* xlat, const float* xctx) {
;     ...
;         if (hc) {
;             const LAS f32x4* gq = vq + 2 * (D / 4); u32x2* xw_ = (u32x2*)((bf16_t*)(F.ws + WS_XC) + (size_t)(r - MLAT) * D) + lane;
; #pragma unroll
;             for (int j = 0; j < 8; ++j) { f32x4 p = {0.f, 0.f, 0.f, 0.f};
; #pragma unroll
;                 for (int q = 0; q < 4; ++q) { const u32x2 w = aux[q][j]; p += (f32x4){bf_lo(w.x), bf_hi(w.x), bf_lo(w.y), bf_hi(w.y)}; }
;                 v[j] += gq[64 * j] * p; u32x2 w; w.x = cvt_pk_bf16(v[j].x, v[j].y); w.y = cvt_pk_bf16(v[j].z, v[j].w); xw_[64 * j] = w; }
	v_pk_fma_f32 v[46:47], v[146:147], v[142:143], v[46:47]
	v_pk_fma_f32 v[44:45], v[144:145], v[140:141], v[44:45]
	v_cvt_pk_bf16_f32 v141, v46, v47
	v_cvt_pk_bf16_f32 v140, v44, v45
	global_store_dwordx2 v[0:1], v[140:141], off offset:1536 sc1
	v_lshlrev_b32_e32 v140, 16, v80
	v_and_b32_e32 v141, 0xffff0000, v80
	v_lshlrev_b32_e32 v142, 16, v81
	v_and_b32_e32 v143, 0xffff0000, v81
	v_pk_add_f32 v[28:29], v[28:29], v[140:141]
	v_pk_add_f32 v[138:139], v[138:139], v[142:143]
	v_lshlrev_b32_e32 v140, 16, v108
	v_and_b32_e32 v141, 0xffff0000, v108
	v_lshlrev_b32_e32 v142, 16, v109
	v_and_b32_e32 v143, 0xffff0000, v109
	v_pk_add_f32 v[138:139], v[138:139], v[142:143]
	v_pk_add_f32 v[28:29], v[28:29], v[140:141]
	v_lshlrev_b32_e32 v140, 16, v128
	v_and_b32_e32 v141, 0xffff0000, v128
	v_lshlrev_b32_e32 v142, 16, v129
	v_and_b32_e32 v143, 0xffff0000, v129
	v_pk_add_f32 v[28:29], v[28:29], v[140:141]
	v_pk_add_f32 v[142:143], v[138:139], v[142:143]
	ds_read_b128 v[138:141], v157 offset:20480
	s_waitcnt lgkmcnt(0)
	v_pk_fma_f32 v[48:49], v[28:29], v[138:139], v[48:49]
	v_lshlrev_b32_e32 v138, 16, v79
	v_and_b32_e32 v139, 0xffff0000, v79
	v_pk_add_f32 v[24:25], v[24:25], v[138:139]
	v_lshlrev_b32_e32 v138, 16, v107
	v_and_b32_e32 v139, 0xffff0000, v107
	v_pk_fma_f32 v[50:51], v[142:143], v[140:141], v[50:51]
	v_pk_add_f32 v[24:25], v[24:25], v[138:139]
	v_lshlrev_b32_e32 v138, 16, v127
	v_and_b32_e32 v139, 0xffff0000, v127
	v_cvt_pk_bf16_f32 v28, v48, v49
	v_cvt_pk_bf16_f32 v29, v50, v51
	v_pk_add_f32 v[24:25], v[24:25], v[138:139]
	ds_read_b128 v[138:141], v157 offset:21504
	global_store_dwordx2 v[0:1], v[28:29], off offset:2048 sc1
	v_lshlrev_b32_e32 v28, 16, v78
	v_and_b32_e32 v29, 0xffff0000, v78
	v_pk_add_f32 v[20:21], v[20:21], v[28:29]
	v_lshlrev_b32_e32 v28, 16, v106
	v_and_b32_e32 v29, 0xffff0000, v106
	v_pk_add_f32 v[20:21], v[20:21], v[28:29]
	v_lshlrev_b32_e32 v28, 16, v126
	v_and_b32_e32 v29, 0xffff0000, v126
	v_pk_add_f32 v[20:21], v[20:21], v[28:29]
	s_waitcnt lgkmcnt(0)
	v_pk_fma_f32 v[54:55], v[24:25], v[140:141], v[54:55]
	v_pk_fma_f32 v[52:53], v[20:21], v[138:139], v[52:53]
	v_cvt_pk_bf16_f32 v21, v54, v55
	v_cvt_pk_bf16_f32 v20, v52, v53
	ds_read_b128 v[138:141], v157 offset:22528
	global_store_dwordx2 v[0:1], v[20:21], off offset:2560 sc1
	v_lshlrev_b32_e32 v20, 16, v76
	v_and_b32_e32 v21, 0xffff0000, v76
	v_lshlrev_b32_e32 v24, 16, v77
	v_and_b32_e32 v25, 0xffff0000, v77
	v_pk_add_f32 v[12:13], v[12:13], v[20:21]
	v_pk_add_f32 v[16:17], v[16:17], v[24:25]
	v_lshlrev_b32_e32 v20, 16, v104
	v_and_b32_e32 v21, 0xffff0000, v104
	v_lshlrev_b32_e32 v24, 16, v105
	v_and_b32_e32 v25, 0xffff0000, v105
	v_pk_add_f32 v[16:17], v[16:17], v[24:25]
	v_pk_add_f32 v[12:13], v[12:13], v[20:21]
	v_lshlrev_b32_e32 v20, 16, v124
	v_and_b32_e32 v21, 0xffff0000, v124
	v_lshlrev_b32_e32 v24, 16, v125
	v_and_b32_e32 v25, 0xffff0000, v125
	v_pk_add_f32 v[12:13], v[12:13], v[20:21]
	v_pk_add_f32 v[16:17], v[16:17], v[24:25]
	s_waitcnt lgkmcnt(0)
	v_pk_fma_f32 v[56:57], v[12:13], v[138:139], v[56:57]
	v_pk_fma_f32 v[58:59], v[16:17], v[140:141], v[58:59]
	v_cvt_pk_bf16_f32 v12, v56, v57
	v_cvt_pk_bf16_f32 v13, v58, v59
	ds_read_b128 v[138:141], v157 offset:23552
	global_store_dwordx2 v[0:1], v[12:13], off offset:3072 sc1
	v_lshlrev_b32_e32 v12, 16, v74
	v_and_b32_e32 v13, 0xffff0000, v74
	v_lshlrev_b32_e32 v16, 16, v75
	v_and_b32_e32 v17, 0xffff0000, v75
	v_pk_add_f32 v[4:5], v[4:5], v[12:13]
	v_pk_add_f32 v[8:9], v[8:9], v[16:17]
	v_lshlrev_b32_e32 v12, 16, v102
	v_and_b32_e32 v13, 0xffff0000, v102
	v_lshlrev_b32_e32 v16, 16, v103
	v_and_b32_e32 v17, 0xffff0000, v103
	v_pk_add_f32 v[8:9], v[8:9], v[16:17]
	v_pk_add_f32 v[4:5], v[4:5], v[12:13]
	v_lshlrev_b32_e32 v12, 16, v122
	v_and_b32_e32 v13, 0xffff0000, v122
	v_lshlrev_b32_e32 v16, 16, v123
	v_and_b32_e32 v17, 0xffff0000, v123
	v_pk_add_f32 v[4:5], v[4:5], v[12:13]
	v_pk_add_f32 v[8:9], v[8:9], v[16:17]
	s_waitcnt lgkmcnt(0)
	v_pk_fma_f32 v[60:61], v[4:5], v[138:139], v[60:61]
	v_pk_fma_f32 v[62:63], v[8:9], v[140:141], v[62:63]
	v_cvt_pk_bf16_f32 v4, v60, v61
	v_cvt_pk_bf16_f32 v5, v62, v63
	global_store_dwordx2 v[0:1], v[4:5], off offset:3584 sc1
	s_branch .LBB0_1041

; __device__ __forceinline__ int fresh_lane() { int l; asm volatile("v_mbcnt_lo_u32_b32 %0, -1, 0\n\tv_mbcnt_hi_u32_b32 %0, -1, %0" : "=v"(l)); return l; }
; #define PG8_STAGE(bufoff, gbase, voff) do { _Pragma("unroll") for (int _i = 0; _i < 2; ++_i) \
;         __builtin_amdgcn_global_load_lds((const unsigned*)((const char*)(gbase) + (voff)[_i]), (LAS unsigned*)(lds + (bufoff) + ldsw + _i * 8192), 16, 0, 0); } while (0)
; #define PG8_WAIT_V(n) asm volatile("s_waitcnt vmcnt(" #n ")" ::: "memory")
; #define PG8_BAR __builtin_amdgcn_s_barrier()
; template <class Epi, class Sched, bool ALIGN_EPI>
; __device__ __forceinline__ void gemm_phase(LAS unsigned char* lds, const int wid, const int lda_, const int ldb_, const int K_, const Sched& S, const Epi& E) {
;     ...
;     const int lane = fresh_lane(), tid = wid * 64 + lane;
;     const int wr = wid >> 2, wc = wid & 3, fr = lane & 15, fq = lane >> 4;
;     unsigned voffA[2], voffB[2];
; #pragma unroll
;     for (int i = 0; i < 2; ++i) { int R, C; stage_rc(tid * 16 + i * 8192, R, C); const int Rb = Epi::PERM ? ((R & ~31) + perm32(R & 31)) : R;
;         voffA[i] = (unsigned)(R * lda + C) * 2u; voffB[i] = (unsigned)(Rb * ldb + C) * 2u; }
;     const size_t kstep = (size_t)(BK * 2);
;     const size_t hstepA = (size_t)HALF * lda * 2, hstepB = (size_t)HALF * ldb * 2;
;     const unsigned ldsw = (unsigned)wid * 1024u;
;     const int aoff = lds_byte(wr * 64 + fr, fq * 8), boff = lds_byte(wc * 32 + fr, fq * 8);
;     ...
;     Unit cur, nxt; int ui = 0;
;     if (!S.next(0, cur)) return;
;     f32x4 acc[2][2][4][2];
; #pragma unroll
;     for (int a = 0; a < 2; ++a)
; #pragma unroll
;         for (int b = 0; b < 2; ++b)
; #pragma unroll
;             for (int m = 0; m < 4; ++m)
; #pragma unroll
;                 for (int n = 0; n < 2; ++n) acc[a][b][m][n] = (f32x4){0.f, 0.f, 0.f, 0.f};
;     bf16x8 At[4][2], B0[2][2], B1[2][2];
;     const char* cA = S.a(cur); const char* cB = S.b(cur);
;     PG8_STAGE(PG8_SB(0, 0), cB, voffB); PG8_STAGE(PG8_SB(0, 1), cB + hstepB, voffB); PG8_STAGE(PG8_SA(0, 0), cA, voffA); PG8_STAGE(PG8_SA(0, 1), cA + hstepA, voffA);
;     if (wr == 1) PG8_BAR;
;     PG8_WAIT_V(2); PG8_BAR;
;     PG8_STAGE(PG8_SB(1, 0), cB + kstep, voffB); PG8_STAGE(PG8_SA(1, 0), cA + kstep, voffA); PG8_STAGE(PG8_SB(1, 1), cB + hstepB + kstep, voffB);
;     PG8_WAIT_V(6); PG8_BAR;
.LBB0_1116:
	v_mov_b32_e32 v129, v177
	v_lshl_add_u64 v[12:13], s[4:5], 0, v[176:177]
	v_lshl_add_u64 v[14:15], s[4:5], 0, v[128:129]
	v_and_b32_e32 v7, 15, v6
	v_readlane_b32 s4, v252, 46
	v_and_b32_e32 v23, 48, v6
	v_ashrrev_i32_e32 v21, 6, v6
	v_or_b32_e32 v134, s4, v7
	v_lshlrev_b32_e32 v22, 6, v134
	s_movk_i32 s4, 0x3c0
	v_and_or_b32 v22, v22, s4, v23
	v_readlane_b32 s4, v252, 47
	v_ashrrev_i32_e32 v20, 1, v6
	v_lshlrev_b32_e32 v6, 2, v6
	v_lshl_add_u32 v24, v21, 10, s4
	v_readlane_b32 s4, v252, 49
	v_lshl_add_u64 v[8:9], s[50:51], 0, v[176:177]
	v_lshl_or_b32 v7, v7, 6, v23
	v_add_lshl_u32 v21, v21, s4, 10
	v_and_b32_e32 v6, 32, v6
	v_lshl_add_u64 v[10:11], s[50:51], 0, v[128:129]
	v_mov_b32_e32 v133, v177
	v_bitop3_b32 v135, v7, v21, v6 bitop3:0xde
	v_lshl_add_u64 v[6:7], v[8:9], 0, s[24:25]
	s_add_i32 m0, s16, 0x18000
	v_lshl_add_u64 v[16:17], s[40:41], 0, v[132:133]
	v_mov_b32_e32 v131, v177
	s_waitcnt vmcnt(2)
	s_barrier
	global_load_lds_dwordx4 v[6:7], off
	v_lshl_add_u64 v[6:7], v[10:11], 0, s[24:25]
	s_add_i32 m0, s16, 0x1a000
	s_add_i32 s73, s16, 0x8000
	v_lshl_add_u64 v[18:19], s[40:41], 0, v[130:131]
	global_load_lds_dwordx4 v[6:7], off
	v_lshl_add_u64 v[6:7], v[16:17], 0, s[24:25]
	s_mov_b32 m0, s73
	s_add_i32 s74, s16, 0xa000
	global_load_lds_dwordx4 v[6:7], off
	v_lshl_add_u64 v[6:7], v[18:19], 0, s[24:25]
	s_mov_b32 m0, s74
	v_add_u32_e32 v0, v2, v0
	global_load_lds_dwordx4 v[6:7], off
	v_lshl_add_u64 v[6:7], v[12:13], 0, s[24:25]
	s_add_i32 m0, s16, 0x1c000
	v_lshlrev_b32_e32 v25, 2, v134
	global_load_lds_dwordx4 v[6:7], off
	v_lshl_add_u64 v[6:7], v[14:15], 0, s[24:25]
	s_add_i32 m0, s16, 0x1e000
	v_add_lshl_u32 v0, v0, v1, 1
	global_load_lds_dwordx4 v[6:7], off
	v_mov_b32_e32 v1, v177
	v_and_b32_e32 v20, -8, v20
	v_and_b32_e32 v25, 32, v25
	s_waitcnt vmcnt(6)
	v_readlane_b32 s4, v252, 48
	v_lshl_add_u64 v[152:153], s[10:11], 0, v[0:1]
	v_add_u32_e32 v0, v5, v3
	v_bitop3_b32 v22, v22, v24, v25 bitop3:0xde
	v_add_u32_e32 v136, s4, v20
	v_add_lshl_u32 v0, v0, v4, 1
	v_ashrrev_i32_e32 v137, 31, v136
	v_or_b32_e32 v138, 16, v134
	v_or_b32_e32 v140, 32, v134
	v_or_b32_e32 v142, 48, v134
	v_add_u32_e32 v144, 0x80, v134
	v_add_u32_e32 v146, 0x90, v134
	v_add_u32_e32 v148, 0xa0, v134
	v_add_u32_e32 v150, 0xb0, v134
	v_lshl_add_u64 v[154:155], s[10:11], 0, v[0:1]
	s_mov_b32 s75, 0
	v_add_u32_e32 v139, 0, v22
	s_barrier
	v_add_u32_e32 v141, 0x10000, v135
	ds_read_b128 v[160:163], v141
	ds_read_b128 v[164:167], v141 offset:1024
	ds_read_b128 v[168:171], v141 offset:2048
	ds_read_b128 v[172:175], v141 offset:3072
	v_add_u32_e32 v141, 0x14000, v135
	ds_read_b128 v[180:183], v141
	ds_read_b128 v[184:187], v141 offset:1024
	ds_read_b128 v[188:191], v141 offset:2048
	ds_read_b128 v[192:195], v141 offset:3072
	ds_read_b128 v[196:199], v139
	ds_read_b128 v[200:203], v139 offset:1024
	ds_read_b128 v[204:207], v139 offset:2048
	ds_read_b128 v[208:211], v139 offset:3072
	ds_read_b128 v[212:215], v139 offset:4096
	ds_read_b128 v[216:219], v139 offset:5120
	ds_read_b128 v[220:223], v139 offset:6144
	ds_read_b128 v[224:227], v139 offset:7168

; #define PG8_STAGE(bufoff, gbase, voff) do { _Pragma("unroll") for (int _i = 0; _i < 2; ++_i) \
;         __builtin_amdgcn_global_load_lds((const unsigned*)((const char*)(gbase) + (voff)[_i]), (LAS unsigned*)(lds + (bufoff) + ldsw + _i * 8192), 16, 0, 0); } while (0)
; #define PG8_LDA(dst, b, h) do { _Pragma("unroll") for (int m = 0; m < 4; ++m) _Pragma("unroll") for (int k = 0; k < 2; ++k) dst[m][k] = *(const LAS bf16x8*)(lds + PG8_SA(b, h) + aoff + m * 2048 + k * 1024); } while (0)
; #define PG8_LDB(dst, b, h) do { _Pragma("unroll") for (int n = 0; n < 2; ++n) _Pragma("unroll") for (int k = 0; k < 2; ++k) dst[n][k] = *(const LAS bf16x8*)(lds + PG8_SB(b, h) + boff + n * 2048 + k * 1024); } while (0)
; #define PG8_MMA(ai, bj, At, Bt) do { __builtin_amdgcn_s_setprio(1); _Pragma("unroll") for (int m = 0; m < 4; ++m) _Pragma("unroll") for (int n = 0; n < 2; ++n) _Pragma("unroll") for (int k = 0; k < 2; ++k) \
;         acc[ai][bj][m][n] = __builtin_amdgcn_mfma_f32_16x16x32_bf16(Bt[n][k], At[m][k], acc[ai][bj][m][n], 0, 0, 0); __builtin_amdgcn_s_setprio(0); } while (0)
; template <class Epi, class Sched, bool ALIGN_EPI>
; __device__ __forceinline__ void gemm_phase(LAS unsigned char* lds, const int wid, const int lda_, const int ldb_, const int K_, const Sched& S, const Epi& E) {
;     ...
;         const bool has_next = S.next(ui + 1, nxt);
;         const int nt = S.nt(cur);
;         const char* nA = has_next ? S.a(nxt) : cA; const char* nB = has_next ? S.b(nxt) : cB;
; #pragma unroll 1
;         for (int t = 0; t < nt; t += 2) {
;             const bool last = (t == nt - 2);
;             const char* a1 = cA + (size_t)(t + 1) * kstep;
;             const char* a2 = last ? nA : cA + (size_t)(t + 2) * kstep; const char* b2 = last ? nB : cB + (size_t)(t + 2) * kstep;
;             const char* a3 = a2 + kstep; const char* b3 = b2 + kstep;
;             PG8_LDB(B0, 0, 0); PG8_LDB(B1, 0, 1); PG8_SCHED; PG8_LDA(At, 0, 0); PG8_STAGE(PG8_SA(1, 1), a1 + hstepA, voffA);
;             PG8_WAIT_V(8); PG8_WAIT_L(0); PG8_BAR; PG8_MMA(0, 0, At, B0); PG8_MMA(0, 1, At, B1); PG8_BAR; PG8_SCHED;
;             PG8_LDA(At, 0, 1); PG8_STAGE(PG8_SB(0, 0), b2, voffB); PG8_STAGE(PG8_SB(0, 1), b2 + hstepB, voffB); PG8_STAGE(PG8_SA(0, 0), a2, voffA);
;             PG8_WAIT_V(8); PG8_WAIT_L(0); PG8_BAR; PG8_MMA(1, 0, At, B0); PG8_MMA(1, 1, At, B1); PG8_BAR; PG8_SCHED;
.LBB0_1119:
	v_mov_b64_e32 v[0:1], s[0:1]
	s_ashr_i32 s45, s44, 31
	v_cmp_lt_i64_e32 vcc, s[4:5], v[0:1]
	s_lshl_b64 s[4:5], s[44:45], 20
	v_readlane_b32 s46, v253, 52
	v_readlane_b32 s47, v253, 53
	s_add_u32 s46, s46, s4
	s_addc_u32 s47, s47, s5
	s_and_b64 s[4:5], vcc, exec
	s_cselect_b32 s4, s47, s41
	s_cselect_b32 s5, s46, s40
	s_ashr_i32 s43, s42, 31
	s_lshl_b64 s[48:49], s[42:43], 20
	s_add_u32 s48, s15, s48
	s_addc_u32 s49, s26, s49
	s_and_b64 s[76:77], vcc, exec
	s_cselect_b32 s43, s49, s51
	s_cselect_b32 s45, s48, s50
	s_add_u32 s76, s40, 0x80
	s_addc_u32 s77, s41, 0
	v_lshl_add_u64 v[156:157], s[76:77], 0, v[152:153]
	v_lshl_add_u64 v[158:159], s[76:77], 0, v[154:155]
	s_add_u32 s76, s50, 0x100
	s_addc_u32 s77, s51, 0
	s_mov_b32 s78, -2
	s_mov_b64 s[50:51], 0
	s_add_u32 s17, s40, s50
	s_addc_u32 s27, s41, s51
	s_add_u32 s17, s17, 0x100
	s_addc_u32 s27, s27, 0
	s_add_u32 s79, s76, s50
	s_addc_u32 s80, s77, s51
	s_add_i32 s86, 0, 0x10000
	s_cmpk_eq_i32 s50, 0xf00
	s_cselect_b32 s95, s4, s27
	s_cselect_b32 s94, s5, s17
	s_cselect_b32 s81, s43, s80
	s_cselect_b32 s80, s45, s79
	s_add_i32 s17, 0, 0x14000
	v_lshl_add_u64 v[228:229], v[158:159], 0, s[50:51]
	s_add_i32 m0, s16, 0xc000
	global_load_lds_dwordx4 v[228:229], off
	v_lshl_add_u64 v[228:229], v[156:157], 0, s[50:51]
	s_add_i32 m0, s16, 0xe000
	s_nop 0
	global_load_lds_dwordx4 v[228:229], off
	s_waitcnt vmcnt(8)
	s_waitcnt lgkmcnt(0)
	s_barrier
	s_setprio 1
	s_waitcnt lgkmcnt(0)
	v_mfma_f32_16x16x32_bf16 v[124:127], v[160:163], v[196:199], 0
	v_mfma_f32_16x16x32_bf16 v[120:123], v[168:171], v[196:199], 0
	v_mfma_f32_16x16x32_bf16 v[116:119], v[160:163], v[204:207], 0
	v_mfma_f32_16x16x32_bf16 v[112:115], v[168:171], v[204:207], 0
	v_mfma_f32_16x16x32_bf16 v[100:103], v[160:163], v[212:215], 0
	v_mfma_f32_16x16x32_bf16 v[96:99], v[168:171], v[212:215], 0
	v_mfma_f32_16x16x32_bf16 v[84:87], v[160:163], v[220:223], 0
	v_mfma_f32_16x16x32_bf16 v[80:83], v[168:171], v[220:223], 0
	v_mfma_f32_16x16x32_bf16 v[124:127], v[164:167], v[200:203], v[124:127]
	v_mfma_f32_16x16x32_bf16 v[120:123], v[172:175], v[200:203], v[120:123]
	v_mfma_f32_16x16x32_bf16 v[116:119], v[164:167], v[208:211], v[116:119]
	v_mfma_f32_16x16x32_bf16 v[112:115], v[172:175], v[208:211], v[112:115]
	v_mfma_f32_16x16x32_bf16 v[100:103], v[164:167], v[216:219], v[100:103]
	v_mfma_f32_16x16x32_bf16 v[96:99], v[172:175], v[216:219], v[96:99]
	v_mfma_f32_16x16x32_bf16 v[84:87], v[164:167], v[224:227], v[84:87]
	v_mfma_f32_16x16x32_bf16 v[80:83], v[172:175], v[224:227], v[80:83]
	s_setprio 0
	s_setprio 1
	v_mfma_f32_16x16x32_bf16 v[108:111], v[180:183], v[196:199], 0
	v_mfma_f32_16x16x32_bf16 v[104:107], v[188:191], v[196:199], 0
	v_mfma_f32_16x16x32_bf16 v[92:95], v[180:183], v[204:207], 0
	v_mfma_f32_16x16x32_bf16 v[88:91], v[188:191], v[204:207], 0
	v_mfma_f32_16x16x32_bf16 v[76:79], v[180:183], v[212:215], 0
	v_mfma_f32_16x16x32_bf16 v[72:75], v[188:191], v[212:215], 0
	v_mfma_f32_16x16x32_bf16 v[68:71], v[180:183], v[220:223], 0
	v_mfma_f32_16x16x32_bf16 v[64:67], v[188:191], v[220:223], 0
	v_mfma_f32_16x16x32_bf16 v[108:111], v[184:187], v[200:203], v[108:111]
	v_mfma_f32_16x16x32_bf16 v[104:107], v[192:195], v[200:203], v[104:107]
	v_mfma_f32_16x16x32_bf16 v[92:95], v[184:187], v[208:211], v[92:95]
	v_mfma_f32_16x16x32_bf16 v[88:91], v[192:195], v[208:211], v[88:91]
	v_mfma_f32_16x16x32_bf16 v[76:79], v[184:187], v[216:219], v[76:79]
	v_mfma_f32_16x16x32_bf16 v[72:75], v[192:195], v[216:219], v[72:75]
	v_mfma_f32_16x16x32_bf16 v[68:71], v[184:187], v[224:227], v[68:71]
	v_mfma_f32_16x16x32_bf16 v[64:67], v[192:195], v[224:227], v[64:67]
	s_setprio 0
	s_barrier
	s_add_i32 s27, s86, s3
	v_lshl_add_u64 v[228:229], s[80:81], 0, v[176:177]
	s_mov_b32 m0, s27
	ds_read_b128 v[196:199], v139 offset:16384
	ds_read_b128 v[200:203], v139 offset:17408
	ds_read_b128 v[204:207], v139 offset:18432
	ds_read_b128 v[208:211], v139 offset:19456
	ds_read_b128 v[212:215], v139 offset:20480
	ds_read_b128 v[216:219], v139 offset:21504
	ds_read_b128 v[220:223], v139 offset:22528
	ds_read_b128 v[224:227], v139 offset:23552
	global_load_lds_dwordx4 v[228:229], off
	s_add_i32 m0, s27, 0x2000
	v_lshl_add_u64 v[230:231], s[80:81], 0, v[128:129]
	s_add_u32 s80, s80, s30
	s_addc_u32 s81, s81, s31
	s_add_i32 s17, s17, s3
	global_load_lds_dwordx4 v[230:231], off
	v_lshl_add_u64 v[232:233], s[80:81], 0, v[176:177]
	s_mov_b32 m0, s17
	v_lshl_add_u64 v[234:235], s[80:81], 0, v[128:129]
	global_load_lds_dwordx4 v[232:233], off
	s_add_i32 m0, s17, 0x2000
	v_lshl_add_u64 v[236:237], s[94:95], 0, v[132:133]
	global_load_lds_dwordx4 v[234:235], off
	s_mov_b32 m0, s16
	v_lshl_add_u64 v[246:247], s[94:95], 0, v[130:131]
	global_load_lds_dwordx4 v[236:237], off
	s_mov_b32 m0, s35
	s_nop 0
	global_load_lds_dwordx4 v[246:247], off
	s_waitcnt vmcnt(8)
	s_waitcnt lgkmcnt(0)
	s_barrier
	s_setprio 1
	s_waitcnt lgkmcnt(0)
	v_mfma_f32_16x16x32_bf16 v[60:63], v[160:163], v[196:199], 0
	v_mfma_f32_16x16x32_bf16 v[56:59], v[168:171], v[196:199], 0
	v_mfma_f32_16x16x32_bf16 v[52:55], v[160:163], v[204:207], 0
	v_mfma_f32_16x16x32_bf16 v[48:51], v[168:171], v[204:207], 0
	v_mfma_f32_16x16x32_bf16 v[36:39], v[160:163], v[212:215], 0
	v_mfma_f32_16x16x32_bf16 v[32:35], v[168:171], v[212:215], 0
	v_mfma_f32_16x16x32_bf16 v[20:23], v[160:163], v[220:223], 0
	v_mfma_f32_16x16x32_bf16 v[16:19], v[168:171], v[220:223], 0
	v_mfma_f32_16x16x32_bf16 v[60:63], v[164:167], v[200:203], v[60:63]
	v_mfma_f32_16x16x32_bf16 v[56:59], v[172:175], v[200:203], v[56:59]
	v_mfma_f32_16x16x32_bf16 v[52:55], v[164:167], v[208:211], v[52:55]
	v_mfma_f32_16x16x32_bf16 v[48:51], v[172:175], v[208:211], v[48:51]
	v_mfma_f32_16x16x32_bf16 v[36:39], v[164:167], v[216:219], v[36:39]
	v_mfma_f32_16x16x32_bf16 v[32:35], v[172:175], v[216:219], v[32:35]
	v_mfma_f32_16x16x32_bf16 v[20:23], v[164:167], v[224:227], v[20:23]
	v_mfma_f32_16x16x32_bf16 v[16:19], v[172:175], v[224:227], v[16:19]
	s_setprio 0
	s_setprio 1
	v_mfma_f32_16x16x32_bf16 v[44:47], v[180:183], v[196:199], 0
	v_mfma_f32_16x16x32_bf16 v[40:43], v[188:191], v[196:199], 0
	v_mfma_f32_16x16x32_bf16 v[28:31], v[180:183], v[204:207], 0
	v_mfma_f32_16x16x32_bf16 v[24:27], v[188:191], v[204:207], 0
	v_mfma_f32_16x16x32_bf16 v[12:15], v[180:183], v[212:215], 0
	v_mfma_f32_16x16x32_bf16 v[8:11], v[188:191], v[212:215], 0
	v_mfma_f32_16x16x32_bf16 v[4:7], v[180:183], v[220:223], 0
	v_mfma_f32_16x16x32_bf16 v[0:3], v[188:191], v[220:223], 0
	v_mfma_f32_16x16x32_bf16 v[44:47], v[184:187], v[200:203], v[44:47]
	v_mfma_f32_16x16x32_bf16 v[40:43], v[192:195], v[200:203], v[40:43]
	v_mfma_f32_16x16x32_bf16 v[28:31], v[184:187], v[208:211], v[28:31]
	v_mfma_f32_16x16x32_bf16 v[24:27], v[192:195], v[208:211], v[24:27]
	v_mfma_f32_16x16x32_bf16 v[12:15], v[184:187], v[216:219], v[12:15]
	v_mfma_f32_16x16x32_bf16 v[8:11], v[192:195], v[216:219], v[8:11]
	v_mfma_f32_16x16x32_bf16 v[4:7], v[184:187], v[224:227], v[4:7]
	v_mfma_f32_16x16x32_bf16 v[0:3], v[192:195], v[224:227], v[0:3]
	s_setprio 0
	s_barrier
	s_branch .Lgemm_join_1120

; #define PG8_STAGE(bufoff, gbase, voff) do { _Pragma("unroll") for (int _i = 0; _i < 2; ++_i) \
;         __builtin_amdgcn_global_load_lds((const unsigned*)((const char*)(gbase) + (voff)[_i]), (LAS unsigned*)(lds + (bufoff) + ldsw + _i * 8192), 16, 0, 0); } while (0)
; #define PG8_LDA(dst, b, h) do { _Pragma("unroll") for (int m = 0; m < 4; ++m) _Pragma("unroll") for (int k = 0; k < 2; ++k) dst[m][k] = *(const LAS bf16x8*)(lds + PG8_SA(b, h) + aoff + m * 2048 + k * 1024); } while (0)
; #define PG8_LDB(dst, b, h) do { _Pragma("unroll") for (int n = 0; n < 2; ++n) _Pragma("unroll") for (int k = 0; k < 2; ++k) dst[n][k] = *(const LAS bf16x8*)(lds + PG8_SB(b, h) + boff + n * 2048 + k * 1024); } while (0)
; #define PG8_MMA(ai, bj, At, Bt) do { __builtin_amdgcn_s_setprio(1); _Pragma("unroll") for (int m = 0; m < 4; ++m) _Pragma("unroll") for (int n = 0; n < 2; ++n) _Pragma("unroll") for (int k = 0; k < 2; ++k) \
;         acc[ai][bj][m][n] = __builtin_amdgcn_mfma_f32_16x16x32_bf16(Bt[n][k], At[m][k], acc[ai][bj][m][n], 0, 0, 0); __builtin_amdgcn_s_setprio(0); } while (0)
; #define PG8_WAIT_V(n) asm volatile("s_waitcnt vmcnt(" #n ")" ::: "memory")
; #define PG8_WAIT_L(n) asm volatile("s_waitcnt lgkmcnt(" #n ")" ::: "memory")
; #define PG8_BAR __builtin_amdgcn_s_barrier()
; #define PG8_SCHED __builtin_amdgcn_sched_barrier(0)
; template <class Epi, class Sched, bool ALIGN_EPI>
; __device__ __forceinline__ void gemm_phase(LAS unsigned char* lds, const int wid, const int lda_, const int ldb_, const int K_, const Sched& S, const Epi& E) {
;     ...
;             PG8_LDB(B0, 1, 0); PG8_LDB(B1, 1, 1); PG8_SCHED; PG8_LDA(At, 1, 0); PG8_STAGE(PG8_SA(0, 1), a2 + hstepA, voffA);
;             PG8_WAIT_V(8); PG8_WAIT_L(0); PG8_BAR; PG8_MMA(0, 0, At, B0); PG8_MMA(0, 1, At, B1); PG8_BAR; PG8_SCHED;
;             PG8_LDA(At, 1, 1); PG8_STAGE(PG8_SB(1, 0), b3, voffB); PG8_STAGE(PG8_SB(1, 1), b3 + hstepB, voffB); PG8_STAGE(PG8_SA(1, 0), a3, voffA);
;             PG8_WAIT_V(8); PG8_WAIT_L(0); PG8_BAR; PG8_MMA(1, 0, At, B0); PG8_MMA(1, 1, At, B1); PG8_BAR; PG8_SCHED;
.Lgemm_join_1120:
	s_add_i32 s17, 0, 0x18000
	v_add_u32_e32 v141, s17, v135
	s_add_i32 s27, 0, 0x1c000
	ds_read_b128 v[160:163], v141
	ds_read_b128 v[164:167], v141 offset:1024
	ds_read_b128 v[168:171], v141 offset:2048
	ds_read_b128 v[172:175], v141 offset:3072
	v_add_u32_e32 v141, s27, v135
	ds_read_b128 v[180:183], v141
	ds_read_b128 v[184:187], v141 offset:1024
	ds_read_b128 v[188:191], v141 offset:2048
	ds_read_b128 v[192:195], v141 offset:3072
	s_add_u32 s80, s94, s10
	s_addc_u32 s81, s95, s11
	s_mov_b32 m0, s39
	v_lshl_add_u64 v[248:249], s[80:81], 0, v[132:133]
	ds_read_b128 v[196:199], v139 offset:32768
	ds_read_b128 v[200:203], v139 offset:33792
	ds_read_b128 v[204:207], v139 offset:34816
	ds_read_b128 v[208:211], v139 offset:35840
	ds_read_b128 v[212:215], v139 offset:36864
	ds_read_b128 v[216:219], v139 offset:37888
	ds_read_b128 v[220:223], v139 offset:38912
	ds_read_b128 v[224:227], v139 offset:39936
	global_load_lds_dwordx4 v[248:249], off
	v_lshl_add_u64 v[248:249], s[80:81], 0, v[130:131]
	s_mov_b32 m0, s72
	s_nop 0
	global_load_lds_dwordx4 v[248:249], off
	s_waitcnt vmcnt(8)
	s_waitcnt lgkmcnt(0)
	s_barrier
	s_setprio 1
	s_waitcnt lgkmcnt(0)
	v_mfma_f32_16x16x32_bf16 v[124:127], v[160:163], v[196:199], v[124:127]
	v_mfma_f32_16x16x32_bf16 v[120:123], v[168:171], v[196:199], v[120:123]
	v_mfma_f32_16x16x32_bf16 v[116:119], v[160:163], v[204:207], v[116:119]
	v_mfma_f32_16x16x32_bf16 v[112:115], v[168:171], v[204:207], v[112:115]
	v_mfma_f32_16x16x32_bf16 v[100:103], v[160:163], v[212:215], v[100:103]
	v_mfma_f32_16x16x32_bf16 v[96:99], v[168:171], v[212:215], v[96:99]
	v_mfma_f32_16x16x32_bf16 v[84:87], v[160:163], v[220:223], v[84:87]
	v_mfma_f32_16x16x32_bf16 v[80:83], v[168:171], v[220:223], v[80:83]
	v_mfma_f32_16x16x32_bf16 v[124:127], v[164:167], v[200:203], v[124:127]
	v_mfma_f32_16x16x32_bf16 v[120:123], v[172:175], v[200:203], v[120:123]
	v_mfma_f32_16x16x32_bf16 v[116:119], v[164:167], v[208:211], v[116:119]
	v_mfma_f32_16x16x32_bf16 v[112:115], v[172:175], v[208:211], v[112:115]
	v_mfma_f32_16x16x32_bf16 v[100:103], v[164:167], v[216:219], v[100:103]
	v_mfma_f32_16x16x32_bf16 v[96:99], v[172:175], v[216:219], v[96:99]
	v_mfma_f32_16x16x32_bf16 v[84:87], v[164:167], v[224:227], v[84:87]
	v_mfma_f32_16x16x32_bf16 v[80:83], v[172:175], v[224:227], v[80:83]
	s_setprio 0
	s_setprio 1
	v_mfma_f32_16x16x32_bf16 v[108:111], v[180:183], v[196:199], v[108:111]
	v_mfma_f32_16x16x32_bf16 v[104:107], v[188:191], v[196:199], v[104:107]
	v_mfma_f32_16x16x32_bf16 v[92:95], v[180:183], v[204:207], v[92:95]
	v_mfma_f32_16x16x32_bf16 v[88:91], v[188:191], v[204:207], v[88:91]
	v_mfma_f32_16x16x32_bf16 v[76:79], v[180:183], v[212:215], v[76:79]
	v_mfma_f32_16x16x32_bf16 v[72:75], v[188:191], v[212:215], v[72:75]
	v_mfma_f32_16x16x32_bf16 v[68:71], v[180:183], v[220:223], v[68:71]
	v_mfma_f32_16x16x32_bf16 v[64:67], v[188:191], v[220:223], v[64:67]
	v_mfma_f32_16x16x32_bf16 v[108:111], v[184:187], v[200:203], v[108:111]
	v_mfma_f32_16x16x32_bf16 v[104:107], v[192:195], v[200:203], v[104:107]
	v_mfma_f32_16x16x32_bf16 v[92:95], v[184:187], v[208:211], v[92:95]
	v_mfma_f32_16x16x32_bf16 v[88:91], v[192:195], v[208:211], v[88:91]
	v_mfma_f32_16x16x32_bf16 v[76:79], v[184:187], v[216:219], v[76:79]
	v_mfma_f32_16x16x32_bf16 v[72:75], v[192:195], v[216:219], v[72:75]
	v_mfma_f32_16x16x32_bf16 v[68:71], v[184:187], v[224:227], v[68:71]
	v_mfma_f32_16x16x32_bf16 v[64:67], v[192:195], v[224:227], v[64:67]
	s_setprio 0
	s_barrier
	s_add_i32 s17, s17, s3
	v_lshl_add_u64 v[228:229], v[228:229], 0, s[24:25]
	s_mov_b32 m0, s17
	ds_read_b128 v[196:199], v139 offset:49152
	ds_read_b128 v[200:203], v139 offset:50176
	ds_read_b128 v[204:207], v139 offset:51200
	ds_read_b128 v[208:211], v139 offset:52224
	ds_read_b128 v[212:215], v139 offset:53248
	ds_read_b128 v[216:219], v139 offset:54272
	ds_read_b128 v[220:223], v139 offset:55296
	ds_read_b128 v[224:227], v139 offset:56320
	global_load_lds_dwordx4 v[228:229], off
	v_lshl_add_u64 v[228:229], v[230:231], 0, s[24:25]
	s_add_i32 m0, s17, 0x2000
	s_add_i32 s17, s27, s3
	global_load_lds_dwordx4 v[228:229], off
	v_lshl_add_u64 v[228:229], v[232:233], 0, s[24:25]
	s_mov_b32 m0, s17
	s_nop 0
	global_load_lds_dwordx4 v[228:229], off
	v_lshl_add_u64 v[228:229], v[234:235], 0, s[24:25]
	s_add_i32 m0, s17, 0x2000
	s_nop 0
	global_load_lds_dwordx4 v[228:229], off
	v_lshl_add_u64 v[228:229], v[236:237], 0, s[24:25]
	s_mov_b32 m0, s73
	s_nop 0
	global_load_lds_dwordx4 v[228:229], off
	v_lshl_add_u64 v[228:229], v[246:247], 0, s[24:25]
	s_mov_b32 m0, s74
	s_nop 0
	global_load_lds_dwordx4 v[228:229], off
	s_waitcnt vmcnt(8)
	s_waitcnt lgkmcnt(0)
	s_barrier
; #define PG8_STAGE(bufoff, gbase, voff) do { _Pragma("unroll") for (int _i = 0; _i < 2; ++_i) \
;         __builtin_amdgcn_global_load_lds((const unsigned*)((const char*)(gbase) + (voff)[_i]), (LAS unsigned*)(lds + (bufoff) + ldsw + _i * 8192), 16, 0, 0); } while (0)
; #define PG8_LDA(dst, b, h) do { _Pragma("unroll") for (int m = 0; m < 4; ++m) _Pragma("unroll") for (int k = 0; k < 2; ++k) dst[m][k] = *(const LAS bf16x8*)(lds + PG8_SA(b, h) + aoff + m * 2048 + k * 1024); } while (0)
; #define PG8_LDB(dst, b, h) do { _Pragma("unroll") for (int n = 0; n < 2; ++n) _Pragma("unroll") for (int k = 0; k < 2; ++k) dst[n][k] = *(const LAS bf16x8*)(lds + PG8_SB(b, h) + boff + n * 2048 + k * 1024); } while (0)
; #define PG8_WAIT_V(n) asm volatile("s_waitcnt vmcnt(" #n ")" ::: "memory")
; template <class Epi, class Sched, bool ALIGN_EPI>
; __device__ __forceinline__ void gemm_phase(LAS unsigned char* lds, const int wid, const int lda_, const int ldb_, const int K_, const Sched& S, const Epi& E) {
;     ...
;         for (int t = 0; t < nt; t += 2) {
;             const bool last = (t == nt - 2);
;             const char* a1 = cA + (size_t)(t + 1) * kstep;
;             const char* a2 = last ? nA : cA + (size_t)(t + 2) * kstep; const char* b2 = last ? nB : cB + (size_t)(t + 2) * kstep;
;             const char* a3 = a2 + kstep; const char* b3 = b2 + kstep;
;             PG8_LDB(B0, 0, 0); PG8_LDB(B1, 0, 1); PG8_SCHED; PG8_LDA(At, 0, 0); PG8_STAGE(PG8_SA(1, 1), a1 + hstepA, voffA);
;             PG8_WAIT_V(8); PG8_WAIT_L(0); PG8_BAR; PG8_MMA(0, 0, At, B0); PG8_MMA(0, 1, At, B1); PG8_BAR; PG8_SCHED;
;             PG8_LDA(At, 0, 1); PG8_STAGE(PG8_SB(0, 0), b2, voffB); PG8_STAGE(PG8_SB(0, 1), b2 + hstepB, voffB); PG8_STAGE(PG8_SA(0, 0), a2, voffA);
;             PG8_WAIT_V(8); PG8_WAIT_L(0); PG8_BAR; PG8_MMA(1, 0, At, B0); PG8_MMA(1, 1, At, B1); PG8_BAR; PG8_SCHED;
;             PG8_LDB(B0, 1, 0); PG8_LDB(B1, 1, 1); PG8_SCHED; PG8_LDA(At, 1, 0); PG8_STAGE(PG8_SA(0, 1), a2 + hstepA, voffA);
;             PG8_WAIT_V(8); PG8_WAIT_L(0); PG8_BAR; PG8_MMA(0, 0, At, B0); PG8_MMA(0, 1, At, B1); PG8_BAR; PG8_SCHED;
;             PG8_LDA(At, 1, 1); PG8_STAGE(PG8_SB(1, 0), b3, voffB); PG8_STAGE(PG8_SB(1, 1), b3 + hstepB, voffB); PG8_STAGE(PG8_SA(1, 0), a3, voffA);
;             PG8_WAIT_V(8); PG8_WAIT_L(0); PG8_BAR; PG8_MMA(1, 0, At, B0); PG8_MMA(1, 1, At, B1); PG8_BAR; PG8_SCHED;
	s_setprio 1
	s_waitcnt lgkmcnt(0)
	v_mfma_f32_16x16x32_bf16 v[60:63], v[160:163], v[196:199], v[60:63]
	v_mfma_f32_16x16x32_bf16 v[56:59], v[168:171], v[196:199], v[56:59]
	v_mfma_f32_16x16x32_bf16 v[52:55], v[160:163], v[204:207], v[52:55]
	v_mfma_f32_16x16x32_bf16 v[48:51], v[168:171], v[204:207], v[48:51]
	v_mfma_f32_16x16x32_bf16 v[36:39], v[160:163], v[212:215], v[36:39]
	v_mfma_f32_16x16x32_bf16 v[32:35], v[168:171], v[212:215], v[32:35]
	v_mfma_f32_16x16x32_bf16 v[20:23], v[160:163], v[220:223], v[20:23]
	v_mfma_f32_16x16x32_bf16 v[16:19], v[168:171], v[220:223], v[16:19]
	v_mfma_f32_16x16x32_bf16 v[60:63], v[164:167], v[200:203], v[60:63]
	v_mfma_f32_16x16x32_bf16 v[56:59], v[172:175], v[200:203], v[56:59]
	v_mfma_f32_16x16x32_bf16 v[52:55], v[164:167], v[208:211], v[52:55]
	v_mfma_f32_16x16x32_bf16 v[48:51], v[172:175], v[208:211], v[48:51]
	v_mfma_f32_16x16x32_bf16 v[36:39], v[164:167], v[216:219], v[36:39]
	v_mfma_f32_16x16x32_bf16 v[32:35], v[172:175], v[216:219], v[32:35]
	v_mfma_f32_16x16x32_bf16 v[20:23], v[164:167], v[224:227], v[20:23]
	v_mfma_f32_16x16x32_bf16 v[16:19], v[172:175], v[224:227], v[16:19]
	s_setprio 0
	s_setprio 1
	v_mfma_f32_16x16x32_bf16 v[44:47], v[180:183], v[196:199], v[44:47]
	v_mfma_f32_16x16x32_bf16 v[40:43], v[188:191], v[196:199], v[40:43]
	v_mfma_f32_16x16x32_bf16 v[28:31], v[180:183], v[204:207], v[28:31]
	v_mfma_f32_16x16x32_bf16 v[24:27], v[188:191], v[204:207], v[24:27]
	v_mfma_f32_16x16x32_bf16 v[12:15], v[180:183], v[212:215], v[12:15]
	v_mfma_f32_16x16x32_bf16 v[8:11], v[188:191], v[212:215], v[8:11]
	v_mfma_f32_16x16x32_bf16 v[4:7], v[180:183], v[220:223], v[4:7]
	v_mfma_f32_16x16x32_bf16 v[0:3], v[188:191], v[220:223], v[0:3]
	v_mfma_f32_16x16x32_bf16 v[44:47], v[184:187], v[200:203], v[44:47]
	v_mfma_f32_16x16x32_bf16 v[40:43], v[192:195], v[200:203], v[40:43]
	v_mfma_f32_16x16x32_bf16 v[28:31], v[184:187], v[208:211], v[28:31]
	v_mfma_f32_16x16x32_bf16 v[24:27], v[192:195], v[208:211], v[24:27]
	v_mfma_f32_16x16x32_bf16 v[12:15], v[184:187], v[216:219], v[12:15]
	v_mfma_f32_16x16x32_bf16 v[8:11], v[192:195], v[216:219], v[8:11]
	v_mfma_f32_16x16x32_bf16 v[4:7], v[184:187], v[224:227], v[4:7]
	v_mfma_f32_16x16x32_bf16 v[0:3], v[192:195], v[224:227], v[0:3]
	s_setprio 0
	s_barrier
	s_add_i32 s78, s78, 2
	s_add_u32 s50, s50, 0x100
	s_addc_u32 s51, s51, 0
	s_cmp_gt_u32 s78, 29
	s_cbranch_scc0 .LBB0_1120
; __device__ __forceinline__ unsigned cvt_pk_bf16(float lo, float hi) { const f32x2 v = {lo, hi}; return __builtin_bit_cast(unsigned, __builtin_convertvector(v, bf16x2_t)); }
;     template <class Sched> __device__ __forceinline__ void operator()(const f32x4 (&acc)[2][2][4][2], const Unit& u, const Sched& S, int wr, int wc, int fr, int fq) const {
;         const int rl0 = wr * 64 + fr, cl0 = wc * 32 + 8 * fq;
;         char* uo; int ldo, kind; S.out(u, uo, ldo, kind);
;         asm volatile("" : "+s"(ldo));
;         if (kind == 0) {
;             bf16_t* base = (bf16_t*)uo;
; #pragma unroll
;             for (int ai = 0; ai < 2; ++ai)
; #pragma unroll
;                 for (int m = 0; m < 4; ++m) { bf16_t* rowp = base + (size_t)(rl0 + ai * HALF + m * 16) * ldo + cl0;
; #pragma unroll
;                     for (int bj = 0; bj < 2; ++bj) { const f32x4 v0 = acc[ai][bj][m][0], v1 = acc[ai][bj][m][1];
;                         u32x4 w; w.x = cvt_pk_bf16(v0[0], v0[1]); w.y = cvt_pk_bf16(v0[2], v0[3]); w.z = cvt_pk_bf16(v1[0], v1[1]); w.w = cvt_pk_bf16(v1[2], v1[3]);
;                         *(u32x4*)(rowp + bj * HALF) = w; } }
	s_setprio 2
	v_add_u32_e32 v141, 0x10000, v135
	ds_read_b128 v[160:163], v141
	ds_read_b128 v[164:167], v141 offset:1024
	ds_read_b128 v[168:171], v141 offset:2048
	ds_read_b128 v[172:175], v141 offset:3072
	v_add_u32_e32 v141, 0x14000, v135
	ds_read_b128 v[180:183], v141
	ds_read_b128 v[184:187], v141 offset:1024
	ds_read_b128 v[188:191], v141 offset:2048
	ds_read_b128 v[192:195], v141 offset:3072
	ds_read_b128 v[196:199], v139
	ds_read_b128 v[200:203], v139 offset:1024
	ds_read_b128 v[204:207], v139 offset:2048
	ds_read_b128 v[208:211], v139 offset:3072
	ds_read_b128 v[212:215], v139 offset:4096
	ds_read_b128 v[216:219], v139 offset:5120
	ds_read_b128 v[220:223], v139 offset:6144
	ds_read_b128 v[224:227], v139 offset:7168
	s_sub_i32 s4, s38, 22
	s_ashr_i32 s5, s38, 31
	s_cmp_lt_i32 s38, 22
	s_cselect_b32 s5, s5, 0
	s_cselect_b32 s4, s38, s4
	s_mov_b32 s17, 0x2bc00000
	s_cselect_b32 s17, 0x1f600000, s17
	s_lshl_b64 s[4:5], s[4:5], 9
	s_add_u32 s4, s66, s4
	s_addc_u32 s5, s67, s5
	s_add_u32 s4, s4, s17
	s_addc_u32 s5, s5, 0
	s_mul_i32 s27, s34, 0x2c0000
	s_mul_hi_i32 s17, s34, 0x2c0000
	s_add_u32 s4, s4, s27
	s_addc_u32 s5, s5, s17
	s_movk_i32 s17, 0x1600
	v_lshl_add_u64 v[156:157], v[136:137], 1, s[4:5]
	v_mad_i64_i32 v[158:159], s[4:5], s17, v134, 0
	v_lshl_add_u64 v[158:159], v[158:159], 1, v[156:157]
	v_cvt_pk_bf16_f32 v108, v108, v109
	v_cvt_pk_bf16_f32 v109, v110, v111
	v_cvt_pk_bf16_f32 v110, v104, v105
	v_cvt_pk_bf16_f32 v111, v106, v107
	v_mad_i64_i32 v[104:105], s[4:5], s17, v138, 0
	v_cvt_pk_bf16_f32 v124, v124, v125
	v_cvt_pk_bf16_f32 v125, v126, v127
	v_cvt_pk_bf16_f32 v126, v120, v121
	v_cvt_pk_bf16_f32 v127, v122, v123
	global_store_dwordx4 v[158:159], v[108:111], off offset:256
	v_cvt_pk_bf16_f32 v92, v92, v93
	v_cvt_pk_bf16_f32 v93, v94, v95
	v_lshl_add_u64 v[108:109], v[104:105], 1, v[156:157]
	v_cvt_pk_bf16_f32 v94, v88, v89
	v_cvt_pk_bf16_f32 v95, v90, v91
	v_mad_i64_i32 v[88:89], s[4:5], s17, v140, 0
	global_store_dwordx4 v[158:159], v[124:127], off
	v_cvt_pk_bf16_f32 v104, v116, v117
	v_cvt_pk_bf16_f32 v105, v118, v119
	v_cvt_pk_bf16_f32 v106, v112, v113
	v_cvt_pk_bf16_f32 v107, v114, v115
	global_store_dwordx4 v[108:109], v[92:95], off offset:256
	v_cvt_pk_bf16_f32 v76, v76, v77
	v_cvt_pk_bf16_f32 v77, v78, v79
	v_lshl_add_u64 v[92:93], v[88:89], 1, v[156:157]
	v_cvt_pk_bf16_f32 v78, v72, v73
	v_cvt_pk_bf16_f32 v79, v74, v75
	v_mad_i64_i32 v[72:73], s[4:5], s17, v142, 0
	v_cvt_pk_bf16_f32 v68, v68, v69
	v_cvt_pk_bf16_f32 v69, v70, v71
	v_cvt_pk_bf16_f32 v70, v64, v65
	v_mad_i64_i32 v[64:65], s[4:5], s17, v144, 0
	global_store_dwordx4 v[108:109], v[104:107], off
	v_cvt_pk_bf16_f32 v88, v100, v101
	v_cvt_pk_bf16_f32 v89, v102, v103
	v_cvt_pk_bf16_f32 v90, v96, v97
	v_cvt_pk_bf16_f32 v91, v98, v99
	global_store_dwordx4 v[92:93], v[76:79], off offset:256
	v_cvt_pk_bf16_f32 v74, v80, v81
	v_cvt_pk_bf16_f32 v75, v82, v83
	v_lshl_add_u64 v[76:77], v[72:73], 1, v[156:157]
	v_cvt_pk_bf16_f32 v72, v84, v85
	v_cvt_pk_bf16_f32 v73, v86, v87
	v_cvt_pk_bf16_f32 v71, v66, v67
	v_lshl_add_u64 v[64:65], v[64:65], 1, v[156:157]
	v_cvt_pk_bf16_f32 v44, v44, v45
	v_cvt_pk_bf16_f32 v45, v46, v47
	v_cvt_pk_bf16_f32 v46, v40, v41
	v_cvt_pk_bf16_f32 v47, v42, v43
	v_mad_i64_i32 v[40:41], s[4:5], s17, v146, 0
	global_store_dwordx4 v[92:93], v[88:91], off
	global_store_dwordx4 v[76:77], v[72:75], off
	global_store_dwordx4 v[76:77], v[68:71], off offset:256
	v_cvt_pk_bf16_f32 v60, v60, v61
	v_cvt_pk_bf16_f32 v61, v62, v63
	v_cvt_pk_bf16_f32 v62, v56, v57
	v_cvt_pk_bf16_f32 v63, v58, v59
	global_store_dwordx4 v[64:65], v[44:47], off offset:256
	v_cvt_pk_bf16_f32 v28, v28, v29
	v_cvt_pk_bf16_f32 v29, v30, v31
	v_lshl_add_u64 v[44:45], v[40:41], 1, v[156:157]
	v_cvt_pk_bf16_f32 v30, v24, v25
	v_cvt_pk_bf16_f32 v31, v26, v27
	v_mad_i64_i32 v[24:25], s[4:5], s17, v148, 0
	global_store_dwordx4 v[64:65], v[60:63], off
	v_cvt_pk_bf16_f32 v40, v52, v53
	v_cvt_pk_bf16_f32 v41, v54, v55
	v_cvt_pk_bf16_f32 v42, v48, v49
	v_cvt_pk_bf16_f32 v43, v50, v51
	global_store_dwordx4 v[44:45], v[28:31], off offset:256
	v_cvt_pk_bf16_f32 v12, v12, v13
	v_cvt_pk_bf16_f32 v13, v14, v15
	v_lshl_add_u64 v[28:29], v[24:25], 1, v[156:157]
	v_cvt_pk_bf16_f32 v14, v8, v9
	v_cvt_pk_bf16_f32 v15, v10, v11
	v_mad_i64_i32 v[8:9], s[4:5], s17, v150, 0
	global_store_dwordx4 v[44:45], v[40:43], off
	v_cvt_pk_bf16_f32 v24, v36, v37
	v_cvt_pk_bf16_f32 v25, v38, v39
	v_cvt_pk_bf16_f32 v26, v32, v33
	v_cvt_pk_bf16_f32 v27, v34, v35
	global_store_dwordx4 v[28:29], v[12:15], off offset:256
	v_cvt_pk_bf16_f32 v10, v16, v17
	v_cvt_pk_bf16_f32 v11, v18, v19
	v_lshl_add_u64 v[12:13], v[8:9], 1, v[156:157]
	v_cvt_pk_bf16_f32 v8, v20, v21
	v_cvt_pk_bf16_f32 v9, v22, v23
	v_cvt_pk_bf16_f32 v4, v4, v5
	v_cvt_pk_bf16_f32 v5, v6, v7
	v_cvt_pk_bf16_f32 v6, v0, v1
	v_cvt_pk_bf16_f32 v7, v2, v3
	s_and_b64 vcc, exec, s[36:37]
	s_mov_b32 s38, s42
	s_mov_b32 s34, s44
	s_mov_b64 s[50:51], s[48:49]
	s_mov_b64 s[40:41], s[46:47]
	global_store_dwordx4 v[28:29], v[24:27], off
	global_store_dwordx4 v[12:13], v[8:11], off
	global_store_dwordx4 v[12:13], v[4:7], off offset:256
	s_cbranch_vccz .LBB0_1117
	v_readlane_b32 s4, v253, 1
	s_waitcnt vmcnt(0)
	v_readlane_b32 s5, v253, 2
	s_andn2_b64 vcc, exec, s[4:5]
	s_cbranch_vccnz .LBB0_1124
	s_barrier

.LBB0_1205:
	s_or_b64 exec, exec, s[4:5]
	s_waitcnt vmcnt(8)
	v_lshlrev_b32_e32 v156, 16, v12
	v_and_b32_e32 v157, 0xffff0000, v12
	v_lshlrev_b32_e32 v12, 16, v13
	v_and_b32_e32 v13, 0xffff0000, v13
	v_lshlrev_b32_e32 v160, 16, v20
	v_and_b32_e32 v161, 0xffff0000, v20
	v_lshlrev_b32_e32 v20, 16, v21
	v_and_b32_e32 v21, 0xffff0000, v21
	s_waitcnt vmcnt(4)
	v_pk_fma_f32 v[12:13], v[134:135], v[12:13], v[130:131]
	v_lshlrev_b32_e32 v158, 16, v14
	v_and_b32_e32 v159, 0xffff0000, v14
	v_lshlrev_b32_e32 v164, 16, v0
	v_and_b32_e32 v165, 0xffff0000, v0
	v_lshlrev_b32_e32 v0, 16, v1
	v_and_b32_e32 v1, 0xffff0000, v1
	s_waitcnt vmcnt(3)
	v_pk_fma_f32 v[12:13], v[142:143], v[20:21], v[12:13]
	v_lshlrev_b32_e32 v162, 16, v22
	v_and_b32_e32 v163, 0xffff0000, v22
	s_waitcnt vmcnt(1)
	v_pk_fma_f32 v[172:173], v[150:151], v[0:1], v[12:13]
	v_pk_fma_f32 v[12:13], v[124:125], v[158:159], v[120:121]
	v_lshlrev_b32_e32 v14, 16, v15
	v_and_b32_e32 v15, 0xffff0000, v15
	v_lshlrev_b32_e32 v168, 16, v2
	v_and_b32_e32 v169, 0xffff0000, v2
	v_pk_fma_f32 v[12:13], v[136:137], v[162:163], v[12:13]
	v_pk_fma_f32 v[20:21], v[134:135], v[20:21], v[130:131]
	v_lshlrev_b32_e32 v22, 16, v23
	v_and_b32_e32 v23, 0xffff0000, v23
	s_waitcnt vmcnt(0)
	v_pk_fma_f32 v[174:175], v[144:145], v[168:169], v[12:13]
	v_pk_fma_f32 v[12:13], v[126:127], v[14:15], v[122:123]
	v_lshlrev_b32_e32 v14, 16, v29
	v_and_b32_e32 v15, 0xffff0000, v29
	v_pk_fma_f32 v[20:21], v[142:143], v[0:1], v[20:21]
	v_lshlrev_b32_e32 v2, 16, v3
	v_and_b32_e32 v3, 0xffff0000, v3
	v_pk_fma_f32 v[156:157], v[132:133], v[156:157], v[128:129]
	v_pk_fma_f32 v[12:13], v[138:139], v[22:23], v[12:13]
	v_pk_fma_f32 v[158:159], v[150:151], v[14:15], v[20:21]
	v_pk_fma_f32 v[20:21], v[124:125], v[162:163], v[120:121]
	v_pk_fma_f32 v[156:157], v[140:141], v[160:161], v[156:157]
	v_pk_fma_f32 v[180:181], v[146:147], v[2:3], v[12:13]
	v_lshlrev_b32_e32 v12, 16, v28
	v_and_b32_e32 v13, 0xffff0000, v28
	v_lshlrev_b32_e32 v28, 16, v30
	v_and_b32_e32 v29, 0xffff0000, v30
	v_pk_fma_f32 v[20:21], v[136:137], v[168:169], v[20:21]
	v_pk_fma_f32 v[170:171], v[148:149], v[164:165], v[156:157]
	v_pk_fma_f32 v[156:157], v[132:133], v[160:161], v[128:129]
	v_pk_fma_f32 v[160:161], v[144:145], v[28:29], v[20:21]
	v_pk_fma_f32 v[20:21], v[126:127], v[22:23], v[122:123]
	v_lshlrev_b32_e32 v30, 16, v31
	v_and_b32_e32 v31, 0xffff0000, v31
	v_pk_fma_f32 v[20:21], v[138:139], v[2:3], v[20:21]
	v_pk_fma_f32 v[0:1], v[134:135], v[0:1], v[130:131]
	v_pk_fma_f32 v[162:163], v[146:147], v[30:31], v[20:21]
	v_lshlrev_b32_e32 v20, 16, v4
	v_and_b32_e32 v21, 0xffff0000, v4
	v_lshlrev_b32_e32 v4, 16, v5
	v_and_b32_e32 v5, 0xffff0000, v5
	v_pk_fma_f32 v[0:1], v[142:143], v[14:15], v[0:1]
	v_lshlrev_b32_e32 v22, 16, v6
	v_pk_fma_f32 v[166:167], v[150:151], v[4:5], v[0:1]
	v_pk_fma_f32 v[0:1], v[124:125], v[168:169], v[120:121]
	v_and_b32_e32 v23, 0xffff0000, v6
	v_pk_fma_f32 v[0:1], v[136:137], v[28:29], v[0:1]
	v_pk_fma_f32 v[156:157], v[140:141], v[164:165], v[156:157]
	v_pk_fma_f32 v[164:165], v[132:133], v[164:165], v[128:129]
	v_pk_fma_f32 v[168:169], v[144:145], v[22:23], v[0:1]
	v_pk_fma_f32 v[0:1], v[126:127], v[2:3], v[122:123]
	v_pk_fma_f32 v[156:157], v[148:149], v[12:13], v[156:157]
	v_lshlrev_b32_e32 v6, 16, v7
	v_and_b32_e32 v7, 0xffff0000, v7
	v_pk_fma_f32 v[164:165], v[140:141], v[12:13], v[164:165]
	v_pk_fma_f32 v[0:1], v[138:139], v[30:31], v[0:1]
	v_pk_fma_f32 v[12:13], v[132:133], v[12:13], v[128:129]
	v_pk_fma_f32 v[188:189], v[146:147], v[6:7], v[0:1]
	v_lshlrev_b32_e32 v0, 16, v68
	v_and_b32_e32 v1, 0xffff0000, v68
	v_pk_fma_f32 v[12:13], v[140:141], v[20:21], v[12:13]
	v_lshlrev_b32_e32 v2, 16, v69
	v_pk_fma_f32 v[190:191], v[148:149], v[0:1], v[12:13]
	v_pk_fma_f32 v[12:13], v[134:135], v[14:15], v[130:131]
	v_and_b32_e32 v3, 0xffff0000, v69
	v_pk_fma_f32 v[12:13], v[142:143], v[4:5], v[12:13]
	v_lshlrev_b32_e32 v68, 16, v70
	v_pk_fma_f32 v[192:193], v[150:151], v[2:3], v[12:13]
	v_pk_fma_f32 v[12:13], v[124:125], v[28:29], v[120:121]
	v_and_b32_e32 v69, 0xffff0000, v70
	v_pk_fma_f32 v[12:13], v[136:137], v[22:23], v[12:13]
	v_lshlrev_b32_e32 v70, 16, v71
	v_pk_fma_f32 v[194:195], v[144:145], v[68:69], v[12:13]
	v_pk_fma_f32 v[12:13], v[126:127], v[30:31], v[122:123]
	v_and_b32_e32 v71, 0xffff0000, v71
	v_pk_fma_f32 v[12:13], v[138:139], v[6:7], v[12:13]
	v_pk_fma_f32 v[4:5], v[134:135], v[4:5], v[130:131]
	v_pk_fma_f32 v[196:197], v[146:147], v[70:71], v[12:13]
	v_lshlrev_b32_e32 v12, 16, v8
	v_and_b32_e32 v13, 0xffff0000, v8
	v_lshlrev_b32_e32 v8, 16, v9
	v_and_b32_e32 v9, 0xffff0000, v9
	v_pk_fma_f32 v[4:5], v[142:143], v[2:3], v[4:5]
	v_lshlrev_b32_e32 v14, 16, v10
	v_pk_fma_f32 v[200:201], v[150:151], v[8:9], v[4:5]
	v_pk_fma_f32 v[4:5], v[124:125], v[22:23], v[120:121]
	v_and_b32_e32 v15, 0xffff0000, v10
	v_pk_fma_f32 v[4:5], v[136:137], v[68:69], v[4:5]
	v_pk_fma_f32 v[164:165], v[148:149], v[20:21], v[164:165]
	v_pk_fma_f32 v[20:21], v[132:133], v[20:21], v[128:129]
	v_pk_fma_f32 v[202:203], v[144:145], v[14:15], v[4:5]
	v_pk_fma_f32 v[4:5], v[126:127], v[6:7], v[122:123]
	v_lshlrev_b32_e32 v10, 16, v11
	v_and_b32_e32 v11, 0xffff0000, v11
	v_pk_fma_f32 v[20:21], v[140:141], v[0:1], v[20:21]
	v_pk_fma_f32 v[4:5], v[138:139], v[70:71], v[4:5]
	v_pk_fma_f32 v[0:1], v[132:133], v[0:1], v[128:129]
	v_pk_fma_f32 v[212:213], v[146:147], v[10:11], v[4:5]
	v_lshlrev_b32_e32 v4, 16, v112
	v_and_b32_e32 v5, 0xffff0000, v112
	v_pk_fma_f32 v[0:1], v[140:141], v[12:13], v[0:1]
	v_lshlrev_b32_e32 v6, 16, v113
	v_pk_fma_f32 v[214:215], v[148:149], v[4:5], v[0:1]
	v_pk_fma_f32 v[0:1], v[134:135], v[2:3], v[130:131]
;     __device__ __forceinline__ const char* a(const pg8::Unit& u) const { return (const char*)ws + aoff + (size_t)u.pm * 256 * K_ * 2 + (u.kq < 0 ? 0 : u.kq * (K_ / 4) * 2); }
;     __device__ __forceinline__ const char* b(const pg8::Unit& u) const { return (const char*)ws + boff + (size_t)u.pn * 256 * K_ * 2 + (u.kq < 0 ? 0 : u.kq * (K_ / 4) * 2); }
;     __device__ __forceinline__ const char* a(const pg8::Unit& u) const { return (const char*)ws + WS_A + (size_t)u.pm * 256 * D * 2; }
;     __device__ __forceinline__ const char* b(const pg8::Unit& u) const { return (const char*)ws + boff + (size_t)u.pn * 256 * D * 2; }
;     __device__ __forceinline__ const char* a(const pg8::Unit& u) const { return (const char*)ws + WS_A + (size_t)u.pm * 256 * D * 2; }
;     __device__ __forceinline__ const char* b(const pg8::Unit& u) const { return (const char*)ws + boff + (size_t)u.pn * 256 * D * 2; }
;     __device__ __forceinline__ const char* a(const pg8::Unit& u) const { return (const char*)ws + WS_W1 + (size_t)(u.pm & 1) * 256 * 256 * 2; }
;     __device__ __forceinline__ const char* b(const pg8::Unit& u) const { return (const char*)ws + WS_A + ((size_t)u.pn * 256 * D + (size_t)(u.pm >> 1) * 256) * 2; }
;     __device__ __forceinline__ const char* a(const pg8::Unit& u) const { return (const char*)ws + (u.pm < 64 ? WS_W2 : WS_W2C); }
; __device__ __forceinline__ void ffn_conv_phase(Frame& F, int L, int nrows, bool probe_alt = false) {
;     ...
;         FFN_LOAD_ROW(0); FFN_LOAD_ROW(1);
;         f32x2 acc[8][4];
;         { const f32x4* p = (const f32x4*)(cb_ + c0); const f32x4 a = p[0], b = p[1];
; #pragma unroll
;           for (int i = 0; i < 8; ++i) { acc[i][0] = (f32x2){a.x, a.y}; acc[i][1] = (f32x2){a.z, a.w}; acc[i][2] = (f32x2){b.x, b.y}; acc[i][3] = (f32x2){b.z, b.w}; } }
;         FFN_ACC_ROW(0);
;         FFN_LOAD_ROW(2);
; #pragma unroll
;         for (int i = 0; i < 8; ++i) rv[i] = __builtin_nontemporal_load((const u32x4*)(val + (size_t)(rb + tq * 8 + i) * DFF + c0));
;         FFN_ACC_ROW(1);
	v_and_b32_e32 v7, 0xffff0000, v113
	v_pk_fma_f32 v[0:1], v[142:143], v[8:9], v[0:1]
	v_pk_fma_f32 v[198:199], v[148:149], v[12:13], v[20:21]
	v_pk_fma_f32 v[216:217], v[150:151], v[6:7], v[0:1]
	v_pk_fma_f32 v[0:1], v[124:125], v[68:69], v[120:121]
	v_lshlrev_b32_e32 v20, 16, v114
	v_and_b32_e32 v21, 0xffff0000, v114
	v_pk_fma_f32 v[0:1], v[136:137], v[14:15], v[0:1]
	v_pk_fma_f32 v[8:9], v[134:135], v[8:9], v[130:131]
	v_pk_fma_f32 v[218:219], v[144:145], v[20:21], v[0:1]
	v_pk_fma_f32 v[0:1], v[126:127], v[70:71], v[122:123]
	v_lshlrev_b32_e32 v2, 16, v17
	v_and_b32_e32 v3, 0xffff0000, v17
	v_pk_fma_f32 v[8:9], v[142:143], v[6:7], v[8:9]
	v_lshlrev_b32_e32 v22, 16, v115
	v_and_b32_e32 v23, 0xffff0000, v115
	v_pk_fma_f32 v[0:1], v[138:139], v[10:11], v[0:1]
	v_pk_fma_f32 v[224:225], v[150:151], v[2:3], v[8:9]
	v_pk_fma_f32 v[8:9], v[124:125], v[14:15], v[120:121]
	v_pk_fma_f32 v[220:221], v[146:147], v[22:23], v[0:1]
	v_lshlrev_b32_e32 v0, 16, v16
	v_and_b32_e32 v1, 0xffff0000, v16
	v_lshlrev_b32_e32 v16, 16, v18
	v_and_b32_e32 v17, 0xffff0000, v18
	v_pk_fma_f32 v[8:9], v[136:137], v[20:21], v[8:9]
	v_pk_fma_f32 v[12:13], v[132:133], v[12:13], v[128:129]
	v_pk_fma_f32 v[226:227], v[144:145], v[16:17], v[8:9]
	v_pk_fma_f32 v[8:9], v[126:127], v[10:11], v[122:123]
	v_lshlrev_b32_e32 v18, 16, v19
	v_and_b32_e32 v19, 0xffff0000, v19
	v_pk_fma_f32 v[12:13], v[140:141], v[4:5], v[12:13]
	v_pk_fma_f32 v[8:9], v[138:139], v[22:23], v[8:9]
	v_pk_fma_f32 v[4:5], v[132:133], v[4:5], v[128:129]
	v_pk_fma_f32 v[222:223], v[148:149], v[0:1], v[12:13]
	v_pk_fma_f32 v[228:229], v[146:147], v[18:19], v[8:9]
	v_lshlrev_b32_e32 v8, 16, v116
	v_and_b32_e32 v9, 0xffff0000, v116
	v_pk_fma_f32 v[0:1], v[140:141], v[0:1], v[4:5]
	v_lshlrev_b32_e32 v10, 16, v117
	v_pk_fma_f32 v[230:231], v[148:149], v[8:9], v[0:1]
	v_pk_fma_f32 v[0:1], v[134:135], v[6:7], v[130:131]
	v_and_b32_e32 v11, 0xffff0000, v117
	v_pk_fma_f32 v[0:1], v[142:143], v[2:3], v[0:1]
	v_lshlrev_b32_e32 v12, 16, v118
	v_pk_fma_f32 v[232:233], v[150:151], v[10:11], v[0:1]
	v_pk_fma_f32 v[0:1], v[124:125], v[20:21], v[120:121]
	v_and_b32_e32 v13, 0xffff0000, v118
	v_pk_fma_f32 v[0:1], v[136:137], v[16:17], v[0:1]
	v_lshlrev_b32_e32 v14, 16, v119
	v_pk_fma_f32 v[234:235], v[144:145], v[12:13], v[0:1]
	v_pk_fma_f32 v[0:1], v[126:127], v[22:23], v[122:123]
	v_and_b32_e32 v15, 0xffff0000, v119
	v_pk_fma_f32 v[0:1], v[138:139], v[18:19], v[0:1]
	s_mul_i32 s4, s26, s78
	v_pk_fma_f32 v[236:237], v[146:147], v[14:15], v[0:1]
	v_subrev_u32_e32 v0, s4, v176
	v_readlane_b32 s4, v253, 46
	v_add_u32_e32 v2, s101, v0
	v_readlane_b32 s5, v253, 47
	v_add_u32_e32 v3, -7, v2
	v_lshl_add_u64 v[116:117], s[30:31], 0, v[152:153]
	v_lshl_add_u64 v[0:1], v[154:155], 1, s[4:5]
	v_mad_i64_i32 v[150:151], s[4:5], v3, s89, v[0:1]
	v_add_u32_e32 v3, -6, v2
	v_mad_i64_i32 v[148:149], s[4:5], v3, s89, v[0:1]
	v_add_u32_e32 v3, -5, v2
	v_mad_i64_i32 v[146:147], s[4:5], v3, s89, v[0:1]
	v_add_u32_e32 v3, -4, v2
	v_mad_i64_i32 v[144:145], s[4:5], v3, s89, v[0:1]
	v_add_u32_e32 v3, -3, v2
	v_mad_i64_i32 v[142:143], s[4:5], v3, s89, v[0:1]
	v_add_u32_e32 v3, -2, v2
	v_mad_i64_i32 v[140:141], s[4:5], v3, s89, v[0:1]
	v_add_u32_e32 v3, -1, v2
	v_mad_i64_i32 v[138:139], s[4:5], v3, s89, v[0:1]
	v_mad_i64_i32 v[136:137], s[4:5], v2, s89, v[0:1]
	global_load_dwordx4 v[68:71], v[150:151], off nt
	global_load_dwordx4 v[28:31], v[148:149], off nt
	global_load_dwordx4 v[20:23], v[146:147], off nt
	global_load_dwordx4 v[16:19], v[144:145], off nt
	global_load_dwordx4 v[12:15], v[142:143], off nt
	global_load_dwordx4 v[8:11], v[140:141], off nt
	global_load_dwordx4 v[4:7], v[138:139], off nt
	global_load_dwordx4 v[0:3], v[136:137], off nt
	global_load_dwordx4 v[112:115], v[116:117], off offset:16
	global_load_dwordx4 v[120:123], v[116:117], off
	v_lshl_add_u64 v[124:125], s[34:35], 0, v[152:153]
	global_load_dwordx4 v[116:119], v[124:125], off offset:16
	global_load_dwordx4 v[128:131], v[124:125], off
	v_lshl_add_u64 v[132:133], s[44:45], 0, v[152:153]
	global_load_dwordx4 v[124:127], v[132:133], off offset:16
	s_nop 0
	global_load_dwordx4 v[132:135], v[132:133], off
	v_lshlrev_b32_e32 v154, 16, v72
	v_and_b32_e32 v155, 0xffff0000, v72
	v_lshlrev_b32_e32 v72, 16, v73
	v_and_b32_e32 v73, 0xffff0000, v73
	v_lshlrev_b32_e32 v184, 16, v92
	v_and_b32_e32 v185, 0xffff0000, v92
	v_lshlrev_b32_e32 v92, 16, v93
	v_and_b32_e32 v93, 0xffff0000, v93
	v_lshlrev_b32_e32 v182, 16, v74
	v_and_b32_e32 v183, 0xffff0000, v74
	v_lshlrev_b32_e32 v246, 16, v88
	v_and_b32_e32 v247, 0xffff0000, v88
	v_lshlrev_b32_e32 v88, 16, v89
	v_and_b32_e32 v89, 0xffff0000, v89
	v_lshlrev_b32_e32 v186, 16, v94
	v_and_b32_e32 v187, 0xffff0000, v94
	v_lshlrev_b32_e32 v74, 16, v75
	v_and_b32_e32 v75, 0xffff0000, v75
	v_lshlrev_b32_e32 v248, 16, v90
	v_and_b32_e32 v249, 0xffff0000, v90
	v_lshlrev_b32_e32 v94, 16, v95
	v_and_b32_e32 v95, 0xffff0000, v95
	v_lshlrev_b32_e32 v90, 16, v91
	v_and_b32_e32 v91, 0xffff0000, v91
	v_readlane_b32 s4, v255, 28
	s_add_i32 s77, s77, s4
	s_add_i32 s72, s72, s74
	s_cmp_lt_i32 s77, s7
	v_readlane_b32 s5, v255, 29
	s_waitcnt vmcnt(4)
	v_pk_fma_f32 v[72:73], v[122:123], v[72:73], v[172:173]
	v_pk_fma_f32 v[154:155], v[120:121], v[154:155], v[170:171]
	s_waitcnt vmcnt(2)
	v_pk_fma_f32 v[72:73], v[130:131], v[92:93], v[72:73]
	v_pk_fma_f32 v[92:93], v[122:123], v[92:93], v[158:159]
	s_waitcnt vmcnt(0)
	v_pk_fma_f32 v[206:207], v[134:135], v[88:89], v[72:73]
	v_pk_fma_f32 v[72:73], v[112:113], v[182:183], v[174:175]
	v_pk_fma_f32 v[92:93], v[130:131], v[88:89], v[92:93]
	v_pk_fma_f32 v[72:73], v[116:117], v[186:187], v[72:73]
	v_pk_fma_f32 v[88:89], v[122:123], v[88:89], v[166:167]
	v_pk_fma_f32 v[208:209], v[124:125], v[248:249], v[72:73]
	v_pk_fma_f32 v[72:73], v[114:115], v[74:75], v[180:181]
	v_lshlrev_b32_e32 v74, 16, v105
	v_and_b32_e32 v75, 0xffff0000, v105
	v_pk_fma_f32 v[72:73], v[118:119], v[94:95], v[72:73]
	v_pk_fma_f32 v[172:173], v[134:135], v[74:75], v[92:93]
	v_pk_fma_f32 v[92:93], v[112:113], v[186:187], v[160:161]
	v_pk_fma_f32 v[210:211], v[126:127], v[90:91], v[72:73]
	v_lshlrev_b32_e32 v72, 16, v104
	v_and_b32_e32 v73, 0xffff0000, v104
	v_lshlrev_b32_e32 v104, 16, v106
	v_and_b32_e32 v105, 0xffff0000, v106
	v_pk_fma_f32 v[92:93], v[116:117], v[248:249], v[92:93]
	v_lshlrev_b32_e32 v106, 16, v107
	v_pk_fma_f32 v[174:175], v[124:125], v[104:105], v[92:93]
	v_pk_fma_f32 v[92:93], v[114:115], v[94:95], v[162:163]
	v_and_b32_e32 v107, 0xffff0000, v107
	v_pk_fma_f32 v[92:93], v[118:119], v[90:91], v[92:93]
	v_pk_fma_f32 v[154:155], v[128:129], v[184:185], v[154:155]
	v_pk_fma_f32 v[180:181], v[126:127], v[106:107], v[92:93]
	v_lshlrev_b32_e32 v92, 16, v80
	v_and_b32_e32 v93, 0xffff0000, v80
	v_lshlrev_b32_e32 v80, 16, v81
	v_and_b32_e32 v81, 0xffff0000, v81
	v_pk_fma_f32 v[88:89], v[130:131], v[74:75], v[88:89]
	v_pk_fma_f32 v[204:205], v[132:133], v[246:247], v[154:155]
	v_pk_fma_f32 v[154:155], v[120:121], v[184:185], v[156:157]
	v_pk_fma_f32 v[184:185], v[134:135], v[80:81], v[88:89]
	v_pk_fma_f32 v[88:89], v[112:113], v[248:249], v[168:169]
	v_pk_fma_f32 v[154:155], v[128:129], v[246:247], v[154:155]
	v_lshlrev_b32_e32 v94, 16, v82
	v_and_b32_e32 v95, 0xffff0000, v82
	v_pk_fma_f32 v[88:89], v[116:117], v[104:105], v[88:89]
	v_pk_fma_f32 v[170:171], v[132:133], v[72:73], v[154:155]
	v_pk_fma_f32 v[154:155], v[120:121], v[246:247], v[164:165]
	v_pk_fma_f32 v[186:187], v[124:125], v[94:95], v[88:89]
	v_pk_fma_f32 v[88:89], v[114:115], v[90:91], v[188:189]
	v_lshlrev_b32_e32 v82, 16, v83
	v_and_b32_e32 v83, 0xffff0000, v83
	v_pk_fma_f32 v[154:155], v[128:129], v[72:73], v[154:155]
	v_pk_fma_f32 v[88:89], v[118:119], v[106:107], v[88:89]
	v_pk_fma_f32 v[72:73], v[120:121], v[72:73], v[190:191]
	v_pk_fma_f32 v[188:189], v[126:127], v[82:83], v[88:89]
	v_lshlrev_b32_e32 v88, 16, v100
	v_and_b32_e32 v89, 0xffff0000, v100
	v_pk_fma_f32 v[72:73], v[128:129], v[92:93], v[72:73]
	v_lshlrev_b32_e32 v90, 16, v101
	v_and_b32_e32 v91, 0xffff0000, v101
	v_pk_fma_f32 v[100:101], v[132:133], v[88:89], v[72:73]
	v_pk_fma_f32 v[72:73], v[122:123], v[74:75], v[192:193]
	v_pk_fma_f32 v[182:183], v[132:133], v[92:93], v[154:155]
	v_pk_fma_f32 v[72:73], v[130:131], v[80:81], v[72:73]
	v_lshlrev_b32_e32 v154, 16, v102
	v_pk_fma_f32 v[190:191], v[134:135], v[90:91], v[72:73]
	v_pk_fma_f32 v[72:73], v[112:113], v[104:105], v[194:195]
	v_and_b32_e32 v155, 0xffff0000, v102
	v_pk_fma_f32 v[72:73], v[116:117], v[94:95], v[72:73]
	v_pk_fma_f32 v[80:81], v[122:123], v[80:81], v[200:201]
	v_pk_fma_f32 v[192:193], v[124:125], v[154:155], v[72:73]
	v_pk_fma_f32 v[72:73], v[114:115], v[106:107], v[196:197]
	v_lshlrev_b32_e32 v74, 16, v77
	v_and_b32_e32 v75, 0xffff0000, v77
	v_pk_fma_f32 v[80:81], v[130:131], v[90:91], v[80:81]
	v_lshlrev_b32_e32 v102, 16, v103
	v_and_b32_e32 v103, 0xffff0000, v103
	v_pk_fma_f32 v[72:73], v[118:119], v[82:83], v[72:73]
	v_pk_fma_f32 v[92:93], v[120:121], v[92:93], v[198:199]
	v_pk_fma_f32 v[198:199], v[134:135], v[74:75], v[80:81]
	v_pk_fma_f32 v[80:81], v[112:113], v[94:95], v[202:203]
	v_pk_fma_f32 v[194:195], v[126:127], v[102:103], v[72:73]
	v_lshlrev_b32_e32 v72, 16, v76
	v_and_b32_e32 v73, 0xffff0000, v76
	v_lshlrev_b32_e32 v76, 16, v78
	v_and_b32_e32 v77, 0xffff0000, v78
	v_pk_fma_f32 v[80:81], v[116:117], v[154:155], v[80:81]
	v_lshlrev_b32_e32 v78, 16, v79
	v_pk_fma_f32 v[200:201], v[124:125], v[76:77], v[80:81]
	v_pk_fma_f32 v[80:81], v[114:115], v[82:83], v[212:213]
	v_and_b32_e32 v79, 0xffff0000, v79
	v_pk_fma_f32 v[92:93], v[128:129], v[88:89], v[92:93]
	v_pk_fma_f32 v[80:81], v[118:119], v[102:103], v[80:81]
	v_pk_fma_f32 v[88:89], v[120:121], v[88:89], v[214:215]
	v_pk_fma_f32 v[202:203], v[126:127], v[78:79], v[80:81]
	v_lshlrev_b32_e32 v80, 16, v96
	v_and_b32_e32 v81, 0xffff0000, v96
	v_pk_fma_f32 v[88:89], v[128:129], v[72:73], v[88:89]
	v_lshlrev_b32_e32 v82, 16, v97
	v_pk_fma_f32 v[168:169], v[132:133], v[80:81], v[88:89]
	v_pk_fma_f32 v[88:89], v[122:123], v[90:91], v[216:217]
	v_and_b32_e32 v83, 0xffff0000, v97
	v_pk_fma_f32 v[88:89], v[130:131], v[74:75], v[88:89]
	v_pk_fma_f32 v[196:197], v[132:133], v[72:73], v[92:93]
	v_pk_fma_f32 v[166:167], v[134:135], v[82:83], v[88:89]
	v_pk_fma_f32 v[88:89], v[112:113], v[154:155], v[218:219]
	v_lshlrev_b32_e32 v92, 16, v98
	v_and_b32_e32 v93, 0xffff0000, v98
	v_pk_fma_f32 v[88:89], v[116:117], v[76:77], v[88:89]
	v_lshlrev_b32_e32 v94, 16, v99
	v_pk_fma_f32 v[164:165], v[124:125], v[92:93], v[88:89]
	v_pk_fma_f32 v[88:89], v[114:115], v[102:103], v[220:221]
	v_and_b32_e32 v95, 0xffff0000, v99
	v_pk_fma_f32 v[88:89], v[118:119], v[78:79], v[88:89]
	v_pk_fma_f32 v[72:73], v[120:121], v[72:73], v[222:223]
	v_pk_fma_f32 v[162:163], v[126:127], v[94:95], v[88:89]
	v_lshlrev_b32_e32 v88, 16, v84
	v_and_b32_e32 v89, 0xffff0000, v84
	v_pk_fma_f32 v[72:73], v[128:129], v[80:81], v[72:73]
	v_lshlrev_b32_e32 v84, 16, v85
	v_pk_fma_f32 v[160:161], v[132:133], v[88:89], v[72:73]
	v_pk_fma_f32 v[72:73], v[122:123], v[74:75], v[224:225]
	v_and_b32_e32 v85, 0xffff0000, v85
;     __device__ __forceinline__ const char* a(const pg8::Unit& u) const { return (const char*)ws + aoff + (size_t)u.pm * 256 * K_ * 2 + (u.kq < 0 ? 0 : u.kq * (K_ / 4) * 2); }
;     __device__ __forceinline__ const char* b(const pg8::Unit& u) const { return (const char*)ws + boff + (size_t)u.pn * 256 * K_ * 2 + (u.kq < 0 ? 0 : u.kq * (K_ / 4) * 2); }
;     __device__ __forceinline__ const char* a(const pg8::Unit& u) const { return (const char*)ws + WS_A + (size_t)u.pm * 256 * D * 2; }
;     __device__ __forceinline__ const char* b(const pg8::Unit& u) const { return (const char*)ws + boff + (size_t)u.pn * 256 * D * 2; }
;     __device__ __forceinline__ const char* a(const pg8::Unit& u) const { return (const char*)ws + WS_A + (size_t)u.pm * 256 * D * 2; }
;     __device__ __forceinline__ const char* b(const pg8::Unit& u) const { return (const char*)ws + boff + (size_t)u.pn * 256 * D * 2; }
;     __device__ __forceinline__ const char* a(const pg8::Unit& u) const { return (const char*)ws + WS_W1 + (size_t)(u.pm & 1) * 256 * 256 * 2; }
;     __device__ __forceinline__ const char* b(const pg8::Unit& u) const { return (const char*)ws + WS_A + ((size_t)u.pn * 256 * D + (size_t)(u.pm >> 1) * 256) * 2; }
;     __device__ __forceinline__ const char* a(const pg8::Unit& u) const { return (const char*)ws + (u.pm < 64 ? WS_W2 : WS_W2C); }
; __device__ __forceinline__ void ffn_conv_phase(Frame& F, int L, int nrows, bool probe_alt = false) {
;     ...
;         FFN_LOAD_ROW(0); FFN_LOAD_ROW(1);
;         f32x2 acc[8][4];
;         { const f32x4* p = (const f32x4*)(cb_ + c0); const f32x4 a = p[0], b = p[1];
; #pragma unroll
;           for (int i = 0; i < 8; ++i) { acc[i][0] = (f32x2){a.x, a.y}; acc[i][1] = (f32x2){a.z, a.w}; acc[i][2] = (f32x2){b.x, b.y}; acc[i][3] = (f32x2){b.z, b.w}; } }
;         FFN_ACC_ROW(0);
;         FFN_LOAD_ROW(2);
; #pragma unroll
;         for (int i = 0; i < 8; ++i) rv[i] = __builtin_nontemporal_load((const u32x4*)(val + (size_t)(rb + tq * 8 + i) * DFF + c0));
;         FFN_ACC_ROW(1);
;         FFN_ACC_ROW(2);
	v_pk_fma_f32 v[72:73], v[130:131], v[82:83], v[72:73]
	v_lshlrev_b32_e32 v90, 16, v86
	v_pk_fma_f32 v[158:159], v[134:135], v[84:85], v[72:73]
	v_pk_fma_f32 v[72:73], v[112:113], v[76:77], v[226:227]
	v_and_b32_e32 v91, 0xffff0000, v86
	v_pk_fma_f32 v[72:73], v[116:117], v[92:93], v[72:73]
	v_lshlrev_b32_e32 v86, 16, v87
	v_pk_fma_f32 v[156:157], v[124:125], v[90:91], v[72:73]
	v_pk_fma_f32 v[72:73], v[114:115], v[78:79], v[228:229]
	v_and_b32_e32 v87, 0xffff0000, v87
	v_pk_fma_f32 v[72:73], v[118:119], v[94:95], v[72:73]
	v_pk_fma_f32 v[80:81], v[120:121], v[80:81], v[230:231]
	v_pk_fma_f32 v[154:155], v[126:127], v[86:87], v[72:73]
	v_lshlrev_b32_e32 v72, 16, v108
	v_and_b32_e32 v73, 0xffff0000, v108
	v_pk_fma_f32 v[80:81], v[128:129], v[88:89], v[80:81]
	v_lshlrev_b32_e32 v76, 16, v110
	v_and_b32_e32 v77, 0xffff0000, v110
	v_lshlrev_b32_e32 v78, 16, v111
	v_and_b32_e32 v79, 0xffff0000, v111
	v_pk_fma_f32 v[110:111], v[132:133], v[72:73], v[80:81]
	v_pk_fma_f32 v[72:73], v[122:123], v[82:83], v[232:233]
	v_lshlrev_b32_e32 v74, 16, v109
	v_and_b32_e32 v75, 0xffff0000, v109
	v_pk_fma_f32 v[72:73], v[130:131], v[84:85], v[72:73]
	v_lshl_add_u64 v[84:85], s[48:49], 0, v[152:153]
	v_pk_fma_f32 v[106:107], v[134:135], v[74:75], v[72:73]
	v_pk_fma_f32 v[72:73], v[112:113], v[92:93], v[234:235]
	v_lshl_add_u64 v[92:93], s[50:51], 0, v[152:153]
	v_pk_fma_f32 v[72:73], v[116:117], v[90:91], v[72:73]
	v_lshlrev_b32_e32 v96, 16, v24
	v_pk_fma_f32 v[104:105], v[124:125], v[76:77], v[72:73]
	v_pk_fma_f32 v[72:73], v[114:115], v[94:95], v[236:237]
	v_lshl_add_u64 v[76:77], s[46:47], 0, v[152:153]
	v_pk_fma_f32 v[72:73], v[118:119], v[86:87], v[72:73]
	v_and_b32_e32 v97, 0xffff0000, v24
	v_pk_fma_f32 v[102:103], v[126:127], v[78:79], v[72:73]
	global_load_dwordx4 v[72:75], v[76:77], off offset:16
	global_load_dwordx4 v[80:83], v[76:77], off
	s_nop 0
	global_load_dwordx4 v[76:79], v[84:85], off offset:16
	global_load_dwordx4 v[88:91], v[84:85], off
	s_nop 0
	global_load_dwordx4 v[84:87], v[92:93], off offset:16
	s_nop 0
	global_load_dwordx4 v[92:95], v[92:93], off
	v_lshlrev_b32_e32 v24, 16, v25
	v_and_b32_e32 v25, 0xffff0000, v25
	v_lshlrev_b32_e32 v108, 16, v48
	v_and_b32_e32 v109, 0xffff0000, v48
	v_lshlrev_b32_e32 v48, 16, v49
	v_and_b32_e32 v49, 0xffff0000, v49
	v_lshlrev_b32_e32 v98, 16, v26
	v_and_b32_e32 v99, 0xffff0000, v26
	v_lshlrev_b32_e32 v114, 16, v44
	v_and_b32_e32 v115, 0xffff0000, v44
	v_lshlrev_b32_e32 v44, 16, v45
	v_and_b32_e32 v45, 0xffff0000, v45
	v_lshlrev_b32_e32 v112, 16, v50
	v_and_b32_e32 v113, 0xffff0000, v50
	v_lshlrev_b32_e32 v26, 16, v27
	v_and_b32_e32 v27, 0xffff0000, v27
	v_lshlrev_b32_e32 v152, 16, v46
	v_and_b32_e32 v153, 0xffff0000, v46
	v_lshlrev_b32_e32 v50, 16, v51
	v_and_b32_e32 v51, 0xffff0000, v51
	v_lshlrev_b32_e32 v46, 16, v47
	v_and_b32_e32 v47, 0xffff0000, v47
	s_waitcnt vmcnt(4)
	v_pk_fma_f32 v[24:25], v[82:83], v[24:25], v[206:207]
	s_waitcnt vmcnt(2)
	v_pk_fma_f32 v[24:25], v[90:91], v[48:49], v[24:25]
	v_pk_fma_f32 v[48:49], v[82:83], v[48:49], v[172:173]
	s_waitcnt vmcnt(0)
	v_pk_fma_f32 v[132:133], v[94:95], v[44:45], v[24:25]
	v_pk_fma_f32 v[24:25], v[72:73], v[98:99], v[208:209]
	v_pk_fma_f32 v[48:49], v[90:91], v[44:45], v[48:49]
	v_pk_fma_f32 v[24:25], v[76:77], v[112:113], v[24:25]
	v_pk_fma_f32 v[96:97], v[80:81], v[96:97], v[204:205]
	v_pk_fma_f32 v[130:131], v[84:85], v[152:153], v[24:25]
	v_pk_fma_f32 v[24:25], v[74:75], v[26:27], v[210:211]
	v_lshlrev_b32_e32 v26, 16, v65
	v_and_b32_e32 v27, 0xffff0000, v65
	v_pk_fma_f32 v[24:25], v[78:79], v[50:51], v[24:25]
	v_pk_fma_f32 v[124:125], v[94:95], v[26:27], v[48:49]
	v_pk_fma_f32 v[48:49], v[72:73], v[112:113], v[174:175]
	v_pk_fma_f32 v[128:129], v[86:87], v[46:47], v[24:25]
	v_lshlrev_b32_e32 v24, 16, v64
	v_and_b32_e32 v25, 0xffff0000, v64
	v_lshlrev_b32_e32 v64, 16, v66
	v_and_b32_e32 v65, 0xffff0000, v66
	v_pk_fma_f32 v[48:49], v[76:77], v[152:153], v[48:49]
	v_lshlrev_b32_e32 v66, 16, v67
	v_pk_fma_f32 v[122:123], v[84:85], v[64:65], v[48:49]
	v_pk_fma_f32 v[48:49], v[74:75], v[50:51], v[180:181]
	v_and_b32_e32 v67, 0xffff0000, v67
	v_pk_fma_f32 v[48:49], v[78:79], v[46:47], v[48:49]
	v_pk_fma_f32 v[44:45], v[82:83], v[44:45], v[184:185]
	v_pk_fma_f32 v[96:97], v[88:89], v[108:109], v[96:97]
	v_pk_fma_f32 v[120:121], v[86:87], v[66:67], v[48:49]
	v_lshlrev_b32_e32 v48, 16, v40
	v_and_b32_e32 v49, 0xffff0000, v40
	v_lshlrev_b32_e32 v40, 16, v41
	v_and_b32_e32 v41, 0xffff0000, v41
	v_pk_fma_f32 v[44:45], v[90:91], v[26:27], v[44:45]
	v_pk_fma_f32 v[134:135], v[92:93], v[114:115], v[96:97]
	v_pk_fma_f32 v[96:97], v[80:81], v[108:109], v[170:171]
	v_pk_fma_f32 v[116:117], v[94:95], v[40:41], v[44:45]
	v_pk_fma_f32 v[44:45], v[72:73], v[152:153], v[186:187]
	v_pk_fma_f32 v[96:97], v[88:89], v[114:115], v[96:97]
	v_lshlrev_b32_e32 v50, 16, v42
	v_and_b32_e32 v51, 0xffff0000, v42
	v_pk_fma_f32 v[44:45], v[76:77], v[64:65], v[44:45]
	v_pk_fma_f32 v[126:127], v[92:93], v[24:25], v[96:97]
	v_pk_fma_f32 v[96:97], v[80:81], v[114:115], v[182:183]
	v_pk_fma_f32 v[114:115], v[84:85], v[50:51], v[44:45]
	v_pk_fma_f32 v[44:45], v[74:75], v[46:47], v[188:189]
	v_lshlrev_b32_e32 v42, 16, v43
	v_and_b32_e32 v43, 0xffff0000, v43
	v_pk_fma_f32 v[96:97], v[88:89], v[24:25], v[96:97]
	v_pk_fma_f32 v[44:45], v[78:79], v[66:67], v[44:45]
	v_pk_fma_f32 v[24:25], v[80:81], v[24:25], v[100:101]
	v_pk_fma_f32 v[112:113], v[86:87], v[42:43], v[44:45]
	v_lshlrev_b32_e32 v44, 16, v60
	v_and_b32_e32 v45, 0xffff0000, v60
	v_pk_fma_f32 v[24:25], v[88:89], v[48:49], v[24:25]
	v_lshlrev_b32_e32 v46, 16, v61
	v_pk_fma_f32 v[108:109], v[92:93], v[44:45], v[24:25]
; __device__ __forceinline__ float silu_f(float v) { return v * __builtin_amdgcn_rcpf(1.0f + __expf(-v)); }
; __device__ __forceinline__ void ffn_conv_phase(Frame& F, int L, int nrows, bool probe_alt = false) {
;     ...
;         FFN_ACC_ROW(1);
;         FFN_ACC_ROW(2);
;     ...
; #pragma unroll
;         for (int i = 0; i < 8; ++i) { bf16_t* vp = val + (size_t)(rb + tq * 8 + i) * DFF + c0; float v[8]; unpack8(rv[i], v);
; #pragma unroll
;             for (int c = 0; c < 4; ++c) { v[2 * c] *= silu_f(acc[i][c].x); v[2 * c + 1] *= silu_f(acc[i][c].y); }
	v_pk_fma_f32 v[24:25], v[82:83], v[26:27], v[190:191]
	v_and_b32_e32 v47, 0xffff0000, v61
	v_pk_fma_f32 v[24:25], v[90:91], v[40:41], v[24:25]
	v_lshlrev_b32_e32 v152, 16, v62
	v_pk_fma_f32 v[100:101], v[94:95], v[46:47], v[24:25]
	v_pk_fma_f32 v[24:25], v[72:73], v[64:65], v[192:193]
	v_and_b32_e32 v153, 0xffff0000, v62
	v_pk_fma_f32 v[24:25], v[76:77], v[50:51], v[24:25]
	v_lshlrev_b32_e32 v170, 16, v63
	v_pk_fma_f32 v[98:99], v[84:85], v[152:153], v[24:25]
	v_pk_fma_f32 v[24:25], v[74:75], v[66:67], v[194:195]
	v_and_b32_e32 v171, 0xffff0000, v63
	v_pk_fma_f32 v[24:25], v[78:79], v[42:43], v[24:25]
	v_pk_fma_f32 v[118:119], v[92:93], v[48:49], v[96:97]
	v_pk_fma_f32 v[96:97], v[86:87], v[170:171], v[24:25]
	v_lshlrev_b32_e32 v24, 16, v36
	v_and_b32_e32 v25, 0xffff0000, v36
	v_lshlrev_b32_e32 v26, 16, v37
	v_and_b32_e32 v27, 0xffff0000, v37
	v_lshlrev_b32_e32 v36, 16, v38
	v_and_b32_e32 v37, 0xffff0000, v38
	v_lshlrev_b32_e32 v172, 16, v39
	v_and_b32_e32 v173, 0xffff0000, v39
	v_pk_fma_f32 v[38:39], v[80:81], v[48:49], v[196:197]
	v_lshlrev_b32_e32 v174, 16, v56
	v_pk_fma_f32 v[38:39], v[88:89], v[44:45], v[38:39]
	v_and_b32_e32 v175, 0xffff0000, v56
	v_pk_fma_f32 v[66:67], v[92:93], v[24:25], v[38:39]
	v_pk_fma_f32 v[38:39], v[82:83], v[40:41], v[198:199]
	v_lshlrev_b32_e32 v56, 16, v57
	v_pk_fma_f32 v[38:39], v[90:91], v[46:47], v[38:39]
	v_and_b32_e32 v57, 0xffff0000, v57
	v_pk_fma_f32 v[64:65], v[94:95], v[26:27], v[38:39]
	v_pk_fma_f32 v[38:39], v[72:73], v[50:51], v[200:201]
	v_lshlrev_b32_e32 v180, 16, v58
	v_pk_fma_f32 v[38:39], v[76:77], v[152:153], v[38:39]
	v_and_b32_e32 v181, 0xffff0000, v58
	v_pk_fma_f32 v[62:63], v[84:85], v[36:37], v[38:39]
	v_pk_fma_f32 v[38:39], v[74:75], v[42:43], v[202:203]
	v_lshlrev_b32_e32 v58, 16, v59
	v_pk_fma_f32 v[38:39], v[78:79], v[170:171], v[38:39]
	v_and_b32_e32 v59, 0xffff0000, v59
	v_pk_fma_f32 v[60:61], v[86:87], v[172:173], v[38:39]
	v_pk_fma_f32 v[38:39], v[80:81], v[44:45], v[168:169]
	s_nop 0
	v_pk_fma_f32 v[38:39], v[88:89], v[24:25], v[38:39]
	v_pk_fma_f32 v[24:25], v[80:81], v[24:25], v[160:161]
	v_pk_fma_f32 v[50:51], v[92:93], v[174:175], v[38:39]
	v_pk_fma_f32 v[38:39], v[82:83], v[46:47], v[166:167]
	v_pk_fma_f32 v[24:25], v[88:89], v[174:175], v[24:25]
	v_pk_fma_f32 v[38:39], v[90:91], v[26:27], v[38:39]
	s_nop 0
	v_pk_fma_f32 v[48:49], v[94:95], v[56:57], v[38:39]
	v_pk_fma_f32 v[38:39], v[72:73], v[152:153], v[164:165]
	v_lshlrev_b32_e32 v152, 16, v32
	v_and_b32_e32 v153, 0xffff0000, v32
	v_pk_fma_f32 v[42:43], v[92:93], v[152:153], v[24:25]
	v_pk_fma_f32 v[24:25], v[82:83], v[26:27], v[158:159]
	v_pk_fma_f32 v[38:39], v[76:77], v[36:37], v[38:39]
	v_lshlrev_b32_e32 v32, 16, v33
	v_and_b32_e32 v33, 0xffff0000, v33
	v_pk_fma_f32 v[24:25], v[90:91], v[56:57], v[24:25]
	v_pk_fma_f32 v[46:47], v[84:85], v[180:181], v[38:39]
	v_pk_fma_f32 v[38:39], v[74:75], v[170:171], v[162:163]
	v_pk_fma_f32 v[40:41], v[94:95], v[32:33], v[24:25]
	v_pk_fma_f32 v[24:25], v[72:73], v[36:37], v[156:157]
	v_pk_fma_f32 v[38:39], v[78:79], v[172:173], v[38:39]
	v_lshlrev_b32_e32 v162, 16, v34
	v_and_b32_e32 v163, 0xffff0000, v34
	v_pk_fma_f32 v[24:25], v[76:77], v[180:181], v[24:25]
	v_pk_fma_f32 v[44:45], v[86:87], v[58:59], v[38:39]
	v_pk_fma_f32 v[38:39], v[84:85], v[162:163], v[24:25]
	v_pk_fma_f32 v[24:25], v[74:75], v[172:173], v[154:155]
	v_lshlrev_b32_e32 v164, 16, v35
	v_and_b32_e32 v165, 0xffff0000, v35
	v_pk_fma_f32 v[24:25], v[78:79], v[58:59], v[24:25]
	v_pk_fma_f32 v[34:35], v[80:81], v[174:175], v[110:111]
	v_pk_fma_f32 v[36:37], v[86:87], v[164:165], v[24:25]
	v_lshlrev_b32_e32 v24, 16, v52
	v_and_b32_e32 v25, 0xffff0000, v52
	v_pk_fma_f32 v[34:35], v[88:89], v[152:153], v[34:35]
	v_lshlrev_b32_e32 v26, 16, v53
	v_pk_fma_f32 v[34:35], v[92:93], v[24:25], v[34:35]
	v_pk_fma_f32 v[24:25], v[82:83], v[56:57], v[106:107]
	v_and_b32_e32 v27, 0xffff0000, v53
	v_pk_fma_f32 v[24:25], v[90:91], v[32:33], v[24:25]
	v_lshlrev_b32_e32 v52, 16, v54
	v_pk_fma_f32 v[32:33], v[94:95], v[26:27], v[24:25]
	v_pk_fma_f32 v[24:25], v[72:73], v[180:181], v[104:105]
	v_and_b32_e32 v53, 0xffff0000, v54
	v_pk_fma_f32 v[24:25], v[76:77], v[162:163], v[24:25]
	v_lshlrev_b32_e32 v54, 16, v55
	v_pk_fma_f32 v[26:27], v[84:85], v[52:53], v[24:25]
	v_mul_f32_e32 v52, 0xbfb8aa3b, v134
	v_mul_f32_e32 v53, 0xbfb8aa3b, v135
	v_exp_f32_e32 v52, v52
	v_exp_f32_e32 v53, v53
	v_pk_fma_f32 v[24:25], v[74:75], v[58:59], v[102:103]
	v_and_b32_e32 v55, 0xffff0000, v55
	v_add_f32_e32 v52, 1.0, v52
	v_add_f32_e32 v53, 1.0, v53
	v_rcp_f32_e32 v52, v52
	v_rcp_f32_e32 v53, v53
	v_pk_fma_f32 v[24:25], v[78:79], v[164:165], v[24:25]
	v_lshlrev_b32_e32 v56, 16, v69
	v_pk_fma_f32 v[24:25], v[86:87], v[54:55], v[24:25]
	v_lshlrev_b32_e32 v54, 16, v68
	v_and_b32_e32 v55, 0xffff0000, v68
	v_pk_mul_f32 v[52:53], v[134:135], v[52:53]
	v_and_b32_e32 v57, 0xffff0000, v69
	v_pk_mul_f32 v[52:53], v[52:53], v[54:55]
	v_mul_f32_e32 v54, 0xbfb8aa3b, v132
	v_mul_f32_e32 v55, 0xbfb8aa3b, v133
	v_exp_f32_e32 v54, v54
	v_exp_f32_e32 v55, v55
	v_lshlrev_b32_e32 v58, 16, v70
	v_and_b32_e32 v59, 0xffff0000, v70
	v_add_f32_e32 v54, 1.0, v54
	v_add_f32_e32 v55, 1.0, v55
	v_rcp_f32_e32 v54, v54
	v_rcp_f32_e32 v55, v55
	v_lshlrev_b32_e32 v68, 16, v71
	v_and_b32_e32 v69, 0xffff0000, v71
	v_cvt_pk_bf16_f32 v52, v52, v53
	v_pk_mul_f32 v[54:55], v[132:133], v[54:55]
	s_nop 0
	v_pk_mul_f32 v[54:55], v[54:55], v[56:57]
	v_mul_f32_e32 v56, 0xbfb8aa3b, v130
	v_mul_f32_e32 v57, 0xbfb8aa3b, v131
	v_exp_f32_e32 v56, v56
	v_exp_f32_e32 v57, v57
	v_cvt_pk_bf16_f32 v53, v54, v55
	v_add_f32_e32 v56, 1.0, v56
	v_add_f32_e32 v57, 1.0, v57
	v_rcp_f32_e32 v56, v56
; __device__ __forceinline__ float silu_f(float v) { return v * __builtin_amdgcn_rcpf(1.0f + __expf(-v)); }
; __device__ __forceinline__ u32x4 pack8(const float (&f)[8]) { u32x4 w; w.x = cvt_pk_bf16(f[0], f[1]); w.y = cvt_pk_bf16(f[2], f[3]); w.z = cvt_pk_bf16(f[4], f[5]); w.w = cvt_pk_bf16(f[6], f[7]); return w; }
; __device__ __forceinline__ void ffn_conv_phase(Frame& F, int L, int nrows, bool probe_alt = false) {
;     ...
; #pragma unroll
;         for (int i = 0; i < 8; ++i) { bf16_t* vp = val + (size_t)(rb + tq * 8 + i) * DFF + c0; float v[8]; unpack8(rv[i], v);
; #pragma unroll
;             for (int c = 0; c < 4; ++c) { v[2 * c] *= silu_f(acc[i][c].x); v[2 * c + 1] *= silu_f(acc[i][c].y); }
;             *(u32x4*)(probe_alt ? vp + (size_t)202 * MiB / 2 : vp) = pack8(v); }
	v_rcp_f32_e32 v57, v57
	s_nop 0
	v_pk_mul_f32 v[56:57], v[130:131], v[56:57]
	s_nop 0
	v_pk_mul_f32 v[56:57], v[56:57], v[58:59]
	v_mul_f32_e32 v58, 0xbfb8aa3b, v128
	v_mul_f32_e32 v59, 0xbfb8aa3b, v129
	v_exp_f32_e32 v58, v58
	v_exp_f32_e32 v59, v59
	v_cvt_pk_bf16_f32 v54, v56, v57
	v_lshlrev_b32_e32 v56, 16, v30
	v_add_f32_e32 v58, 1.0, v58
	v_add_f32_e32 v59, 1.0, v59
	v_rcp_f32_e32 v58, v58
	v_rcp_f32_e32 v59, v59
	v_and_b32_e32 v57, 0xffff0000, v30
	v_lshlrev_b32_e32 v30, 16, v31
	v_and_b32_e32 v31, 0xffff0000, v31
	v_pk_mul_f32 v[58:59], v[128:129], v[58:59]
	s_nop 0
	v_pk_mul_f32 v[58:59], v[58:59], v[68:69]
	s_nop 0
	v_cvt_pk_bf16_f32 v55, v58, v59
	global_store_dwordx4 v[150:151], v[52:55], off sc1
	s_nop 1
	v_mul_f32_e32 v52, 0xbfb8aa3b, v126
	v_mul_f32_e32 v53, 0xbfb8aa3b, v127
	v_exp_f32_e32 v52, v52
	v_exp_f32_e32 v53, v53
	v_lshlrev_b32_e32 v54, 16, v28
	v_and_b32_e32 v55, 0xffff0000, v28
	v_add_f32_e32 v52, 1.0, v52
	v_add_f32_e32 v53, 1.0, v53
	v_mul_f32_e32 v28, 0xbfb8aa3b, v124
	v_rcp_f32_e32 v52, v52
	v_rcp_f32_e32 v53, v53
	v_exp_f32_e32 v28, v28
	v_pk_mul_f32 v[52:53], v[126:127], v[52:53]
	v_add_f32_e32 v28, 1.0, v28
	v_pk_mul_f32 v[52:53], v[52:53], v[54:55]
	v_rcp_f32_e32 v54, v28
	v_mul_f32_e32 v28, 0xbfb8aa3b, v125
	v_exp_f32_e32 v28, v28
	s_nop 0
	v_add_f32_e32 v28, 1.0, v28
	v_rcp_f32_e32 v55, v28
	v_lshlrev_b32_e32 v28, 16, v29
	v_and_b32_e32 v29, 0xffff0000, v29
	v_pk_mul_f32 v[54:55], v[124:125], v[54:55]
	s_nop 0
	v_pk_mul_f32 v[54:55], v[54:55], v[28:29]
	v_mul_f32_e32 v28, 0xbfb8aa3b, v122
	v_mul_f32_e32 v29, 0xbfb8aa3b, v123
	v_exp_f32_e32 v28, v28
	v_exp_f32_e32 v29, v29
	v_add_f32_e32 v28, 1.0, v28
	v_add_f32_e32 v29, 1.0, v29
	v_rcp_f32_e32 v28, v28
	v_rcp_f32_e32 v29, v29
	s_nop 0
	v_pk_mul_f32 v[28:29], v[122:123], v[28:29]
	s_nop 0
	v_pk_mul_f32 v[56:57], v[28:29], v[56:57]
	v_mul_f32_e32 v28, 0xbfb8aa3b, v120
	v_mul_f32_e32 v29, 0xbfb8aa3b, v121
	v_exp_f32_e32 v28, v28
	v_exp_f32_e32 v29, v29
	v_add_f32_e32 v28, 1.0, v28
	v_add_f32_e32 v29, 1.0, v29
	v_rcp_f32_e32 v28, v28
	v_rcp_f32_e32 v29, v29
	s_nop 0
	v_pk_mul_f32 v[28:29], v[120:121], v[28:29]
	s_nop 0
	v_pk_mul_f32 v[58:59], v[28:29], v[30:31]
	v_cvt_pk_bf16_f32 v28, v52, v53
	v_cvt_pk_bf16_f32 v29, v54, v55
	v_cvt_pk_bf16_f32 v30, v56, v57
	v_cvt_pk_bf16_f32 v31, v58, v59
	global_store_dwordx4 v[148:149], v[28:31], off sc1
	v_lshlrev_b32_e32 v52, 16, v22
	v_and_b32_e32 v53, 0xffff0000, v22
	v_mul_f32_e32 v28, 0xbfb8aa3b, v118
	v_mul_f32_e32 v29, 0xbfb8aa3b, v119
	v_exp_f32_e32 v28, v28
	v_exp_f32_e32 v29, v29
	v_lshlrev_b32_e32 v30, 16, v20
	v_and_b32_e32 v31, 0xffff0000, v20
	v_add_f32_e32 v28, 1.0, v28
	v_add_f32_e32 v29, 1.0, v29
	v_mul_f32_e32 v20, 0xbfb8aa3b, v116
	v_rcp_f32_e32 v28, v28
	v_rcp_f32_e32 v29, v29
	v_exp_f32_e32 v20, v20
	v_lshlrev_b32_e32 v22, 16, v23
	v_and_b32_e32 v23, 0xffff0000, v23
	v_pk_mul_f32 v[28:29], v[118:119], v[28:29]
	v_add_f32_e32 v20, 1.0, v20
	v_pk_mul_f32 v[28:29], v[28:29], v[30:31]
	v_rcp_f32_e32 v30, v20
	v_mul_f32_e32 v20, 0xbfb8aa3b, v117
	v_exp_f32_e32 v20, v20
	s_nop 0
	v_add_f32_e32 v20, 1.0, v20
	v_rcp_f32_e32 v31, v20
	v_lshlrev_b32_e32 v20, 16, v21
	v_and_b32_e32 v21, 0xffff0000, v21
	v_pk_mul_f32 v[30:31], v[116:117], v[30:31]
	s_nop 0
	v_pk_mul_f32 v[30:31], v[30:31], v[20:21]
	v_mul_f32_e32 v20, 0xbfb8aa3b, v114
	v_mul_f32_e32 v21, 0xbfb8aa3b, v115
	v_exp_f32_e32 v20, v20
	v_exp_f32_e32 v21, v21
	v_add_f32_e32 v20, 1.0, v20
	v_add_f32_e32 v21, 1.0, v21
	v_rcp_f32_e32 v20, v20
	v_rcp_f32_e32 v21, v21
	s_nop 0
	v_pk_mul_f32 v[20:21], v[114:115], v[20:21]
	s_nop 0
	v_pk_mul_f32 v[52:53], v[20:21], v[52:53]
	v_mul_f32_e32 v20, 0xbfb8aa3b, v112
	v_mul_f32_e32 v21, 0xbfb8aa3b, v113
	v_exp_f32_e32 v20, v20
	v_exp_f32_e32 v21, v21
	v_add_f32_e32 v20, 1.0, v20
	v_add_f32_e32 v21, 1.0, v21
	v_rcp_f32_e32 v20, v20
	v_rcp_f32_e32 v21, v21
	s_nop 0
	v_pk_mul_f32 v[20:21], v[112:113], v[20:21]
	s_nop 0
	v_pk_mul_f32 v[54:55], v[20:21], v[22:23]
	v_cvt_pk_bf16_f32 v20, v28, v29
	v_cvt_pk_bf16_f32 v21, v30, v31
	v_cvt_pk_bf16_f32 v22, v52, v53
	v_cvt_pk_bf16_f32 v23, v54, v55
	global_store_dwordx4 v[146:147], v[20:23], off sc1
	v_lshlrev_b32_e32 v28, 16, v18
	v_and_b32_e32 v29, 0xffff0000, v18
	v_mul_f32_e32 v20, 0xbfb8aa3b, v108
	v_mul_f32_e32 v21, 0xbfb8aa3b, v109
	v_exp_f32_e32 v20, v20
	v_exp_f32_e32 v21, v21
	v_lshlrev_b32_e32 v22, 16, v16
	v_and_b32_e32 v23, 0xffff0000, v16
	v_add_f32_e32 v20, 1.0, v20
	v_add_f32_e32 v21, 1.0, v21
	v_mul_f32_e32 v16, 0xbfb8aa3b, v100
	v_rcp_f32_e32 v20, v20
	v_rcp_f32_e32 v21, v21
	v_exp_f32_e32 v16, v16
	v_lshlrev_b32_e32 v18, 16, v19
	v_and_b32_e32 v19, 0xffff0000, v19
	v_pk_mul_f32 v[20:21], v[108:109], v[20:21]
	v_add_f32_e32 v16, 1.0, v16
	v_pk_mul_f32 v[20:21], v[20:21], v[22:23]
	v_rcp_f32_e32 v22, v16
	v_mul_f32_e32 v16, 0xbfb8aa3b, v101
	v_exp_f32_e32 v16, v16
	s_nop 0
	v_add_f32_e32 v16, 1.0, v16
	v_rcp_f32_e32 v23, v16
	v_lshlrev_b32_e32 v16, 16, v17
	v_and_b32_e32 v17, 0xffff0000, v17
	v_pk_mul_f32 v[22:23], v[100:101], v[22:23]
	s_nop 0
	v_pk_mul_f32 v[22:23], v[22:23], v[16:17]
	v_mul_f32_e32 v16, 0xbfb8aa3b, v98
	v_mul_f32_e32 v17, 0xbfb8aa3b, v99
	v_exp_f32_e32 v16, v16
	v_exp_f32_e32 v17, v17
	v_add_f32_e32 v16, 1.0, v16
	v_add_f32_e32 v17, 1.0, v17
	v_rcp_f32_e32 v16, v16
	v_rcp_f32_e32 v17, v17
	s_nop 0
	v_pk_mul_f32 v[16:17], v[98:99], v[16:17]
	s_nop 0
	v_pk_mul_f32 v[28:29], v[16:17], v[28:29]
	v_mul_f32_e32 v16, 0xbfb8aa3b, v96
	v_mul_f32_e32 v17, 0xbfb8aa3b, v97
	v_exp_f32_e32 v16, v16
	v_exp_f32_e32 v17, v17
	v_add_f32_e32 v16, 1.0, v16
	v_add_f32_e32 v17, 1.0, v17
	v_rcp_f32_e32 v16, v16
	v_rcp_f32_e32 v17, v17
	s_nop 0
; __device__ __forceinline__ float silu_f(float v) { return v * __builtin_amdgcn_rcpf(1.0f + __expf(-v)); }
; __device__ __forceinline__ u32x4 pack8(const float (&f)[8]) { u32x4 w; w.x = cvt_pk_bf16(f[0], f[1]); w.y = cvt_pk_bf16(f[2], f[3]); w.z = cvt_pk_bf16(f[4], f[5]); w.w = cvt_pk_bf16(f[6], f[7]); return w; }
; __device__ __forceinline__ void ffn_conv_phase(Frame& F, int L, int nrows, bool probe_alt = false) {
;     ...
; #pragma unroll
;         for (int i = 0; i < 8; ++i) { bf16_t* vp = val + (size_t)(rb + tq * 8 + i) * DFF + c0; float v[8]; unpack8(rv[i], v);
; #pragma unroll
;             for (int c = 0; c < 4; ++c) { v[2 * c] *= silu_f(acc[i][c].x); v[2 * c + 1] *= silu_f(acc[i][c].y); }
;             *(u32x4*)(probe_alt ? vp + (size_t)202 * MiB / 2 : vp) = pack8(v); }
	v_pk_mul_f32 v[16:17], v[96:97], v[16:17]
	s_nop 0
	v_pk_mul_f32 v[30:31], v[16:17], v[18:19]
	v_cvt_pk_bf16_f32 v16, v20, v21
	v_cvt_pk_bf16_f32 v17, v22, v23
	v_cvt_pk_bf16_f32 v18, v28, v29
	v_cvt_pk_bf16_f32 v19, v30, v31
	global_store_dwordx4 v[144:145], v[16:19], off sc1
	v_lshlrev_b32_e32 v20, 16, v14
	v_and_b32_e32 v21, 0xffff0000, v14
	v_mul_f32_e32 v16, 0xbfb8aa3b, v66
	v_mul_f32_e32 v17, 0xbfb8aa3b, v67
	v_exp_f32_e32 v16, v16
	v_exp_f32_e32 v17, v17
	v_lshlrev_b32_e32 v18, 16, v12
	v_and_b32_e32 v19, 0xffff0000, v12
	v_add_f32_e32 v16, 1.0, v16
	v_add_f32_e32 v17, 1.0, v17
	v_mul_f32_e32 v12, 0xbfb8aa3b, v64
	v_rcp_f32_e32 v16, v16
	v_rcp_f32_e32 v17, v17
	v_exp_f32_e32 v12, v12
	v_lshlrev_b32_e32 v14, 16, v15
	v_and_b32_e32 v15, 0xffff0000, v15
	v_pk_mul_f32 v[16:17], v[66:67], v[16:17]
	v_add_f32_e32 v12, 1.0, v12
	v_pk_mul_f32 v[16:17], v[16:17], v[18:19]
	v_rcp_f32_e32 v18, v12
	v_mul_f32_e32 v12, 0xbfb8aa3b, v65
	v_exp_f32_e32 v12, v12
	s_nop 0
	v_add_f32_e32 v12, 1.0, v12
	v_rcp_f32_e32 v19, v12
	v_lshlrev_b32_e32 v12, 16, v13
	v_and_b32_e32 v13, 0xffff0000, v13
	v_pk_mul_f32 v[18:19], v[64:65], v[18:19]
	s_nop 0
	v_pk_mul_f32 v[18:19], v[18:19], v[12:13]
	v_mul_f32_e32 v12, 0xbfb8aa3b, v62
	v_mul_f32_e32 v13, 0xbfb8aa3b, v63
	v_exp_f32_e32 v12, v12
	v_exp_f32_e32 v13, v13
	v_add_f32_e32 v12, 1.0, v12
	v_add_f32_e32 v13, 1.0, v13
	v_rcp_f32_e32 v12, v12
	v_rcp_f32_e32 v13, v13
	s_nop 0
	v_pk_mul_f32 v[12:13], v[62:63], v[12:13]
	s_nop 0
	v_pk_mul_f32 v[20:21], v[12:13], v[20:21]
	v_mul_f32_e32 v12, 0xbfb8aa3b, v60
	v_mul_f32_e32 v13, 0xbfb8aa3b, v61
	v_exp_f32_e32 v12, v12
	v_exp_f32_e32 v13, v13
	v_add_f32_e32 v12, 1.0, v12
	v_add_f32_e32 v13, 1.0, v13
	v_rcp_f32_e32 v12, v12
	v_rcp_f32_e32 v13, v13
	s_nop 0
	v_pk_mul_f32 v[12:13], v[60:61], v[12:13]
	s_nop 0
	v_pk_mul_f32 v[22:23], v[12:13], v[14:15]
	v_cvt_pk_bf16_f32 v12, v16, v17
	v_cvt_pk_bf16_f32 v13, v18, v19
	v_cvt_pk_bf16_f32 v14, v20, v21
	v_cvt_pk_bf16_f32 v15, v22, v23
	global_store_dwordx4 v[142:143], v[12:15], off sc1
	v_lshlrev_b32_e32 v16, 16, v10
	v_and_b32_e32 v17, 0xffff0000, v10
	v_mul_f32_e32 v12, 0xbfb8aa3b, v50
	v_mul_f32_e32 v13, 0xbfb8aa3b, v51
	v_exp_f32_e32 v12, v12
	v_exp_f32_e32 v13, v13
	v_lshlrev_b32_e32 v14, 16, v8
	v_and_b32_e32 v15, 0xffff0000, v8
	v_add_f32_e32 v12, 1.0, v12
	v_add_f32_e32 v13, 1.0, v13
	v_mul_f32_e32 v8, 0xbfb8aa3b, v48
	v_rcp_f32_e32 v12, v12
	v_rcp_f32_e32 v13, v13
	v_exp_f32_e32 v8, v8
	v_lshlrev_b32_e32 v10, 16, v11
	v_and_b32_e32 v11, 0xffff0000, v11
	v_pk_mul_f32 v[12:13], v[50:51], v[12:13]
	v_add_f32_e32 v8, 1.0, v8
	v_pk_mul_f32 v[12:13], v[12:13], v[14:15]
	v_rcp_f32_e32 v14, v8
	v_mul_f32_e32 v8, 0xbfb8aa3b, v49
	v_exp_f32_e32 v8, v8
	s_nop 0
	v_add_f32_e32 v8, 1.0, v8
	v_rcp_f32_e32 v15, v8
	v_lshlrev_b32_e32 v8, 16, v9
	v_and_b32_e32 v9, 0xffff0000, v9
	v_pk_mul_f32 v[14:15], v[48:49], v[14:15]
	s_nop 0
	v_pk_mul_f32 v[14:15], v[14:15], v[8:9]
	v_mul_f32_e32 v8, 0xbfb8aa3b, v46
	v_mul_f32_e32 v9, 0xbfb8aa3b, v47
	v_exp_f32_e32 v8, v8
	v_exp_f32_e32 v9, v9
	v_add_f32_e32 v8, 1.0, v8
	v_add_f32_e32 v9, 1.0, v9
	v_rcp_f32_e32 v8, v8
	v_rcp_f32_e32 v9, v9
	s_nop 0
	v_pk_mul_f32 v[8:9], v[46:47], v[8:9]
	s_nop 0
	v_pk_mul_f32 v[16:17], v[8:9], v[16:17]
	v_mul_f32_e32 v8, 0xbfb8aa3b, v44
	v_mul_f32_e32 v9, 0xbfb8aa3b, v45
	v_exp_f32_e32 v8, v8
	v_exp_f32_e32 v9, v9
	v_add_f32_e32 v8, 1.0, v8
	v_add_f32_e32 v9, 1.0, v9
	v_rcp_f32_e32 v8, v8
	v_rcp_f32_e32 v9, v9
	s_nop 0
	v_pk_mul_f32 v[8:9], v[44:45], v[8:9]
	s_nop 0
; __device__ __forceinline__ float silu_f(float v) { return v * __builtin_amdgcn_rcpf(1.0f + __expf(-v)); }
; __device__ __forceinline__ u32x4 pack8(const float (&f)[8]) { u32x4 w; w.x = cvt_pk_bf16(f[0], f[1]); w.y = cvt_pk_bf16(f[2], f[3]); w.z = cvt_pk_bf16(f[4], f[5]); w.w = cvt_pk_bf16(f[6], f[7]); return w; }
; __device__ __forceinline__ void ffn_conv_phase(Frame& F, int L, int nrows, bool probe_alt = false) {
;     ...
; #pragma unroll
;         for (int i = 0; i < 8; ++i) { bf16_t* vp = val + (size_t)(rb + tq * 8 + i) * DFF + c0; float v[8]; unpack8(rv[i], v);
; #pragma unroll
;             for (int c = 0; c < 4; ++c) { v[2 * c] *= silu_f(acc[i][c].x); v[2 * c + 1] *= silu_f(acc[i][c].y); }
;             *(u32x4*)(probe_alt ? vp + (size_t)202 * MiB / 2 : vp) = pack8(v); }
	v_pk_mul_f32 v[18:19], v[8:9], v[10:11]
	v_cvt_pk_bf16_f32 v8, v12, v13
	v_cvt_pk_bf16_f32 v9, v14, v15
	v_cvt_pk_bf16_f32 v10, v16, v17
	v_cvt_pk_bf16_f32 v11, v18, v19
	global_store_dwordx4 v[140:141], v[8:11], off sc1
	v_lshlrev_b32_e32 v12, 16, v6
	v_and_b32_e32 v13, 0xffff0000, v6
	v_mul_f32_e32 v8, 0xbfb8aa3b, v42
	v_mul_f32_e32 v9, 0xbfb8aa3b, v43
	v_exp_f32_e32 v8, v8
	v_exp_f32_e32 v9, v9
	v_lshlrev_b32_e32 v10, 16, v4
	v_and_b32_e32 v11, 0xffff0000, v4
	v_add_f32_e32 v8, 1.0, v8
	v_add_f32_e32 v9, 1.0, v9
	v_mul_f32_e32 v4, 0xbfb8aa3b, v40
	v_rcp_f32_e32 v8, v8
	v_rcp_f32_e32 v9, v9
	v_exp_f32_e32 v4, v4
	v_lshlrev_b32_e32 v6, 16, v7
	v_and_b32_e32 v7, 0xffff0000, v7
	v_pk_mul_f32 v[8:9], v[42:43], v[8:9]
	v_add_f32_e32 v4, 1.0, v4
	v_pk_mul_f32 v[8:9], v[8:9], v[10:11]
	v_rcp_f32_e32 v10, v4
	v_mul_f32_e32 v4, 0xbfb8aa3b, v41
	v_exp_f32_e32 v4, v4
	s_nop 0
	v_add_f32_e32 v4, 1.0, v4
	v_rcp_f32_e32 v11, v4
	v_lshlrev_b32_e32 v4, 16, v5
	v_and_b32_e32 v5, 0xffff0000, v5
	v_pk_mul_f32 v[10:11], v[40:41], v[10:11]
	s_nop 0
	v_pk_mul_f32 v[10:11], v[10:11], v[4:5]
	v_mul_f32_e32 v4, 0xbfb8aa3b, v38
	v_mul_f32_e32 v5, 0xbfb8aa3b, v39
	v_exp_f32_e32 v4, v4
	v_exp_f32_e32 v5, v5
	v_add_f32_e32 v4, 1.0, v4
	v_add_f32_e32 v5, 1.0, v5
	v_rcp_f32_e32 v4, v4
	v_rcp_f32_e32 v5, v5
	s_nop 0
	v_pk_mul_f32 v[4:5], v[38:39], v[4:5]
	s_nop 0
	v_pk_mul_f32 v[12:13], v[4:5], v[12:13]
	v_mul_f32_e32 v4, 0xbfb8aa3b, v36
	v_mul_f32_e32 v5, 0xbfb8aa3b, v37
	v_exp_f32_e32 v4, v4
	v_exp_f32_e32 v5, v5
	v_add_f32_e32 v4, 1.0, v4
	v_add_f32_e32 v5, 1.0, v5
	v_rcp_f32_e32 v4, v4
	v_rcp_f32_e32 v5, v5
	s_nop 0
	v_pk_mul_f32 v[4:5], v[36:37], v[4:5]
	s_nop 0
	v_pk_mul_f32 v[14:15], v[4:5], v[6:7]
	v_cvt_pk_bf16_f32 v4, v8, v9
	v_cvt_pk_bf16_f32 v5, v10, v11
	v_cvt_pk_bf16_f32 v6, v12, v13
	v_cvt_pk_bf16_f32 v7, v14, v15
	global_store_dwordx4 v[138:139], v[4:7], off sc1
	v_lshlrev_b32_e32 v8, 16, v2
	v_and_b32_e32 v9, 0xffff0000, v2
	v_mul_f32_e32 v4, 0xbfb8aa3b, v34
	v_mul_f32_e32 v5, 0xbfb8aa3b, v35
	v_exp_f32_e32 v4, v4
	v_exp_f32_e32 v5, v5
	v_lshlrev_b32_e32 v6, 16, v0
	v_and_b32_e32 v7, 0xffff0000, v0
	v_add_f32_e32 v4, 1.0, v4
	v_add_f32_e32 v5, 1.0, v5
	v_mul_f32_e32 v0, 0xbfb8aa3b, v32
	v_rcp_f32_e32 v4, v4
	v_rcp_f32_e32 v5, v5
	v_exp_f32_e32 v0, v0
	v_lshlrev_b32_e32 v2, 16, v3
	v_and_b32_e32 v3, 0xffff0000, v3
	v_pk_mul_f32 v[4:5], v[34:35], v[4:5]
	v_add_f32_e32 v0, 1.0, v0
	v_pk_mul_f32 v[4:5], v[4:5], v[6:7]
	v_rcp_f32_e32 v6, v0
	v_mul_f32_e32 v0, 0xbfb8aa3b, v33
	v_exp_f32_e32 v0, v0
	s_nop 0
	v_add_f32_e32 v0, 1.0, v0
	v_rcp_f32_e32 v7, v0
	v_lshlrev_b32_e32 v0, 16, v1
	v_and_b32_e32 v1, 0xffff0000, v1
	v_pk_mul_f32 v[6:7], v[32:33], v[6:7]
	s_nop 0
	v_pk_mul_f32 v[6:7], v[6:7], v[0:1]
	v_mul_f32_e32 v0, 0xbfb8aa3b, v26
	v_mul_f32_e32 v1, 0xbfb8aa3b, v27
	v_exp_f32_e32 v0, v0
	v_exp_f32_e32 v1, v1
	v_add_f32_e32 v0, 1.0, v0
	v_add_f32_e32 v1, 1.0, v1
	v_rcp_f32_e32 v0, v0
	v_rcp_f32_e32 v1, v1
	s_nop 0
	v_pk_mul_f32 v[0:1], v[26:27], v[0:1]
	s_nop 0
	v_pk_mul_f32 v[8:9], v[0:1], v[8:9]
	v_mul_f32_e32 v0, 0xbfb8aa3b, v24
	v_mul_f32_e32 v1, 0xbfb8aa3b, v25
	v_exp_f32_e32 v0, v0
	v_exp_f32_e32 v1, v1
	v_add_f32_e32 v0, 1.0, v0
	v_add_f32_e32 v1, 1.0, v1
	v_rcp_f32_e32 v0, v0
	v_rcp_f32_e32 v1, v1
	s_nop 0
	v_pk_mul_f32 v[0:1], v[24:25], v[0:1]
	s_nop 0
	v_pk_mul_f32 v[10:11], v[0:1], v[2:3]
	v_cvt_pk_bf16_f32 v0, v4, v5
	v_cvt_pk_bf16_f32 v1, v6, v7
	v_cvt_pk_bf16_f32 v2, v8, v9
	v_cvt_pk_bf16_f32 v3, v10, v11
	global_store_dwordx4 v[136:137], v[0:3], off sc1
	s_cbranch_scc0 .LBB0_1266

; __device__ __forceinline__ int fresh_lane() { int l; asm volatile("v_mbcnt_lo_u32_b32 %0, -1, 0\n\tv_mbcnt_hi_u32_b32 %0, -1, %0" : "=v"(l)); return l; }
; #define PG8_STAGE(bufoff, gbase, voff) do { _Pragma("unroll") for (int _i = 0; _i < 2; ++_i) \
;         __builtin_amdgcn_global_load_lds((const unsigned*)((const char*)(gbase) + (voff)[_i]), (LAS unsigned*)(lds + (bufoff) + ldsw + _i * 8192), 16, 0, 0); } while (0)
; #define PG8_WAIT_V(n) asm volatile("s_waitcnt vmcnt(" #n ")" ::: "memory")
; #define PG8_BAR __builtin_amdgcn_s_barrier()
; template <class Epi, class Sched, bool ALIGN_EPI>
; __device__ __forceinline__ void gemm_phase(LAS unsigned char* lds, const int wid, const int lda_, const int ldb_, const int K_, const Sched& S, const Epi& E) {
;     ...
;     const int lane = fresh_lane(), tid = wid * 64 + lane;
;     const int wr = wid >> 2, wc = wid & 3, fr = lane & 15, fq = lane >> 4;
;     unsigned voffA[2], voffB[2];
; #pragma unroll
;     for (int i = 0; i < 2; ++i) { int R, C; stage_rc(tid * 16 + i * 8192, R, C); const int Rb = Epi::PERM ? ((R & ~31) + perm32(R & 31)) : R;
;         voffA[i] = (unsigned)(R * lda + C) * 2u; voffB[i] = (unsigned)(Rb * ldb + C) * 2u; }
;     const size_t kstep = (size_t)(BK * 2);
;     const size_t hstepA = (size_t)HALF * lda * 2, hstepB = (size_t)HALF * ldb * 2;
;     const unsigned ldsw = (unsigned)wid * 1024u;
;     const int aoff = lds_byte(wr * 64 + fr, fq * 8), boff = lds_byte(wc * 32 + fr, fq * 8);
;     ...
;     Unit cur, nxt; int ui = 0;
;     if (!S.next(0, cur)) return;
;     f32x4 acc[2][2][4][2];
; #pragma unroll
;     for (int a = 0; a < 2; ++a)
; #pragma unroll
;         for (int b = 0; b < 2; ++b)
; #pragma unroll
;             for (int m = 0; m < 4; ++m)
; #pragma unroll
;                 for (int n = 0; n < 2; ++n) acc[a][b][m][n] = (f32x4){0.f, 0.f, 0.f, 0.f};
;     bf16x8 At[4][2], B0[2][2], B1[2][2];
;     const char* cA = S.a(cur); const char* cB = S.b(cur);
;     PG8_STAGE(PG8_SB(0, 0), cB, voffB); PG8_STAGE(PG8_SB(0, 1), cB + hstepB, voffB); PG8_STAGE(PG8_SA(0, 0), cA, voffA); PG8_STAGE(PG8_SA(0, 1), cA + hstepA, voffA);
;     if (wr == 1) PG8_BAR;
;     PG8_WAIT_V(2); PG8_BAR;
;     PG8_STAGE(PG8_SB(1, 0), cB + kstep, voffB); PG8_STAGE(PG8_SA(1, 0), cA + kstep, voffA); PG8_STAGE(PG8_SB(1, 1), cB + hstepB + kstep, voffB);
;     PG8_WAIT_V(6); PG8_BAR;
.LBB0_1325:
	v_mov_b32_e32 v133, v177
	v_lshl_add_u64 v[12:13], s[4:5], 0, v[176:177]
	v_lshl_add_u64 v[14:15], s[4:5], 0, v[132:133]
	v_and_b32_e32 v7, 15, v6
	v_readlane_b32 s4, v252, 46
	v_and_b32_e32 v23, 48, v6
	v_ashrrev_i32_e32 v21, 6, v6
	v_or_b32_e32 v134, s4, v7
	v_lshlrev_b32_e32 v22, 6, v134
	s_movk_i32 s4, 0x3c0
	v_and_or_b32 v22, v22, s4, v23
	v_readlane_b32 s4, v252, 47
	v_ashrrev_i32_e32 v20, 1, v6
	v_lshlrev_b32_e32 v6, 2, v6
	v_lshl_add_u32 v24, v21, 10, s4
	v_readlane_b32 s4, v252, 49
	v_lshl_add_u64 v[8:9], s[48:49], 0, v[176:177]
	v_lshl_or_b32 v7, v7, 6, v23
	v_add_lshl_u32 v21, v21, s4, 10
	v_and_b32_e32 v6, 32, v6
	v_lshl_add_u64 v[10:11], s[48:49], 0, v[132:133]
	v_mov_b32_e32 v129, v177
	v_bitop3_b32 v135, v7, v21, v6 bitop3:0xde
	v_lshl_add_u64 v[6:7], v[8:9], 0, s[24:25]
	s_add_i32 m0, s16, 0x18000
	v_lshl_add_u64 v[16:17], s[46:47], 0, v[128:129]
	v_mov_b32_e32 v131, v177
	s_waitcnt vmcnt(2)
	s_barrier
	global_load_lds_dwordx4 v[6:7], off
	v_lshl_add_u64 v[6:7], v[10:11], 0, s[24:25]
	s_add_i32 m0, s16, 0x1a000
	s_add_i32 s50, s16, 0x8000
	v_lshl_add_u64 v[18:19], s[46:47], 0, v[130:131]
	global_load_lds_dwordx4 v[6:7], off
	v_lshl_add_u64 v[6:7], v[16:17], 0, s[24:25]
	s_mov_b32 m0, s50
	s_add_i32 s51, s16, 0xa000
	global_load_lds_dwordx4 v[6:7], off
	v_lshl_add_u64 v[6:7], v[18:19], 0, s[24:25]
	s_mov_b32 m0, s51
	v_add_u32_e32 v0, v2, v0
	global_load_lds_dwordx4 v[6:7], off
	v_lshl_add_u64 v[6:7], v[12:13], 0, s[24:25]
	s_add_i32 m0, s16, 0x1c000
	v_lshlrev_b32_e32 v25, 2, v134
	global_load_lds_dwordx4 v[6:7], off
	v_lshl_add_u64 v[6:7], v[14:15], 0, s[24:25]
	s_add_i32 m0, s16, 0x1e000
	v_add_lshl_u32 v0, v0, v1, 1
	global_load_lds_dwordx4 v[6:7], off
	v_mov_b32_e32 v1, v177
	v_and_b32_e32 v20, -8, v20
	v_and_b32_e32 v25, 32, v25
	s_waitcnt vmcnt(6)
	v_readlane_b32 s4, v252, 48
	v_lshl_add_u64 v[152:153], s[0:1], 0, v[0:1]
	v_add_u32_e32 v0, v5, v3
	v_bitop3_b32 v22, v22, v24, v25 bitop3:0xde
	v_add_u32_e32 v136, s4, v20
	v_add_lshl_u32 v0, v0, v4, 1
	v_ashrrev_i32_e32 v137, 31, v136
	v_or_b32_e32 v138, 16, v134
	v_or_b32_e32 v140, 32, v134
	v_or_b32_e32 v142, 48, v134
	v_add_u32_e32 v144, 0x80, v134
	v_add_u32_e32 v146, 0x90, v134
	v_add_u32_e32 v148, 0xa0, v134
	v_add_u32_e32 v150, 0xb0, v134
	v_lshl_add_u64 v[154:155], s[0:1], 0, v[0:1]
	s_mov_b32 s72, 0
	v_add_u32_e32 v139, 0, v22
	s_barrier
	v_add_u32_e32 v141, 0x10000, v135
	ds_read_b128 v[160:163], v141 offset:1024
	ds_read_b128 v[164:167], v141 offset:2048
	ds_read_b128 v[168:171], v141 offset:3072
	v_add_u32_e32 v141, 0x14000, v135
	ds_read_b128 v[172:175], v141
	ds_read_b128 v[180:183], v141 offset:1024
	ds_read_b128 v[184:187], v141 offset:2048
	ds_read_b128 v[188:191], v141 offset:3072
	ds_read_b128 v[192:195], v139
	ds_read_b128 v[196:199], v139 offset:1024
	ds_read_b128 v[200:203], v139 offset:2048
	ds_read_b128 v[204:207], v139 offset:3072
	ds_read_b128 v[208:211], v139 offset:4096
	ds_read_b128 v[212:215], v139 offset:5120
	ds_read_b128 v[216:219], v139 offset:6144
	ds_read_b128 v[220:223], v139 offset:7168
	s_branch .LBB0_1327

; #define PG8_STAGE(bufoff, gbase, voff) do { _Pragma("unroll") for (int _i = 0; _i < 2; ++_i) \
;         __builtin_amdgcn_global_load_lds((const unsigned*)((const char*)(gbase) + (voff)[_i]), (LAS unsigned*)(lds + (bufoff) + ldsw + _i * 8192), 16, 0, 0); } while (0)
; #define PG8_LDA(dst, b, h) do { _Pragma("unroll") for (int m = 0; m < 4; ++m) _Pragma("unroll") for (int k = 0; k < 2; ++k) dst[m][k] = *(const LAS bf16x8*)(lds + PG8_SA(b, h) + aoff + m * 2048 + k * 1024); } while (0)
; #define PG8_LDB(dst, b, h) do { _Pragma("unroll") for (int n = 0; n < 2; ++n) _Pragma("unroll") for (int k = 0; k < 2; ++k) dst[n][k] = *(const LAS bf16x8*)(lds + PG8_SB(b, h) + boff + n * 2048 + k * 1024); } while (0)
; #define PG8_MMA(ai, bj, At, Bt) do { __builtin_amdgcn_s_setprio(1); _Pragma("unroll") for (int m = 0; m < 4; ++m) _Pragma("unroll") for (int n = 0; n < 2; ++n) _Pragma("unroll") for (int k = 0; k < 2; ++k) \
;         acc[ai][bj][m][n] = __builtin_amdgcn_mfma_f32_16x16x32_bf16(Bt[n][k], At[m][k], acc[ai][bj][m][n], 0, 0, 0); __builtin_amdgcn_s_setprio(0); } while (0)
; template <class Epi, class Sched, bool ALIGN_EPI>
; __device__ __forceinline__ void gemm_phase(LAS unsigned char* lds, const int wid, const int lda_, const int ldb_, const int K_, const Sched& S, const Epi& E) {
;     ...
;         const bool has_next = S.next(ui + 1, nxt);
;         const int nt = S.nt(cur);
;         const char* nA = has_next ? S.a(nxt) : cA; const char* nB = has_next ? S.b(nxt) : cB;
; #pragma unroll 1
;         for (int t = 0; t < nt; t += 2) {
;             const bool last = (t == nt - 2);
;             const char* a1 = cA + (size_t)(t + 1) * kstep;
;             const char* a2 = last ? nA : cA + (size_t)(t + 2) * kstep; const char* b2 = last ? nB : cB + (size_t)(t + 2) * kstep;
;             const char* a3 = a2 + kstep; const char* b3 = b2 + kstep;
;             PG8_LDB(B0, 0, 0); PG8_LDB(B1, 0, 1); PG8_SCHED; PG8_LDA(At, 0, 0); PG8_STAGE(PG8_SA(1, 1), a1 + hstepA, voffA);
;             PG8_WAIT_V(8); PG8_WAIT_L(0); PG8_BAR; PG8_MMA(0, 0, At, B0); PG8_MMA(0, 1, At, B1); PG8_BAR; PG8_SCHED;
;             PG8_LDA(At, 0, 1); PG8_STAGE(PG8_SB(0, 0), b2, voffB); PG8_STAGE(PG8_SB(0, 1), b2 + hstepB, voffB); PG8_STAGE(PG8_SA(0, 0), a2, voffA);
;             PG8_WAIT_V(8); PG8_WAIT_L(0); PG8_BAR; PG8_MMA(1, 0, At, B0); PG8_MMA(1, 1, At, B1); PG8_BAR; PG8_SCHED;
.LBB0_1340:
	s_cmp_gt_i32 s38, -1
	s_cselect_b64 s[44:45], -1, 0
	s_cmp_lt_i32 s38, 0
	s_cselect_b32 s4, 0x58, 22
	s_add_i32 s5, s4, -2
	s_add_u32 s46, s46, 0x80
	s_addc_u32 s47, s47, 0
	s_add_u32 s31, s48, 0x100
	s_mov_b32 s39, 0
	s_addc_u32 s35, s49, 0
	s_add_i32 s76, s39, 2
	s_add_u32 s17, s46, 0x80
	s_addc_u32 s27, s47, 0
	s_add_i32 s77, 0, 0x10000
	s_cmp_eq_u32 s5, s39
	s_cselect_b32 s49, s43, s27
	s_cselect_b32 s48, s42, s17
	v_add_u32_e32 v141, 0x10000, v135
	ds_read_b128 v[156:159], v141
	s_cselect_b32 s79, s37, s35
	s_cselect_b32 s78, s36, s31
	s_add_i32 s17, 0, 0x14000
	v_lshl_add_u64 v[224:225], s[46:47], 0, v[152:153]
	s_add_i32 m0, s16, 0xc000
	global_load_lds_dwordx4 v[224:225], off
	v_lshl_add_u64 v[224:225], s[46:47], 0, v[154:155]
	s_add_i32 m0, s16, 0xe000
	s_nop 0
	global_load_lds_dwordx4 v[224:225], off
	s_waitcnt vmcnt(8)
	s_waitcnt lgkmcnt(0)
	s_barrier
	s_setprio 1
	s_waitcnt lgkmcnt(0)
	v_mfma_f32_16x16x32_bf16 v[124:127], v[156:159], v[192:195], 0
	v_mfma_f32_16x16x32_bf16 v[120:123], v[164:167], v[192:195], 0
	v_mfma_f32_16x16x32_bf16 v[116:119], v[156:159], v[200:203], 0
	v_mfma_f32_16x16x32_bf16 v[112:115], v[164:167], v[200:203], 0
	v_mfma_f32_16x16x32_bf16 v[100:103], v[156:159], v[208:211], 0
	v_mfma_f32_16x16x32_bf16 v[96:99], v[164:167], v[208:211], 0
	v_mfma_f32_16x16x32_bf16 v[84:87], v[156:159], v[216:219], 0
	v_mfma_f32_16x16x32_bf16 v[80:83], v[164:167], v[216:219], 0
	v_mfma_f32_16x16x32_bf16 v[124:127], v[160:163], v[196:199], v[124:127]
	v_mfma_f32_16x16x32_bf16 v[120:123], v[168:171], v[196:199], v[120:123]
	v_mfma_f32_16x16x32_bf16 v[116:119], v[160:163], v[204:207], v[116:119]
	v_mfma_f32_16x16x32_bf16 v[112:115], v[168:171], v[204:207], v[112:115]
	v_mfma_f32_16x16x32_bf16 v[100:103], v[160:163], v[212:215], v[100:103]
	v_mfma_f32_16x16x32_bf16 v[96:99], v[168:171], v[212:215], v[96:99]
	v_mfma_f32_16x16x32_bf16 v[84:87], v[160:163], v[220:223], v[84:87]
	v_mfma_f32_16x16x32_bf16 v[80:83], v[168:171], v[220:223], v[80:83]
	s_setprio 0
	s_setprio 1
	v_mfma_f32_16x16x32_bf16 v[108:111], v[172:175], v[192:195], 0
	v_mfma_f32_16x16x32_bf16 v[104:107], v[184:187], v[192:195], 0
	v_mfma_f32_16x16x32_bf16 v[92:95], v[172:175], v[200:203], 0
	v_mfma_f32_16x16x32_bf16 v[88:91], v[184:187], v[200:203], 0
	v_mfma_f32_16x16x32_bf16 v[76:79], v[172:175], v[208:211], 0
	v_mfma_f32_16x16x32_bf16 v[72:75], v[184:187], v[208:211], 0
	v_mfma_f32_16x16x32_bf16 v[68:71], v[172:175], v[216:219], 0
	v_mfma_f32_16x16x32_bf16 v[64:67], v[184:187], v[216:219], 0
	v_mfma_f32_16x16x32_bf16 v[108:111], v[180:183], v[196:199], v[108:111]
	v_mfma_f32_16x16x32_bf16 v[104:107], v[188:191], v[196:199], v[104:107]
	v_mfma_f32_16x16x32_bf16 v[92:95], v[180:183], v[204:207], v[92:95]
	v_mfma_f32_16x16x32_bf16 v[88:91], v[188:191], v[204:207], v[88:91]
	v_mfma_f32_16x16x32_bf16 v[76:79], v[180:183], v[212:215], v[76:79]
	v_mfma_f32_16x16x32_bf16 v[72:75], v[188:191], v[212:215], v[72:75]
	v_mfma_f32_16x16x32_bf16 v[68:71], v[180:183], v[220:223], v[68:71]
	v_mfma_f32_16x16x32_bf16 v[64:67], v[188:191], v[220:223], v[64:67]
	s_setprio 0
	s_barrier
	s_add_i32 s27, s77, s3
	v_lshl_add_u64 v[224:225], s[78:79], 0, v[176:177]
	s_mov_b32 m0, s27
	ds_read_b128 v[192:195], v139 offset:16384
	ds_read_b128 v[196:199], v139 offset:17408
	ds_read_b128 v[200:203], v139 offset:18432
	ds_read_b128 v[204:207], v139 offset:19456
	ds_read_b128 v[208:211], v139 offset:20480
	ds_read_b128 v[212:215], v139 offset:21504
	ds_read_b128 v[216:219], v139 offset:22528
	ds_read_b128 v[220:223], v139 offset:23552
	global_load_lds_dwordx4 v[224:225], off
	s_add_i32 m0, s27, 0x2000
	v_lshl_add_u64 v[226:227], s[78:79], 0, v[132:133]
	s_add_u32 s78, s78, s10
	s_addc_u32 s79, s79, s11
	s_add_i32 s17, s17, s3
	global_load_lds_dwordx4 v[226:227], off
	v_lshl_add_u64 v[228:229], s[78:79], 0, v[176:177]
	s_mov_b32 m0, s17
	v_lshl_add_u64 v[230:231], s[78:79], 0, v[132:133]
	global_load_lds_dwordx4 v[228:229], off
	s_add_i32 m0, s17, 0x2000
	v_lshl_add_u64 v[232:233], s[48:49], 0, v[128:129]
	global_load_lds_dwordx4 v[230:231], off
	s_mov_b32 m0, s16
	v_lshl_add_u64 v[234:235], s[48:49], 0, v[130:131]
	global_load_lds_dwordx4 v[232:233], off
	s_mov_b32 m0, s14
	s_nop 0
	global_load_lds_dwordx4 v[234:235], off
	s_waitcnt vmcnt(8)
	s_waitcnt lgkmcnt(0)
	s_barrier
	s_setprio 1
	s_waitcnt lgkmcnt(0)
	v_mfma_f32_16x16x32_bf16 v[60:63], v[156:159], v[192:195], 0
	v_mfma_f32_16x16x32_bf16 v[56:59], v[164:167], v[192:195], 0
	v_mfma_f32_16x16x32_bf16 v[52:55], v[156:159], v[200:203], 0
	v_mfma_f32_16x16x32_bf16 v[48:51], v[164:167], v[200:203], 0
	v_mfma_f32_16x16x32_bf16 v[36:39], v[156:159], v[208:211], 0
	v_mfma_f32_16x16x32_bf16 v[32:35], v[164:167], v[208:211], 0
	v_mfma_f32_16x16x32_bf16 v[20:23], v[156:159], v[216:219], 0
	v_mfma_f32_16x16x32_bf16 v[16:19], v[164:167], v[216:219], 0
	v_mfma_f32_16x16x32_bf16 v[60:63], v[160:163], v[196:199], v[60:63]
	v_mfma_f32_16x16x32_bf16 v[56:59], v[168:171], v[196:199], v[56:59]
	v_mfma_f32_16x16x32_bf16 v[52:55], v[160:163], v[204:207], v[52:55]
	v_mfma_f32_16x16x32_bf16 v[48:51], v[168:171], v[204:207], v[48:51]
	v_mfma_f32_16x16x32_bf16 v[36:39], v[160:163], v[212:215], v[36:39]
	v_mfma_f32_16x16x32_bf16 v[32:35], v[168:171], v[212:215], v[32:35]
	v_mfma_f32_16x16x32_bf16 v[20:23], v[160:163], v[220:223], v[20:23]
	v_mfma_f32_16x16x32_bf16 v[16:19], v[168:171], v[220:223], v[16:19]
	s_setprio 0
	s_setprio 1
	v_mfma_f32_16x16x32_bf16 v[44:47], v[172:175], v[192:195], 0
	v_mfma_f32_16x16x32_bf16 v[40:43], v[184:187], v[192:195], 0
	v_mfma_f32_16x16x32_bf16 v[28:31], v[172:175], v[200:203], 0
	v_mfma_f32_16x16x32_bf16 v[24:27], v[184:187], v[200:203], 0
	v_mfma_f32_16x16x32_bf16 v[12:15], v[172:175], v[208:211], 0
	v_mfma_f32_16x16x32_bf16 v[8:11], v[184:187], v[208:211], 0
	v_mfma_f32_16x16x32_bf16 v[4:7], v[172:175], v[216:219], 0
	v_mfma_f32_16x16x32_bf16 v[0:3], v[184:187], v[216:219], 0
	v_mfma_f32_16x16x32_bf16 v[44:47], v[180:183], v[196:199], v[44:47]
	v_mfma_f32_16x16x32_bf16 v[40:43], v[188:191], v[196:199], v[40:43]
	v_mfma_f32_16x16x32_bf16 v[28:31], v[180:183], v[204:207], v[28:31]
	v_mfma_f32_16x16x32_bf16 v[24:27], v[188:191], v[204:207], v[24:27]
	v_mfma_f32_16x16x32_bf16 v[12:15], v[180:183], v[212:215], v[12:15]
	v_mfma_f32_16x16x32_bf16 v[8:11], v[188:191], v[212:215], v[8:11]
	v_mfma_f32_16x16x32_bf16 v[4:7], v[180:183], v[220:223], v[4:7]
	v_mfma_f32_16x16x32_bf16 v[0:3], v[188:191], v[220:223], v[0:3]
	s_setprio 0
	s_barrier
	s_branch .Lgemm_join_1341

; #define PG8_STAGE(bufoff, gbase, voff) do { _Pragma("unroll") for (int _i = 0; _i < 2; ++_i) \
;         __builtin_amdgcn_global_load_lds((const unsigned*)((const char*)(gbase) + (voff)[_i]), (LAS unsigned*)(lds + (bufoff) + ldsw + _i * 8192), 16, 0, 0); } while (0)
; #define PG8_LDA(dst, b, h) do { _Pragma("unroll") for (int m = 0; m < 4; ++m) _Pragma("unroll") for (int k = 0; k < 2; ++k) dst[m][k] = *(const LAS bf16x8*)(lds + PG8_SA(b, h) + aoff + m * 2048 + k * 1024); } while (0)
; #define PG8_LDB(dst, b, h) do { _Pragma("unroll") for (int n = 0; n < 2; ++n) _Pragma("unroll") for (int k = 0; k < 2; ++k) dst[n][k] = *(const LAS bf16x8*)(lds + PG8_SB(b, h) + boff + n * 2048 + k * 1024); } while (0)
; #define PG8_MMA(ai, bj, At, Bt) do { __builtin_amdgcn_s_setprio(1); _Pragma("unroll") for (int m = 0; m < 4; ++m) _Pragma("unroll") for (int n = 0; n < 2; ++n) _Pragma("unroll") for (int k = 0; k < 2; ++k) \
;         acc[ai][bj][m][n] = __builtin_amdgcn_mfma_f32_16x16x32_bf16(Bt[n][k], At[m][k], acc[ai][bj][m][n], 0, 0, 0); __builtin_amdgcn_s_setprio(0); } while (0)
; #define PG8_WAIT_V(n) asm volatile("s_waitcnt vmcnt(" #n ")" ::: "memory")
; #define PG8_WAIT_L(n) asm volatile("s_waitcnt lgkmcnt(" #n ")" ::: "memory")
; #define PG8_BAR __builtin_amdgcn_s_barrier()
; #define PG8_SCHED __builtin_amdgcn_sched_barrier(0)
; template <class Epi, class Sched, bool ALIGN_EPI>
; __device__ __forceinline__ void gemm_phase(LAS unsigned char* lds, const int wid, const int lda_, const int ldb_, const int K_, const Sched& S, const Epi& E) {
;     ...
;             PG8_LDB(B0, 1, 0); PG8_LDB(B1, 1, 1); PG8_SCHED; PG8_LDA(At, 1, 0); PG8_STAGE(PG8_SA(0, 1), a2 + hstepA, voffA);
;             PG8_WAIT_V(8); PG8_WAIT_L(0); PG8_BAR; PG8_MMA(0, 0, At, B0); PG8_MMA(0, 1, At, B1); PG8_BAR; PG8_SCHED;
;             PG8_LDA(At, 1, 1); PG8_STAGE(PG8_SB(1, 0), b3, voffB); PG8_STAGE(PG8_SB(1, 1), b3 + hstepB, voffB); PG8_STAGE(PG8_SA(1, 0), a3, voffA);
;             PG8_WAIT_V(8); PG8_WAIT_L(0); PG8_BAR; PG8_MMA(1, 0, At, B0); PG8_MMA(1, 1, At, B1); PG8_BAR; PG8_SCHED;
.Lgemm_join_1341:
	s_add_i32 s17, 0, 0x18000
	v_add_u32_e32 v141, s17, v135
	s_add_i32 s27, 0, 0x1c000
	ds_read_b128 v[156:159], v141
	ds_read_b128 v[160:163], v141 offset:1024
	ds_read_b128 v[164:167], v141 offset:2048
	ds_read_b128 v[168:171], v141 offset:3072
	v_add_u32_e32 v141, s27, v135
	ds_read_b128 v[172:175], v141
	ds_read_b128 v[180:183], v141 offset:1024
	ds_read_b128 v[184:187], v141 offset:2048
	ds_read_b128 v[188:191], v141 offset:3072
	s_add_u32 s48, s48, s0
	s_addc_u32 s49, s49, s1
	s_mov_b32 m0, s15
	v_lshl_add_u64 v[236:237], s[48:49], 0, v[128:129]
	ds_read_b128 v[192:195], v139 offset:32768
	ds_read_b128 v[196:199], v139 offset:33792
	ds_read_b128 v[200:203], v139 offset:34816
	ds_read_b128 v[204:207], v139 offset:35840
	ds_read_b128 v[208:211], v139 offset:36864
	ds_read_b128 v[212:215], v139 offset:37888
	ds_read_b128 v[216:219], v139 offset:38912
	ds_read_b128 v[220:223], v139 offset:39936
	global_load_lds_dwordx4 v[236:237], off
	v_lshl_add_u64 v[236:237], s[48:49], 0, v[130:131]
	s_mov_b32 m0, s26
	s_nop 0
	global_load_lds_dwordx4 v[236:237], off
	s_waitcnt vmcnt(8)
	s_waitcnt lgkmcnt(0)
	s_barrier
	s_setprio 1
	s_waitcnt lgkmcnt(0)
	v_mfma_f32_16x16x32_bf16 v[124:127], v[156:159], v[192:195], v[124:127]
	v_mfma_f32_16x16x32_bf16 v[120:123], v[164:167], v[192:195], v[120:123]
	v_mfma_f32_16x16x32_bf16 v[116:119], v[156:159], v[200:203], v[116:119]
	v_mfma_f32_16x16x32_bf16 v[112:115], v[164:167], v[200:203], v[112:115]
	v_mfma_f32_16x16x32_bf16 v[100:103], v[156:159], v[208:211], v[100:103]
	v_mfma_f32_16x16x32_bf16 v[96:99], v[164:167], v[208:211], v[96:99]
	v_mfma_f32_16x16x32_bf16 v[84:87], v[156:159], v[216:219], v[84:87]
	v_mfma_f32_16x16x32_bf16 v[80:83], v[164:167], v[216:219], v[80:83]
	v_mfma_f32_16x16x32_bf16 v[124:127], v[160:163], v[196:199], v[124:127]
	v_mfma_f32_16x16x32_bf16 v[120:123], v[168:171], v[196:199], v[120:123]
	v_mfma_f32_16x16x32_bf16 v[116:119], v[160:163], v[204:207], v[116:119]
	v_mfma_f32_16x16x32_bf16 v[112:115], v[168:171], v[204:207], v[112:115]
	v_mfma_f32_16x16x32_bf16 v[100:103], v[160:163], v[212:215], v[100:103]
	v_mfma_f32_16x16x32_bf16 v[96:99], v[168:171], v[212:215], v[96:99]
	v_mfma_f32_16x16x32_bf16 v[84:87], v[160:163], v[220:223], v[84:87]
	v_mfma_f32_16x16x32_bf16 v[80:83], v[168:171], v[220:223], v[80:83]
	s_setprio 0
	s_setprio 1
	v_mfma_f32_16x16x32_bf16 v[108:111], v[172:175], v[192:195], v[108:111]
	v_mfma_f32_16x16x32_bf16 v[104:107], v[184:187], v[192:195], v[104:107]
	v_mfma_f32_16x16x32_bf16 v[92:95], v[172:175], v[200:203], v[92:95]
	v_mfma_f32_16x16x32_bf16 v[88:91], v[184:187], v[200:203], v[88:91]
	v_mfma_f32_16x16x32_bf16 v[76:79], v[172:175], v[208:211], v[76:79]
	v_mfma_f32_16x16x32_bf16 v[72:75], v[184:187], v[208:211], v[72:75]
	v_mfma_f32_16x16x32_bf16 v[68:71], v[172:175], v[216:219], v[68:71]
	v_mfma_f32_16x16x32_bf16 v[64:67], v[184:187], v[216:219], v[64:67]
	v_mfma_f32_16x16x32_bf16 v[108:111], v[180:183], v[196:199], v[108:111]
	v_mfma_f32_16x16x32_bf16 v[104:107], v[188:191], v[196:199], v[104:107]
	v_mfma_f32_16x16x32_bf16 v[92:95], v[180:183], v[204:207], v[92:95]
	v_mfma_f32_16x16x32_bf16 v[88:91], v[188:191], v[204:207], v[88:91]
	v_mfma_f32_16x16x32_bf16 v[76:79], v[180:183], v[212:215], v[76:79]
	v_mfma_f32_16x16x32_bf16 v[72:75], v[188:191], v[212:215], v[72:75]
	v_mfma_f32_16x16x32_bf16 v[68:71], v[180:183], v[220:223], v[68:71]
	v_mfma_f32_16x16x32_bf16 v[64:67], v[188:191], v[220:223], v[64:67]
	s_setprio 0
	s_barrier
	s_add_i32 s17, s17, s3
	v_lshl_add_u64 v[224:225], v[224:225], 0, s[24:25]
	s_mov_b32 m0, s17
	ds_read_b128 v[192:195], v139 offset:49152
	ds_read_b128 v[196:199], v139 offset:50176
	ds_read_b128 v[200:203], v139 offset:51200
	ds_read_b128 v[204:207], v139 offset:52224
	ds_read_b128 v[208:211], v139 offset:53248
	ds_read_b128 v[212:215], v139 offset:54272
	ds_read_b128 v[216:219], v139 offset:55296
	ds_read_b128 v[220:223], v139 offset:56320
	global_load_lds_dwordx4 v[224:225], off
	v_lshl_add_u64 v[224:225], v[226:227], 0, s[24:25]
	s_add_i32 m0, s17, 0x2000
	s_add_i32 s17, s27, s3
	global_load_lds_dwordx4 v[224:225], off
	v_lshl_add_u64 v[224:225], v[228:229], 0, s[24:25]
	s_mov_b32 m0, s17
	s_nop 0
	global_load_lds_dwordx4 v[224:225], off
	v_lshl_add_u64 v[224:225], v[230:231], 0, s[24:25]
	s_add_i32 m0, s17, 0x2000
	s_nop 0
	global_load_lds_dwordx4 v[224:225], off
	v_lshl_add_u64 v[224:225], v[232:233], 0, s[24:25]
	s_mov_b32 m0, s50
	s_nop 0
	global_load_lds_dwordx4 v[224:225], off
	v_lshl_add_u64 v[224:225], v[234:235], 0, s[24:25]
	s_mov_b32 m0, s51
	s_nop 0
	global_load_lds_dwordx4 v[224:225], off
	s_waitcnt vmcnt(8)
	s_waitcnt lgkmcnt(0)
	s_barrier
; #define PG8_STAGE(bufoff, gbase, voff) do { _Pragma("unroll") for (int _i = 0; _i < 2; ++_i) \
;         __builtin_amdgcn_global_load_lds((const unsigned*)((const char*)(gbase) + (voff)[_i]), (LAS unsigned*)(lds + (bufoff) + ldsw + _i * 8192), 16, 0, 0); } while (0)
; #define PG8_LDA(dst, b, h) do { _Pragma("unroll") for (int m = 0; m < 4; ++m) _Pragma("unroll") for (int k = 0; k < 2; ++k) dst[m][k] = *(const LAS bf16x8*)(lds + PG8_SA(b, h) + aoff + m * 2048 + k * 1024); } while (0)
; #define PG8_LDB(dst, b, h) do { _Pragma("unroll") for (int n = 0; n < 2; ++n) _Pragma("unroll") for (int k = 0; k < 2; ++k) dst[n][k] = *(const LAS bf16x8*)(lds + PG8_SB(b, h) + boff + n * 2048 + k * 1024); } while (0)
; #define PG8_WAIT_V(n) asm volatile("s_waitcnt vmcnt(" #n ")" ::: "memory")
; #define PG8_WAIT_L(n) asm volatile("s_waitcnt lgkmcnt(" #n ")" ::: "memory")
; #define PG8_BAR __builtin_amdgcn_s_barrier()
; #define PG8_SCHED __builtin_amdgcn_sched_barrier(0)
; template <class Epi, class Sched, bool ALIGN_EPI>
; __device__ __forceinline__ void gemm_phase(LAS unsigned char* lds, const int wid, const int lda_, const int ldb_, const int K_, const Sched& S, const Epi& E) {
;     ...
;             PG8_LDB(B0, 0, 0); PG8_LDB(B1, 0, 1); PG8_SCHED; PG8_LDA(At, 0, 0); PG8_STAGE(PG8_SA(1, 1), a1 + hstepA, voffA);
;             PG8_WAIT_V(8); PG8_WAIT_L(0); PG8_BAR; PG8_MMA(0, 0, At, B0); PG8_MMA(0, 1, At, B1); PG8_BAR; PG8_SCHED;
;             PG8_LDA(At, 0, 1); PG8_STAGE(PG8_SB(0, 0), b2, voffB); PG8_STAGE(PG8_SB(0, 1), b2 + hstepB, voffB); PG8_STAGE(PG8_SA(0, 0), a2, voffA);
;             PG8_WAIT_V(8); PG8_WAIT_L(0); PG8_BAR; PG8_MMA(1, 0, At, B0); PG8_MMA(1, 1, At, B1); PG8_BAR; PG8_SCHED;
;             PG8_LDB(B0, 1, 0); PG8_LDB(B1, 1, 1); PG8_SCHED; PG8_LDA(At, 1, 0); PG8_STAGE(PG8_SA(0, 1), a2 + hstepA, voffA);
;             PG8_WAIT_V(8); PG8_WAIT_L(0); PG8_BAR; PG8_MMA(0, 0, At, B0); PG8_MMA(0, 1, At, B1); PG8_BAR; PG8_SCHED;
;             PG8_LDA(At, 1, 1); PG8_STAGE(PG8_SB(1, 0), b3, voffB); PG8_STAGE(PG8_SB(1, 1), b3 + hstepB, voffB); PG8_STAGE(PG8_SA(1, 0), a3, voffA);
;             PG8_WAIT_V(8); PG8_WAIT_L(0); PG8_BAR; PG8_MMA(1, 0, At, B0); PG8_MMA(1, 1, At, B1); PG8_BAR; PG8_SCHED;
;         }
;         if constexpr (ALIGN_EPI) { if (wr == 0) PG8_BAR; }
;         E(acc, cur, S, wr, wc, fr, fq);
;         if (!has_next) break;
	s_setprio 1
	s_waitcnt lgkmcnt(0)
	v_mfma_f32_16x16x32_bf16 v[60:63], v[156:159], v[192:195], v[60:63]
	v_mfma_f32_16x16x32_bf16 v[56:59], v[164:167], v[192:195], v[56:59]
	v_mfma_f32_16x16x32_bf16 v[52:55], v[156:159], v[200:203], v[52:55]
	v_mfma_f32_16x16x32_bf16 v[48:51], v[164:167], v[200:203], v[48:51]
	v_mfma_f32_16x16x32_bf16 v[36:39], v[156:159], v[208:211], v[36:39]
	v_mfma_f32_16x16x32_bf16 v[32:35], v[164:167], v[208:211], v[32:35]
	v_mfma_f32_16x16x32_bf16 v[20:23], v[156:159], v[216:219], v[20:23]
	v_mfma_f32_16x16x32_bf16 v[16:19], v[164:167], v[216:219], v[16:19]
	v_mfma_f32_16x16x32_bf16 v[60:63], v[160:163], v[196:199], v[60:63]
	v_mfma_f32_16x16x32_bf16 v[56:59], v[168:171], v[196:199], v[56:59]
	v_mfma_f32_16x16x32_bf16 v[52:55], v[160:163], v[204:207], v[52:55]
	v_mfma_f32_16x16x32_bf16 v[48:51], v[168:171], v[204:207], v[48:51]
	v_mfma_f32_16x16x32_bf16 v[36:39], v[160:163], v[212:215], v[36:39]
	v_mfma_f32_16x16x32_bf16 v[32:35], v[168:171], v[212:215], v[32:35]
	v_mfma_f32_16x16x32_bf16 v[20:23], v[160:163], v[220:223], v[20:23]
	v_mfma_f32_16x16x32_bf16 v[16:19], v[168:171], v[220:223], v[16:19]
	s_setprio 0
	s_setprio 1
	v_mfma_f32_16x16x32_bf16 v[44:47], v[172:175], v[192:195], v[44:47]
	v_mfma_f32_16x16x32_bf16 v[40:43], v[184:187], v[192:195], v[40:43]
	v_mfma_f32_16x16x32_bf16 v[28:31], v[172:175], v[200:203], v[28:31]
	v_mfma_f32_16x16x32_bf16 v[24:27], v[184:187], v[200:203], v[24:27]
	v_mfma_f32_16x16x32_bf16 v[12:15], v[172:175], v[208:211], v[12:15]
	v_mfma_f32_16x16x32_bf16 v[8:11], v[184:187], v[208:211], v[8:11]
	v_mfma_f32_16x16x32_bf16 v[4:7], v[172:175], v[216:219], v[4:7]
	v_mfma_f32_16x16x32_bf16 v[0:3], v[184:187], v[216:219], v[0:3]
	v_mfma_f32_16x16x32_bf16 v[44:47], v[180:183], v[196:199], v[44:47]
	v_mfma_f32_16x16x32_bf16 v[40:43], v[188:191], v[196:199], v[40:43]
	v_mfma_f32_16x16x32_bf16 v[28:31], v[180:183], v[204:207], v[28:31]
	v_mfma_f32_16x16x32_bf16 v[24:27], v[188:191], v[204:207], v[24:27]
	v_mfma_f32_16x16x32_bf16 v[12:15], v[180:183], v[212:215], v[12:15]
	v_mfma_f32_16x16x32_bf16 v[8:11], v[188:191], v[212:215], v[8:11]
	v_mfma_f32_16x16x32_bf16 v[4:7], v[180:183], v[220:223], v[4:7]
	v_mfma_f32_16x16x32_bf16 v[0:3], v[188:191], v[220:223], v[0:3]
	s_setprio 0
	s_barrier
	s_add_u32 s46, s46, 0x100
	s_addc_u32 s47, s47, 0
	s_add_u32 s31, s31, 0x100
	s_addc_u32 s35, s35, 0
	s_cmp_ge_u32 s76, s4
	s_mov_b32 s39, s76
	s_cbranch_scc0 .LBB0_1341
	s_setprio 2
	v_add_u32_e32 v141, 0x10000, v135
	ds_read_b128 v[160:163], v141 offset:1024
	ds_read_b128 v[164:167], v141 offset:2048
	ds_read_b128 v[168:171], v141 offset:3072
	v_add_u32_e32 v141, 0x14000, v135
	ds_read_b128 v[172:175], v141
	ds_read_b128 v[180:183], v141 offset:1024
	ds_read_b128 v[184:187], v141 offset:2048
	ds_read_b128 v[188:191], v141 offset:3072
	ds_read_b128 v[192:195], v139
	ds_read_b128 v[196:199], v139 offset:1024
	ds_read_b128 v[200:203], v139 offset:2048
	ds_read_b128 v[204:207], v139 offset:3072
	ds_read_b128 v[208:211], v139 offset:4096
	ds_read_b128 v[212:215], v139 offset:5120
	ds_read_b128 v[216:219], v139 offset:6144
	ds_read_b128 v[220:223], v139 offset:7168
	s_mov_b64 s[46:47], -1
	s_and_b64 vcc, exec, s[44:45]
	s_cbranch_vccz .LBB0_1344
	s_mov_b32 s39, s92
	s_ashr_i32 s31, s30, 31
	s_ashr_i32 s35, s34, 31
	s_lshl_b64 s[4:5], s[30:31], 20
	s_lshl_b64 s[44:45], s[34:35], 9
	s_lshl_b64 s[38:39], s[38:39], 23
	v_readlane_b32 s46, v251, 28
	v_readlane_b32 s47, v251, 29
	s_add_u32 s17, s46, s44
	s_addc_u32 s27, s47, s45
	s_add_u32 s17, s17, s38
	s_addc_u32 s27, s27, s39
	s_add_u32 s4, s17, s4
	s_addc_u32 s5, s27, s5
	s_add_u32 s4, s4, 0xfc000000
	s_addc_u32 s5, s5, -1
	s_mov_b64 s[46:47], 0

; __device__ __forceinline__ float bf_lo(unsigned u) { return __uint_as_float(u << 16); }
; __device__ __forceinline__ float bf_hi(unsigned u) { return __uint_as_float(u & 0xffff0000u); }
; __device__ __forceinline__ void final_norm_phase(Frame& F) {
;     ...
;         f32x4* xr = (f32x4*)(F.out + (size_t)r * D) + lane; const u32x2* xb = (const u32x2*)((const bf16_t*)(F.ws + WS_XB) + (size_t)r * D) + lane;
;         const u32x2* yp = (const u32x2*)((const bf16_t*)(F.ws + WS_Y) + (size_t)r * D) + lane; const u32x2* yp2 = (const u32x2*)((const bf16_t*)(F.ws + WS_Y2) + (size_t)r * D) + lane;
;         const f32x4* gq = (const f32x4*)((const float*)(F.ws + WS_MOD) + ((size_t)(DEPTH - 1) * 9 + (r >> 11)) * MODW + 2 * D) + lane; const f32x4* gq2 = gq + 3 * D / 4;
;         f32x4 v[8]; float ss = 0.f;
; #pragma unroll
;         for (int j = 0; j < 8; ++j) { const u32x2 yy = __builtin_nontemporal_load(yp + 64 * j), y2 = __builtin_nontemporal_load(yp2 + 64 * j);
;             const f32x4 y4 = {bf_lo(yy.x), bf_hi(yy.x), bf_lo(yy.y), bf_hi(yy.y)}, z4 = {bf_lo(y2.x), bf_hi(y2.x), bf_lo(y2.y), bf_hi(y2.y)};
;             const u32x2 xw = __builtin_nontemporal_load(xb + 64 * j); v[j] = (f32x4){bf_lo(xw.x), bf_hi(xw.x), bf_lo(xw.y), bf_hi(xw.y)} + gq[64 * j] * y4; v[j] += gq2[64 * j] * z4;
;             ss += (v[j].x * v[j].x + v[j].y * v[j].y) + (v[j].z * v[j].z + v[j].w * v[j].w); }
.LBB0_1402:
	s_ashr_i32 s9, s14, 11
	s_add_i32 s9, s9, 27
	v_add_co_u32_e32 v28, vcc, 0xdd00000, v16
	s_mul_hi_i32 s11, s9, 0xc000
	s_mul_i32 s9, s9, 0xc000
	v_addc_co_u32_e32 v29, vcc, 0, v17, vcc
	s_add_u32 s10, s66, s9
	v_add_co_u32_e32 v34, vcc, s4, v16
	s_addc_u32 s11, s67, s11
	s_nop 0
	v_addc_co_u32_e32 v35, vcc, 0, v17, vcc
	v_lshl_add_u64 v[66:67], v[4:5], 4, s[10:11]
	v_lshl_add_u64 v[42:43], v[66:67], 0, s[2:3]
	v_add_co_u32_e32 v62, vcc, s6, v66
	global_load_dwordx2 v[20:21], v[16:17], off nt
	global_load_dwordx2 v[22:23], v[16:17], off offset:512 nt
	global_load_dwordx2 v[24:25], v[16:17], off offset:1024 nt
	global_load_dwordx2 v[26:27], v[16:17], off offset:1536 nt
	global_load_dwordx2 v[30:31], v[16:17], off offset:2048 nt
	global_load_dwordx2 v[98:99], v[16:17], off offset:2560 nt
	global_load_dwordx2 v[100:101], v[16:17], off offset:3072 nt
	global_load_dwordx2 v[102:103], v[16:17], off offset:3584 nt
	global_load_dwordx4 v[0:3], v[6:7], off
	global_load_dwordx2 v[104:105], v[28:29], off nt
	global_load_dwordx2 v[106:107], v[28:29], off offset:512 nt
	global_load_dwordx2 v[108:109], v[28:29], off offset:1024 nt
	global_load_dwordx2 v[110:111], v[28:29], off offset:1536 nt
	global_load_dwordx2 v[112:113], v[28:29], off offset:2048 nt
	global_load_dwordx2 v[114:115], v[28:29], off offset:2560 nt
	global_load_dwordx2 v[116:117], v[28:29], off offset:3072 nt
	s_nop 0
	global_load_dwordx2 v[28:29], v[28:29], off offset:3584 nt
	s_nop 0
	global_load_dwordx2 v[118:119], v[34:35], off nt
	global_load_dwordx2 v[120:121], v[34:35], off offset:512 nt
	global_load_dwordx2 v[122:123], v[34:35], off offset:1024 nt
	global_load_dwordx2 v[124:125], v[34:35], off offset:1536 nt
	global_load_dwordx2 v[126:127], v[34:35], off offset:2048 nt
	global_load_dwordx2 v[128:129], v[34:35], off offset:2560 nt
	global_load_dwordx2 v[130:131], v[34:35], off offset:3072 nt
	global_load_dwordx2 v[132:133], v[34:35], off offset:3584 nt
	v_addc_co_u32_e32 v63, vcc, 0, v67, vcc
	global_load_dwordx4 v[34:37], v[42:43], off offset:1024
	global_load_dwordx4 v[38:41], v[42:43], off offset:2048
	s_nop 0
	global_load_dwordx4 v[42:45], v[42:43], off offset:3072
	s_nop 0
	global_load_dwordx4 v[46:49], v[62:63], off offset:-4096
	v_add_co_u32_e32 v74, vcc, s5, v66
	global_load_dwordx4 v[50:53], v[62:63], off
	global_load_dwordx4 v[54:57], v[62:63], off offset:1024
	global_load_dwordx4 v[58:61], v[62:63], off offset:2048
	s_nop 0
	global_load_dwordx4 v[62:65], v[62:63], off offset:3072
	v_addc_co_u32_e32 v75, vcc, 0, v67, vcc
	v_add_co_u32_e32 v94, vcc, s7, v66
	v_mov_b32_e32 v182, 0
	s_nop 0
	v_addc_co_u32_e32 v95, vcc, 0, v67, vcc
	global_load_dwordx4 v[66:69], v[74:75], off offset:1024
	global_load_dwordx4 v[70:73], v[74:75], off offset:2048
	s_nop 0
	global_load_dwordx4 v[74:77], v[74:75], off offset:3072
	s_nop 0
	global_load_dwordx4 v[78:81], v[94:95], off offset:-4096
	global_load_dwordx4 v[82:85], v[94:95], off
	global_load_dwordx4 v[86:89], v[94:95], off offset:1024
	global_load_dwordx4 v[90:93], v[94:95], off offset:2048
	s_nop 0
	global_load_dwordx4 v[94:97], v[94:95], off offset:3072
	v_mov_b32_e32 v183, 0
	s_add_i32 s14, s14, s72
	v_lshl_add_u64 v[16:17], v[16:17], 0, s[0:1]
	s_cmpk_lt_i32 s14, 0x4000
	s_waitcnt vmcnt(31)
	v_lshlrev_b32_e32 v150, 16, v104
	v_and_b32_e32 v151, 0xffff0000, v104
	v_lshlrev_b32_e32 v104, 16, v105
	v_and_b32_e32 v105, 0xffff0000, v105
	s_waitcnt vmcnt(30)
	v_lshlrev_b32_e32 v152, 16, v106
	v_and_b32_e32 v153, 0xffff0000, v106
	v_lshlrev_b32_e32 v106, 16, v107
	v_and_b32_e32 v107, 0xffff0000, v107
	s_waitcnt vmcnt(29)
	v_lshlrev_b32_e32 v154, 16, v108
	v_and_b32_e32 v155, 0xffff0000, v108
	v_lshlrev_b32_e32 v108, 16, v109
	v_and_b32_e32 v109, 0xffff0000, v109
	s_waitcnt vmcnt(23)
	v_lshlrev_b32_e32 v166, 16, v118
	v_and_b32_e32 v167, 0xffff0000, v118
	v_lshlrev_b32_e32 v118, 16, v119
	v_and_b32_e32 v119, 0xffff0000, v119
	s_waitcnt vmcnt(22)
	v_lshlrev_b32_e32 v168, 16, v120
	v_and_b32_e32 v169, 0xffff0000, v120
	v_lshlrev_b32_e32 v120, 16, v121
	v_and_b32_e32 v121, 0xffff0000, v121
	s_waitcnt vmcnt(21)
	v_lshlrev_b32_e32 v170, 16, v122
	v_and_b32_e32 v171, 0xffff0000, v122
	v_lshlrev_b32_e32 v122, 16, v123
	v_and_b32_e32 v123, 0xffff0000, v123
	v_lshlrev_b32_e32 v134, 16, v20
	v_and_b32_e32 v135, 0xffff0000, v20
	v_lshlrev_b32_e32 v20, 16, v21
	v_and_b32_e32 v21, 0xffff0000, v21
	v_lshlrev_b32_e32 v136, 16, v22
	v_and_b32_e32 v137, 0xffff0000, v22
	v_lshlrev_b32_e32 v22, 16, v23
	v_and_b32_e32 v23, 0xffff0000, v23
	v_lshlrev_b32_e32 v138, 16, v24
	v_and_b32_e32 v139, 0xffff0000, v24
	v_lshlrev_b32_e32 v24, 16, v25
	v_and_b32_e32 v25, 0xffff0000, v25
	v_lshlrev_b32_e32 v156, 16, v110
	v_and_b32_e32 v157, 0xffff0000, v110
	v_lshlrev_b32_e32 v110, 16, v111
	v_and_b32_e32 v111, 0xffff0000, v111
	s_waitcnt vmcnt(20)
	v_lshlrev_b32_e32 v172, 16, v124
	v_and_b32_e32 v173, 0xffff0000, v124
	v_lshlrev_b32_e32 v124, 16, v125
	v_and_b32_e32 v125, 0xffff0000, v125
	s_waitcnt vmcnt(15)
	v_pk_fma_f32 v[36:37], v[36:37], v[106:107], v[120:121]
	v_pk_fma_f32 v[34:35], v[34:35], v[152:153], v[168:169]
	s_waitcnt vmcnt(14)
	v_pk_fma_f32 v[40:41], v[40:41], v[108:109], v[122:123]
	s_waitcnt vmcnt(12)
	v_pk_fma_f32 v[46:47], v[46:47], v[150:151], v[166:167]
	v_pk_fma_f32 v[48:49], v[48:49], v[104:105], v[118:119]
	v_lshlrev_b32_e32 v140, 16, v26
	v_and_b32_e32 v141, 0xffff0000, v26
	v_lshlrev_b32_e32 v26, 16, v27
	v_and_b32_e32 v27, 0xffff0000, v27
	v_pk_fma_f32 v[38:39], v[38:39], v[154:155], v[170:171]
	v_pk_fma_f32 v[44:45], v[44:45], v[110:111], v[124:125]
	s_waitcnt vmcnt(7)
; __device__ __forceinline__ float bf_lo(unsigned u) { return __uint_as_float(u << 16); }
; __device__ __forceinline__ float bf_hi(unsigned u) { return __uint_as_float(u & 0xffff0000u); }
; __device__ __forceinline__ void final_norm_phase(Frame& F) {
;     ...
;         for (int j = 0; j < 8; ++j) { const u32x2 yy = __builtin_nontemporal_load(yp + 64 * j), y2 = __builtin_nontemporal_load(yp2 + 64 * j);
;             const f32x4 y4 = {bf_lo(yy.x), bf_hi(yy.x), bf_lo(yy.y), bf_hi(yy.y)}, z4 = {bf_lo(y2.x), bf_hi(y2.x), bf_lo(y2.y), bf_hi(y2.y)};
;             const u32x2 xw = __builtin_nontemporal_load(xb + 64 * j); v[j] = (f32x4){bf_lo(xw.x), bf_hi(xw.x), bf_lo(xw.y), bf_hi(xw.y)} + gq[64 * j] * y4; v[j] += gq2[64 * j] * z4;
;             ss += (v[j].x * v[j].x + v[j].y * v[j].y) + (v[j].z * v[j].z + v[j].w * v[j].w); }
	v_pk_fma_f32 v[22:23], v[68:69], v[22:23], v[36:37]
	v_pk_fma_f32 v[34:35], v[66:67], v[136:137], v[34:35]
	s_waitcnt vmcnt(6)
	v_pk_fma_f32 v[24:25], v[72:73], v[24:25], v[40:41]
	s_waitcnt vmcnt(4)
	v_pk_fma_f32 v[20:21], v[80:81], v[20:21], v[48:49]
	v_pk_fma_f32 v[40:41], v[78:79], v[134:135], v[46:47]
	v_lshlrev_b32_e32 v164, 16, v28
	v_and_b32_e32 v165, 0xffff0000, v28
	v_lshlrev_b32_e32 v28, 16, v29
	v_and_b32_e32 v29, 0xffff0000, v29
	v_lshlrev_b32_e32 v180, 16, v132
	v_and_b32_e32 v181, 0xffff0000, v132
	v_lshlrev_b32_e32 v132, 16, v133
	v_and_b32_e32 v133, 0xffff0000, v133
	v_pk_fma_f32 v[42:43], v[42:43], v[156:157], v[172:173]
	v_pk_fma_f32 v[36:37], v[70:71], v[138:139], v[38:39]
	v_pk_fma_f32 v[26:27], v[76:77], v[26:27], v[44:45]
	v_mov_b32_e32 v45, v35
	v_mov_b32_e32 v49, v23
	v_mov_b32_e32 v44, v41
	v_mov_b32_e32 v48, v21
	v_lshlrev_b32_e32 v158, 16, v112
	v_and_b32_e32 v159, 0xffff0000, v112
	v_lshlrev_b32_e32 v112, 16, v113
	v_and_b32_e32 v113, 0xffff0000, v113
	v_lshlrev_b32_e32 v174, 16, v126
	v_and_b32_e32 v175, 0xffff0000, v126
	v_lshlrev_b32_e32 v126, 16, v127
	v_and_b32_e32 v127, 0xffff0000, v127
	v_pk_fma_f32 v[28:29], v[64:65], v[28:29], v[132:133]
	v_pk_fma_f32 v[38:39], v[74:75], v[140:141], v[42:43]
	v_mov_b32_e32 v43, v34
	v_mov_b32_e32 v47, v22
	v_pk_mul_f32 v[64:65], v[24:25], v[24:25]
	v_pk_mul_f32 v[66:67], v[36:37], v[36:37]
	v_mov_b32_e32 v42, v40
	v_mov_b32_e32 v46, v20
	v_pk_mul_f32 v[44:45], v[44:45], v[44:45]
	v_pk_mul_f32 v[48:49], v[48:49], v[48:49]
	v_lshlrev_b32_e32 v142, 16, v30
	v_and_b32_e32 v143, 0xffff0000, v30
	v_lshlrev_b32_e32 v30, 16, v31
	v_and_b32_e32 v31, 0xffff0000, v31
	v_lshlrev_b32_e32 v160, 16, v114
	v_and_b32_e32 v161, 0xffff0000, v114
	v_lshlrev_b32_e32 v114, 16, v115
	v_and_b32_e32 v115, 0xffff0000, v115
	v_lshlrev_b32_e32 v176, 16, v128
	v_and_b32_e32 v177, 0xffff0000, v128
	v_lshlrev_b32_e32 v128, 16, v129
	v_and_b32_e32 v129, 0xffff0000, v129
	v_pk_fma_f32 v[50:51], v[50:51], v[158:159], v[174:175]
	v_pk_fma_f32 v[52:53], v[52:53], v[112:113], v[126:127]
	v_pk_mov_b32 v[70:71], v[66:67], v[64:65] op_sel:[1,0]
	v_mov_b32_e32 v67, v65
	v_pk_fma_f32 v[42:43], v[42:43], v[42:43], v[44:45]
	v_pk_fma_f32 v[44:45], v[46:47], v[46:47], v[48:49]
	v_lshlrev_b32_e32 v144, 16, v98
	v_and_b32_e32 v145, 0xffff0000, v98
	v_lshlrev_b32_e32 v98, 16, v99
	v_and_b32_e32 v99, 0xffff0000, v99
	v_pk_fma_f32 v[54:55], v[54:55], v[160:161], v[176:177]
	v_pk_fma_f32 v[56:57], v[56:57], v[114:115], v[128:129]
	s_waitcnt vmcnt(3)
	v_pk_fma_f32 v[30:31], v[84:85], v[30:31], v[52:53]
	v_pk_fma_f32 v[50:51], v[82:83], v[142:143], v[50:51]
	v_mul_f32_e32 v52, v39, v39
	v_mul_f32_e32 v68, v27, v27
	v_pk_add_f32 v[66:67], v[70:71], v[66:67]
	v_pk_add_f32 v[42:43], v[42:43], v[44:45]
	v_lshlrev_b32_e32 v162, 16, v116
	v_and_b32_e32 v163, 0xffff0000, v116
	v_lshlrev_b32_e32 v116, 16, v117
	v_and_b32_e32 v117, 0xffff0000, v117
	v_lshlrev_b32_e32 v178, 16, v130
	v_and_b32_e32 v179, 0xffff0000, v130
	v_lshlrev_b32_e32 v130, 16, v131
	v_and_b32_e32 v131, 0xffff0000, v131
	s_waitcnt vmcnt(2)
	v_pk_fma_f32 v[56:57], v[88:89], v[98:99], v[56:57]
	v_pk_fma_f32 v[54:55], v[86:87], v[144:145], v[54:55]
	v_mul_f32_e32 v77, v50, v50
	v_mul_f32_e32 v78, v51, v51
	v_mul_f32_e32 v75, v30, v30
	v_mul_f32_e32 v79, v31, v31
	v_pk_fma_f32 v[52:53], v[38:39], v[38:39], v[52:53] op_sel_hi:[1,1,0]
	v_pk_fma_f32 v[64:65], v[26:27], v[26:27], v[68:69] op_sel_hi:[1,1,0]
	v_pk_add_f32 v[46:47], v[66:67], v[66:67] op_sel:[0,1] op_sel_hi:[1,0]
	v_pk_add_f32 v[42:43], v[42:43], v[42:43] op_sel:[0,1] op_sel_hi:[1,0]
	v_lshlrev_b32_e32 v146, 16, v100
	v_and_b32_e32 v147, 0xffff0000, v100
	v_lshlrev_b32_e32 v100, 16, v101
	v_and_b32_e32 v101, 0xffff0000, v101
	v_pk_fma_f32 v[58:59], v[58:59], v[162:163], v[178:179]
	v_pk_fma_f32 v[60:61], v[60:61], v[116:117], v[130:131]
	v_pk_mul_f32 v[68:69], v[54:55], v[54:55]
	v_pk_mul_f32 v[72:73], v[56:57], v[56:57]
	v_mov_b32_e32 v53, v75
	v_mov_b32_e32 v65, v79
	v_mov_b32_e32 v47, v78
	v_mov_b32_e32 v43, v77
	v_lshlrev_b32_e32 v148, 16, v102
	v_and_b32_e32 v149, 0xffff0000, v102
	v_lshlrev_b32_e32 v102, 16, v103
	v_and_b32_e32 v103, 0xffff0000, v103
	v_pk_fma_f32 v[62:63], v[62:63], v[164:165], v[180:181]
	s_waitcnt vmcnt(1)
; #define WS_SHR(c) v += __builtin_bit_cast(float, __builtin_amdgcn_update_dpp(0, __builtin_bit_cast(int, v), c, 0xf, 0xf, true))
; __device__ __forceinline__ float wave_sum(float v, int lane) {
;     ...
;     WS_SHR(0x111); WS_SHR(0x112); WS_SHR(0x114); WS_SHR(0x118);
;     ...
;     v += __builtin_bit_cast(float, __builtin_amdgcn_update_dpp(0, __builtin_bit_cast(int, v), 0x142, 0xa, 0xf, false));
;     v += __builtin_bit_cast(float, __builtin_amdgcn_update_dpp(0, __builtin_bit_cast(int, v), 0x143, 0xc, 0xf, false));
;     return __builtin_bit_cast(float, __builtin_amdgcn_readlane(__builtin_bit_cast(int, v), 63));
; __device__ __forceinline__ void final_norm_phase(Frame& F) {
;     ...
;             ss += (v[j].x * v[j].x + v[j].y * v[j].y) + (v[j].z * v[j].z + v[j].w * v[j].w); }
;         const float rstd = rsqrtf(wave_sum(ss, lane) * (1.0f / D) + EPS);
; #pragma unroll
;         for (int j = 0; j < 8; ++j) xr[64 * j] = v[j] * rstd * gp[64 * j];
	v_pk_fma_f32 v[60:61], v[92:93], v[100:101], v[60:61]
	v_pk_fma_f32 v[58:59], v[90:91], v[146:147], v[58:59]
	v_pk_mov_b32 v[70:71], v[68:69], v[72:73] op_sel:[1,0]
	v_mov_b32_e32 v69, v73
	v_pk_add_f32 v[48:49], v[52:53], v[64:65]
	v_pk_add_f32 v[42:43], v[42:43], v[46:47]
	s_waitcnt vmcnt(0)
	v_pk_fma_f32 v[28:29], v[96:97], v[102:103], v[28:29]
	v_pk_fma_f32 v[62:63], v[94:95], v[148:149], v[62:63]
	v_mul_f32_e32 v74, v59, v59
	v_mul_f32_e32 v76, v61, v61
	v_pk_add_f32 v[52:53], v[70:71], v[68:69]
	v_pk_add_f32 v[42:43], v[42:43], v[48:49]
	v_mul_f32_e32 v80, v62, v62
	v_mul_f32_e32 v81, v63, v63
	v_mul_f32_e32 v82, v28, v28
	v_mul_f32_e32 v83, v29, v29
	v_pk_fma_f32 v[72:73], v[58:59], v[58:59], v[74:75] op_sel_hi:[1,1,0]
	v_pk_fma_f32 v[74:75], v[60:61], v[60:61], v[76:77] op_sel_hi:[1,1,0]
	v_pk_add_f32 v[44:45], v[52:53], v[52:53] op_sel:[0,1] op_sel_hi:[1,0]
	v_pk_add_f32 v[42:43], v[42:43], v[42:43] op_sel:[0,1] op_sel_hi:[1,0]
	v_mov_b32_e32 v73, v82
	v_mov_b32_e32 v75, v83
	v_mov_b32_e32 v45, v81
	v_mov_b32_e32 v43, v80
	v_pk_add_f32 v[52:53], v[72:73], v[74:75]
	v_pk_add_f32 v[42:43], v[42:43], v[44:45]
	s_nop 0
	v_pk_add_f32 v[42:43], v[42:43], v[52:53]
	s_nop 0
	v_add_f32_e32 v42, v42, v43
	s_nop 1
	v_add_f32_dpp v42, v42, v42 row_shr:1 row_mask:0xf bank_mask:0xf bound_ctrl:1
	s_nop 1
	v_add_f32_dpp v42, v42, v42 row_shr:2 row_mask:0xf bank_mask:0xf bound_ctrl:1
	s_nop 1
	v_add_f32_dpp v42, v42, v42 row_shr:4 row_mask:0xf bank_mask:0xf bound_ctrl:1
	s_nop 1
	v_add_f32_dpp v42, v42, v42 row_shr:8 row_mask:0xf bank_mask:0xf bound_ctrl:1
	s_nop 1
	v_mov_b32_dpp v182, v42 row_bcast:15 row_mask:0xa bank_mask:0xf
	v_add_f32_e32 v42, v42, v182
	s_nop 1
	v_mov_b32_dpp v183, v42 row_bcast:31 row_mask:0xc bank_mask:0xf
	v_add_f32_e32 v42, v42, v183
	s_nop 0
	v_readlane_b32 s9, v42, 63
	s_nop 1
	v_fma_f32 v42, s9, v33, v32
	v_mul_f32_e32 v43, 0x4b800000, v42
	v_cmp_gt_f32_e32 vcc, s8, v42
	s_nop 1
	v_cndmask_b32_e32 v42, v42, v43, vcc
	v_rsq_f32_e32 v42, v42
	s_nop 0
	v_mul_f32_e32 v43, 0x45800000, v42
	v_cndmask_b32_e32 v42, v42, v43, vcc
	v_pk_mul_f32 v[40:41], v[40:41], v[42:43] op_sel_hi:[1,0]
	v_pk_mul_f32 v[20:21], v[20:21], v[42:43] op_sel_hi:[1,0]
	v_pk_mul_f32 v[0:1], v[0:1], v[40:41]
	v_pk_mul_f32 v[2:3], v[2:3], v[20:21]
	global_store_dwordx4 v[18:19], v[0:3], off offset:-4096 sc1
	v_pk_mul_f32 v[20:21], v[22:23], v[42:43] op_sel_hi:[1,0]
	v_pk_mul_f32 v[22:23], v[34:35], v[42:43] op_sel_hi:[1,0]
	v_pk_mul_f32 v[2:3], v[186:187], v[20:21]
	v_pk_mul_f32 v[0:1], v[184:185], v[22:23]
	global_store_dwordx4 v[18:19], v[0:3], off offset:-3072 sc1
	v_pk_mul_f32 v[20:21], v[24:25], v[42:43] op_sel_hi:[1,0]
	v_pk_mul_f32 v[22:23], v[36:37], v[42:43] op_sel_hi:[1,0]
	v_pk_mul_f32 v[2:3], v[190:191], v[20:21]
	v_pk_mul_f32 v[0:1], v[188:189], v[22:23]
	global_store_dwordx4 v[18:19], v[0:3], off offset:-2048 sc1
	v_pk_mul_f32 v[20:21], v[26:27], v[42:43] op_sel_hi:[1,0]
	v_pk_mul_f32 v[22:23], v[38:39], v[42:43] op_sel_hi:[1,0]
	v_pk_mul_f32 v[2:3], v[194:195], v[20:21]
	v_pk_mul_f32 v[0:1], v[192:193], v[22:23]
	global_store_dwordx4 v[18:19], v[0:3], off offset:-1024 sc1
	v_pk_mul_f32 v[20:21], v[30:31], v[42:43] op_sel_hi:[1,0]
	v_pk_mul_f32 v[22:23], v[50:51], v[42:43] op_sel_hi:[1,0]
	v_pk_mul_f32 v[2:3], v[198:199], v[20:21]
	v_pk_mul_f32 v[0:1], v[196:197], v[22:23]
	global_store_dwordx4 v[18:19], v[0:3], off sc1
	v_pk_mul_f32 v[20:21], v[56:57], v[42:43] op_sel_hi:[1,0]
	v_pk_mul_f32 v[22:23], v[54:55], v[42:43] op_sel_hi:[1,0]
	v_pk_mul_f32 v[2:3], v[20:21], v[202:203]
	v_pk_mul_f32 v[0:1], v[22:23], v[200:201]
	global_store_dwordx4 v[18:19], v[0:3], off offset:1024 sc1
	v_pk_mul_f32 v[20:21], v[60:61], v[42:43] op_sel_hi:[1,0]
	v_pk_mul_f32 v[22:23], v[58:59], v[42:43] op_sel_hi:[1,0]
	v_pk_mul_f32 v[2:3], v[20:21], v[206:207]
	v_pk_mul_f32 v[0:1], v[22:23], v[204:205]
	global_store_dwordx4 v[18:19], v[0:3], off offset:2048 sc1
	v_pk_mul_f32 v[20:21], v[28:29], v[42:43] op_sel_hi:[1,0]
	v_pk_mul_f32 v[22:23], v[62:63], v[42:43] op_sel_hi:[1,0]
	v_pk_mul_f32 v[2:3], v[20:21], v[210:211]
	v_pk_mul_f32 v[0:1], v[22:23], v[208:209]
	global_store_dwordx4 v[18:19], v[0:3], off offset:3072 sc1
	v_lshl_add_u64 v[18:19], v[18:19], 0, s[16:17]
	s_cbranch_scc1 .LBB0_1402
